# v9 + instruction selection: 151 f32->bf16 RNE bit-trick packs (bfe/add3/lshr/and_or) replaced by v_cvt_pk_bf16_f32, 630 dead chain instructions removed (hazard-window checked)
# speedup vs baseline: 1.0212x; 1.0020x over previous
; #define LAS __attribute__((address_space(3)))
; __device__ __forceinline__ unsigned pk2(float lo, float hi) { return f2bf(lo) | (f2bf(hi) << 16); }
; template <bool PHASE_B>
; __device__ __forceinline__ void lru_item(const Params& p, LAS unsigned char* lds, int ci, int ci_next, int jb, const int tid, v4u (&xvn)[3]) {
;     ...
;     const LAS float* CW = (const LAS float*)(lds + LR_CW); const LAS float* CB = (const LAS float*)(lds + LR_CB); const LAS float* GC = (const LAS float*)(lds + LR_GC);
;     bf16x8 af[2];
; #pragma unroll
;     for (int ks = 0; ks < 2; ++ks) { const int cb0 = 32 * ks + 8 * fq;
;         f32x4 s0 = *(const LAS f32x4*)(CB + cb0), s1 = *(const LAS f32x4*)(CB + cb0 + 4);
; #pragma unroll
;         for (int tap = 0; tap < 4; ++tap) { const v4u v = *(const LAS v4u*)(lds + LR_XR + (16 * rt + fr + tap) * 144 + cb0 * 2);
;             const f32x4 w0 = *(const LAS f32x4*)(CW + tap * 64 + cb0), w1 = *(const LAS f32x4*)(CW + tap * 64 + cb0 + 4);
;             s0 += (f32x4){bflo(v.x), bfhi(v.x), bflo(v.y), bfhi(v.y)} * w0; s1 += (f32x4){bflo(v.z), bfhi(v.z), bflo(v.w), bfhi(v.w)} * w1; }
;         v4u o; o.x = pk2(s0[0], s0[1]); o.y = pk2(s0[2], s0[3]); o.z = pk2(s1[0], s1[1]); o.w = pk2(s1[2], s1[3]);
;         af[ks] = __builtin_bit_cast(bf16x8, o); }
.LBB0_339:
	v_add_u32_e32 v1, v167, v157
	ds_read_b128 v[14:17], v165 offset:56832
	ds_read_b128 v[18:21], v165 offset:56848
	ds_read_b128 v[22:25], v1
	v_add_u32_e32 v31, v167, v166
	ds_read_b128 v[26:29], v31 offset:55808
	ds_read_b128 v[36:39], v31 offset:55824
	v_add_u32_e32 v50, 0xd800, v170
	v_add_u32_e32 v51, 0xdc00, v170
	s_waitcnt lgkmcnt(2)
	v_lshlrev_b32_e32 v40, 16, v22
	v_and_b32_e32 v41, 0xffff0000, v22
	v_lshlrev_b32_e32 v22, 16, v23
	v_and_b32_e32 v23, 0xffff0000, v23
	s_waitcnt lgkmcnt(1)
	v_pk_fma_f32 v[28:29], v[28:29], v[22:23], v[16:17]
	v_pk_fma_f32 v[26:27], v[26:27], v[40:41], v[14:15]
	v_lshlrev_b32_e32 v14, 16, v24
	v_and_b32_e32 v15, 0xffff0000, v24
	v_lshlrev_b32_e32 v16, 16, v25
	v_and_b32_e32 v17, 0xffff0000, v25
	s_waitcnt lgkmcnt(0)
	v_pk_fma_f32 v[38:39], v[38:39], v[16:17], v[20:21]
	v_pk_fma_f32 v[36:37], v[36:37], v[14:15], v[18:19]
	ds_read_b128 v[14:17], v1 offset:144
	ds_read_b128 v[18:21], v31 offset:56064
	ds_read_b128 v[22:25], v31 offset:56080
	v_add_u32_e32 v132, v173, v166
	s_and_b64 vcc, exec, s[6:7]
	s_waitcnt lgkmcnt(2)
	v_lshlrev_b32_e32 v40, 16, v14
	v_and_b32_e32 v41, 0xffff0000, v14
	v_lshlrev_b32_e32 v14, 16, v15
	v_and_b32_e32 v15, 0xffff0000, v15
	s_waitcnt lgkmcnt(1)
	v_pk_fma_f32 v[28:29], v[20:21], v[14:15], v[28:29]
	v_lshlrev_b32_e32 v14, 16, v16
	v_and_b32_e32 v15, 0xffff0000, v16
	v_lshlrev_b32_e32 v16, 16, v17
	v_and_b32_e32 v17, 0xffff0000, v17
	v_pk_fma_f32 v[26:27], v[18:19], v[40:41], v[26:27]
	s_waitcnt lgkmcnt(0)
	v_pk_fma_f32 v[38:39], v[24:25], v[16:17], v[38:39]
	v_pk_fma_f32 v[36:37], v[22:23], v[14:15], v[36:37]
	ds_read_b128 v[14:17], v1 offset:288
	ds_read_b128 v[18:21], v31 offset:56320
	ds_read_b128 v[22:25], v31 offset:56336
	s_waitcnt lgkmcnt(2)
	v_lshlrev_b32_e32 v40, 16, v14
	v_and_b32_e32 v41, 0xffff0000, v14
	v_lshlrev_b32_e32 v14, 16, v15
	v_and_b32_e32 v15, 0xffff0000, v15
	s_waitcnt lgkmcnt(1)
	v_pk_fma_f32 v[28:29], v[20:21], v[14:15], v[28:29]
	v_lshlrev_b32_e32 v14, 16, v16
	v_and_b32_e32 v15, 0xffff0000, v16
	v_lshlrev_b32_e32 v16, 16, v17
	v_and_b32_e32 v17, 0xffff0000, v17
	v_pk_fma_f32 v[26:27], v[18:19], v[40:41], v[26:27]
	s_waitcnt lgkmcnt(0)
	v_pk_fma_f32 v[36:37], v[22:23], v[14:15], v[36:37]
	v_pk_fma_f32 v[38:39], v[24:25], v[16:17], v[38:39]
	ds_read_b128 v[14:17], v1 offset:432
	ds_read_b128 v[18:21], v31 offset:56576
	ds_read_b128 v[22:25], v31 offset:56592
	s_waitcnt lgkmcnt(2)
	v_lshlrev_b32_e32 v40, 16, v14
	v_and_b32_e32 v41, 0xffff0000, v14
	v_lshlrev_b32_e32 v14, 16, v15
	v_and_b32_e32 v15, 0xffff0000, v15
	s_waitcnt lgkmcnt(1)
	v_pk_fma_f32 v[20:21], v[20:21], v[14:15], v[28:29]
	v_pk_fma_f32 v[14:15], v[18:19], v[40:41], v[26:27]
	v_lshlrev_b32_e32 v18, 16, v16
	v_bfe_u32 v1, v14, 16, 1
	v_add3_u32 v1, v14, v1, s33
	v_bfe_u32 v14, v15, 16, 1
	v_lshrrev_b32_e32 v1, 16, v1
	v_add3_u32 v14, v15, v14, s33
	v_and_or_b32 v14, v14, s11, v1
	v_and_b32_e32 v19, 0xffff0000, v16
	v_lshlrev_b32_e32 v16, 16, v17
	v_and_b32_e32 v17, 0xffff0000, v17
	s_waitcnt lgkmcnt(0)
	v_pk_fma_f32 v[24:25], v[24:25], v[16:17], v[38:39]
	v_pk_fma_f32 v[16:17], v[22:23], v[18:19], v[36:37]
	v_cvt_pk_bf16_f32 v15, v20, v21
	v_bfe_u32 v1, v16, 16, 1
	v_add3_u32 v1, v16, v1, s33
	v_bfe_u32 v16, v17, 16, 1
	v_lshrrev_b32_e32 v1, 16, v1
	v_add3_u32 v16, v17, v16, s33
	v_and_or_b32 v16, v16, s11, v1
	v_bfe_u32 v1, v24, 16, 1
	v_bfe_u32 v17, v25, 16, 1
	v_add3_u32 v1, v24, v1, s33
	v_add3_u32 v17, v25, v17, s33
	ds_read_b128 v[18:21], v31 offset:56960
	ds_read_b128 v[22:25], v31 offset:56976
	ds_read_b128 v[26:29], v198
	ds_read_b128 v[36:39], v31 offset:55936
	ds_read_b128 v[40:43], v31 offset:55952
	v_lshrrev_b32_e32 v1, 16, v1
	v_and_or_b32 v17, v17, s11, v1
	s_waitcnt lgkmcnt(2)
	v_lshlrev_b32_e32 v44, 16, v26
	v_and_b32_e32 v45, 0xffff0000, v26
	v_lshlrev_b32_e32 v26, 16, v27
	v_and_b32_e32 v27, 0xffff0000, v27
	s_waitcnt lgkmcnt(1)
	v_pk_fma_f32 v[38:39], v[38:39], v[26:27], v[20:21]
	v_pk_fma_f32 v[36:37], v[36:37], v[44:45], v[18:19]
	v_lshlrev_b32_e32 v18, 16, v28
	v_and_b32_e32 v19, 0xffff0000, v28
	v_lshlrev_b32_e32 v20, 16, v29
	v_and_b32_e32 v21, 0xffff0000, v29
	s_waitcnt lgkmcnt(0)
	v_pk_fma_f32 v[42:43], v[42:43], v[20:21], v[24:25]
	v_pk_fma_f32 v[40:41], v[40:41], v[18:19], v[22:23]
	ds_read_b128 v[18:21], v198 offset:144
	ds_read_b128 v[22:25], v31 offset:56192
	ds_read_b128 v[26:29], v31 offset:56208
	s_waitcnt lgkmcnt(2)
	v_lshlrev_b32_e32 v44, 16, v18
	v_and_b32_e32 v45, 0xffff0000, v18
	v_lshlrev_b32_e32 v18, 16, v19
	v_and_b32_e32 v19, 0xffff0000, v19
	s_waitcnt lgkmcnt(1)
	v_pk_fma_f32 v[38:39], v[24:25], v[18:19], v[38:39]
	v_lshlrev_b32_e32 v18, 16, v20
	v_and_b32_e32 v19, 0xffff0000, v20
	v_lshlrev_b32_e32 v20, 16, v21
	v_and_b32_e32 v21, 0xffff0000, v21
	v_pk_fma_f32 v[36:37], v[22:23], v[44:45], v[36:37]
	s_waitcnt lgkmcnt(0)
	v_pk_fma_f32 v[42:43], v[28:29], v[20:21], v[42:43]
	v_pk_fma_f32 v[40:41], v[26:27], v[18:19], v[40:41]
	ds_read_b128 v[18:21], v198 offset:288
	ds_read_b128 v[22:25], v31 offset:56448
	ds_read_b128 v[26:29], v31 offset:56464
	s_waitcnt lgkmcnt(2)
	v_lshlrev_b32_e32 v44, 16, v18
	v_and_b32_e32 v45, 0xffff0000, v18
	v_lshlrev_b32_e32 v18, 16, v19
	v_and_b32_e32 v19, 0xffff0000, v19
	s_waitcnt lgkmcnt(1)
	v_pk_fma_f32 v[38:39], v[24:25], v[18:19], v[38:39]
	v_lshlrev_b32_e32 v18, 16, v20
	v_and_b32_e32 v19, 0xffff0000, v20
	v_lshlrev_b32_e32 v20, 16, v21
	v_and_b32_e32 v21, 0xffff0000, v21
	v_pk_fma_f32 v[36:37], v[22:23], v[44:45], v[36:37]
	s_waitcnt lgkmcnt(0)
	v_pk_fma_f32 v[42:43], v[28:29], v[20:21], v[42:43]
	v_pk_fma_f32 v[40:41], v[26:27], v[18:19], v[40:41]
	ds_read_b128 v[18:21], v198 offset:432
	ds_read_b128 v[22:25], v31 offset:56704
	ds_read_b128 v[26:29], v31 offset:56720
	s_waitcnt lgkmcnt(2)
; #define LAS __attribute__((address_space(3)))
; __device__ __forceinline__ unsigned pk2(float lo, float hi) { return f2bf(lo) | (f2bf(hi) << 16); }
; template <bool PHASE_B>
; __device__ __forceinline__ void lru_item(const Params& p, LAS unsigned char* lds, int ci, int ci_next, int jb, const int tid, v4u (&xvn)[3]) {
;     ...
;     for (int ks = 0; ks < 2; ++ks) { const int cb0 = 32 * ks + 8 * fq;
;         f32x4 s0 = *(const LAS f32x4*)(CB + cb0), s1 = *(const LAS f32x4*)(CB + cb0 + 4);
; #pragma unroll
;         for (int tap = 0; tap < 4; ++tap) { const v4u v = *(const LAS v4u*)(lds + LR_XR + (16 * rt + fr + tap) * 144 + cb0 * 2);
;             const f32x4 w0 = *(const LAS f32x4*)(CW + tap * 64 + cb0), w1 = *(const LAS f32x4*)(CW + tap * 64 + cb0 + 4);
;             s0 += (f32x4){bflo(v.x), bfhi(v.x), bflo(v.y), bfhi(v.y)} * w0; s1 += (f32x4){bflo(v.z), bfhi(v.z), bflo(v.w), bfhi(v.w)} * w1; }
;         v4u o; o.x = pk2(s0[0], s0[1]); o.y = pk2(s0[2], s0[3]); o.z = pk2(s1[0], s1[1]); o.w = pk2(s1[2], s1[3]);
;         af[ks] = __builtin_bit_cast(bf16x8, o); }
;     float xc[4][4];
; #pragma unroll
;     for (int ct = 0; ct < 4; ++ct) { const int ch = 16 * ct + fr; float xr7[7];
; #pragma unroll
;         for (int j = 0; j < 7; ++j) xr7[j] = __builtin_bit_cast(float, (unsigned)(*(const LAS bf16*)(lds + LR_XR + (16 * rt + 4 * fq + j) * 144 + ch * 2)) << 16);
;         const float w0 = CW[ch], w1 = CW[64 + ch], w2 = CW[128 + ch], w3 = CW[192 + ch], b = CB[ch];
; #pragma unroll
;         for (int e = 0; e < 4; ++e) xc[ct][e] = b + xr7[e] * w0 + xr7[e + 1] * w1 + xr7[e + 2] * w2 + xr7[e + 3] * w3; }
	v_lshlrev_b32_e32 v44, 16, v18
	v_and_b32_e32 v45, 0xffff0000, v18
	v_lshlrev_b32_e32 v18, 16, v19
	v_and_b32_e32 v19, 0xffff0000, v19
	s_waitcnt lgkmcnt(1)
	v_pk_fma_f32 v[24:25], v[24:25], v[18:19], v[38:39]
	v_pk_fma_f32 v[18:19], v[22:23], v[44:45], v[36:37]
	v_lshlrev_b32_e32 v22, 16, v20
	v_bfe_u32 v1, v18, 16, 1
	v_add3_u32 v1, v18, v1, s33
	v_bfe_u32 v18, v19, 16, 1
	v_lshrrev_b32_e32 v1, 16, v1
	v_add3_u32 v18, v19, v18, s33
	v_and_or_b32 v18, v18, s11, v1
	v_and_b32_e32 v23, 0xffff0000, v20
	v_lshlrev_b32_e32 v20, 16, v21
	v_and_b32_e32 v21, 0xffff0000, v21
	s_waitcnt lgkmcnt(0)
	v_pk_fma_f32 v[28:29], v[28:29], v[20:21], v[42:43]
	v_pk_fma_f32 v[20:21], v[26:27], v[22:23], v[40:41]
	v_cvt_pk_bf16_f32 v19, v24, v25
	v_bfe_u32 v1, v20, 16, 1
	v_add3_u32 v1, v20, v1, s33
	v_bfe_u32 v20, v21, 16, 1
	v_lshrrev_b32_e32 v1, 16, v1
	v_add3_u32 v20, v21, v20, s33
	v_and_or_b32 v20, v20, s11, v1
	v_cvt_pk_bf16_f32 v21, v28, v29
	v_add_u32_e32 v1, v168, v169
	ds_read_u16 v22, v1
	s_waitcnt lgkmcnt(0)
	v_lshlrev_b32_e32 v23, 16, v22
	ds_read_u16 v22, v1 offset:144
	ds_read_u16 v31, v1 offset:288
	ds_read_u16 v38, v1 offset:432
	ds_read_u16 v39, v1 offset:576
	ds_read_u16 v46, v1 offset:720
	ds_read_u16 v1, v1 offset:864
	ds_read2_b32 v[24:25], v50 offset0:128 offset1:144
	ds_read2_b32 v[26:27], v50 offset0:192 offset1:208
	ds_read2_b32 v[28:29], v51 offset1:16
	ds_read2_b32 v[36:37], v51 offset0:64 offset1:80
	ds_read2_b32 v[40:41], v51 offset0:128 offset1:144
	s_waitcnt lgkmcnt(10)
	v_lshlrev_b32_e32 v45, 16, v22
	s_waitcnt lgkmcnt(8)
	v_lshlrev_b32_e32 v43, 16, v38
	s_waitcnt lgkmcnt(7)
	v_lshlrev_b32_e32 v42, 16, v39
	s_waitcnt lgkmcnt(3)
	v_mov_b32_e32 v38, v26
	v_mov_b32_e32 v39, v24
	v_mov_b32_e32 v22, v45
	v_pk_mul_f32 v[22:23], v[38:39], v[22:23]
	v_lshlrev_b32_e32 v44, 16, v31
	s_waitcnt lgkmcnt(0)
	v_add_f32_e32 v23, v23, v40
	v_add_f32_e32 v24, v22, v23
	v_pk_mul_f32 v[22:23], v[38:39], v[44:45]
	v_mov_b32_e32 v47, v28
	v_add_f32_e32 v23, v23, v40
	v_add_f32_e32 v26, v22, v23
	v_pk_mov_b32 v[22:23], v[42:43], v[44:45] op_sel:[1,0]
	s_nop 0
	v_pk_mul_f32 v[44:45], v[38:39], v[22:23]
	v_pk_mul_f32 v[38:39], v[38:39], v[42:43]
	v_add_f32_e32 v31, v45, v40
	v_lshlrev_b32_e32 v45, 16, v46
	v_mov_b32_e32 v46, v36
	v_pk_mul_f32 v[48:49], v[46:47], v[22:23]
	v_pk_mul_f32 v[22:23], v[46:47], v[42:43]
	v_add_f32_e32 v31, v44, v31
	v_lshlrev_b32_e32 v44, 16, v1
	v_add_f32_e32 v1, v23, v26
	v_add_f32_e32 v108, v22, v1
	v_pk_mov_b32 v[22:23], v[44:45], v[42:43] op_sel:[1,0]
	v_add_f32_e32 v39, v39, v40
	v_pk_mul_f32 v[22:23], v[46:47], v[22:23]
	v_add_f32_e32 v38, v38, v39
	v_add_f32_e32 v1, v23, v31
	v_add_f32_e32 v106, v22, v1
	v_pk_mul_f32 v[22:23], v[46:47], v[44:45]
	v_add_f32_e32 v39, v49, v24
	v_add_f32_e32 v1, v23, v38
	v_add_f32_e32 v101, v22, v1
	ds_read_u16 v1, v199
	v_add_f32_e32 v110, v48, v39
	s_waitcnt lgkmcnt(0)
	v_lshlrev_b32_e32 v23, 16, v1
	ds_read_u16 v1, v199 offset:144
	ds_read_u16 v22, v199 offset:288
	ds_read_u16 v24, v199 offset:432
	ds_read_u16 v26, v199 offset:576
	ds_read_u16 v28, v199 offset:720
	ds_read_u16 v31, v199 offset:864
	s_waitcnt lgkmcnt(3)
	v_lshlrev_b32_e32 v43, 16, v24
	v_mov_b32_e32 v24, v27
	v_lshlrev_b32_e32 v27, 16, v1
	s_waitcnt lgkmcnt(2)
	v_lshlrev_b32_e32 v42, 16, v26
	v_lshlrev_b32_e32 v26, 16, v22
	v_mov_b32_e32 v22, v27
	v_pk_mul_f32 v[22:23], v[24:25], v[22:23]
	s_nop 0
	v_add_f32_e32 v1, v23, v41
	v_add_f32_e32 v1, v22, v1
	v_pk_mul_f32 v[22:23], v[24:25], v[26:27]
	s_nop 0
	v_add_f32_e32 v23, v23, v41
	v_add_f32_e32 v36, v22, v23
	v_pk_mov_b32 v[22:23], v[42:43], v[26:27] op_sel:[1,0]
	s_nop 0
	v_pk_mul_f32 v[26:27], v[24:25], v[22:23]
	v_pk_mul_f32 v[24:25], v[24:25], v[42:43]
	v_add_f32_e32 v27, v27, v41
	v_add_f32_e32 v25, v25, v41
	v_add_f32_e32 v26, v26, v27
	v_add_f32_e32 v27, v24, v25
	s_waitcnt lgkmcnt(1)
	v_lshlrev_b32_e32 v25, 16, v28
	v_mov_b32_e32 v28, v37
	v_pk_mul_f32 v[64:65], v[28:29], v[22:23]
	v_pk_mul_f32 v[22:23], v[28:29], v[42:43]
	s_waitcnt lgkmcnt(0)
	v_lshlrev_b32_e32 v24, 16, v31
	v_add_f32_e32 v57, v65, v1
	v_add_f32_e32 v1, v23, v36
	v_add_f32_e32 v120, v22, v1
	v_pk_mov_b32 v[22:23], v[24:25], v[42:43] op_sel:[1,0]
	v_add_f32_e32 v122, v64, v57
	v_pk_mul_f32 v[22:23], v[28:29], v[22:23]
	s_nop 0
	v_add_f32_e32 v1, v23, v26
	v_add_f32_e32 v118, v22, v1
	v_pk_mul_f32 v[22:23], v[28:29], v[24:25]
	s_nop 0
	v_add_f32_e32 v1, v23, v27
	v_add_f32_e32 v113, v22, v1
	ds_read_u16 v1, v200
	s_waitcnt lgkmcnt(0)
	v_lshlrev_b32_e32 v23, 16, v1
	ds_read_u16 v1, v200 offset:144
	ds_read_u16 v22, v200 offset:288
	ds_read_u16 v31, v200 offset:432
	ds_read_u16 v38, v200 offset:576
	ds_read_u16 v49, v200 offset:720
	ds_read_u16 v52, v200 offset:864
	ds_read2_b32 v[24:25], v50 offset0:160 offset1:176
	ds_read2_b32 v[26:27], v50 offset0:224 offset1:240
	ds_read2_b32 v[28:29], v51 offset0:32 offset1:48
	ds_read2_b32 v[36:37], v51 offset0:96 offset1:112
	ds_read2_b32 v[40:41], v51 offset0:160 offset1:176
	s_waitcnt lgkmcnt(10)
	v_lshlrev_b32_e32 v47, 16, v1
	s_waitcnt lgkmcnt(3)
	v_mov_b32_e32 v44, v26
	v_mov_b32_e32 v45, v24
	v_lshlrev_b32_e32 v46, 16, v22
	v_mov_b32_e32 v22, v47
	v_pk_mul_f32 v[22:23], v[44:45], v[22:23]
	v_lshlrev_b32_e32 v43, 16, v31
	s_waitcnt lgkmcnt(0)
; template <bool PHASE_B>
; __device__ __forceinline__ void lru_item(const Params& p, LAS unsigned char* lds, int ci, int ci_next, int jb, const int tid, v4u (&xvn)[3]) {
;     ...
;     for (int ct = 0; ct < 4; ++ct) { const int ch = 16 * ct + fr; float xr7[7];
; #pragma unroll
;         for (int j = 0; j < 7; ++j) xr7[j] = __builtin_bit_cast(float, (unsigned)(*(const LAS bf16*)(lds + LR_XR + (16 * rt + 4 * fq + j) * 144 + ch * 2)) << 16);
;         const float w0 = CW[ch], w1 = CW[64 + ch], w2 = CW[128 + ch], w3 = CW[192 + ch], b = CB[ch];
; #pragma unroll
;         for (int e = 0; e < 4; ++e) xc[ct][e] = b + xr7[e] * w0 + xr7[e + 1] * w1 + xr7[e + 2] * w2 + xr7[e + 3] * w3; }
;     float av[2][4][4], uv[2][4][4], pA[2][4], pH[2][4];
; #pragma unroll
;     for (int dir = 0; dir < 2; ++dir) {
; #pragma unroll
;         for (int ct = 0; ct < 4; ++ct) {
;             f32x4 ga = (f32x4){0.f, 0.f, 0.f, 0.f}, gx = (f32x4){0.f, 0.f, 0.f, 0.f};
; #pragma unroll
;             for (int ks = 0; ks < 2; ++ks) {
;                 const bf16x8 wa = *(const LAS bf16x8*)(lds + LR_WG + ((dir * 2 + 0) * 64 + 16 * ct + fr) * 144 + (32 * ks + 8 * fq) * 2);
;                 const bf16x8 wx = *(const LAS bf16x8*)(lds + LR_WG + ((dir * 2 + 1) * 64 + 16 * ct + fr) * 144 + (32 * ks + 8 * fq) * 2);
;                 ga = MFMA16(af[ks], wa, ga); gx = MFMA16(af[ks], wx, gx); }
;             const int ch = 16 * ct + fr; const float bav = GC[(dir * 3 + 0) * 64 + ch], bxv = GC[(dir * 3 + 1) * 64 + ch], c8 = GC[(dir * 3 + 2) * 64 + ch];
;             float Al = 1.f, Hl = 0.f;
; #pragma unroll
;             for (int ee = 0; ee < 4; ++ee) { const int e = dir ? 3 - ee : ee;
;                 const float r = __builtin_amdgcn_rcpf(1.f + __expf(-(ga[e] + bav))), ig = __builtin_amdgcn_rcpf(1.f + __expf(-(gx[e] + bxv)));
;                 const float la = -c8 * r; const float a = __expf(la); const float u = __builtin_amdgcn_sqrtf((1.f - a) * (1.f + a)) * (ig * xc[ct][e]);
;                 av[dir][ct][e] = a; uv[dir][ct][e] = u; Hl = a * Hl + u; Al *= a; }
;             const int o = dir ? 3 - fq : fq; const bool odd = (o & 1) != 0, hi2 = (o & 2) != 0;
;             const float A1 = __shfl_xor(Al, 16), H1 = __shfl_xor(Hl, 16);
;             const float pxA = odd ? A1 : 1.f, pxH = odd ? H1 : 0.f;
;             const float gA = Al * A1, gH = odd ? (Al * H1 + Hl) : (A1 * Hl + H1);
	v_add_f32_e32 v1, v23, v40
	v_add_f32_e32 v1, v22, v1
	v_pk_mul_f32 v[22:23], v[44:45], v[46:47]
	v_lshlrev_b32_e32 v42, 16, v38
	v_add_f32_e32 v23, v23, v40
	v_add_f32_e32 v24, v22, v23
	v_pk_mov_b32 v[22:23], v[42:43], v[46:47] op_sel:[1,0]
	v_mov_b32_e32 v50, v36
	v_pk_mul_f32 v[46:47], v[44:45], v[22:23]
	v_pk_mul_f32 v[44:45], v[44:45], v[42:43]
	v_mov_b32_e32 v51, v28
	v_add_f32_e32 v31, v45, v40
	v_add_f32_e32 v26, v47, v40
	v_add_f32_e32 v31, v44, v31
	v_pk_mul_f32 v[44:45], v[50:51], v[22:23]
	v_pk_mul_f32 v[22:23], v[50:51], v[42:43]
	v_add_f32_e32 v26, v46, v26
	v_lshlrev_b32_e32 v47, 16, v49
	v_lshlrev_b32_e32 v46, 16, v52
	v_add_f32_e32 v45, v45, v1
	v_add_f32_e32 v1, v23, v24
	v_add_f32_e32 v130, v22, v1
	v_pk_mov_b32 v[22:23], v[46:47], v[42:43] op_sel:[1,0]
	s_nop 0
	v_pk_mul_f32 v[22:23], v[50:51], v[22:23]
	s_nop 0
	v_add_f32_e32 v1, v23, v26
	v_add_f32_e32 v128, v22, v1
	v_pk_mul_f32 v[22:23], v[50:51], v[46:47]
	s_nop 0
	v_add_f32_e32 v1, v23, v31
	v_add_f32_e32 v125, v22, v1
	ds_read_u16 v1, v201
	s_waitcnt lgkmcnt(0)
	v_lshlrev_b32_e32 v23, 16, v1
	ds_read_u16 v1, v201 offset:144
	ds_read_u16 v22, v201 offset:288
	ds_read_u16 v24, v201 offset:432
	ds_read_u16 v26, v201 offset:576
	ds_read_u16 v28, v201 offset:720
	ds_read_u16 v31, v201 offset:864
	s_waitcnt lgkmcnt(3)
	v_lshlrev_b32_e32 v43, 16, v24
	v_mov_b32_e32 v24, v27
	v_lshlrev_b32_e32 v27, 16, v1
	s_waitcnt lgkmcnt(2)
	v_lshlrev_b32_e32 v42, 16, v26
	v_lshlrev_b32_e32 v26, 16, v22
	v_mov_b32_e32 v22, v27
	v_pk_mul_f32 v[22:23], v[24:25], v[22:23]
	s_nop 0
	v_add_f32_e32 v1, v23, v41
	v_add_f32_e32 v1, v22, v1
	v_pk_mul_f32 v[22:23], v[24:25], v[26:27]
	s_nop 0
	v_add_f32_e32 v23, v23, v41
	v_add_f32_e32 v38, v22, v23
	v_pk_mov_b32 v[22:23], v[42:43], v[26:27] op_sel:[1,0]
	s_nop 0
	v_pk_mul_f32 v[26:27], v[24:25], v[22:23]
	v_pk_mul_f32 v[24:25], v[24:25], v[42:43]
	v_add_f32_e32 v27, v27, v41
	v_add_f32_e32 v25, v25, v41
	v_add_f32_e32 v26, v26, v27
	v_add_f32_e32 v27, v24, v25
	s_waitcnt lgkmcnt(1)
	v_lshlrev_b32_e32 v25, 16, v28
	v_mov_b32_e32 v28, v37
	v_pk_mul_f32 v[36:37], v[28:29], v[22:23]
	v_pk_mul_f32 v[22:23], v[28:29], v[42:43]
	s_waitcnt lgkmcnt(0)
	v_lshlrev_b32_e32 v24, 16, v31
	v_add_f32_e32 v37, v37, v1
	v_add_f32_e32 v1, v23, v38
	v_add_f32_e32 v31, v22, v1
	v_pk_mov_b32 v[22:23], v[24:25], v[42:43] op_sel:[1,0]
	s_nop 0
	v_pk_mul_f32 v[22:23], v[28:29], v[22:23]
	s_nop 0
	v_add_f32_e32 v1, v23, v26
	v_add_f32_e32 v136, v22, v1
	v_pk_mul_f32 v[22:23], v[28:29], v[24:25]
	s_nop 0
	v_add_f32_e32 v1, v23, v27
	v_add_f32_e32 v133, v22, v1
	ds_read_b128 v[22:25], v132 offset:18944
	ds_read_b128 v[26:29], v132 offset:28160
	s_waitcnt lgkmcnt(1)
	v_mfma_f32_16x16x32_bf16 v[22:25], v[14:17], v[22:25], 0
	s_waitcnt lgkmcnt(0)
	v_mfma_f32_16x16x32_bf16 v[40:43], v[14:17], v[26:29], 0
	ds_read_b128 v[26:29], v132 offset:19008
	ds_read_b128 v[50:53], v132 offset:28224
	ds_read_b32 v49, v174 offset:57088
	ds_read_b32 v47, v174 offset:57344
	ds_read_b32 v46, v174 offset:57600
	s_waitcnt lgkmcnt(4)
	v_mfma_f32_16x16x32_bf16 v[26:29], v[18:21], v[26:29], v[22:25]
	s_waitcnt lgkmcnt(3)
	v_mfma_f32_16x16x32_bf16 v[22:25], v[18:21], v[50:53], v[40:43]
	s_waitcnt lgkmcnt(2)
	s_nop 4
	v_add_f32_e32 v1, v26, v49
	v_mul_f32_e32 v1, 0xbfb8aa3b, v1
	v_exp_f32_e32 v1, v1
	s_nop 0
	v_add_f32_e32 v1, 1.0, v1
	v_rcp_f32_e32 v1, v1
	s_waitcnt lgkmcnt(1)
	v_add_f32_e32 v22, v22, v47
	v_mul_f32_e32 v22, 0xbfb8aa3b, v22
	v_exp_f32_e32 v22, v22
	s_waitcnt lgkmcnt(0)
	v_mul_f32_e32 v1, v1, v46
	v_mul_f32_e32 v1, 0xbfb8aa3b, v1
	v_exp_f32_e32 v38, v1
	v_add_f32_e32 v22, 1.0, v22
	v_rcp_f32_e32 v50, v22
	v_add_f32_e32 v23, v23, v47
	v_sub_f32_e32 v1, 1.0, v38
	v_add_f32_e32 v22, 1.0, v38
	v_mul_f32_e32 v1, v1, v22
	v_add_f32_e32 v22, v27, v49
	v_mul_f32_e32 v22, 0xbfb8aa3b, v22
	v_exp_f32_e32 v22, v22
	v_mul_f32_e32 v23, 0xbfb8aa3b, v23
	v_exp_f32_e32 v23, v23
	v_add_f32_e32 v24, v24, v47
	v_add_f32_e32 v22, 1.0, v22
	v_rcp_f32_e32 v22, v22
	v_add_f32_e32 v23, 1.0, v23
	v_rcp_f32_e32 v23, v23
	v_add_f32_e32 v25, v25, v47
	v_mul_f32_e32 v22, v22, v46
	v_mul_f32_e32 v22, 0xbfb8aa3b, v22
	v_exp_f32_e32 v41, v22
	v_mul_f32_e32 v24, 0xbfb8aa3b, v24
	v_mul_f32_e32 v25, 0xbfb8aa3b, v25
	v_sqrt_f32_e32 v1, v1
	v_sub_f32_e32 v22, 1.0, v41
	v_add_f32_e32 v26, 1.0, v41
	v_mul_f32_e32 v22, v22, v26
	v_add_f32_e32 v26, v28, v49
	v_mul_f32_e32 v26, 0xbfb8aa3b, v26
	v_exp_f32_e32 v26, v26
	v_sqrt_f32_e32 v40, v22
	v_mul_f32_e32 v22, v108, v23
	v_mul_f32_e32 v23, v38, v41
	v_add_f32_e32 v26, 1.0, v26
	v_rcp_f32_e32 v26, v26
	v_exp_f32_e32 v24, v24
	v_exp_f32_e32 v25, v25
	v_mul_f32_e32 v39, v110, v50
	v_mul_f32_e32 v26, v26, v46
	v_mul_f32_e32 v26, 0xbfb8aa3b, v26
	v_exp_f32_e32 v43, v26
	v_add_f32_e32 v24, 1.0, v24
	v_add_f32_e32 v25, 1.0, v25
	v_rcp_f32_e32 v24, v24
	v_sub_f32_e32 v26, 1.0, v43
	v_add_f32_e32 v27, 1.0, v43
	v_mul_f32_e32 v26, v26, v27
	v_sqrt_f32_e32 v42, v26
	v_add_f32_e32 v26, v29, v49
	v_mul_f32_e32 v26, 0xbfb8aa3b, v26
	v_exp_f32_e32 v26, v26
	v_mul_f32_e32 v23, v43, v23
	v_pk_mul_f32 v[48:49], v[38:39], v[0:1]
	v_rcp_f32_e32 v25, v25
	v_add_f32_e32 v26, 1.0, v26
	v_rcp_f32_e32 v26, v26
	v_pk_fma_f32 v[50:51], v[38:39], v[0:1], v[48:49] op_sel_hi:[1,1,0]
	v_mul_f32_e32 v24, v106, v24
	v_mul_f32_e32 v26, v26, v46
	v_mul_f32_e32 v26, 0xbfb8aa3b, v26
	v_exp_f32_e32 v47, v26
	s_nop 0
	v_mul_f32_e32 v29, v47, v23
	ds_bpermute_b32 v56, v171, v29
	v_sub_f32_e32 v26, 1.0, v47
	v_add_f32_e32 v27, 1.0, v47
	v_mul_f32_e32 v26, v26, v27
	v_sqrt_f32_e32 v46, v26
	s_waitcnt lgkmcnt(0)
	v_mul_f32_e32 v59, v29, v56
	ds_bpermute_b32 v60, v172, v59
	v_cndmask_b32_e64 v58, v56, 1.0, s[50:51]
	v_mul_f32_e32 v26, v101, v25
	s_waitcnt lgkmcnt(0)
; #define LAS __attribute__((address_space(3)))
; #define MFMA16(a, b, c) __builtin_amdgcn_mfma_f32_16x16x32_bf16(a, b, c, 0, 0, 0)
; template <bool PHASE_B>
; __device__ __forceinline__ void lru_item(const Params& p, LAS unsigned char* lds, int ci, int ci_next, int jb, const int tid, v4u (&xvn)[3]) {
;     ...
;     for (int dir = 0; dir < 2; ++dir) {
; #pragma unroll
;         for (int ct = 0; ct < 4; ++ct) {
;             f32x4 ga = (f32x4){0.f, 0.f, 0.f, 0.f}, gx = (f32x4){0.f, 0.f, 0.f, 0.f};
; #pragma unroll
;             for (int ks = 0; ks < 2; ++ks) {
;                 const bf16x8 wa = *(const LAS bf16x8*)(lds + LR_WG + ((dir * 2 + 0) * 64 + 16 * ct + fr) * 144 + (32 * ks + 8 * fq) * 2);
;                 const bf16x8 wx = *(const LAS bf16x8*)(lds + LR_WG + ((dir * 2 + 1) * 64 + 16 * ct + fr) * 144 + (32 * ks + 8 * fq) * 2);
;                 ga = MFMA16(af[ks], wa, ga); gx = MFMA16(af[ks], wx, gx); }
;             const int ch = 16 * ct + fr; const float bav = GC[(dir * 3 + 0) * 64 + ch], bxv = GC[(dir * 3 + 1) * 64 + ch], c8 = GC[(dir * 3 + 2) * 64 + ch];
;             float Al = 1.f, Hl = 0.f;
; #pragma unroll
;             for (int ee = 0; ee < 4; ++ee) { const int e = dir ? 3 - ee : ee;
;                 const float r = __builtin_amdgcn_rcpf(1.f + __expf(-(ga[e] + bav))), ig = __builtin_amdgcn_rcpf(1.f + __expf(-(gx[e] + bxv)));
;                 const float la = -c8 * r; const float a = __expf(la); const float u = __builtin_amdgcn_sqrtf((1.f - a) * (1.f + a)) * (ig * xc[ct][e]);
;                 av[dir][ct][e] = a; uv[dir][ct][e] = u; Hl = a * Hl + u; Al *= a; }
;             const int o = dir ? 3 - fq : fq; const bool odd = (o & 1) != 0, hi2 = (o & 2) != 0;
;             const float A1 = __shfl_xor(Al, 16), H1 = __shfl_xor(Hl, 16);
;             const float pxA = odd ? A1 : 1.f, pxH = odd ? H1 : 0.f;
;             const float gA = Al * A1, gH = odd ? (Al * H1 + Hl) : (A1 * Hl + H1);
;             const float A2 = __shfl_xor(gA, 32), H2 = __shfl_xor(gH, 32);
;             const float PA = hi2 ? pxA * A2 : pxA, PH = hi2 ? (pxA * H2 + pxH) : pxH;
;             const float TA = gA * A2, TH = hi2 ? (gA * H2 + gH) : (A2 * gH + H2);
;             pA[dir][ct] = PA; pH[dir][ct] = PH;
;             ((LAS f32x2*)(lds + LR_SEG))[(dir * 8 + rt) * 64 + ch] = (f32x2){TA, TH};
	v_mul_f32_e32 v23, v58, v60
	v_cndmask_b32_e64 v206, v23, v58, s[52:53]
	v_mov_b32_e32 v23, v51
	v_pk_mul_f32 v[50:51], v[22:23], v[40:41]
	v_mul_f32_e32 v28, v59, v60
	v_pk_fma_f32 v[22:23], v[22:23], v[40:41], v[50:51] op_sel_hi:[1,1,0]
	s_nop 0
	v_mov_b32_e32 v25, v23
	v_pk_mul_f32 v[52:53], v[24:25], v[42:43]
	s_nop 0
	v_pk_fma_f32 v[22:23], v[24:25], v[42:43], v[52:53] op_sel_hi:[1,1,0]
	s_nop 0
	v_mov_b32_e32 v27, v23
	v_pk_mul_f32 v[54:55], v[26:27], v[46:47]
	s_nop 0
	v_add_f32_e32 v1, v54, v55
	ds_bpermute_b32 v22, v171, v1
	s_waitcnt lgkmcnt(0)
	v_cndmask_b32_e64 v23, v22, 0, s[50:51]
	v_fma_f32 v24, v29, v22, v1
	v_fmac_f32_e32 v22, v1, v56
	v_cndmask_b32_e64 v1, v24, v22, s[50:51]
	ds_bpermute_b32 v22, v172, v1
	s_waitcnt lgkmcnt(0)
	v_fma_f32 v24, v58, v22, v23
	v_cndmask_b32_e64 v39, v24, v23, s[52:53]
	v_fma_f32 v23, v59, v22, v1
	v_fmac_f32_e32 v22, v1, v60
	v_cndmask_b32_e64 v29, v23, v22, s[52:53]
	ds_write_b64 v175, v[28:29] offset:58624
	ds_read_b128 v[22:25], v132 offset:21248
	ds_read_b128 v[26:29], v132 offset:30464
	s_waitcnt lgkmcnt(1)
	v_mfma_f32_16x16x32_bf16 v[22:25], v[14:17], v[22:25], 0
	s_waitcnt lgkmcnt(0)
	v_mfma_f32_16x16x32_bf16 v[58:61], v[14:17], v[26:29], 0
	ds_read_b128 v[26:29], v132 offset:21312
	ds_read_b128 v[66:69], v132 offset:30528
	ds_read_b32 v40, v174 offset:57152
	ds_read_b32 v42, v174 offset:57408
	ds_read_b32 v46, v174 offset:57664
	s_waitcnt lgkmcnt(4)
	v_mfma_f32_16x16x32_bf16 v[26:29], v[18:21], v[26:29], v[22:25]
	s_waitcnt lgkmcnt(3)
	v_mfma_f32_16x16x32_bf16 v[22:25], v[18:21], v[66:69], v[58:61]
	s_waitcnt lgkmcnt(2)
	s_nop 4
	v_add_f32_e32 v1, v26, v40
	v_mul_f32_e32 v1, 0xbfb8aa3b, v1
	v_exp_f32_e32 v1, v1
	s_nop 0
	v_add_f32_e32 v1, 1.0, v1
	v_rcp_f32_e32 v1, v1
	s_waitcnt lgkmcnt(1)
	v_add_f32_e32 v22, v22, v42
	v_mul_f32_e32 v22, 0xbfb8aa3b, v22
	v_exp_f32_e32 v22, v22
	s_waitcnt lgkmcnt(0)
	v_mul_f32_e32 v1, v1, v46
	v_mul_f32_e32 v1, 0xbfb8aa3b, v1
	v_exp_f32_e32 v56, v1
	v_add_f32_e32 v22, 1.0, v22
	v_rcp_f32_e32 v48, v22
	v_add_f32_e32 v23, v23, v42
	v_sub_f32_e32 v1, 1.0, v56
	v_add_f32_e32 v22, 1.0, v56
	v_mul_f32_e32 v1, v1, v22
	v_add_f32_e32 v22, v27, v40
	v_mul_f32_e32 v22, 0xbfb8aa3b, v22
	v_exp_f32_e32 v22, v22
	v_mul_f32_e32 v23, 0xbfb8aa3b, v23
	v_exp_f32_e32 v23, v23
	v_add_f32_e32 v24, v24, v42
	v_add_f32_e32 v22, 1.0, v22
	v_rcp_f32_e32 v22, v22
	v_add_f32_e32 v23, 1.0, v23
	v_rcp_f32_e32 v23, v23
	v_add_f32_e32 v25, v25, v42
	v_mul_f32_e32 v22, v22, v46
	v_mul_f32_e32 v22, 0xbfb8aa3b, v22
	v_exp_f32_e32 v59, v22
	v_mul_f32_e32 v24, 0xbfb8aa3b, v24
	v_mul_f32_e32 v25, 0xbfb8aa3b, v25
	v_sqrt_f32_e32 v1, v1
	v_sub_f32_e32 v22, 1.0, v59
	v_add_f32_e32 v26, 1.0, v59
	v_mul_f32_e32 v22, v22, v26
	v_add_f32_e32 v26, v28, v40
	v_mul_f32_e32 v26, 0xbfb8aa3b, v26
	v_exp_f32_e32 v26, v26
	v_sqrt_f32_e32 v58, v22
	v_mul_f32_e32 v22, v120, v23
	v_mul_f32_e32 v23, v56, v59
	v_add_f32_e32 v26, 1.0, v26
	v_rcp_f32_e32 v26, v26
	v_exp_f32_e32 v24, v24
	v_exp_f32_e32 v25, v25
	v_mul_f32_e32 v57, v122, v48
	v_mul_f32_e32 v26, v26, v46
	v_mul_f32_e32 v26, 0xbfb8aa3b, v26
	v_exp_f32_e32 v61, v26
	v_add_f32_e32 v24, 1.0, v24
	v_add_f32_e32 v25, 1.0, v25
	v_pk_mul_f32 v[64:65], v[56:57], v[0:1]
	v_sub_f32_e32 v26, 1.0, v61
	v_add_f32_e32 v27, 1.0, v61
	v_mul_f32_e32 v26, v26, v27
	v_sqrt_f32_e32 v60, v26
	v_add_f32_e32 v26, v29, v40
	v_mul_f32_e32 v26, 0xbfb8aa3b, v26
	v_exp_f32_e32 v26, v26
	v_mul_f32_e32 v23, v61, v23
	v_rcp_f32_e32 v24, v24
	v_rcp_f32_e32 v25, v25
	v_add_f32_e32 v26, 1.0, v26
	v_rcp_f32_e32 v26, v26
	v_pk_fma_f32 v[66:67], v[56:57], v[0:1], v[64:65] op_sel_hi:[1,1,0]
	v_mul_f32_e32 v24, v118, v24
	v_mul_f32_e32 v26, v26, v46
	v_mul_f32_e32 v26, 0xbfb8aa3b, v26
	v_exp_f32_e32 v63, v26
	s_nop 0
	v_mul_f32_e32 v29, v63, v23
	ds_bpermute_b32 v42, v171, v29
	v_sub_f32_e32 v26, 1.0, v63
	v_add_f32_e32 v27, 1.0, v63
	v_mul_f32_e32 v26, v26, v27
	v_sqrt_f32_e32 v62, v26
	s_waitcnt lgkmcnt(0)
	v_mul_f32_e32 v51, v29, v42
	ds_bpermute_b32 v53, v172, v51
	v_cndmask_b32_e64 v46, v42, 1.0, s[50:51]
	v_mul_f32_e32 v26, v113, v25
	s_waitcnt lgkmcnt(0)
	v_mul_f32_e32 v23, v46, v53
	v_cndmask_b32_e64 v40, v23, v46, s[52:53]
	v_mov_b32_e32 v23, v67
	v_pk_mul_f32 v[66:67], v[22:23], v[58:59]
	v_mul_f32_e32 v28, v51, v53
	v_pk_fma_f32 v[22:23], v[22:23], v[58:59], v[66:67] op_sel_hi:[1,1,0]
	s_nop 0
	v_mov_b32_e32 v25, v23
	v_pk_mul_f32 v[68:69], v[24:25], v[60:61]
	s_nop 0
	v_pk_fma_f32 v[22:23], v[24:25], v[60:61], v[68:69] op_sel_hi:[1,1,0]
	v_add_f32_e32 v69, v44, v45
	v_mov_b32_e32 v27, v23
	v_pk_mul_f32 v[70:71], v[26:27], v[62:63]
	s_nop 0
	v_add_f32_e32 v1, v70, v71
	ds_bpermute_b32 v22, v171, v1
	v_add_f32_e32 v71, v36, v37
	s_waitcnt lgkmcnt(0)
	v_cndmask_b32_e64 v23, v22, 0, s[50:51]
	v_fma_f32 v24, v29, v22, v1
	v_fmac_f32_e32 v22, v1, v42
	v_cndmask_b32_e64 v1, v24, v22, s[50:51]
	ds_bpermute_b32 v22, v172, v1
	s_waitcnt lgkmcnt(0)
	v_fma_f32 v24, v46, v22, v23
	v_cndmask_b32_e64 v42, v24, v23, s[52:53]
	v_fma_f32 v23, v51, v22, v1
	v_fmac_f32_e32 v22, v1, v53
	v_cndmask_b32_e64 v29, v23, v22, s[52:53]
	ds_write_b64 v175, v[28:29] offset:58752
	ds_read_b128 v[22:25], v132 offset:23552
	ds_read_b128 v[26:29], v132 offset:32768
	s_waitcnt lgkmcnt(1)
	v_mfma_f32_16x16x32_bf16 v[22:25], v[14:17], v[22:25], 0
	ds_read_b128 v[72:75], v132 offset:23616
	ds_read_b128 v[76:79], v132 offset:32832
	s_waitcnt lgkmcnt(2)
	v_mfma_f32_16x16x32_bf16 v[26:29], v[14:17], v[26:29], 0
	s_waitcnt lgkmcnt(1)
	v_mfma_f32_16x16x32_bf16 v[80:83], v[18:21], v[72:75], v[22:25]
	s_waitcnt lgkmcnt(0)
; #define LAS __attribute__((address_space(3)))
; #define MFMA16(a, b, c) __builtin_amdgcn_mfma_f32_16x16x32_bf16(a, b, c, 0, 0, 0)
; template <bool PHASE_B>
; __device__ __forceinline__ void lru_item(const Params& p, LAS unsigned char* lds, int ci, int ci_next, int jb, const int tid, v4u (&xvn)[3]) {
;     ...
;     for (int dir = 0; dir < 2; ++dir) {
; #pragma unroll
;         for (int ct = 0; ct < 4; ++ct) {
;             f32x4 ga = (f32x4){0.f, 0.f, 0.f, 0.f}, gx = (f32x4){0.f, 0.f, 0.f, 0.f};
; #pragma unroll
;             for (int ks = 0; ks < 2; ++ks) {
;                 const bf16x8 wa = *(const LAS bf16x8*)(lds + LR_WG + ((dir * 2 + 0) * 64 + 16 * ct + fr) * 144 + (32 * ks + 8 * fq) * 2);
;                 const bf16x8 wx = *(const LAS bf16x8*)(lds + LR_WG + ((dir * 2 + 1) * 64 + 16 * ct + fr) * 144 + (32 * ks + 8 * fq) * 2);
;                 ga = MFMA16(af[ks], wa, ga); gx = MFMA16(af[ks], wx, gx); }
;             const int ch = 16 * ct + fr; const float bav = GC[(dir * 3 + 0) * 64 + ch], bxv = GC[(dir * 3 + 1) * 64 + ch], c8 = GC[(dir * 3 + 2) * 64 + ch];
;             float Al = 1.f, Hl = 0.f;
; #pragma unroll
;             for (int ee = 0; ee < 4; ++ee) { const int e = dir ? 3 - ee : ee;
;                 const float r = __builtin_amdgcn_rcpf(1.f + __expf(-(ga[e] + bav))), ig = __builtin_amdgcn_rcpf(1.f + __expf(-(gx[e] + bxv)));
;                 const float la = -c8 * r; const float a = __expf(la); const float u = __builtin_amdgcn_sqrtf((1.f - a) * (1.f + a)) * (ig * xc[ct][e]);
;                 av[dir][ct][e] = a; uv[dir][ct][e] = u; Hl = a * Hl + u; Al *= a; }
;             const int o = dir ? 3 - fq : fq; const bool odd = (o & 1) != 0, hi2 = (o & 2) != 0;
;             const float A1 = __shfl_xor(Al, 16), H1 = __shfl_xor(Hl, 16);
;             const float pxA = odd ? A1 : 1.f, pxH = odd ? H1 : 0.f;
;             const float gA = Al * A1, gH = odd ? (Al * H1 + Hl) : (A1 * Hl + H1);
;             const float A2 = __shfl_xor(gA, 32), H2 = __shfl_xor(gH, 32);
;             const float PA = hi2 ? pxA * A2 : pxA, PH = hi2 ? (pxA * H2 + pxH) : pxH;
;             const float TA = gA * A2, TH = hi2 ? (gA * H2 + gH) : (A2 * gH + H2);
;             pA[dir][ct] = PA; pH[dir][ct] = PH;
;             ((LAS f32x2*)(lds + LR_SEG))[(dir * 8 + rt) * 64 + ch] = (f32x2){TA, TH};
	v_mfma_f32_16x16x32_bf16 v[22:25], v[18:21], v[76:79], v[26:29]
	s_nop 3
	ds_read_b32 v26, v174 offset:57216
	ds_read_b32 v27, v174 offset:57472
	ds_read_b32 v28, v174 offset:57728
	s_waitcnt lgkmcnt(2)
	v_add_f32_e32 v1, v80, v26
	v_mul_f32_e32 v1, 0xbfb8aa3b, v1
	v_exp_f32_e32 v1, v1
	s_waitcnt lgkmcnt(1)
	v_add_f32_e32 v22, v22, v27
	v_mul_f32_e32 v22, 0xbfb8aa3b, v22
	v_exp_f32_e32 v22, v22
	v_add_f32_e32 v1, 1.0, v1
	v_rcp_f32_e32 v1, v1
	v_add_f32_e32 v23, v23, v27
	v_add_f32_e32 v22, 1.0, v22
	v_rcp_f32_e32 v29, v22
	s_waitcnt lgkmcnt(0)
	v_mul_f32_e32 v1, v1, v28
	v_mul_f32_e32 v1, 0xbfb8aa3b, v1
	v_exp_f32_e32 v72, v1
	v_mul_f32_e32 v23, 0xbfb8aa3b, v23
	v_exp_f32_e32 v23, v23
	v_add_f32_e32 v24, v24, v27
	v_sub_f32_e32 v1, 1.0, v72
	v_add_f32_e32 v22, 1.0, v72
	v_mul_f32_e32 v1, v1, v22
	v_add_f32_e32 v22, v81, v26
	v_mul_f32_e32 v22, 0xbfb8aa3b, v22
	v_exp_f32_e32 v22, v22
	v_add_f32_e32 v23, 1.0, v23
	v_rcp_f32_e32 v23, v23
	v_add_f32_e32 v25, v25, v27
	v_add_f32_e32 v22, 1.0, v22
	v_rcp_f32_e32 v22, v22
	v_mul_f32_e32 v24, 0xbfb8aa3b, v24
	v_mul_f32_e32 v25, 0xbfb8aa3b, v25
	v_sqrt_f32_e32 v1, v1
	v_mul_f32_e32 v22, v22, v28
	v_mul_f32_e32 v22, 0xbfb8aa3b, v22
	v_exp_f32_e32 v75, v22
	v_exp_f32_e32 v24, v24
	v_exp_f32_e32 v25, v25
	v_mul_f32_e32 v73, v69, v29
	v_sub_f32_e32 v22, 1.0, v75
	v_add_f32_e32 v46, 1.0, v75
	v_mul_f32_e32 v22, v22, v46
	v_add_f32_e32 v46, v82, v26
	v_mul_f32_e32 v46, 0xbfb8aa3b, v46
	v_add_f32_e32 v26, v83, v26
	v_exp_f32_e32 v46, v46
	v_mul_f32_e32 v26, 0xbfb8aa3b, v26
	v_exp_f32_e32 v26, v26
	v_sqrt_f32_e32 v74, v22
	v_add_f32_e32 v46, 1.0, v46
	v_rcp_f32_e32 v46, v46
	v_add_f32_e32 v26, 1.0, v26
	v_rcp_f32_e32 v26, v26
	v_mul_f32_e32 v22, v130, v23
	v_mul_f32_e32 v46, v46, v28
	v_mul_f32_e32 v46, 0xbfb8aa3b, v46
	v_mul_f32_e32 v26, v26, v28
	v_exp_f32_e32 v77, v46
	v_mul_f32_e32 v26, 0xbfb8aa3b, v26
	v_exp_f32_e32 v79, v26
	v_mul_f32_e32 v23, v72, v75
	v_sub_f32_e32 v46, 1.0, v77
	v_add_f32_e32 v48, 1.0, v77
	v_mul_f32_e32 v23, v77, v23
	v_mul_f32_e32 v46, v46, v48
	v_mul_f32_e32 v48, v79, v23
	ds_bpermute_b32 v51, v171, v48
	v_add_f32_e32 v24, 1.0, v24
	v_add_f32_e32 v25, 1.0, v25
	v_pk_mul_f32 v[44:45], v[72:73], v[0:1]
	v_rcp_f32_e32 v24, v24
	s_waitcnt lgkmcnt(0)
	v_mul_f32_e32 v55, v48, v51
	ds_bpermute_b32 v57, v172, v55
	v_cndmask_b32_e64 v53, v51, 1.0, s[50:51]
	v_rcp_f32_e32 v25, v25
	v_pk_fma_f32 v[80:81], v[72:73], v[0:1], v[44:45] op_sel_hi:[1,1,0]
	v_sqrt_f32_e32 v76, v46
	s_waitcnt lgkmcnt(0)
	v_mul_f32_e32 v23, v53, v57
	v_cndmask_b32_e64 v46, v23, v53, s[52:53]
	v_mov_b32_e32 v23, v81
	v_sub_f32_e32 v26, 1.0, v79
	v_add_f32_e32 v27, 1.0, v79
	v_pk_mul_f32 v[80:81], v[22:23], v[74:75]
	v_mul_f32_e32 v26, v26, v27
	v_pk_fma_f32 v[22:23], v[22:23], v[74:75], v[80:81] op_sel_hi:[1,1,0]
	v_mul_f32_e32 v24, v128, v24
	v_sqrt_f32_e32 v78, v26
	v_mul_f32_e32 v26, v125, v25
	v_mov_b32_e32 v25, v23
	v_pk_mul_f32 v[82:83], v[24:25], v[76:77]
	v_mul_f32_e32 v28, v55, v57
	v_pk_fma_f32 v[22:23], v[24:25], v[76:77], v[82:83] op_sel_hi:[1,1,0]
	s_nop 0
	v_mov_b32_e32 v27, v23
	v_pk_mul_f32 v[84:85], v[26:27], v[78:79]
	s_nop 0
	v_add_f32_e32 v1, v84, v85
	ds_bpermute_b32 v22, v171, v1
	s_waitcnt lgkmcnt(0)
	v_cndmask_b32_e64 v23, v22, 0, s[50:51]
	v_fma_f32 v24, v48, v22, v1
	v_fmac_f32_e32 v22, v1, v51
	v_cndmask_b32_e64 v1, v24, v22, s[50:51]
	ds_bpermute_b32 v22, v172, v1
	s_waitcnt lgkmcnt(0)
	v_fma_f32 v24, v53, v22, v23
	v_cndmask_b32_e64 v44, v24, v23, s[52:53]
	v_fma_f32 v23, v55, v22, v1
	v_fmac_f32_e32 v22, v1, v57
	v_cndmask_b32_e64 v29, v23, v22, s[52:53]
	ds_write_b64 v175, v[28:29] offset:58880
	ds_read_b128 v[22:25], v132 offset:25856
	ds_read_b128 v[26:29], v132 offset:35072
	s_waitcnt lgkmcnt(1)
	v_mfma_f32_16x16x32_bf16 v[22:25], v[14:17], v[22:25], 0
	ds_read_b128 v[86:89], v132 offset:25920
	ds_read_b128 v[90:93], v132 offset:35136
	s_waitcnt lgkmcnt(2)
	v_mfma_f32_16x16x32_bf16 v[26:29], v[14:17], v[26:29], 0
	s_waitcnt lgkmcnt(1)
	v_mfma_f32_16x16x32_bf16 v[94:97], v[18:21], v[86:89], v[22:25]
	s_waitcnt lgkmcnt(0)
	v_mfma_f32_16x16x32_bf16 v[22:25], v[18:21], v[90:93], v[26:29]
	s_nop 3
	ds_read_b32 v26, v174 offset:57280
	ds_read_b32 v27, v174 offset:57536
	ds_read_b32 v28, v174 offset:57792
	s_waitcnt lgkmcnt(2)
	v_add_f32_e32 v1, v94, v26
	v_mul_f32_e32 v1, 0xbfb8aa3b, v1
	v_exp_f32_e32 v1, v1
	s_waitcnt lgkmcnt(1)
	v_add_f32_e32 v22, v22, v27
	v_mul_f32_e32 v22, 0xbfb8aa3b, v22
	v_exp_f32_e32 v22, v22
	v_add_f32_e32 v1, 1.0, v1
	v_rcp_f32_e32 v1, v1
	v_add_f32_e32 v23, v23, v27
	v_add_f32_e32 v22, 1.0, v22
	v_rcp_f32_e32 v29, v22
	s_waitcnt lgkmcnt(0)
	v_mul_f32_e32 v1, v1, v28
	v_mul_f32_e32 v1, 0xbfb8aa3b, v1
	v_exp_f32_e32 v86, v1
	v_mul_f32_e32 v23, 0xbfb8aa3b, v23
	v_exp_f32_e32 v23, v23
	v_add_f32_e32 v24, v24, v27
	v_sub_f32_e32 v1, 1.0, v86
	v_add_f32_e32 v22, 1.0, v86
	v_mul_f32_e32 v1, v1, v22
	v_add_f32_e32 v22, v95, v26
	v_mul_f32_e32 v22, 0xbfb8aa3b, v22
	v_exp_f32_e32 v22, v22
	v_add_f32_e32 v23, 1.0, v23
	v_rcp_f32_e32 v23, v23
	v_add_f32_e32 v25, v25, v27
	v_add_f32_e32 v22, 1.0, v22
	v_rcp_f32_e32 v22, v22
	v_mul_f32_e32 v24, 0xbfb8aa3b, v24
	v_mul_f32_e32 v25, 0xbfb8aa3b, v25
	v_sqrt_f32_e32 v1, v1
	v_mul_f32_e32 v22, v22, v28
	v_mul_f32_e32 v22, 0xbfb8aa3b, v22
	v_exp_f32_e32 v89, v22
	v_exp_f32_e32 v24, v24
	v_exp_f32_e32 v25, v25
	v_mul_f32_e32 v87, v71, v29
	v_sub_f32_e32 v22, 1.0, v89
	v_add_f32_e32 v48, 1.0, v89
	v_mul_f32_e32 v22, v22, v48
	v_add_f32_e32 v48, v96, v26
	v_mul_f32_e32 v48, 0xbfb8aa3b, v48
	v_add_f32_e32 v26, v97, v26
	v_exp_f32_e32 v48, v48
	v_mul_f32_e32 v26, 0xbfb8aa3b, v26
	v_exp_f32_e32 v26, v26
	v_sqrt_f32_e32 v88, v22
	v_add_f32_e32 v48, 1.0, v48
	v_rcp_f32_e32 v48, v48
	v_add_f32_e32 v26, 1.0, v26
	v_rcp_f32_e32 v26, v26
	v_mul_f32_e32 v22, v31, v23
	v_mul_f32_e32 v48, v48, v28
	v_mul_f32_e32 v48, 0xbfb8aa3b, v48
	v_mul_f32_e32 v26, v26, v28
	v_exp_f32_e32 v91, v48
	v_mul_f32_e32 v26, 0xbfb8aa3b, v26
	v_exp_f32_e32 v93, v26
	v_mul_f32_e32 v23, v86, v89
	v_sub_f32_e32 v48, 1.0, v91
	v_add_f32_e32 v51, 1.0, v91
	v_mul_f32_e32 v23, v91, v23
	v_mul_f32_e32 v48, v48, v51
	v_mul_f32_e32 v51, v93, v23
	ds_bpermute_b32 v53, v171, v51
	v_add_f32_e32 v24, 1.0, v24
	v_add_f32_e32 v25, 1.0, v25
	v_pk_mul_f32 v[36:37], v[86:87], v[0:1]
	v_rcp_f32_e32 v24, v24
	s_waitcnt lgkmcnt(0)
; #define LAS __attribute__((address_space(3)))
; #define MFMA16(a, b, c) __builtin_amdgcn_mfma_f32_16x16x32_bf16(a, b, c, 0, 0, 0)
; template <bool PHASE_B>
; __device__ __forceinline__ void lru_item(const Params& p, LAS unsigned char* lds, int ci, int ci_next, int jb, const int tid, v4u (&xvn)[3]) {
;     ...
;     for (int dir = 0; dir < 2; ++dir) {
; #pragma unroll
;         for (int ct = 0; ct < 4; ++ct) {
;             f32x4 ga = (f32x4){0.f, 0.f, 0.f, 0.f}, gx = (f32x4){0.f, 0.f, 0.f, 0.f};
; #pragma unroll
;             for (int ks = 0; ks < 2; ++ks) {
;                 const bf16x8 wa = *(const LAS bf16x8*)(lds + LR_WG + ((dir * 2 + 0) * 64 + 16 * ct + fr) * 144 + (32 * ks + 8 * fq) * 2);
;                 const bf16x8 wx = *(const LAS bf16x8*)(lds + LR_WG + ((dir * 2 + 1) * 64 + 16 * ct + fr) * 144 + (32 * ks + 8 * fq) * 2);
;                 ga = MFMA16(af[ks], wa, ga); gx = MFMA16(af[ks], wx, gx); }
;             const int ch = 16 * ct + fr; const float bav = GC[(dir * 3 + 0) * 64 + ch], bxv = GC[(dir * 3 + 1) * 64 + ch], c8 = GC[(dir * 3 + 2) * 64 + ch];
;             float Al = 1.f, Hl = 0.f;
; #pragma unroll
;             for (int ee = 0; ee < 4; ++ee) { const int e = dir ? 3 - ee : ee;
;                 const float r = __builtin_amdgcn_rcpf(1.f + __expf(-(ga[e] + bav))), ig = __builtin_amdgcn_rcpf(1.f + __expf(-(gx[e] + bxv)));
;                 const float la = -c8 * r; const float a = __expf(la); const float u = __builtin_amdgcn_sqrtf((1.f - a) * (1.f + a)) * (ig * xc[ct][e]);
;                 av[dir][ct][e] = a; uv[dir][ct][e] = u; Hl = a * Hl + u; Al *= a; }
;             const int o = dir ? 3 - fq : fq; const bool odd = (o & 1) != 0, hi2 = (o & 2) != 0;
;             const float A1 = __shfl_xor(Al, 16), H1 = __shfl_xor(Hl, 16);
;             const float pxA = odd ? A1 : 1.f, pxH = odd ? H1 : 0.f;
;             const float gA = Al * A1, gH = odd ? (Al * H1 + Hl) : (A1 * Hl + H1);
;             const float A2 = __shfl_xor(gA, 32), H2 = __shfl_xor(gH, 32);
;             const float PA = hi2 ? pxA * A2 : pxA, PH = hi2 ? (pxA * H2 + pxH) : pxH;
;             const float TA = gA * A2, TH = hi2 ? (gA * H2 + gH) : (A2 * gH + H2);
;             pA[dir][ct] = PA; pH[dir][ct] = PH;
;             ((LAS f32x2*)(lds + LR_SEG))[(dir * 8 + rt) * 64 + ch] = (f32x2){TA, TH};
	v_mul_f32_e32 v57, v51, v53
	ds_bpermute_b32 v58, v172, v57
	v_cndmask_b32_e64 v55, v53, 1.0, s[50:51]
	v_rcp_f32_e32 v25, v25
	v_pk_fma_f32 v[94:95], v[86:87], v[0:1], v[36:37] op_sel_hi:[1,1,0]
	v_sqrt_f32_e32 v90, v48
	s_waitcnt lgkmcnt(0)
	v_mul_f32_e32 v23, v55, v58
	v_cndmask_b32_e64 v48, v23, v55, s[52:53]
	v_mov_b32_e32 v23, v95
	v_sub_f32_e32 v26, 1.0, v93
	v_add_f32_e32 v27, 1.0, v93
	v_pk_mul_f32 v[94:95], v[22:23], v[88:89]
	v_mul_f32_e32 v26, v26, v27
	v_pk_fma_f32 v[22:23], v[22:23], v[88:89], v[94:95] op_sel_hi:[1,1,0]
	v_mul_f32_e32 v24, v136, v24
	v_sqrt_f32_e32 v92, v26
	v_mul_f32_e32 v26, v133, v25
	v_mov_b32_e32 v25, v23
	v_pk_mul_f32 v[96:97], v[24:25], v[90:91]
	v_mul_f32_e32 v28, v57, v58
	v_pk_fma_f32 v[22:23], v[24:25], v[90:91], v[96:97] op_sel_hi:[1,1,0]
	s_nop 0
	v_mov_b32_e32 v27, v23
	v_pk_mul_f32 v[98:99], v[26:27], v[92:93]
	s_nop 0
	v_add_f32_e32 v1, v98, v99
	ds_bpermute_b32 v22, v171, v1
	s_waitcnt lgkmcnt(0)
	v_cndmask_b32_e64 v23, v22, 0, s[50:51]
	v_fma_f32 v24, v51, v22, v1
	v_fmac_f32_e32 v22, v1, v53
	v_cndmask_b32_e64 v1, v24, v22, s[50:51]
	ds_bpermute_b32 v22, v172, v1
	s_waitcnt lgkmcnt(0)
	v_fma_f32 v24, v55, v22, v23
	v_cndmask_b32_e64 v36, v24, v23, s[52:53]
	v_fma_f32 v23, v57, v22, v1
	v_fmac_f32_e32 v22, v1, v58
	v_cndmask_b32_e64 v29, v23, v22, s[52:53]
	ds_write_b64 v175, v[28:29] offset:59008
	ds_read_b128 v[22:25], v132 offset:37376
	ds_read_b128 v[26:29], v132 offset:46592
	s_waitcnt lgkmcnt(1)
	v_mfma_f32_16x16x32_bf16 v[22:25], v[14:17], v[22:25], 0
	s_waitcnt lgkmcnt(0)
	v_mfma_f32_16x16x32_bf16 v[102:105], v[14:17], v[26:29], 0
	ds_read_b128 v[26:29], v132 offset:37440
	ds_read_b128 v[114:117], v132 offset:46656
	ds_read_b32 v55, v174 offset:57856
	ds_read_b32 v57, v174 offset:58112
	ds_read_b32 v58, v174 offset:58368
	s_waitcnt lgkmcnt(4)
	v_mfma_f32_16x16x32_bf16 v[26:29], v[18:21], v[26:29], v[22:25]
	s_waitcnt lgkmcnt(3)
	v_mfma_f32_16x16x32_bf16 v[22:25], v[18:21], v[114:117], v[102:105]
	s_waitcnt lgkmcnt(2)
	s_nop 4
	v_add_f32_e32 v1, v29, v55
	v_mul_f32_e32 v1, 0xbfb8aa3b, v1
	v_exp_f32_e32 v1, v1
	s_nop 0
	v_add_f32_e32 v1, 1.0, v1
	v_rcp_f32_e32 v1, v1
	s_waitcnt lgkmcnt(1)
	v_add_f32_e32 v25, v25, v57
	v_mul_f32_e32 v25, 0xbfb8aa3b, v25
	v_exp_f32_e32 v25, v25
	s_waitcnt lgkmcnt(0)
	v_mul_f32_e32 v1, v1, v58
	v_mul_f32_e32 v1, 0xbfb8aa3b, v1
	v_exp_f32_e32 v100, v1
	v_add_f32_e32 v25, 1.0, v25
	v_rcp_f32_e32 v25, v25
	v_add_f32_e32 v23, v23, v57
	v_sub_f32_e32 v1, 1.0, v100
	v_add_f32_e32 v29, 1.0, v100
	v_mul_f32_e32 v1, v1, v29
	v_sqrt_f32_e32 v1, v1
	v_mul_f32_e32 v101, v101, v25
	v_mul_f32_e32 v23, 0xbfb8aa3b, v23
	v_exp_f32_e32 v23, v23
	v_pk_mul_f32 v[102:103], v[100:101], v[0:1]
	v_add_f32_e32 v24, v24, v57
	v_pk_fma_f32 v[114:115], v[100:101], v[0:1], v[102:103] op_sel_hi:[1,1,0]
	v_add_f32_e32 v1, v28, v55
	v_mul_f32_e32 v1, 0xbfb8aa3b, v1
	v_exp_f32_e32 v1, v1
	v_add_f32_e32 v23, 1.0, v23
	v_rcp_f32_e32 v23, v23
	v_mul_f32_e32 v24, 0xbfb8aa3b, v24
	v_add_f32_e32 v1, 1.0, v1
	v_rcp_f32_e32 v1, v1
	v_mul_f32_e32 v23, v108, v23
	v_exp_f32_e32 v24, v24
	v_add_f32_e32 v22, v22, v57
	v_mul_f32_e32 v1, v1, v58
	v_mul_f32_e32 v1, 0xbfb8aa3b, v1
	v_exp_f32_e32 v105, v1
	v_mul_f32_e32 v22, 0xbfb8aa3b, v22
	v_add_f32_e32 v24, 1.0, v24
	v_exp_f32_e32 v22, v22
	v_sub_f32_e32 v1, 1.0, v105
	v_add_f32_e32 v25, 1.0, v105
	v_mul_f32_e32 v1, v1, v25
	v_add_f32_e32 v25, v27, v55
	v_mul_f32_e32 v25, 0xbfb8aa3b, v25
	v_exp_f32_e32 v25, v25
	v_rcp_f32_e32 v24, v24
	v_sqrt_f32_e32 v104, v1
	v_add_f32_e32 v22, 1.0, v22
	v_add_f32_e32 v25, 1.0, v25
	v_rcp_f32_e32 v25, v25
	v_mul_f32_e32 v114, v106, v24
	v_rcp_f32_e32 v22, v22
	v_pk_mul_f32 v[106:107], v[114:115], v[104:105]
	v_mul_f32_e32 v25, v25, v58
	v_mul_f32_e32 v25, 0xbfb8aa3b, v25
	v_exp_f32_e32 v51, v25
	v_add_f32_e32 v1, v106, v107
	v_mul_f32_e32 v24, v100, v105
	v_mul_f32_e32 v22, v110, v22
	v_sub_f32_e32 v25, 1.0, v51
	v_add_f32_e32 v27, 1.0, v51
	v_mul_f32_e32 v25, v25, v27
	v_sqrt_f32_e32 v25, v25
	v_mul_f32_e32 v1, v51, v1
	v_mul_f32_e32 v24, v51, v24
	v_mul_f32_e32 v53, v23, v25
	v_add_f32_e32 v23, v26, v55
	v_mul_f32_e32 v23, 0xbfb8aa3b, v23
	v_exp_f32_e32 v23, v23
	s_nop 0
	v_add_f32_e32 v23, 1.0, v23
	v_rcp_f32_e32 v23, v23
	s_nop 0
	v_mul_f32_e32 v23, v23, v58
	v_mul_f32_e32 v23, 0xbfb8aa3b, v23
	v_exp_f32_e32 v109, v23
	s_nop 0
	v_sub_f32_e32 v23, 1.0, v109
	v_add_f32_e32 v25, 1.0, v109
	v_mul_f32_e32 v23, v23, v25
	v_sqrt_f32_e32 v108, v23
	v_add_f32_e32 v23, v1, v53
	v_pk_mul_f32 v[110:111], v[22:23], v[108:109]
	s_nop 0
	v_add_f32_e32 v1, v110, v111
	v_mul_f32_e32 v22, v109, v24
	ds_bpermute_b32 v23, v171, v22
	ds_bpermute_b32 v24, v171, v1
	s_waitcnt lgkmcnt(1)
	v_mul_f32_e32 v27, v22, v23
	s_waitcnt lgkmcnt(0)
	v_cndmask_b32_e64 v26, v24, 0, s[54:55]
	v_fma_f32 v22, v22, v24, v1
	v_fmac_f32_e32 v24, v1, v23
	v_cndmask_b32_e64 v25, v23, 1.0, s[54:55]
	v_cndmask_b32_e64 v1, v22, v24, s[54:55]
	ds_bpermute_b32 v23, v172, v27
	ds_bpermute_b32 v24, v172, v1
	s_waitcnt lgkmcnt(1)
	v_mul_f32_e32 v22, v25, v23
	v_cndmask_b32_e64 v55, v22, v25, s[56:57]
	s_waitcnt lgkmcnt(0)
	v_fma_f32 v22, v25, v24, v26
	v_fma_f32 v25, v27, v24, v1
	v_fmac_f32_e32 v24, v1, v23
	v_cndmask_b32_e64 v57, v22, v26, s[56:57]
	v_mul_f32_e32 v22, v27, v23
	v_cndmask_b32_e64 v23, v25, v24, s[56:57]
	ds_write_b64 v175, v[22:23] offset:62720
	ds_read_b128 v[22:25], v132 offset:39680
	ds_read_b128 v[26:29], v132 offset:48896
	s_waitcnt lgkmcnt(1)
	v_mfma_f32_16x16x32_bf16 v[22:25], v[14:17], v[22:25], 0
	s_waitcnt lgkmcnt(0)
; #define LAS __attribute__((address_space(3)))
; #define MFMA16(a, b, c) __builtin_amdgcn_mfma_f32_16x16x32_bf16(a, b, c, 0, 0, 0)
; template <bool PHASE_B>
; __device__ __forceinline__ void lru_item(const Params& p, LAS unsigned char* lds, int ci, int ci_next, int jb, const int tid, v4u (&xvn)[3]) {
;     ...
;     for (int dir = 0; dir < 2; ++dir) {
; #pragma unroll
;         for (int ct = 0; ct < 4; ++ct) {
;             f32x4 ga = (f32x4){0.f, 0.f, 0.f, 0.f}, gx = (f32x4){0.f, 0.f, 0.f, 0.f};
; #pragma unroll
;             for (int ks = 0; ks < 2; ++ks) {
;                 const bf16x8 wa = *(const LAS bf16x8*)(lds + LR_WG + ((dir * 2 + 0) * 64 + 16 * ct + fr) * 144 + (32 * ks + 8 * fq) * 2);
;                 const bf16x8 wx = *(const LAS bf16x8*)(lds + LR_WG + ((dir * 2 + 1) * 64 + 16 * ct + fr) * 144 + (32 * ks + 8 * fq) * 2);
;                 ga = MFMA16(af[ks], wa, ga); gx = MFMA16(af[ks], wx, gx); }
;             const int ch = 16 * ct + fr; const float bav = GC[(dir * 3 + 0) * 64 + ch], bxv = GC[(dir * 3 + 1) * 64 + ch], c8 = GC[(dir * 3 + 2) * 64 + ch];
;             float Al = 1.f, Hl = 0.f;
; #pragma unroll
;             for (int ee = 0; ee < 4; ++ee) { const int e = dir ? 3 - ee : ee;
;                 const float r = __builtin_amdgcn_rcpf(1.f + __expf(-(ga[e] + bav))), ig = __builtin_amdgcn_rcpf(1.f + __expf(-(gx[e] + bxv)));
;                 const float la = -c8 * r; const float a = __expf(la); const float u = __builtin_amdgcn_sqrtf((1.f - a) * (1.f + a)) * (ig * xc[ct][e]);
;                 av[dir][ct][e] = a; uv[dir][ct][e] = u; Hl = a * Hl + u; Al *= a; }
;             const int o = dir ? 3 - fq : fq; const bool odd = (o & 1) != 0, hi2 = (o & 2) != 0;
;             const float A1 = __shfl_xor(Al, 16), H1 = __shfl_xor(Hl, 16);
;             const float pxA = odd ? A1 : 1.f, pxH = odd ? H1 : 0.f;
;             const float gA = Al * A1, gH = odd ? (Al * H1 + Hl) : (A1 * Hl + H1);
;             const float A2 = __shfl_xor(gA, 32), H2 = __shfl_xor(gH, 32);
;             const float PA = hi2 ? pxA * A2 : pxA, PH = hi2 ? (pxA * H2 + pxH) : pxH;
;             const float TA = gA * A2, TH = hi2 ? (gA * H2 + gH) : (A2 * gH + H2);
;             pA[dir][ct] = PA; pH[dir][ct] = PH;
;             ((LAS f32x2*)(lds + LR_SEG))[(dir * 8 + rt) * 64 + ch] = (f32x2){TA, TH};
	v_mfma_f32_16x16x32_bf16 v[114:117], v[14:17], v[26:29], 0
	ds_read_b128 v[26:29], v132 offset:39744
	ds_read_b128 v[138:141], v132 offset:48960
	ds_read_b32 v62, v174 offset:57920
	ds_read_b32 v64, v174 offset:58176
	ds_read_b32 v67, v174 offset:58432
	s_waitcnt lgkmcnt(4)
	v_mfma_f32_16x16x32_bf16 v[26:29], v[18:21], v[26:29], v[22:25]
	s_waitcnt lgkmcnt(3)
	v_mfma_f32_16x16x32_bf16 v[22:25], v[18:21], v[138:141], v[114:117]
	s_waitcnt lgkmcnt(2)
	s_nop 4
	v_add_f32_e32 v1, v29, v62
	v_mul_f32_e32 v1, 0xbfb8aa3b, v1
	v_exp_f32_e32 v1, v1
	s_nop 0
	v_add_f32_e32 v1, 1.0, v1
	v_rcp_f32_e32 v1, v1
	s_waitcnt lgkmcnt(1)
	v_add_f32_e32 v25, v25, v64
	v_mul_f32_e32 v25, 0xbfb8aa3b, v25
	v_exp_f32_e32 v25, v25
	s_waitcnt lgkmcnt(0)
	v_mul_f32_e32 v1, v1, v67
	v_mul_f32_e32 v1, 0xbfb8aa3b, v1
	v_exp_f32_e32 v112, v1
	v_add_f32_e32 v25, 1.0, v25
	v_rcp_f32_e32 v25, v25
	v_add_f32_e32 v23, v23, v64
	v_sub_f32_e32 v1, 1.0, v112
	v_add_f32_e32 v29, 1.0, v112
	v_mul_f32_e32 v1, v1, v29
	v_sqrt_f32_e32 v1, v1
	v_mul_f32_e32 v113, v113, v25
	v_mul_f32_e32 v23, 0xbfb8aa3b, v23
	v_exp_f32_e32 v23, v23
	v_pk_mul_f32 v[114:115], v[112:113], v[0:1]
	v_add_f32_e32 v24, v24, v64
	v_pk_fma_f32 v[126:127], v[112:113], v[0:1], v[114:115] op_sel_hi:[1,1,0]
	v_add_f32_e32 v1, v28, v62
	v_mul_f32_e32 v1, 0xbfb8aa3b, v1
	v_exp_f32_e32 v1, v1
	v_add_f32_e32 v23, 1.0, v23
	v_rcp_f32_e32 v23, v23
	v_mul_f32_e32 v24, 0xbfb8aa3b, v24
	v_add_f32_e32 v1, 1.0, v1
	v_rcp_f32_e32 v1, v1
	v_mul_f32_e32 v23, v120, v23
	v_exp_f32_e32 v24, v24
	v_add_f32_e32 v22, v22, v64
	v_mul_f32_e32 v1, v1, v67
	v_mul_f32_e32 v1, 0xbfb8aa3b, v1
	v_exp_f32_e32 v117, v1
	v_mul_f32_e32 v22, 0xbfb8aa3b, v22
	v_add_f32_e32 v24, 1.0, v24
	v_exp_f32_e32 v22, v22
	v_sub_f32_e32 v1, 1.0, v117
	v_add_f32_e32 v25, 1.0, v117
	v_mul_f32_e32 v1, v1, v25
	v_add_f32_e32 v25, v27, v62
	v_mul_f32_e32 v25, 0xbfb8aa3b, v25
	v_exp_f32_e32 v25, v25
	v_rcp_f32_e32 v24, v24
	v_sqrt_f32_e32 v116, v1
	v_add_f32_e32 v22, 1.0, v22
	v_add_f32_e32 v25, 1.0, v25
	v_rcp_f32_e32 v25, v25
	v_mul_f32_e32 v126, v118, v24
	v_rcp_f32_e32 v22, v22
	v_pk_mul_f32 v[118:119], v[126:127], v[116:117]
	v_mul_f32_e32 v25, v25, v67
	v_mul_f32_e32 v25, 0xbfb8aa3b, v25
	v_exp_f32_e32 v58, v25
	v_add_f32_e32 v1, v118, v119
	v_mul_f32_e32 v24, v112, v117
	v_mul_f32_e32 v22, v122, v22
	v_sub_f32_e32 v25, 1.0, v58
	v_add_f32_e32 v27, 1.0, v58
	v_mul_f32_e32 v25, v25, v27
	v_sqrt_f32_e32 v25, v25
	v_mul_f32_e32 v1, v58, v1
	v_mul_f32_e32 v24, v58, v24
	v_mul_f32_e32 v60, v23, v25
	v_add_f32_e32 v23, v26, v62
	v_mul_f32_e32 v23, 0xbfb8aa3b, v23
	v_exp_f32_e32 v23, v23
	s_nop 0
	v_add_f32_e32 v23, 1.0, v23
	v_rcp_f32_e32 v23, v23
	s_nop 0
	v_mul_f32_e32 v23, v23, v67
	v_mul_f32_e32 v23, 0xbfb8aa3b, v23
	v_exp_f32_e32 v121, v23
	s_nop 0
	v_sub_f32_e32 v23, 1.0, v121
	v_add_f32_e32 v25, 1.0, v121
	v_mul_f32_e32 v23, v23, v25
	v_sqrt_f32_e32 v120, v23
	v_add_f32_e32 v23, v1, v60
	v_pk_mul_f32 v[122:123], v[22:23], v[120:121]
	s_nop 0
	v_add_f32_e32 v1, v122, v123
	v_mul_f32_e32 v22, v121, v24
	ds_bpermute_b32 v23, v171, v22
	ds_bpermute_b32 v24, v171, v1
	s_waitcnt lgkmcnt(1)
	v_mul_f32_e32 v27, v22, v23
	s_waitcnt lgkmcnt(0)
	v_cndmask_b32_e64 v26, v24, 0, s[54:55]
	v_fma_f32 v22, v22, v24, v1
	v_fmac_f32_e32 v24, v1, v23
	v_cndmask_b32_e64 v25, v23, 1.0, s[54:55]
	v_cndmask_b32_e64 v1, v22, v24, s[54:55]
	ds_bpermute_b32 v23, v172, v27
	ds_bpermute_b32 v24, v172, v1
	s_waitcnt lgkmcnt(1)
	v_mul_f32_e32 v22, v25, v23
	v_cndmask_b32_e64 v62, v22, v25, s[56:57]
	s_waitcnt lgkmcnt(0)
	v_fma_f32 v22, v25, v24, v26
	v_fma_f32 v25, v27, v24, v1
	v_fmac_f32_e32 v24, v1, v23
	v_cndmask_b32_e64 v64, v22, v26, s[56:57]
	v_mul_f32_e32 v22, v27, v23
	v_cndmask_b32_e64 v23, v25, v24, s[56:57]
	ds_write_b64 v175, v[22:23] offset:62848
	ds_read_b128 v[22:25], v132 offset:41984
	ds_read_b128 v[26:29], v132 offset:51200
	s_waitcnt lgkmcnt(1)
	v_mfma_f32_16x16x32_bf16 v[22:25], v[14:17], v[22:25], 0
	s_waitcnt lgkmcnt(0)
	v_mfma_f32_16x16x32_bf16 v[138:141], v[14:17], v[26:29], 0
	ds_read_b128 v[26:29], v132 offset:42048
	ds_read_b128 v[150:153], v132 offset:51264
	ds_read_b32 v73, v174 offset:57984
	ds_read_b32 v74, v174 offset:58240
	ds_read_b32 v76, v174 offset:58496
	s_waitcnt lgkmcnt(4)
	v_mfma_f32_16x16x32_bf16 v[26:29], v[18:21], v[26:29], v[22:25]
	s_waitcnt lgkmcnt(3)
	v_mfma_f32_16x16x32_bf16 v[22:25], v[18:21], v[150:153], v[138:141]
	s_waitcnt lgkmcnt(2)
	s_nop 4
	v_add_f32_e32 v1, v29, v73
	v_mul_f32_e32 v1, 0xbfb8aa3b, v1
	v_exp_f32_e32 v1, v1
	s_nop 0
	v_add_f32_e32 v1, 1.0, v1
	v_rcp_f32_e32 v1, v1
	s_waitcnt lgkmcnt(1)
	v_add_f32_e32 v25, v25, v74
	v_mul_f32_e32 v25, 0xbfb8aa3b, v25
	v_exp_f32_e32 v25, v25
	s_waitcnt lgkmcnt(0)
; #define LAS __attribute__((address_space(3)))
; #define MFMA16(a, b, c) __builtin_amdgcn_mfma_f32_16x16x32_bf16(a, b, c, 0, 0, 0)
; template <bool PHASE_B>
; __device__ __forceinline__ void lru_item(const Params& p, LAS unsigned char* lds, int ci, int ci_next, int jb, const int tid, v4u (&xvn)[3]) {
;     ...
;     for (int dir = 0; dir < 2; ++dir) {
; #pragma unroll
;         for (int ct = 0; ct < 4; ++ct) {
;             f32x4 ga = (f32x4){0.f, 0.f, 0.f, 0.f}, gx = (f32x4){0.f, 0.f, 0.f, 0.f};
; #pragma unroll
;             for (int ks = 0; ks < 2; ++ks) {
;                 const bf16x8 wa = *(const LAS bf16x8*)(lds + LR_WG + ((dir * 2 + 0) * 64 + 16 * ct + fr) * 144 + (32 * ks + 8 * fq) * 2);
;                 const bf16x8 wx = *(const LAS bf16x8*)(lds + LR_WG + ((dir * 2 + 1) * 64 + 16 * ct + fr) * 144 + (32 * ks + 8 * fq) * 2);
;                 ga = MFMA16(af[ks], wa, ga); gx = MFMA16(af[ks], wx, gx); }
;             const int ch = 16 * ct + fr; const float bav = GC[(dir * 3 + 0) * 64 + ch], bxv = GC[(dir * 3 + 1) * 64 + ch], c8 = GC[(dir * 3 + 2) * 64 + ch];
;             float Al = 1.f, Hl = 0.f;
; #pragma unroll
;             for (int ee = 0; ee < 4; ++ee) { const int e = dir ? 3 - ee : ee;
;                 const float r = __builtin_amdgcn_rcpf(1.f + __expf(-(ga[e] + bav))), ig = __builtin_amdgcn_rcpf(1.f + __expf(-(gx[e] + bxv)));
;                 const float la = -c8 * r; const float a = __expf(la); const float u = __builtin_amdgcn_sqrtf((1.f - a) * (1.f + a)) * (ig * xc[ct][e]);
;                 av[dir][ct][e] = a; uv[dir][ct][e] = u; Hl = a * Hl + u; Al *= a; }
;             const int o = dir ? 3 - fq : fq; const bool odd = (o & 1) != 0, hi2 = (o & 2) != 0;
;             const float A1 = __shfl_xor(Al, 16), H1 = __shfl_xor(Hl, 16);
;             const float pxA = odd ? A1 : 1.f, pxH = odd ? H1 : 0.f;
;             const float gA = Al * A1, gH = odd ? (Al * H1 + Hl) : (A1 * Hl + H1);
;             const float A2 = __shfl_xor(gA, 32), H2 = __shfl_xor(gH, 32);
;             const float PA = hi2 ? pxA * A2 : pxA, PH = hi2 ? (pxA * H2 + pxH) : pxH;
;             const float TA = gA * A2, TH = hi2 ? (gA * H2 + gH) : (A2 * gH + H2);
;             pA[dir][ct] = PA; pH[dir][ct] = PH;
;             ((LAS f32x2*)(lds + LR_SEG))[(dir * 8 + rt) * 64 + ch] = (f32x2){TA, TH};
	v_mul_f32_e32 v1, v1, v76
	v_mul_f32_e32 v1, 0xbfb8aa3b, v1
	v_exp_f32_e32 v124, v1
	v_add_f32_e32 v25, 1.0, v25
	v_rcp_f32_e32 v25, v25
	v_add_f32_e32 v24, v24, v74
	v_sub_f32_e32 v1, 1.0, v124
	v_add_f32_e32 v29, 1.0, v124
	v_mul_f32_e32 v1, v1, v29
	v_sqrt_f32_e32 v1, v1
	v_mul_f32_e32 v125, v125, v25
	v_mul_f32_e32 v24, 0xbfb8aa3b, v24
	v_exp_f32_e32 v24, v24
	v_pk_mul_f32 v[126:127], v[124:125], v[0:1]
	v_add_f32_e32 v23, v23, v74
	v_pk_fma_f32 v[134:135], v[124:125], v[0:1], v[126:127] op_sel_hi:[1,1,0]
	v_add_f32_e32 v1, v28, v73
	v_mul_f32_e32 v1, 0xbfb8aa3b, v1
	v_exp_f32_e32 v1, v1
	v_add_f32_e32 v24, 1.0, v24
	v_rcp_f32_e32 v24, v24
	v_mul_f32_e32 v23, 0xbfb8aa3b, v23
	v_add_f32_e32 v1, 1.0, v1
	v_rcp_f32_e32 v1, v1
	v_mul_f32_e32 v134, v128, v24
	v_exp_f32_e32 v23, v23
	v_add_f32_e32 v22, v22, v74
	v_mul_f32_e32 v1, v1, v76
	v_mul_f32_e32 v1, 0xbfb8aa3b, v1
	v_exp_f32_e32 v29, v1
	v_add_f32_e32 v23, 1.0, v23
	v_rcp_f32_e32 v23, v23
	v_mul_f32_e32 v22, 0xbfb8aa3b, v22
	v_sub_f32_e32 v1, 1.0, v29
	v_add_f32_e32 v25, 1.0, v29
	v_mul_f32_e32 v1, v1, v25
	v_add_f32_e32 v25, v27, v73
	v_mul_f32_e32 v25, 0xbfb8aa3b, v25
	v_exp_f32_e32 v25, v25
	v_sqrt_f32_e32 v28, v1
	v_mul_f32_e32 v23, v130, v23
	v_exp_f32_e32 v22, v22
	v_add_f32_e32 v25, 1.0, v25
	v_rcp_f32_e32 v25, v25
	v_pk_mul_f32 v[128:129], v[134:135], v[28:29]
	v_add_f32_e32 v22, 1.0, v22
	v_rcp_f32_e32 v22, v22
	v_mul_f32_e32 v25, v25, v76
	v_mul_f32_e32 v25, 0xbfb8aa3b, v25
	v_exp_f32_e32 v28, v25
	v_add_f32_e32 v1, v128, v129
	v_mul_f32_e32 v24, v124, v29
	v_mul_f32_e32 v22, v69, v22
	v_sub_f32_e32 v25, 1.0, v28
	v_add_f32_e32 v27, 1.0, v28
	v_mul_f32_e32 v25, v25, v27
	v_sqrt_f32_e32 v25, v25
	v_mul_f32_e32 v1, v28, v1
	v_mul_f32_e32 v24, v28, v24
	v_mul_f32_e32 v67, v23, v25
	v_add_f32_e32 v23, v26, v73
	v_mul_f32_e32 v23, 0xbfb8aa3b, v23
	v_exp_f32_e32 v23, v23
	s_nop 0
	v_add_f32_e32 v23, 1.0, v23
	v_rcp_f32_e32 v23, v23
	s_nop 0
	v_mul_f32_e32 v23, v23, v76
	v_mul_f32_e32 v23, 0xbfb8aa3b, v23
	v_exp_f32_e32 v27, v23
	s_nop 0
	v_sub_f32_e32 v23, 1.0, v27
	v_add_f32_e32 v25, 1.0, v27
	v_mul_f32_e32 v23, v23, v25
	v_sqrt_f32_e32 v26, v23
	v_add_f32_e32 v23, v1, v67
	v_pk_mul_f32 v[130:131], v[22:23], v[26:27]
	s_nop 0
	v_add_f32_e32 v1, v130, v131
	v_mul_f32_e32 v22, v27, v24
	ds_bpermute_b32 v23, v171, v22
	ds_bpermute_b32 v24, v171, v1
	s_waitcnt lgkmcnt(1)
	v_mul_f32_e32 v73, v22, v23
	s_waitcnt lgkmcnt(0)
	v_cndmask_b32_e64 v69, v24, 0, s[54:55]
	v_fma_f32 v22, v22, v24, v1
	v_fmac_f32_e32 v24, v1, v23
	v_cndmask_b32_e64 v25, v23, 1.0, s[54:55]
	v_cndmask_b32_e64 v1, v22, v24, s[54:55]
	ds_bpermute_b32 v23, v172, v73
	ds_bpermute_b32 v24, v172, v1
	s_waitcnt lgkmcnt(1)
	v_mul_f32_e32 v22, v25, v23
	v_cndmask_b32_e64 v26, v22, v25, s[56:57]
	s_waitcnt lgkmcnt(0)
	v_fma_f32 v22, v25, v24, v69
	v_fma_f32 v25, v73, v24, v1
	v_fmac_f32_e32 v24, v1, v23
	v_cndmask_b32_e64 v69, v22, v69, s[56:57]
	v_mul_f32_e32 v22, v73, v23
	v_cndmask_b32_e64 v23, v25, v24, s[56:57]
	ds_write_b64 v175, v[22:23] offset:62976
	ds_read_b128 v[22:25], v132 offset:44288
	ds_read_b128 v[138:141], v132 offset:53504
	s_waitcnt lgkmcnt(1)
	v_mfma_f32_16x16x32_bf16 v[22:25], v[14:17], v[22:25], 0
	s_waitcnt lgkmcnt(0)
	v_mfma_f32_16x16x32_bf16 v[14:17], v[14:17], v[138:141], 0
	ds_read_b128 v[138:141], v132 offset:44352
	ds_read_b128 v[150:153], v132 offset:53568
	s_waitcnt lgkmcnt(1)
	v_mfma_f32_16x16x32_bf16 v[22:25], v[18:21], v[138:141], v[22:25]
	s_waitcnt lgkmcnt(0)
	v_mfma_f32_16x16x32_bf16 v[14:17], v[18:21], v[150:153], v[14:17]
	ds_read_b32 v20, v174 offset:58048
	ds_read_b32 v21, v174 offset:58304
	ds_read_b32 v73, v174 offset:58560
	s_waitcnt lgkmcnt(2)
	s_nop 1
	v_add_f32_e32 v1, v25, v20
	v_mul_f32_e32 v1, 0xbfb8aa3b, v1
	v_exp_f32_e32 v1, v1
	s_waitcnt lgkmcnt(1)
	v_add_f32_e32 v17, v17, v21
	v_mul_f32_e32 v17, 0xbfb8aa3b, v17
	v_exp_f32_e32 v17, v17
	v_add_f32_e32 v1, 1.0, v1
	v_rcp_f32_e32 v1, v1
	v_add_f32_e32 v16, v16, v21
	v_add_f32_e32 v17, 1.0, v17
	v_rcp_f32_e32 v17, v17
	s_waitcnt lgkmcnt(0)
	v_mul_f32_e32 v1, v1, v73
	v_mul_f32_e32 v1, 0xbfb8aa3b, v1
	v_exp_f32_e32 v132, v1
	v_mul_f32_e32 v133, v133, v17
	v_mul_f32_e32 v16, 0xbfb8aa3b, v16
	v_exp_f32_e32 v16, v16
	v_sub_f32_e32 v1, 1.0, v132
	v_add_f32_e32 v18, 1.0, v132
	v_mul_f32_e32 v1, v1, v18
	v_sqrt_f32_e32 v1, v1
	v_add_f32_e32 v16, 1.0, v16
	v_add_f32_e32 v15, v15, v21
	v_rcp_f32_e32 v16, v16
	v_pk_mul_f32 v[134:135], v[132:133], v[0:1]
	v_mul_f32_e32 v15, 0xbfb8aa3b, v15
	v_pk_fma_f32 v[18:19], v[132:133], v[0:1], v[134:135] op_sel_hi:[1,1,0]
	v_add_f32_e32 v1, v24, v20
	v_mul_f32_e32 v1, 0xbfb8aa3b, v1
	v_exp_f32_e32 v1, v1
	v_exp_f32_e32 v15, v15
	v_mul_f32_e32 v18, v136, v16
	v_add_f32_e32 v14, v14, v21
	v_add_f32_e32 v1, 1.0, v1
	v_rcp_f32_e32 v1, v1
	v_add_f32_e32 v15, 1.0, v15
	v_rcp_f32_e32 v15, v15
	v_mul_f32_e32 v14, 0xbfb8aa3b, v14
	v_mul_f32_e32 v1, v1, v73
	v_mul_f32_e32 v1, 0xbfb8aa3b, v1
	v_exp_f32_e32 v25, v1
	v_mul_f32_e32 v15, v31, v15
	v_exp_f32_e32 v14, v14
	v_sub_f32_e32 v1, 1.0, v25
	v_add_f32_e32 v17, 1.0, v25
	v_mul_f32_e32 v1, v1, v17
	v_sqrt_f32_e32 v24, v1
	v_add_f32_e32 v1, v23, v20
	v_mul_f32_e32 v1, 0xbfb8aa3b, v1
	v_exp_f32_e32 v1, v1
	v_pk_mul_f32 v[136:137], v[18:19], v[24:25]
	v_mul_f32_e32 v17, v132, v25
	v_add_f32_e32 v16, v136, v137
	v_add_f32_e32 v1, 1.0, v1
	v_rcp_f32_e32 v1, v1
	v_add_f32_e32 v14, 1.0, v14
	v_rcp_f32_e32 v14, v14
	v_mul_f32_e32 v1, v1, v73
	v_mul_f32_e32 v1, 0xbfb8aa3b, v1
	v_exp_f32_e32 v1, v1
	v_mul_f32_e32 v14, v71, v14
	v_sub_f32_e32 v18, 1.0, v1
	v_add_f32_e32 v19, 1.0, v1
	v_mul_f32_e32 v18, v18, v19
	v_sqrt_f32_e32 v18, v18
	s_nop 0
	v_mul_f32_e32 v24, v15, v18
	v_mul_f32_e32 v15, v1, v16
	v_mul_f32_e32 v16, v1, v17
	v_add_f32_e32 v17, v22, v20
	v_mul_f32_e32 v17, 0xbfb8aa3b, v17
	v_exp_f32_e32 v17, v17
	v_add_f32_e32 v15, v15, v24
	v_add_f32_e32 v17, 1.0, v17
	v_rcp_f32_e32 v17, v17
	s_nop 0
	v_mul_f32_e32 v17, v17, v73
	v_mul_f32_e32 v17, 0xbfb8aa3b, v17
	v_exp_f32_e32 v23, v17
	s_nop 0
	v_sub_f32_e32 v17, 1.0, v23
	v_add_f32_e32 v18, 1.0, v23
	v_mul_f32_e32 v17, v17, v18
	v_sqrt_f32_e32 v22, v17
	s_nop 0
	v_pk_mul_f32 v[138:139], v[14:15], v[22:23]
	s_nop 0
	v_add_f32_e32 v14, v138, v139
	v_mul_f32_e32 v15, v23, v16
	ds_bpermute_b32 v16, v171, v15
	ds_bpermute_b32 v17, v171, v14
	s_waitcnt lgkmcnt(1)
; #define LAS __attribute__((address_space(3)))
; template <bool PHASE_B>
; __device__ __forceinline__ void lru_item(const Params& p, LAS unsigned char* lds, int ci, int ci_next, int jb, const int tid, v4u (&xvn)[3]) {
;     ...
;     if constexpr (PHASE_B) {
; #pragma unroll
;         for (int dir = 0; dir < 2; ++dir)
; #pragma unroll
;             for (int ct = 0; ct < 4; ++ct) cin[dir][ct] = ((const float*)(p.ws + WS_CIN))[(size_t)(ci * 2 + dir) * 768 + jb * 64 + 16 * ct + fr];
;         const bf16* gp = (const bf16*)(p.ws + WS_GR) + (size_t)(t0 + (tid >> 2)) * 768 + jb * 64 + (tid & 3) * 16;
;         gv[0] = *(const v4u*)gp; gv[1] = *(const v4u*)(gp + 8);
;     }
;     __syncthreads();
;     if constexpr (!PHASE_B) {
;         if (tid < 128) { const int dir = tid >> 6, ch = tid & 63; float A = 1.f, H = 0.f;
; #pragma unroll
;             for (int q = 0; q < 8; ++q) { const f32x2 sh = ((const LAS f32x2*)(lds + LR_SEG))[(dir * 8 + (dir ? 7 - q : q)) * 64 + ch]; H = sh.x * H + sh.y; A *= sh.x; }
;             ((f32x2*)(p.ws + WS_CAR))[(size_t)(ci * 2 + dir) * 768 + jb * 64 + ch] = (f32x2){A, H}; }
;     } else {
; #pragma unroll
;         for (int dir = 0; dir < 2; ++dir) { const int ot = dir ? 7 - rt : rt;
; #pragma unroll
;             for (int ct = 0; ct < 4; ++ct) { const int ch = 16 * ct + fr; float h = cin[dir][ct];
; #pragma unroll
;                 for (int q = 0; q < 7; ++q) { const f32x2 sh = ((const LAS f32x2*)(lds + LR_SEG))[(dir * 8 + (dir ? 7 - q : q)) * 64 + ch]; const float nh = sh.x * h + sh.y; h = (q < ot) ? nh : h; }
;                 h = pA[dir][ct] * h + pH[dir][ct];
; #pragma unroll
;                 for (int ee = 0; ee < 4; ++ee) { const int e = dir ? 3 - ee : ee; h = av[dir][ct][e] * h + uv[dir][ct][e];
;                     ((LAS float*)(lds + LR_HB))[(dir * LCH + 16 * rt + 4 * fq + e) * 68 + ch] = h; } } }
	v_mul_f32_e32 v20, v15, v16
	s_waitcnt lgkmcnt(0)
	v_cndmask_b32_e64 v19, v17, 0, s[54:55]
	v_fma_f32 v15, v15, v17, v14
	v_fmac_f32_e32 v17, v14, v16
	v_cndmask_b32_e64 v18, v16, 1.0, s[54:55]
	v_cndmask_b32_e64 v15, v15, v17, s[54:55]
	ds_bpermute_b32 v16, v172, v20
	ds_bpermute_b32 v17, v172, v15
	s_waitcnt lgkmcnt(1)
	v_mul_f32_e32 v14, v18, v16
	v_cndmask_b32_e64 v22, v14, v18, s[56:57]
	s_waitcnt lgkmcnt(0)
	v_fma_f32 v14, v18, v17, v19
	v_fma_f32 v18, v20, v17, v15
	v_fmac_f32_e32 v17, v15, v16
	v_cndmask_b32_e64 v31, v14, v19, s[56:57]
	v_mul_f32_e32 v14, v20, v16
	v_cndmask_b32_e64 v15, v18, v17, s[56:57]
	ds_write_b64 v175, v[14:15] offset:63104
	v_mad_i64_i32 v[14:15], s[0:1], s13, v232, v[32:33]
	global_load_dword v78, v[14:15], off
	global_load_dword v81, v[14:15], off offset:64
	global_load_dword v83, v[14:15], off offset:128
	global_load_dword v85, v[14:15], off offset:192
	s_add_i32 s0, s13, 1
	v_mad_i64_i32 v[14:15], s[0:1], s0, v232, v[32:33]
	s_movk_i32 s0, 0x600
	s_nop 0
	v_mad_i64_i32 v[140:141], s[0:1], v196, s0, v[34:35]
	global_load_dword v76, v[14:15], off
	global_load_dword v74, v[14:15], off offset:64
	global_load_dword v73, v[14:15], off offset:128
	global_load_dword v71, v[14:15], off offset:192
	s_nop 0
	global_load_dwordx4 v[14:17], v[140:141], off offset:16
	global_load_dwordx4 v[18:21], v[140:141], off
	s_waitcnt lgkmcnt(0)
	s_barrier
	ds_read_b64 v[150:151], v176 offset:58624
	v_add_u32_e32 v196, s12, v196
	s_add_i32 s13, s13, s86
	s_waitcnt vmcnt(9) lgkmcnt(0)
	v_fmac_f32_e32 v151, v78, v150
	v_cndmask_b32_e64 v78, v78, v151, s[58:59]
	ds_read_b64 v[150:151], v176 offset:59136
	s_waitcnt lgkmcnt(0)
	v_fmac_f32_e32 v151, v150, v78
	v_cndmask_b32_e64 v78, v78, v151, s[60:61]
	ds_read_b64 v[150:151], v176 offset:59648
	s_waitcnt lgkmcnt(0)
	v_fmac_f32_e32 v151, v150, v78
	v_cndmask_b32_e64 v78, v78, v151, s[62:63]
	ds_read_b64 v[150:151], v176 offset:60160
	s_waitcnt lgkmcnt(0)
	v_fmac_f32_e32 v151, v150, v78
	v_cndmask_b32_e64 v78, v78, v151, s[64:65]
	ds_read_b64 v[150:151], v176 offset:60672
	s_waitcnt lgkmcnt(0)
	v_fmac_f32_e32 v151, v150, v78
	v_cndmask_b32_e64 v78, v78, v151, s[66:67]
	ds_read_b64 v[150:151], v176 offset:61184
	s_waitcnt lgkmcnt(0)
	v_fmac_f32_e32 v151, v150, v78
	v_cndmask_b32_e64 v78, v78, v151, s[68:69]
	ds_read_b64 v[150:151], v176 offset:61696
	s_waitcnt lgkmcnt(0)
	v_fmac_f32_e32 v151, v150, v78
	v_cndmask_b32_e64 v78, v78, v151, s[70:71]
	v_fmac_f32_e32 v39, v206, v78
	v_fmac_f32_e32 v49, v38, v39
	v_fmac_f32_e32 v50, v41, v49
	v_fmac_f32_e32 v52, v43, v50
	v_fmac_f32_e32 v54, v47, v52
	ds_write2_b32 v202, v49, v50 offset1:68
	ds_write2_b32 v202, v52, v54 offset0:136 offset1:204
	ds_read_b64 v[38:39], v176 offset:58752
	s_waitcnt vmcnt(0)
	v_lshlrev_b32_e32 v52, 16, v18
	v_and_b32_e32 v18, 0xffff0000, v18
	s_waitcnt lgkmcnt(0)
	v_fmac_f32_e32 v39, v81, v38
	v_cndmask_b32_e64 v41, v81, v39, s[58:59]
	ds_read_b64 v[38:39], v176 offset:59264
	s_waitcnt lgkmcnt(0)
	v_fmac_f32_e32 v39, v38, v41
	v_cndmask_b32_e64 v41, v41, v39, s[60:61]
	ds_read_b64 v[38:39], v176 offset:59776
	s_waitcnt lgkmcnt(0)
	v_fmac_f32_e32 v39, v38, v41
	v_cndmask_b32_e64 v41, v41, v39, s[62:63]
	ds_read_b64 v[38:39], v176 offset:60288
	s_waitcnt lgkmcnt(0)
	v_fmac_f32_e32 v39, v38, v41
	v_cndmask_b32_e64 v41, v41, v39, s[64:65]
	ds_read_b64 v[38:39], v176 offset:60800
	s_waitcnt lgkmcnt(0)
	v_fmac_f32_e32 v39, v38, v41
	v_cndmask_b32_e64 v41, v41, v39, s[66:67]
	ds_read_b64 v[38:39], v176 offset:61312
	s_waitcnt lgkmcnt(0)
	v_fmac_f32_e32 v39, v38, v41
	v_cndmask_b32_e64 v41, v41, v39, s[68:69]
	ds_read_b64 v[38:39], v176 offset:61824
	s_waitcnt lgkmcnt(0)
	v_fmac_f32_e32 v39, v38, v41
	v_cndmask_b32_e64 v38, v41, v39, s[70:71]
	v_fmac_f32_e32 v42, v40, v38
	v_fmac_f32_e32 v65, v56, v42
	v_fmac_f32_e32 v66, v59, v65
	v_fmac_f32_e32 v68, v61, v66
	v_fmac_f32_e32 v70, v63, v68
	ds_write_b32 v177, v65
	ds_write_b32 v178, v66
	ds_write_b32 v179, v68
	ds_write_b32 v180, v70
	ds_read_b64 v[38:39], v176 offset:58880
	s_waitcnt lgkmcnt(0)
	v_fmac_f32_e32 v39, v83, v38
	v_cndmask_b32_e64 v40, v83, v39, s[58:59]
	ds_read_b64 v[38:39], v176 offset:59392
	s_waitcnt lgkmcnt(0)
	v_fmac_f32_e32 v39, v38, v40
	v_cndmask_b32_e64 v40, v40, v39, s[60:61]
	ds_read_b64 v[38:39], v176 offset:59904
	s_waitcnt lgkmcnt(0)
	v_fmac_f32_e32 v39, v38, v40
	v_cndmask_b32_e64 v40, v40, v39, s[62:63]
	ds_read_b64 v[38:39], v176 offset:60416
	s_waitcnt lgkmcnt(0)
	v_fmac_f32_e32 v39, v38, v40
	v_cndmask_b32_e64 v40, v40, v39, s[64:65]
	ds_read_b64 v[38:39], v176 offset:60928
	s_waitcnt lgkmcnt(0)
	v_fmac_f32_e32 v39, v38, v40
	v_cndmask_b32_e64 v40, v40, v39, s[66:67]
	ds_read_b64 v[38:39], v176 offset:61440
	s_waitcnt lgkmcnt(0)
	v_fmac_f32_e32 v39, v38, v40
	v_cndmask_b32_e64 v40, v40, v39, s[68:69]
	ds_read_b64 v[38:39], v176 offset:61952
	s_waitcnt lgkmcnt(0)
	v_fmac_f32_e32 v39, v38, v40
	v_cndmask_b32_e64 v38, v40, v39, s[70:71]
	v_fmac_f32_e32 v44, v46, v38
	v_fmac_f32_e32 v45, v72, v44
	v_fmac_f32_e32 v80, v75, v45
	v_fmac_f32_e32 v82, v77, v80
	v_fmac_f32_e32 v84, v79, v82
	ds_write_b32 v181, v45
	ds_write_b32 v182, v80
	ds_write_b32 v183, v82
	ds_write_b32 v184, v84
	ds_read_b64 v[38:39], v176 offset:59008
	s_waitcnt lgkmcnt(0)
	v_fmac_f32_e32 v39, v85, v38
	v_cndmask_b32_e64 v40, v85, v39, s[58:59]
	ds_read_b64 v[38:39], v176 offset:59520
	s_waitcnt lgkmcnt(0)
	v_fmac_f32_e32 v39, v38, v40
	v_cndmask_b32_e64 v40, v40, v39, s[60:61]
	ds_read_b64 v[38:39], v176 offset:60032
	s_waitcnt lgkmcnt(0)
	v_fmac_f32_e32 v39, v38, v40
	v_cndmask_b32_e64 v40, v40, v39, s[62:63]
	ds_read_b64 v[38:39], v176 offset:60544
	s_waitcnt lgkmcnt(0)
; #define LAS __attribute__((address_space(3)))
; template <bool PHASE_B>
; __device__ __forceinline__ void lru_item(const Params& p, LAS unsigned char* lds, int ci, int ci_next, int jb, const int tid, v4u (&xvn)[3]) {
;     ...
;     } else {
; #pragma unroll
;         for (int dir = 0; dir < 2; ++dir) { const int ot = dir ? 7 - rt : rt;
; #pragma unroll
;             for (int ct = 0; ct < 4; ++ct) { const int ch = 16 * ct + fr; float h = cin[dir][ct];
; #pragma unroll
;                 for (int q = 0; q < 7; ++q) { const f32x2 sh = ((const LAS f32x2*)(lds + LR_SEG))[(dir * 8 + (dir ? 7 - q : q)) * 64 + ch]; const float nh = sh.x * h + sh.y; h = (q < ot) ? nh : h; }
;                 h = pA[dir][ct] * h + pH[dir][ct];
; #pragma unroll
;                 for (int ee = 0; ee < 4; ++ee) { const int e = dir ? 3 - ee : ee; h = av[dir][ct][e] * h + uv[dir][ct][e];
;                     ((LAS float*)(lds + LR_HB))[(dir * LCH + 16 * rt + 4 * fq + e) * 68 + ch] = h; } } }
;         __syncthreads();
	v_fmac_f32_e32 v39, v38, v40
	v_cndmask_b32_e64 v40, v40, v39, s[64:65]
	ds_read_b64 v[38:39], v176 offset:61056
	s_waitcnt lgkmcnt(0)
	v_fmac_f32_e32 v39, v38, v40
	v_cndmask_b32_e64 v40, v40, v39, s[66:67]
	ds_read_b64 v[38:39], v176 offset:61568
	s_waitcnt lgkmcnt(0)
	v_fmac_f32_e32 v39, v38, v40
	v_cndmask_b32_e64 v40, v40, v39, s[68:69]
	ds_read_b64 v[38:39], v176 offset:62080
	s_waitcnt lgkmcnt(0)
	v_fmac_f32_e32 v39, v38, v40
	v_cndmask_b32_e64 v38, v40, v39, s[70:71]
	v_fmac_f32_e32 v36, v48, v38
	v_fmac_f32_e32 v37, v86, v36
	v_fmac_f32_e32 v94, v89, v37
	v_fmac_f32_e32 v96, v91, v94
	v_fmac_f32_e32 v98, v93, v96
	ds_write_b32 v185, v37
	ds_write_b32 v186, v94
	ds_write_b32 v187, v96
	ds_write_b32 v188, v98
	ds_read2st64_b64 v[36:39], v190 offset0:6 offset1:7
	s_waitcnt lgkmcnt(0)
	v_fma_f32 v38, v76, v38, v39
	v_cndmask_b32_e64 v38, v76, v38, s[72:73]
	v_fmac_f32_e32 v37, v36, v38
	v_cndmask_b32_e64 v38, v38, v37, s[74:75]
	ds_read_b64 v[36:37], v176 offset:65280
	s_waitcnt lgkmcnt(0)
	v_fmac_f32_e32 v37, v36, v38
	v_cndmask_b32_e64 v38, v38, v37, s[76:77]
	ds_read_b64 v[36:37], v176 offset:64768
	s_waitcnt lgkmcnt(0)
	v_fmac_f32_e32 v37, v36, v38
	v_cndmask_b32_e64 v38, v38, v37, s[78:79]
	ds_read_b64 v[36:37], v176 offset:64256
	s_waitcnt lgkmcnt(0)
	v_fmac_f32_e32 v37, v36, v38
	v_cndmask_b32_e64 v38, v38, v37, s[80:81]
	ds_read_b64 v[36:37], v176 offset:63744
	s_waitcnt lgkmcnt(0)
	v_fmac_f32_e32 v37, v36, v38
	v_cndmask_b32_e64 v38, v38, v37, s[82:83]
	ds_read_b64 v[36:37], v176 offset:63232
	s_waitcnt lgkmcnt(0)
	v_fmac_f32_e32 v37, v36, v38
	v_cndmask_b32_e64 v36, v38, v37, s[84:85]
	v_fmac_f32_e32 v57, v55, v36
	v_fmac_f32_e32 v103, v100, v57
	v_fmac_f32_e32 v106, v105, v103
	v_fmac_f32_e32 v53, v51, v106
	v_add_u32_e32 v36, 0x8800, v202
	v_fmac_f32_e32 v110, v109, v53
	ds_write2_b32 v36, v106, v103 offset0:136 offset1:204
	ds_write2_b32 v36, v110, v53 offset1:68
	ds_read2st64_b64 v[36:39], v191 offset0:6 offset1:7
	v_lshlrev_b32_e32 v53, 16, v19
	v_and_b32_e32 v19, 0xffff0000, v19
	s_waitcnt lgkmcnt(0)
	v_fma_f32 v38, v74, v38, v39
	v_cndmask_b32_e64 v38, v74, v38, s[72:73]
	v_fmac_f32_e32 v37, v36, v38
	v_cndmask_b32_e64 v38, v38, v37, s[74:75]
	ds_read_b64 v[36:37], v176 offset:65408
	s_waitcnt lgkmcnt(0)
	v_fmac_f32_e32 v37, v36, v38
	v_cndmask_b32_e64 v38, v38, v37, s[76:77]
	ds_read_b64 v[36:37], v176 offset:64896
	s_waitcnt lgkmcnt(0)
	v_fmac_f32_e32 v37, v36, v38
	v_cndmask_b32_e64 v38, v38, v37, s[78:79]
	ds_read_b64 v[36:37], v176 offset:64384
	s_waitcnt lgkmcnt(0)
	v_fmac_f32_e32 v37, v36, v38
	v_cndmask_b32_e64 v38, v38, v37, s[80:81]
	ds_read_b64 v[36:37], v176 offset:63872
	s_waitcnt lgkmcnt(0)
	v_fmac_f32_e32 v37, v36, v38
	v_cndmask_b32_e64 v38, v38, v37, s[82:83]
	ds_read_b64 v[36:37], v176 offset:63360
	s_waitcnt lgkmcnt(0)
	v_fmac_f32_e32 v37, v36, v38
	v_cndmask_b32_e64 v36, v38, v37, s[84:85]
	v_fmac_f32_e32 v64, v62, v36
	v_fmac_f32_e32 v115, v112, v64
	v_fmac_f32_e32 v118, v117, v115
	v_fmac_f32_e32 v60, v58, v118
	v_add_u32_e32 v36, 0x8800, v203
	v_fmac_f32_e32 v122, v121, v60
	ds_write2_b32 v36, v118, v115 offset0:136 offset1:204
	ds_write2_b32 v36, v122, v60 offset1:68
	ds_read_b64 v[36:37], v192 offset:3584
	s_waitcnt lgkmcnt(0)
	v_fmac_f32_e32 v37, v73, v36
	v_cndmask_b32_e64 v40, v73, v37, s[72:73]
	ds_read2st64_b64 v[36:39], v192 offset0:5 offset1:6
	s_waitcnt lgkmcnt(0)
	v_fma_f32 v38, v38, v40, v39
	v_cndmask_b32_e64 v38, v40, v38, s[74:75]
	v_fmac_f32_e32 v37, v36, v38
	v_cndmask_b32_e64 v38, v38, v37, s[76:77]
	ds_read_b64 v[36:37], v176 offset:65024
	s_waitcnt lgkmcnt(0)
	v_fmac_f32_e32 v37, v36, v38
	v_cndmask_b32_e64 v38, v38, v37, s[78:79]
	ds_read_b64 v[36:37], v176 offset:64512
	s_waitcnt lgkmcnt(0)
	v_fmac_f32_e32 v37, v36, v38
	v_cndmask_b32_e64 v38, v38, v37, s[80:81]
	ds_read_b64 v[36:37], v176 offset:64000
	s_waitcnt lgkmcnt(0)
	v_fmac_f32_e32 v37, v36, v38
	v_cndmask_b32_e64 v38, v38, v37, s[82:83]
	ds_read_b64 v[36:37], v176 offset:63488
	s_waitcnt lgkmcnt(0)
	v_fmac_f32_e32 v37, v36, v38
	v_cndmask_b32_e64 v36, v38, v37, s[84:85]
	v_fmac_f32_e32 v69, v26, v36
	v_fmac_f32_e32 v127, v124, v69
	v_fmac_f32_e32 v128, v29, v127
	v_fmac_f32_e32 v67, v28, v128
	v_add_u32_e32 v26, 0x8800, v204
	v_fmac_f32_e32 v130, v27, v67
	ds_write2_b32 v26, v128, v127 offset0:136 offset1:204
	ds_write2_b32 v26, v130, v67 offset1:68
	ds_read_b64 v[26:27], v194 offset:3584
	s_waitcnt lgkmcnt(0)
	v_fmac_f32_e32 v27, v71, v26
	v_cndmask_b32_e64 v36, v71, v27, s[72:73]
	ds_read2st64_b64 v[26:29], v194 offset0:5 offset1:6
	s_waitcnt lgkmcnt(0)
	v_fma_f32 v28, v28, v36, v29
	v_cndmask_b32_e64 v28, v36, v28, s[74:75]
	v_fmac_f32_e32 v27, v26, v28
	v_cndmask_b32_e64 v28, v28, v27, s[76:77]
	ds_read_b64 v[26:27], v176 offset:65152
	s_waitcnt lgkmcnt(0)
	v_fmac_f32_e32 v27, v26, v28
	v_cndmask_b32_e64 v28, v28, v27, s[78:79]
	ds_read_b64 v[26:27], v176 offset:64640
	s_waitcnt lgkmcnt(0)
	v_fmac_f32_e32 v27, v26, v28
	v_cndmask_b32_e64 v28, v28, v27, s[80:81]
	ds_read_b64 v[26:27], v176 offset:64128
	s_waitcnt lgkmcnt(0)
	v_fmac_f32_e32 v27, v26, v28
	v_cndmask_b32_e64 v28, v28, v27, s[82:83]
	ds_read_b64 v[26:27], v176 offset:63616
	s_waitcnt lgkmcnt(0)
	v_fmac_f32_e32 v27, v26, v28
	v_cndmask_b32_e64 v26, v28, v27, s[84:85]
	v_fmac_f32_e32 v31, v22, v26
	v_fmac_f32_e32 v135, v132, v31
	v_fmac_f32_e32 v136, v25, v135
	v_fmac_f32_e32 v24, v1, v136
	v_add_u32_e32 v22, 0x8800, v205
	v_fmac_f32_e32 v138, v23, v24
	ds_write2_b32 v22, v136, v135 offset0:136 offset1:204
	ds_write2_b32 v22, v138, v24 offset1:68
	s_waitcnt lgkmcnt(0)
	s_barrier
; #define LAS __attribute__((address_space(3)))
; __device__ __forceinline__ unsigned pk2(float lo, float hi) { return f2bf(lo) | (f2bf(hi) << 16); }
; template <bool PHASE_B>
; __device__ __forceinline__ void lru_item(const Params& p, LAS unsigned char* lds, int ci, int ci_next, int jb, const int tid, v4u (&xvn)[3]) {
;     ...
;         { const int t = tid >> 2, c0 = (tid & 3) * 16; bf16* gp = (bf16*)(p.ws + WS_GR) + (size_t)(t0 + t) * 768 + jb * 64 + c0;
;           const LAS float* H0 = (const LAS float*)(lds + LR_HB) + t * 68 + c0; const LAS float* H1 = H0 + LCH * 68;
; #pragma unroll
;           for (int hf = 0; hf < 2; ++hf) { const f32x4 a0 = *(const LAS f32x4*)(H0 + 8 * hf), a1 = *(const LAS f32x4*)(H0 + 8 * hf + 4), b0 = *(const LAS f32x4*)(H1 + 8 * hf), b1 = *(const LAS f32x4*)(H1 + 8 * hf + 4);
;               const v4u g = gv[hf]; v4u o;
;               o.x = pk2(bflo(g.x) * (a0[0] + b0[0]), bfhi(g.x) * (a0[1] + b0[1])); o.y = pk2(bflo(g.y) * (a0[2] + b0[2]), bfhi(g.y) * (a0[3] + b0[3]));
;               o.z = pk2(bflo(g.z) * (a1[0] + b1[0]), bfhi(g.z) * (a1[1] + b1[1])); o.w = pk2(bflo(g.w) * (a1[2] + b1[2]), bfhi(g.w) * (a1[3] + b1[3]));
;               *(v4u*)(gp + 8 * hf) = o; } }
	ds_read_b128 v[22:25], v195
	ds_read_b128 v[26:29], v195 offset:16
	ds_read_b128 v[36:39], v195 offset:32
	ds_read_b128 v[40:43], v195 offset:48
	ds_read_b128 v[44:47], v195 offset:34816
	ds_read_b128 v[48:51], v195 offset:34832
	s_waitcnt lgkmcnt(1)
	v_pk_add_f32 v[24:25], v[24:25], v[46:47]
	v_pk_add_f32 v[22:23], v[22:23], v[44:45]
	v_mov_b32_e32 v45, v24
	v_mov_b32_e32 v24, v23
	v_pk_mul_f32 v[18:19], v[24:25], v[18:19]
	s_waitcnt lgkmcnt(0)
	v_pk_add_f32 v[24:25], v[28:29], v[50:51]
	v_pk_add_f32 v[26:27], v[26:27], v[48:49]
	v_mov_b32_e32 v44, v22
	v_lshlrev_b32_e32 v23, 16, v21
	v_lshlrev_b32_e32 v22, 16, v20
	v_mov_b32_e32 v29, v24
	v_and_b32_e32 v21, 0xffff0000, v21
	v_and_b32_e32 v20, 0xffff0000, v20
	v_mov_b32_e32 v24, v27
	v_mov_b32_e32 v28, v26
	v_pk_mul_f32 v[20:21], v[24:25], v[20:21]
	v_pk_mul_f32 v[44:45], v[44:45], v[52:53]
	v_pk_mul_f32 v[22:23], v[28:29], v[22:23]
	v_bfe_u32 v1, v21, 16, 1
	v_add3_u32 v1, v21, v1, s33
	v_bfe_u32 v26, v23, 16, 1
	v_add3_u32 v23, v23, v26, s33
	v_lshrrev_b32_e32 v21, 16, v23
	v_and_or_b32 v21, v1, s11, v21
	v_cvt_pk_bf16_f32 v20, v22, v20
	v_cvt_pk_bf16_f32 v19, v45, v19
	v_cvt_pk_bf16_f32 v18, v44, v18
	global_store_dwordx4 v[140:141], v[18:21], off
	ds_read_b128 v[18:21], v195 offset:34848
	ds_read_b128 v[22:25], v195 offset:34864
	v_lshlrev_b32_e32 v27, 16, v15
	v_lshlrev_b32_e32 v26, 16, v14
	v_and_b32_e32 v15, 0xffff0000, v15
	s_waitcnt lgkmcnt(1)
	v_pk_add_f32 v[20:21], v[38:39], v[20:21]
	v_pk_add_f32 v[18:19], v[36:37], v[18:19]
	v_mov_b32_e32 v29, v20
	v_and_b32_e32 v14, 0xffff0000, v14
	v_mov_b32_e32 v20, v19
	v_pk_mul_f32 v[14:15], v[20:21], v[14:15]
	s_waitcnt lgkmcnt(0)
	v_pk_add_f32 v[20:21], v[42:43], v[24:25]
	v_pk_add_f32 v[22:23], v[40:41], v[22:23]
	v_mov_b32_e32 v28, v18
	v_lshlrev_b32_e32 v19, 16, v17
	v_lshlrev_b32_e32 v18, 16, v16
	v_mov_b32_e32 v25, v20
	v_and_b32_e32 v17, 0xffff0000, v17
	v_and_b32_e32 v16, 0xffff0000, v16
	v_mov_b32_e32 v20, v23
	v_mov_b32_e32 v24, v22
	v_pk_mul_f32 v[16:17], v[20:21], v[16:17]
	v_pk_mul_f32 v[26:27], v[28:29], v[26:27]
	v_pk_mul_f32 v[18:19], v[24:25], v[18:19]
	v_bfe_u32 v1, v17, 16, 1
	v_bfe_u32 v20, v16, 16, 1
	v_add3_u32 v16, v16, v20, s33
	v_add3_u32 v1, v17, v1, s33
	v_bfe_u32 v21, v18, 16, 1
	v_bfe_u32 v22, v19, 16, 1
	v_add3_u32 v19, v19, v22, s33
	v_add3_u32 v18, v18, v21, s33
	v_lshrrev_b32_e32 v21, 16, v17
	v_lshrrev_b32_e32 v20, 16, v20
	v_lshrrev_b32_e32 v18, 16, v18
	v_lshrrev_b32_e32 v17, 16, v19
	v_and_or_b32 v17, v1, s11, v17
	v_and_or_b32 v16, v16, s11, v18
	v_cvt_pk_bf16_f32 v15, v27, v15
	v_cvt_pk_bf16_f32 v14, v26, v14
	global_store_dwordx4 v[140:141], v[14:17], off offset:16
	s_cbranch_vccnz .LBB0_353

; __device__ __forceinline__ unsigned pk2(float lo, float hi) { return f2bf(lo) | (f2bf(hi) << 16); }
; __device__ __forceinline__ void attn_merge(const Params& p, int gt, int ngt) {
;     ...
;     for (int idx = gt; idx < T * 32; idx += ngt) { const int m = idx >> 5, c8 = idx & 31, h = c8 >> 3;
;         const float l0 = LSE[(size_t)m * 12 + h], l1 = LSE[(size_t)m * 12 + 4 + h], l2 = LSE[(size_t)m * 12 + 8 + h];
;         const float mx = fmaxf(l0, fmaxf(l1, l2)); float w0 = __expf(l0 - mx), w1 = __expf(l1 - mx), w2 = __expf(l2 - mx); const float inv = 1.f / (w0 + w1 + w2); w0 *= inv; w1 *= inv; w2 *= inv;
;         const bf16* o = QKVX + (size_t)m * 3072 + c8 * 8;
;         const v4u a = *(const v4u*)o, b = *(const v4u*)(o + 256), c = *(const v4u*)(o + 512);
;         v4u r;
;         r.x = pk2(w0 * bflo(a.x) + w1 * bflo(b.x) + w2 * bflo(c.x), w0 * bfhi(a.x) + w1 * bfhi(b.x) + w2 * bfhi(c.x));
;         r.y = pk2(w0 * bflo(a.y) + w1 * bflo(b.y) + w2 * bflo(c.y), w0 * bfhi(a.y) + w1 * bfhi(b.y) + w2 * bfhi(c.y));
;         r.z = pk2(w0 * bflo(a.z) + w1 * bflo(b.z) + w2 * bflo(c.z), w0 * bfhi(a.z) + w1 * bfhi(b.z) + w2 * bfhi(c.z));
;         r.w = pk2(w0 * bflo(a.w) + w1 * bflo(b.w) + w2 * bflo(c.w), w0 * bfhi(a.w) + w1 * bfhi(b.w) + w2 * bfhi(c.w));
;         *(v4u*)(AT + (size_t)m * 256 + c8 * 8) = r; }
.LBB0_361:
	v_ashrrev_i32_e32 v20, 5, v1
	v_mad_i64_i32 v[8:9], s[8:9], v20, 48, v[6:7]
	global_load_dword v10, v[8:9], off
	global_load_dword v11, v[8:9], off offset:16
	s_nop 0
	global_load_dword v8, v[8:9], off offset:32
	v_mad_i64_i32 v[16:17], s[8:9], v20, s64, v[2:3]
	v_ashrrev_i32_e32 v21, 31, v20
	v_add_u32_e32 v1, s6, v1
	s_mov_b32 s7, 0xfffff
	s_waitcnt vmcnt(0)
	v_max3_f32 v9, v10, v11, v8
	v_sub_f32_e32 v10, v10, v9
	v_mul_f32_e32 v10, 0x3fb8aa3b, v10
	v_exp_f32_e32 v23, v10
	v_sub_f32_e32 v10, v11, v9
	v_mul_f32_e32 v10, 0x3fb8aa3b, v10
	v_sub_f32_e32 v8, v8, v9
	v_exp_f32_e32 v22, v10
	v_mul_f32_e32 v8, 0x3fb8aa3b, v8
	v_exp_f32_e32 v8, v8
	v_add_f32_e32 v9, v23, v22
	v_add_f32_e32 v9, v8, v9
	v_div_scale_f32 v10, s[8:9], v9, v9, 1.0
	v_rcp_f32_e32 v11, v10
	s_nop 0
	v_fma_f32 v12, -v10, v11, 1.0
	v_fmac_f32_e32 v11, v12, v11
	v_div_scale_f32 v12, vcc, 1.0, v9, 1.0
	v_mul_f32_e32 v13, v12, v11
	v_fma_f32 v14, -v10, v13, v12
	v_fmac_f32_e32 v13, v14, v11
	v_fma_f32 v10, -v10, v13, v12
	v_div_fmas_f32 v10, v10, v11, v13
	v_div_fixup_f32 v24, v10, v9, 1.0
	v_mul_f32_e32 v26, v8, v24
	global_load_dwordx4 v[8:11], v[16:17], off
	global_load_dwordx4 v[12:15], v[16:17], off offset:512
	s_nop 0
	global_load_dwordx4 v[16:19], v[16:17], off offset:1024
	v_pk_mul_f32 v[22:23], v[22:23], v[24:25] op_sel_hi:[1,0]
	v_cmp_lt_i32_e32 vcc, s7, v1
	s_or_b64 s[4:5], vcc, s[4:5]
	s_waitcnt vmcnt(0)
	v_lshlrev_b32_e32 v28, 16, v8
	v_lshlrev_b32_e32 v29, 16, v13
	v_lshlrev_b32_e32 v25, 16, v9
	v_lshlrev_b32_e32 v24, 16, v12
	v_pk_mul_f32 v[28:29], v[22:23], v[28:29] op_sel:[1,0] op_sel_hi:[0,1]
	v_pk_fma_f32 v[24:25], v[22:23], v[24:25], v[28:29]
	v_lshlrev_b32_e32 v29, 16, v17
	v_lshlrev_b32_e32 v28, 16, v16
	v_pk_fma_f32 v[24:25], v[26:27], v[28:29], v[24:25] op_sel_hi:[0,1,1]
	v_and_b32_e32 v29, 0xffff0000, v9
	v_and_b32_e32 v9, 0xffff0000, v13
	v_and_b32_e32 v8, 0xffff0000, v8
	v_and_b32_e32 v28, 0xffff0000, v12
	v_pk_mul_f32 v[8:9], v[22:23], v[8:9] op_sel:[1,0] op_sel_hi:[0,1]
	v_pk_fma_f32 v[8:9], v[22:23], v[28:29], v[8:9]
	v_and_b32_e32 v13, 0xffff0000, v17
	v_and_b32_e32 v12, 0xffff0000, v16
	v_lshlrev_b32_e32 v17, 16, v15
	v_lshlrev_b32_e32 v16, 16, v10
	v_pk_fma_f32 v[8:9], v[26:27], v[12:13], v[8:9] op_sel_hi:[0,1,1]
	v_lshlrev_b32_e32 v13, 16, v11
	v_lshlrev_b32_e32 v12, 16, v14
	v_pk_mul_f32 v[16:17], v[22:23], v[16:17] op_sel:[1,0] op_sel_hi:[0,1]
	v_pk_fma_f32 v[12:13], v[22:23], v[12:13], v[16:17]
	v_lshlrev_b32_e32 v17, 16, v19
	v_lshlrev_b32_e32 v16, 16, v18
	v_pk_fma_f32 v[12:13], v[26:27], v[16:17], v[12:13] op_sel_hi:[0,1,1]
	v_and_b32_e32 v17, 0xffff0000, v11
	v_and_b32_e32 v11, 0xffff0000, v15
	v_and_b32_e32 v10, 0xffff0000, v10
	v_and_b32_e32 v16, 0xffff0000, v14
	v_pk_mul_f32 v[10:11], v[22:23], v[10:11] op_sel:[1,0] op_sel_hi:[0,1]
	v_pk_fma_f32 v[10:11], v[22:23], v[16:17], v[10:11]
	v_and_b32_e32 v15, 0xffff0000, v19
	v_and_b32_e32 v14, 0xffff0000, v18
	v_pk_fma_f32 v[10:11], v[26:27], v[14:15], v[10:11] op_sel_hi:[0,1,1]
	v_bfe_u32 v16, v12, 16, 1
	v_bfe_u32 v17, v13, 16, 1
	v_lshrrev_b32_e32 v14, 16, v14
	v_lshrrev_b32_e32 v15, 16, v15
	v_cvt_pk_bf16_f32 v11, v13, v11
	v_cvt_pk_bf16_f32 v10, v12, v10
	v_lshlrev_b64 v[12:13], 9, v[20:21]
	v_cvt_pk_bf16_f32 v9, v25, v9
	v_cvt_pk_bf16_f32 v8, v24, v8
	v_lshl_add_u64 v[12:13], v[4:5], 0, v[12:13]
	global_store_dwordx4 v[12:13], v[8:11], off
	s_andn2_b64 exec, exec, s[4:5]
	s_cbranch_execnz .LBB0_361

; #define LAS __attribute__((address_space(3)))
; __device__ __forceinline__ unsigned pk2(float lo, float hi) { return f2bf(lo) | (f2bf(hi) << 16); }
; #define MFMA16(a, b, c) __builtin_amdgcn_mfma_f32_16x16x32_bf16(a, b, c, 0, 0, 0)
; __device__ __forceinline__ v4i16_t vtr(const LAS unsigned char* p) { return __builtin_amdgcn_ds_read_tr16_b64_v4i16((LAS v4i16_t*)p); }
; __device__ __forceinline__ void attn_phase(const Params& p, LAS unsigned char* lds, const int bx, const int G, const int tid) {
;     ...
;         const int qi = 16 * wq + fr; float mx = -3e38f;
; #pragma unroll
;         for (int j = 0; j < 9; ++j)
; #pragma unroll
;             for (int e = 0; e < 4; ++e) { const int u = 16 * (wq + j) + 4 * fq + e, jk = X.nb * 64 - 64 + u, dl = u - 64 - qi; const bool ok = jk >= 0 && jk < X.n && dl >= -64 && dl <= 64;
;                 const float b = ((const LAS float*)(L + AT_BIAS))[ok ? dl + 64 : 0]; const float sv = ok ? st[j][e] + b : -1e30f; st[j][e] = sv; mx = fmaxf(mx, sv); }
;         mx = fmaxf(mx, __shfl_xor(mx, 16)); mx = fmaxf(mx, __shfl_xor(mx, 32));
;         float sm = 0.f;
; #pragma unroll
;         for (int j = 0; j < 9; ++j)
; #pragma unroll
;             for (int e = 0; e < 4; ++e) { const float pv = __expf(st[j][e] - mx); st[j][e] = pv; sm += pv; }
;         sm += __shfl_xor(sm, 16); sm += __shfl_xor(sm, 32);
;         f32x4 ot[4];
; #pragma unroll
;         for (int dt = 0; dt < 4; ++dt) ot[dt] = (f32x4){0.f, 0.f, 0.f, 0.f};
; #pragma unroll
;         for (int ks = 0; ks < 5; ++ks) { v4u pw; pw.x = pk2(st[2 * ks][0], st[2 * ks][1]); pw.y = pk2(st[2 * ks][2], st[2 * ks][3]); pw.z = pk2(st[2 * ks + 1][0], st[2 * ks + 1][1]); pw.w = pk2(st[2 * ks + 1][2], st[2 * ks + 1][3]);
;             const bf16x8 pb = __builtin_bit_cast(bf16x8, pw);
; #pragma unroll
;             for (int dt = 0; dt < 4; ++dt) { const LAS unsigned char* vr = vbp + ks * 5120 + dt * 32;
;                 const v4i16_t lo = vtr(vr), hi = vtr(vr + 16 * 160);
;                 ot[dt] = MFMA16(__builtin_shufflevector(lo, hi, 0, 1, 2, 3, 4, 5, 6, 7), pb, ot[dt]); } }
.LBB0_487:
	s_or_b64 exec, exec, s[12:13]
	s_mov_b32 s2, 0xff61b1e6
	v_max3_f32 v60, v66, s2, v65
	v_max3_f32 v60, v60, v96, v67
	v_max3_f32 v60, v60, v98, v97
	v_max3_f32 v60, v60, v93, v92
	v_max3_f32 v60, v60, v95, v94
	v_max3_f32 v60, v60, v89, v88
	v_max3_f32 v60, v60, v91, v90
	v_max3_f32 v60, v60, v85, v84
	v_max3_f32 v60, v60, v87, v86
	v_max3_f32 v60, v60, v99, v80
	v_max3_f32 v60, v60, v82, v81
	v_max3_f32 v60, v60, v83, v76
	v_max3_f32 v60, v60, v188, v187
	v_max3_f32 v60, v60, v73, v72
	v_max3_f32 v60, v60, v75, v74
	v_max3_f32 v60, v60, v190, v68
	v_max3_f32 v60, v60, v192, v191
	v_max3_f32 v60, v60, v195, v194
	ds_bpermute_b32 v62, v122, v60
	s_lshl_b32 s12, s37, 6
	s_add_i32 s13, s12, 0x7fffc000
	s_and_b32 s13, s13, 0x7ffff800
	s_and_b32 s50, s56, s86
	s_waitcnt lgkmcnt(0)
	v_max_f32_e32 v62, v62, v62
	v_max_f32_e32 v60, v60, v62
	ds_bpermute_b32 v62, v123, v60
	s_add_i32 s37, s13, 0x4000
	s_and_b32 s51, s12, 0x2000
	s_and_b64 s[12:13], s[40:41], exec
	s_cselect_b32 s13, 7, 5
	s_waitcnt lgkmcnt(0)
	v_max_f32_e32 v62, v62, v62
	v_max_f32_e32 v60, v60, v62
	v_sub_f32_e32 v63, v65, v60
	v_mul_f32_e32 v63, 0x3fb8aa3b, v63
	v_exp_f32_e32 v107, v63
	v_sub_f32_e32 v63, v96, v60
	v_mul_f32_e32 v63, 0x3fb8aa3b, v63
	v_exp_f32_e32 v96, v63
	v_sub_f32_e32 v63, v67, v60
	v_mul_f32_e32 v63, 0x3fb8aa3b, v63
	v_exp_f32_e32 v150, v63
	v_sub_f32_e32 v63, v98, v60
	v_mul_f32_e32 v63, 0x3fb8aa3b, v63
	v_exp_f32_e32 v98, v63
	v_sub_f32_e32 v63, v97, v60
	v_mul_f32_e32 v63, 0x3fb8aa3b, v63
	v_exp_f32_e32 v97, v63
	v_sub_f32_e32 v63, v93, v60
	v_mul_f32_e32 v63, 0x3fb8aa3b, v63
	v_exp_f32_e32 v151, v63
	v_sub_f32_e32 v63, v92, v60
	v_mul_f32_e32 v63, 0x3fb8aa3b, v63
	v_exp_f32_e32 v152, v63
	v_sub_f32_e32 v63, v95, v60
	v_mul_f32_e32 v63, 0x3fb8aa3b, v63
	v_exp_f32_e32 v92, v63
	v_sub_f32_e32 v63, v94, v60
	v_mul_f32_e32 v63, 0x3fb8aa3b, v63
	v_exp_f32_e32 v93, v63
	v_sub_f32_e32 v63, v89, v60
	v_sub_f32_e32 v62, v66, v60
	v_mul_f32_e32 v63, 0x3fb8aa3b, v63
	v_mul_f32_e32 v62, 0x3fb8aa3b, v62
	v_exp_f32_e32 v89, v63
	v_sub_f32_e32 v63, v88, v60
	v_exp_f32_e32 v105, v62
	v_mul_f32_e32 v63, 0x3fb8aa3b, v63
	v_exp_f32_e32 v88, v63
	v_sub_f32_e32 v63, v91, v60
	v_mul_f32_e32 v63, 0x3fb8aa3b, v63
	v_exp_f32_e32 v91, v63
	v_sub_f32_e32 v63, v90, v60
	v_add_f32_e32 v62, 0, v105
	v_mul_f32_e32 v63, 0x3fb8aa3b, v63
	v_add_f32_e32 v62, v107, v62
	v_exp_f32_e32 v90, v63
	v_sub_f32_e32 v63, v85, v60
	v_add_f32_e32 v62, v96, v62
	v_mul_f32_e32 v63, 0x3fb8aa3b, v63
	v_add_f32_e32 v62, v150, v62
	v_exp_f32_e32 v85, v63
	v_sub_f32_e32 v63, v84, v60
	v_add_f32_e32 v62, v98, v62
	v_mul_f32_e32 v63, 0x3fb8aa3b, v63
	v_add_f32_e32 v62, v97, v62
	v_exp_f32_e32 v196, v63
	v_sub_f32_e32 v63, v87, v60
	v_add_f32_e32 v62, v151, v62
	v_mul_f32_e32 v63, 0x3fb8aa3b, v63
	v_add_f32_e32 v62, v152, v62
	v_exp_f32_e32 v77, v63
	v_sub_f32_e32 v63, v86, v60
	v_add_f32_e32 v62, v92, v62
	v_mul_f32_e32 v63, 0x3fb8aa3b, v63
	v_bfe_u32 v87, v97, 16, 1
	v_bfe_u32 v95, v107, 16, 1
	v_add_f32_e32 v62, v93, v62
	v_exp_f32_e32 v79, v63
	v_sub_f32_e32 v63, v99, v60
	v_add3_u32 v99, v107, v95, s33
	v_add3_u32 v87, v97, v87, s33
	v_bfe_u32 v95, v105, 16, 1
	v_bfe_u32 v97, v96, 16, 1
	v_bfe_u32 v107, v98, 16, 1
	v_add_f32_e32 v62, v89, v62
	v_bfe_u32 v94, v150, 16, 1
	v_add3_u32 v98, v98, v107, s33
	v_add3_u32 v96, v96, v97, s33
	v_add3_u32 v95, v105, v95, s33
	v_add_f32_e32 v62, v88, v62
	v_add3_u32 v94, v150, v94, s33
	v_bfe_u32 v150, v151, 16, 1
	v_lshrrev_b32_e32 v105, 16, v95
	v_lshrrev_b32_e32 v95, 16, v96
	v_lshrrev_b32_e32 v96, 16, v98
	v_add_f32_e32 v62, v91, v62
	v_bfe_u32 v86, v152, 16, 1
	v_add3_u32 v150, v151, v150, s33
	v_and_or_b32 v96, v87, s11, v96
	v_and_or_b32 v95, v94, s11, v95
	v_and_or_b32 v94, v99, s11, v105
	v_bfe_u32 v87, v90, 16, 1
	v_bfe_u32 v98, v88, 16, 1
	v_bfe_u32 v99, v93, 16, 1
	v_add_f32_e32 v62, v90, v62
	v_add3_u32 v86, v152, v86, s33
	v_lshrrev_b32_e32 v97, 16, v150
	ds_read_b64_tr_b16 v[152:153], v186 offset:30208
	ds_read_b64_tr_b16 v[150:151], v186 offset:27648
	ds_read_b64_tr_b16 v[198:199], v186 offset:27680
	ds_read_b64_tr_b16 v[200:201], v186 offset:30240
	v_add3_u32 v93, v93, v99, s33
	v_add3_u32 v98, v88, v98, s33
	v_add3_u32 v87, v90, v87, s33
	v_bfe_u32 v88, v92, 16, 1
	v_bfe_u32 v90, v89, 16, 1
	v_bfe_u32 v99, v91, 16, 1
	v_bfe_u32 v105, v85, 16, 1
	v_add_f32_e32 v62, v85, v62
	v_and_or_b32 v97, v86, s11, v97
	v_add3_u32 v91, v91, v99, s33
	v_add3_u32 v89, v89, v90, s33
	v_add3_u32 v88, v92, v88, s33
	v_lshrrev_b32_e32 v90, 16, v88
	v_lshrrev_b32_e32 v92, 16, v89
	v_lshrrev_b32_e32 v88, 16, v91
	ds_read_b64_tr_b16 v[202:203], v186 offset:27712
	ds_read_b64_tr_b16 v[204:205], v186 offset:30272
	ds_read_b64_tr_b16 v[206:207], v186 offset:27744
	ds_read_b64_tr_b16 v[208:209], v186 offset:30304
	v_cvt_pk_bf16_f32 v89, v85, v196
	v_and_or_b32 v88, v87, s11, v88
	v_and_or_b32 v87, v98, s11, v92
	v_and_or_b32 v86, v93, s11, v90
	ds_read_b64_tr_b16 v[90:91], v186 offset:32768
	ds_read_b64_tr_b16 v[92:93], v186 offset:35328
	s_waitcnt lgkmcnt(8)
	v_mfma_f32_16x16x32_bf16 v[150:153], v[150:153], v[94:97], 0
	v_mul_f32_e32 v63, 0x3fb8aa3b, v63
	v_exp_f32_e32 v78, v63
	v_sub_f32_e32 v63, v80, v60
	s_waitcnt lgkmcnt(0)
	v_mfma_f32_16x16x32_bf16 v[90:93], v[90:93], v[86:89], v[150:153]
	s_nop 2
	ds_read_b64_tr_b16 v[150:151], v186 offset:32800
	ds_read_b64_tr_b16 v[152:153], v186 offset:35360
	v_mul_f32_e32 v63, 0x3fb8aa3b, v63
	v_exp_f32_e32 v80, v63
	v_mfma_f32_16x16x32_bf16 v[198:201], v[198:201], v[94:97], 0
	v_sub_f32_e32 v63, v82, v60
	v_mul_f32_e32 v63, 0x3fb8aa3b, v63
	v_exp_f32_e32 v82, v63
	s_waitcnt lgkmcnt(0)
; #define LAS __attribute__((address_space(3)))
; __device__ __forceinline__ unsigned pk2(float lo, float hi) { return f2bf(lo) | (f2bf(hi) << 16); }
; #define MFMA16(a, b, c) __builtin_amdgcn_mfma_f32_16x16x32_bf16(a, b, c, 0, 0, 0)
; __device__ __forceinline__ v4i16_t vtr(const LAS unsigned char* p) { return __builtin_amdgcn_ds_read_tr16_b64_v4i16((LAS v4i16_t*)p); }
; __device__ __forceinline__ void attn_phase(const Params& p, LAS unsigned char* lds, const int bx, const int G, const int tid) {
;     ...
; #pragma unroll
;         for (int j = 0; j < 9; ++j)
; #pragma unroll
;             for (int e = 0; e < 4; ++e) { const float pv = __expf(st[j][e] - mx); st[j][e] = pv; sm += pv; }
;         sm += __shfl_xor(sm, 16); sm += __shfl_xor(sm, 32);
;         f32x4 ot[4];
; #pragma unroll
;         for (int dt = 0; dt < 4; ++dt) ot[dt] = (f32x4){0.f, 0.f, 0.f, 0.f};
; #pragma unroll
;         for (int ks = 0; ks < 5; ++ks) { v4u pw; pw.x = pk2(st[2 * ks][0], st[2 * ks][1]); pw.y = pk2(st[2 * ks][2], st[2 * ks][3]); pw.z = pk2(st[2 * ks + 1][0], st[2 * ks + 1][1]); pw.w = pk2(st[2 * ks + 1][2], st[2 * ks + 1][3]);
;             const bf16x8 pb = __builtin_bit_cast(bf16x8, pw);
; #pragma unroll
;             for (int dt = 0; dt < 4; ++dt) { const LAS unsigned char* vr = vbp + ks * 5120 + dt * 32;
;                 const v4i16_t lo = vtr(vr), hi = vtr(vr + 16 * 160);
;                 ot[dt] = MFMA16(__builtin_shufflevector(lo, hi, 0, 1, 2, 3, 4, 5, 6, 7), pb, ot[dt]); } }
	v_mfma_f32_16x16x32_bf16 v[150:153], v[150:153], v[86:89], v[198:201]
	s_nop 2
	ds_read_b64_tr_b16 v[198:199], v186 offset:32832
	ds_read_b64_tr_b16 v[200:201], v186 offset:35392
	v_sub_f32_e32 v63, v81, v60
	v_mul_f32_e32 v63, 0x3fb8aa3b, v63
	v_mfma_f32_16x16x32_bf16 v[202:205], v[202:205], v[94:97], 0
	v_exp_f32_e32 v81, v63
	v_sub_f32_e32 v63, v83, v60
	v_add_f32_e32 v62, v196, v62
	v_mul_f32_e32 v63, 0x3fb8aa3b, v63
	s_waitcnt lgkmcnt(0)
	v_mfma_f32_16x16x32_bf16 v[198:201], v[198:201], v[86:89], v[202:205]
	s_nop 2
	ds_read_b64_tr_b16 v[202:203], v186 offset:32864
	ds_read_b64_tr_b16 v[204:205], v186 offset:35424
	v_add_f32_e32 v62, v77, v62
	v_exp_f32_e32 v83, v63
	v_sub_f32_e32 v63, v76, v60
	v_mfma_f32_16x16x32_bf16 v[94:97], v[206:209], v[94:97], 0
	v_add_f32_e32 v62, v79, v62
	v_mul_f32_e32 v63, 0x3fb8aa3b, v63
	v_add_f32_e32 v62, v78, v62
	v_exp_f32_e32 v84, v63
	v_add_f32_e32 v62, v80, v62
	v_add_f32_e32 v62, v82, v62
	s_waitcnt lgkmcnt(0)
	v_mfma_f32_16x16x32_bf16 v[86:89], v[202:205], v[86:89], v[94:97]
	v_add_f32_e32 v62, v81, v62
	v_sub_f32_e32 v63, v188, v60
	v_add_f32_e32 v62, v83, v62
	v_bfe_u32 v94, v81, 16, 1
	v_bfe_u32 v95, v80, 16, 1
	v_bfe_u32 v96, v79, 16, 1
	v_add3_u32 v96, v79, v96, s33
	v_add3_u32 v79, v80, v95, s33
	v_add3_u32 v80, v81, v94, s33
	v_bfe_u32 v94, v82, 16, 1
	v_bfe_u32 v95, v83, 16, 1
	v_mul_f32_e32 v63, 0x3fb8aa3b, v63
	v_bfe_u32 v85, v84, 16, 1
	v_add3_u32 v83, v83, v95, s33
	v_add3_u32 v82, v82, v94, s33
	v_add_f32_e32 v62, v84, v62
	v_exp_f32_e32 v69, v63
	v_sub_f32_e32 v63, v187, v60
	v_add3_u32 v81, v84, v85, s33
	v_bfe_u32 v84, v77, 16, 1
	v_bfe_u32 v85, v78, 16, 1
	v_lshrrev_b32_e32 v82, 16, v82
	v_lshrrev_b32_e32 v83, 16, v83
	v_mul_f32_e32 v63, 0x3fb8aa3b, v63
	v_add3_u32 v78, v78, v85, s33
	v_add3_u32 v77, v77, v84, s33
	v_and_or_b32 v81, v81, s11, v83
	v_and_or_b32 v80, v80, s11, v82
	ds_read_b64_tr_b16 v[82:83], v186 offset:37888
	ds_read_b64_tr_b16 v[84:85], v186 offset:40448
	v_exp_f32_e32 v71, v63
	v_sub_f32_e32 v63, v73, v60
	v_mul_f32_e32 v63, 0x3fb8aa3b, v63
	v_exp_f32_e32 v70, v63
	v_sub_f32_e32 v63, v72, v60
	v_lshrrev_b32_e32 v77, 16, v77
	v_lshrrev_b32_e32 v78, 16, v78
	v_mul_f32_e32 v63, 0x3fb8aa3b, v63
	v_and_or_b32 v79, v79, s11, v78
	v_and_or_b32 v78, v96, s11, v77
	v_exp_f32_e32 v73, v63
	v_sub_f32_e32 v63, v75, v60
	s_waitcnt lgkmcnt(0)
	v_mfma_f32_16x16x32_bf16 v[82:85], v[82:85], v[78:81], v[90:93]
	s_nop 2
	ds_read_b64_tr_b16 v[90:91], v186 offset:37920
	ds_read_b64_tr_b16 v[92:93], v186 offset:40480
	v_mul_f32_e32 v63, 0x3fb8aa3b, v63
	v_exp_f32_e32 v72, v63
	v_sub_f32_e32 v63, v74, v60
	v_mul_f32_e32 v63, 0x3fb8aa3b, v63
	v_exp_f32_e32 v75, v63
	v_sub_f32_e32 v63, v190, v60
	v_mul_f32_e32 v63, 0x3fb8aa3b, v63
	s_waitcnt lgkmcnt(0)
	v_mfma_f32_16x16x32_bf16 v[90:93], v[90:93], v[78:81], v[150:153]
	ds_read_b64_tr_b16 v[94:95], v186 offset:37952
	ds_read_b64_tr_b16 v[96:97], v186 offset:40512
	s_nop 0
	ds_read_b64_tr_b16 v[150:151], v186 offset:37984
	ds_read_b64_tr_b16 v[152:153], v186 offset:40544
	v_add_f32_e32 v62, v69, v62
	v_exp_f32_e32 v74, v63
	v_sub_f32_e32 v63, v68, v60
	v_add_f32_e32 v62, v71, v62
	v_mul_f32_e32 v63, 0x3fb8aa3b, v63
	v_add_f32_e32 v62, v70, v62
	v_exp_f32_e32 v76, v63
	v_add_f32_e32 v62, v73, v62
	v_add_f32_e32 v62, v72, v62
	s_waitcnt lgkmcnt(2)
	v_mfma_f32_16x16x32_bf16 v[94:97], v[94:97], v[78:81], v[198:201]
	v_add_f32_e32 v62, v75, v62
	v_add_f32_e32 v62, v74, v62
	v_bfe_u32 v77, v76, 16, 1
	s_waitcnt lgkmcnt(0)
	v_mfma_f32_16x16x32_bf16 v[78:81], v[150:153], v[78:81], v[86:89]
	v_add_f32_e32 v62, v76, v62
	v_sub_f32_e32 v63, v192, v60
	v_mul_f32_e32 v63, 0x3fb8aa3b, v63
	v_bfe_u32 v86, v75, 16, 1
	v_bfe_u32 v87, v73, 16, 1
	v_bfe_u32 v88, v71, 16, 1
	v_add3_u32 v88, v71, v88, s33
	v_add3_u32 v71, v73, v87, s33
	v_bfe_u32 v87, v74, 16, 1
	v_add3_u32 v74, v74, v87, s33
	v_add3_u32 v73, v76, v77, s33
	v_bfe_u32 v76, v69, 16, 1
	v_bfe_u32 v77, v70, 16, 1
	v_lshrrev_b32_e32 v74, 16, v74
	v_add3_u32 v70, v70, v77, s33
	v_add3_u32 v69, v69, v76, s33
	v_and_or_b32 v73, v73, s11, v74
	v_cvt_pk_bf16_f32 v72, v72, v75
	ds_read_b64_tr_b16 v[74:75], v186 offset:43008
	ds_read_b64_tr_b16 v[76:77], v186 offset:45568
	v_lshrrev_b32_e32 v69, 16, v69
	v_lshrrev_b32_e32 v70, 16, v70
	v_and_or_b32 v71, v71, s11, v70
	v_and_or_b32 v70, v88, s11, v69
	v_exp_f32_e32 v66, v63
	v_sub_f32_e32 v63, v191, v60
	s_waitcnt lgkmcnt(0)
	v_mfma_f32_16x16x32_bf16 v[74:77], v[74:77], v[70:73], v[82:85]
	s_nop 2
	ds_read_b64_tr_b16 v[82:83], v186 offset:43040
	ds_read_b64_tr_b16 v[84:85], v186 offset:45600
	v_mul_f32_e32 v63, 0x3fb8aa3b, v63
	v_exp_f32_e32 v65, v63
	v_sub_f32_e32 v63, v195, v60
	v_mul_f32_e32 v63, 0x3fb8aa3b, v63
	v_exp_f32_e32 v67, v63
	v_sub_f32_e32 v63, v194, v60
	s_waitcnt lgkmcnt(0)
; #define LAS __attribute__((address_space(3)))
; __device__ __forceinline__ unsigned pk2(float lo, float hi) { return f2bf(lo) | (f2bf(hi) << 16); }
; #define MFMA16(a, b, c) __builtin_amdgcn_mfma_f32_16x16x32_bf16(a, b, c, 0, 0, 0)
; __device__ __forceinline__ v4i16_t vtr(const LAS unsigned char* p) { return __builtin_amdgcn_ds_read_tr16_b64_v4i16((LAS v4i16_t*)p); }
; __device__ __forceinline__ void attn_phase(const Params& p, LAS unsigned char* lds, const int bx, const int G, const int tid) {
;     ...
;         for (int ks = 0; ks < 5; ++ks) { v4u pw; pw.x = pk2(st[2 * ks][0], st[2 * ks][1]); pw.y = pk2(st[2 * ks][2], st[2 * ks][3]); pw.z = pk2(st[2 * ks + 1][0], st[2 * ks + 1][1]); pw.w = pk2(st[2 * ks + 1][2], st[2 * ks + 1][3]);
;             const bf16x8 pb = __builtin_bit_cast(bf16x8, pw);
; #pragma unroll
;             for (int dt = 0; dt < 4; ++dt) { const LAS unsigned char* vr = vbp + ks * 5120 + dt * 32;
;                 const v4i16_t lo = vtr(vr), hi = vtr(vr + 16 * 160);
;                 ot[dt] = MFMA16(__builtin_shufflevector(lo, hi, 0, 1, 2, 3, 4, 5, 6, 7), pb, ot[dt]); } }
;         { const size_t m = (size_t)(X.m0 + (X.nb * 64 + qi) * d + X.r); const float inv = 1.f / sm;
; #pragma unroll
;           for (int dt = 0; dt < 4; ++dt) { unsigned long long w = (unsigned long long)pk2(ot[dt][0] * inv, ot[dt][1] * inv) | ((unsigned long long)pk2(ot[dt][2] * inv, ot[dt][3] * inv) << 32);
	v_mfma_f32_16x16x32_bf16 v[82:85], v[82:85], v[70:73], v[90:93]
	ds_read_b64_tr_b16 v[86:87], v186 offset:43072
	ds_read_b64_tr_b16 v[88:89], v186 offset:45632
	s_nop 0
	ds_read_b64_tr_b16 v[90:91], v186 offset:43104
	ds_read_b64_tr_b16 v[92:93], v186 offset:45664
	v_mul_f32_e32 v63, 0x3fb8aa3b, v63
	v_exp_f32_e32 v68, v63
	v_add_f32_e32 v62, v66, v62
	v_add_f32_e32 v62, v65, v62
	v_add_f32_e32 v62, v67, v62
	s_waitcnt lgkmcnt(2)
	v_mfma_f32_16x16x32_bf16 v[86:89], v[86:89], v[70:73], v[94:97]
	v_add_f32_e32 v62, v68, v62
	ds_bpermute_b32 v63, v122, v62
	v_and_b32_sdwa v69, v67, v189 dst_sel:DWORD dst_unused:UNUSED_PAD src0_sel:WORD_1 src1_sel:DWORD
	s_waitcnt lgkmcnt(1)
	v_mfma_f32_16x16x32_bf16 v[70:73], v[90:93], v[70:73], v[78:81]
	v_add3_u32 v67, v67, v69, s33
	v_and_b32_sdwa v69, v68, v189 dst_sel:DWORD dst_unused:UNUSED_PAD src0_sel:WORD_1 src1_sel:DWORD
	v_add3_u32 v68, v68, v69, s33
	v_and_b32_sdwa v78, v66, v189 dst_sel:DWORD dst_unused:UNUSED_PAD src0_sel:WORD_1 src1_sel:DWORD
	v_add3_u32 v66, v66, v78, s33
	v_and_b32_sdwa v78, v65, v189 dst_sel:DWORD dst_unused:UNUSED_PAD src0_sel:WORD_1 src1_sel:DWORD
	v_add3_u32 v65, v65, v78, s33
	ds_read_b64_tr_b16 v[78:79], v186 offset:48128
	ds_read_b64_tr_b16 v[80:81], v186 offset:50688
	v_and_b32_e32 v68, 0xffff0000, v68
	v_and_b32_e32 v65, 0xffff0000, v65
	v_or_b32_sdwa v67, v68, v67 dst_sel:DWORD dst_unused:UNUSED_PAD src0_sel:DWORD src1_sel:WORD_1
	v_or_b32_sdwa v66, v65, v66 dst_sel:DWORD dst_unused:UNUSED_PAD src0_sel:DWORD src1_sel:WORD_1
	v_mov_b32_e32 v68, v0
	v_mov_b32_e32 v69, v0
	s_waitcnt lgkmcnt(2)
	v_add_f32_e32 v62, v62, v63
	ds_bpermute_b32 v63, v123, v62
	s_waitcnt lgkmcnt(1)
	v_mfma_f32_16x16x32_bf16 v[74:77], v[78:81], v[66:69], v[74:77]
	ds_read_b64_tr_b16 v[78:79], v186 offset:48160
	ds_read_b64_tr_b16 v[80:81], v186 offset:50720
	v_sub_u32_e32 v61, s13, v3
	s_cselect_b32 s12, s51, s37
	v_lshrrev_b32_e64 v61, v61, s50
	s_waitcnt lgkmcnt(0)
	v_mfma_f32_16x16x32_bf16 v[78:81], v[78:81], v[66:69], v[82:85]
	s_nop 2
	ds_read_b64_tr_b16 v[82:83], v186 offset:48192
	ds_read_b64_tr_b16 v[84:85], v186 offset:50752
	v_add_f32_e32 v62, v62, v63
	v_or_b32_e32 v63, v64, v121
	v_or_b32_e32 v61, s12, v61
	v_lshl_add_u32 v61, v63, v3, v61
	v_div_scale_f32 v3, s[12:13], v62, v62, 1.0
	v_rcp_f32_e32 v63, v3
	s_waitcnt lgkmcnt(0)
	v_mfma_f32_16x16x32_bf16 v[82:85], v[82:85], v[66:69], v[86:89]
	s_nop 2
	ds_read_b64_tr_b16 v[86:87], v186 offset:48224
	ds_read_b64_tr_b16 v[88:89], v186 offset:50784
	v_mov_b32_e32 v107, v0
	v_fma_f32 v64, -v3, v63, 1.0
	v_fmac_f32_e32 v63, v64, v63
	v_div_scale_f32 v64, vcc, 1.0, v62, 1.0
	v_mul_f32_e32 v65, v64, v63
	s_waitcnt lgkmcnt(0)
	v_mfma_f32_16x16x32_bf16 v[66:69], v[86:89], v[66:69], v[70:73]
	v_readlane_b32 s2, v254, 55
	v_readlane_b32 s3, v254, 56
	s_nop 0
	v_fma_f32 v70, -v3, v65, v64
	v_fmac_f32_e32 v65, v70, v63
	v_fma_f32 v3, -v3, v65, v64
	v_div_fmas_f32 v3, v3, v63, v65
	v_div_fixup_f32 v3, v3, v62, 1.0
	v_mov_b64_e32 v[64:65], s[90:91]
	v_lshlrev_b32_e32 v70, 6, v2
	v_mad_i64_i32 v[64:65], s[12:13], v61, s57, v[64:65]
	v_ashrrev_i32_e32 v71, 31, v70
	v_mul_f32_e32 v63, v3, v74
	v_lshl_add_u64 v[64:65], v[70:71], 1, v[64:65]
	v_mul_f32_e32 v70, v3, v75
	v_bfe_u32 v71, v63, 16, 1
	v_cvt_pk_bf16_f32 v70, v63, v70
	v_mul_f32_e32 v63, v3, v76
	v_mul_f32_e32 v71, v3, v77
	v_lshl_add_u64 v[64:65], v[64:65], 0, v[106:107]
	v_cvt_pk_bf16_f32 v71, v63, v71
	v_mul_f32_e32 v63, v3, v78
	global_store_dwordx2 v[64:65], v[70:71], off
	v_mul_f32_e32 v70, v3, v79
	v_cvt_pk_bf16_f32 v70, v63, v70
	v_mul_f32_e32 v63, v3, v80
	v_mul_f32_e32 v71, v3, v81
	v_cvt_pk_bf16_f32 v71, v63, v71
	v_mul_f32_e32 v63, v3, v82
	global_store_dwordx2 v[64:65], v[70:71], off offset:32
	v_mul_f32_e32 v70, v3, v83
	v_cvt_pk_bf16_f32 v70, v63, v70
	v_mul_f32_e32 v63, v3, v84
	v_mul_f32_e32 v71, v3, v85
	v_bfe_u32 v72, v71, 16, 1
	v_cvt_pk_bf16_f32 v71, v63, v71
	v_mul_f32_e32 v63, v3, v66
	v_mul_f32_e32 v66, v3, v67
	v_cvt_pk_bf16_f32 v66, v63, v66
	v_mul_f32_e32 v63, v3, v68
	v_mul_f32_e32 v3, v3, v69
	v_bfe_u32 v67, v63, 16, 1
	v_add3_u32 v63, v63, v67, s33
	v_bfe_u32 v67, v3, 16, 1
	v_lshrrev_b32_e32 v63, 16, v63
	v_add3_u32 v3, v3, v67, s33
	v_and_or_b32 v67, v3, s11, v63
	global_store_dwordx2 v[64:65], v[70:71], off offset:64
	global_store_dwordx2 v[64:65], v[66:67], off offset:96
	s_and_saveexec_b64 s[12:13], s[2:3]
	s_cbranch_execz .LBB0_386
	s_mov_b32 s37, 0x800000
	v_cmp_gt_f32_e32 vcc, s37, v62
	s_mov_b32 s37, 0x3f317217
	s_mov_b32 s2, 0x7f800000
	v_cndmask_b32_e64 v3, 0, 32, vcc
	v_ldexp_f32 v3, v62, v3
	v_log_f32_e32 v3, v3
	v_cndmask_b32_e32 v62, 0, v233, vcc
	v_mul_f32_e32 v63, 0x3f317217, v3
	v_fma_f32 v63, v3, s37, -v63
	v_fmac_f32_e32 v63, 0x3377d1cf, v3
	v_fmac_f32_e32 v63, 0x3f317217, v3
	v_cmp_lt_f32_e64 vcc, |v3|, s2
	v_readlane_b32 s2, v253, 7
	v_readlane_b32 s3, v253, 8
	v_cndmask_b32_e32 v3, v3, v63, vcc
	v_sub_f32_e32 v3, v3, v62
	v_add_f32_e32 v62, v60, v3
	v_ashrrev_i32_e32 v3, 31, v2
	v_mad_i64_i32 v[60:61], s[40:41], v61, 48, s[2:3]
	v_lshl_add_u64 v[2:3], v[2:3], 2, v[60:61]
	global_store_dword v[2:3], v62, off
	s_branch .LBB0_386

; #define LAS __attribute__((address_space(3)))
; #define MFMA16(a, b, c) __builtin_amdgcn_mfma_f32_16x16x32_bf16(a, b, c, 0, 0, 0)
; __device__ __forceinline__ void memattn_group(const Params& p, LAS unsigned char* lds, int grp, const int tid) {
;     ...
;         f32x4 st[16]; float mx = -3e38f;
; #pragma unroll
;         for (int ct = 0; ct < 16; ++ct) { st[ct] = (f32x4){0.f, 0.f, 0.f, 0.f};
; #pragma unroll
;             for (int ks = 0; ks < 4; ++ks) { const bf16x8 kb = *(const LAS bf16x8*)(lds + MA_KS + (16 * ct + fr) * 272 + (32 * ks + 8 * fq) * 2); st[ct] = MFMA16(kb, qa[ks], st[ct]); }
;             mx = fmaxf(fmaxf(mx, fmaxf(st[ct][0], st[ct][1])), fmaxf(st[ct][2], st[ct][3])); }
.LBB0_500:
	ds_read_b128 v[34:37], v169
	ds_read_b128 v[38:41], v169 offset:64
	s_addk_i32 s5, 0x80
	s_cmpk_lg_i32 s5, 0x200
	s_waitcnt vmcnt(3) lgkmcnt(1)
	v_mfma_f32_16x16x32_bf16 v[34:37], v[34:37], v[30:33], 0
	ds_read_b128 v[42:45], v169 offset:4416
	ds_read_b128 v[150:153], v169 offset:60992
	s_waitcnt vmcnt(2) lgkmcnt(2)
	v_mfma_f32_16x16x32_bf16 v[34:37], v[38:41], v[26:29], v[34:37]
	ds_read_b128 v[38:41], v169 offset:128
	s_waitcnt vmcnt(1) lgkmcnt(0)
	v_mfma_f32_16x16x32_bf16 v[34:37], v[38:41], v[22:25], v[34:37]
	ds_read_b128 v[38:41], v169 offset:192
	s_waitcnt vmcnt(0) lgkmcnt(0)
	v_mfma_f32_16x16x32_bf16 v[34:37], v[38:41], v[18:21], v[34:37]
	s_nop 7
	v_max_f32_e32 v38, v35, v35
	v_max_f32_e32 v39, v34, v34
	v_max_f32_e32 v38, v39, v38
	v_max_f32_e32 v39, v37, v37
	v_max_f32_e32 v40, v36, v36
	v_max_f32_e32 v39, v40, v39
	v_max3_f32 v46, v38, s12, v39
	ds_read_b128 v[38:41], v169 offset:4352
	s_waitcnt lgkmcnt(0)
	v_mfma_f32_16x16x32_bf16 v[38:41], v[38:41], v[30:33], 0
	v_mfma_f32_16x16x32_bf16 v[38:41], v[42:45], v[26:29], v[38:41]
	ds_read_b128 v[42:45], v169 offset:4480
	s_waitcnt lgkmcnt(0)
	v_mfma_f32_16x16x32_bf16 v[38:41], v[42:45], v[22:25], v[38:41]
	ds_read_b128 v[42:45], v169 offset:4544
	s_waitcnt lgkmcnt(0)
	v_mfma_f32_16x16x32_bf16 v[38:41], v[42:45], v[18:21], v[38:41]
	s_nop 7
	v_max_f32_e32 v42, v39, v39
	v_max_f32_e32 v43, v38, v38
	v_max_f32_e32 v42, v43, v42
	v_max_f32_e32 v43, v41, v41
	v_max_f32_e32 v44, v40, v40
	v_max_f32_e32 v43, v44, v43
	v_max3_f32 v50, v46, v42, v43
	ds_read_b128 v[42:45], v169 offset:8704
	ds_read_b128 v[46:49], v169 offset:8768
	s_waitcnt lgkmcnt(1)
	v_mfma_f32_16x16x32_bf16 v[42:45], v[42:45], v[30:33], 0
	s_waitcnt lgkmcnt(0)
	v_mfma_f32_16x16x32_bf16 v[42:45], v[46:49], v[26:29], v[42:45]
	ds_read_b128 v[46:49], v169 offset:8832
	s_waitcnt lgkmcnt(0)
	v_mfma_f32_16x16x32_bf16 v[42:45], v[46:49], v[22:25], v[42:45]
	ds_read_b128 v[46:49], v169 offset:8896
	s_waitcnt lgkmcnt(0)
	v_mfma_f32_16x16x32_bf16 v[42:45], v[46:49], v[18:21], v[42:45]
	s_nop 7
	v_max_f32_e32 v46, v43, v43
	v_max_f32_e32 v47, v42, v42
	v_max_f32_e32 v46, v47, v46
	v_max_f32_e32 v47, v45, v45
	v_max_f32_e32 v48, v44, v44
	v_max_f32_e32 v47, v48, v47
	v_max3_f32 v54, v50, v46, v47
	ds_read_b128 v[46:49], v169 offset:13056
	ds_read_b128 v[50:53], v169 offset:13120
	s_waitcnt lgkmcnt(1)
	v_mfma_f32_16x16x32_bf16 v[46:49], v[46:49], v[30:33], 0
	s_waitcnt lgkmcnt(0)
	v_mfma_f32_16x16x32_bf16 v[46:49], v[50:53], v[26:29], v[46:49]
	ds_read_b128 v[50:53], v169 offset:13184
	s_waitcnt lgkmcnt(0)
	v_mfma_f32_16x16x32_bf16 v[46:49], v[50:53], v[22:25], v[46:49]
	ds_read_b128 v[50:53], v169 offset:13248
	s_waitcnt lgkmcnt(0)
	v_mfma_f32_16x16x32_bf16 v[46:49], v[50:53], v[18:21], v[46:49]
	s_nop 7
	v_max_f32_e32 v50, v47, v47
	v_max_f32_e32 v51, v46, v46
	v_max_f32_e32 v50, v51, v50
	v_max_f32_e32 v51, v49, v49
	v_max_f32_e32 v52, v48, v48
	v_max_f32_e32 v51, v52, v51
	v_max3_f32 v58, v54, v50, v51
	ds_read_b128 v[50:53], v169 offset:17408
	ds_read_b128 v[54:57], v169 offset:17472
	s_waitcnt lgkmcnt(1)
	v_mfma_f32_16x16x32_bf16 v[50:53], v[50:53], v[30:33], 0
	s_waitcnt lgkmcnt(0)
	v_mfma_f32_16x16x32_bf16 v[50:53], v[54:57], v[26:29], v[50:53]
	ds_read_b128 v[54:57], v169 offset:17536
	s_waitcnt lgkmcnt(0)
	v_mfma_f32_16x16x32_bf16 v[50:53], v[54:57], v[22:25], v[50:53]
	ds_read_b128 v[54:57], v169 offset:17600
	s_waitcnt lgkmcnt(0)
	v_mfma_f32_16x16x32_bf16 v[50:53], v[54:57], v[18:21], v[50:53]
	s_nop 7
	v_max_f32_e32 v54, v51, v51
	v_max_f32_e32 v55, v50, v50
	v_max_f32_e32 v54, v55, v54
	v_max_f32_e32 v55, v53, v53
	v_max_f32_e32 v56, v52, v52
	v_max_f32_e32 v55, v56, v55
	v_max3_f32 v62, v58, v54, v55
	ds_read_b128 v[54:57], v169 offset:21760
	ds_read_b128 v[58:61], v169 offset:21824
	s_waitcnt lgkmcnt(1)
	v_mfma_f32_16x16x32_bf16 v[54:57], v[54:57], v[30:33], 0
	s_waitcnt lgkmcnt(0)
	v_mfma_f32_16x16x32_bf16 v[54:57], v[58:61], v[26:29], v[54:57]
	ds_read_b128 v[58:61], v169 offset:21888
	s_waitcnt lgkmcnt(0)
	v_mfma_f32_16x16x32_bf16 v[54:57], v[58:61], v[22:25], v[54:57]
	ds_read_b128 v[58:61], v169 offset:21952
	s_waitcnt lgkmcnt(0)
	v_mfma_f32_16x16x32_bf16 v[54:57], v[58:61], v[18:21], v[54:57]
	s_nop 7
	v_max_f32_e32 v58, v55, v55
	v_max_f32_e32 v59, v54, v54
	v_max_f32_e32 v58, v59, v58
	v_max_f32_e32 v59, v57, v57
	v_max_f32_e32 v60, v56, v56
	v_max_f32_e32 v59, v60, v59
	v_max3_f32 v66, v62, v58, v59
	ds_read_b128 v[58:61], v169 offset:26112
	ds_read_b128 v[62:65], v169 offset:26176
	s_waitcnt lgkmcnt(1)
	v_mfma_f32_16x16x32_bf16 v[58:61], v[58:61], v[30:33], 0
	s_waitcnt lgkmcnt(0)
	v_mfma_f32_16x16x32_bf16 v[58:61], v[62:65], v[26:29], v[58:61]
	ds_read_b128 v[62:65], v169 offset:26240
	s_waitcnt lgkmcnt(0)
	v_mfma_f32_16x16x32_bf16 v[58:61], v[62:65], v[22:25], v[58:61]
	ds_read_b128 v[62:65], v169 offset:26304
	s_waitcnt lgkmcnt(0)
	v_mfma_f32_16x16x32_bf16 v[58:61], v[62:65], v[18:21], v[58:61]
	s_nop 7
	v_max_f32_e32 v62, v59, v59
	v_max_f32_e32 v63, v58, v58
	v_max_f32_e32 v62, v63, v62
	v_max_f32_e32 v63, v61, v61
	v_max_f32_e32 v64, v60, v60
	v_max_f32_e32 v63, v64, v63
	v_max3_f32 v70, v66, v62, v63
	ds_read_b128 v[62:65], v169 offset:30464
	ds_read_b128 v[66:69], v169 offset:30528
	s_waitcnt lgkmcnt(1)
	v_mfma_f32_16x16x32_bf16 v[62:65], v[62:65], v[30:33], 0
	s_waitcnt lgkmcnt(0)
	v_mfma_f32_16x16x32_bf16 v[62:65], v[66:69], v[26:29], v[62:65]
	ds_read_b128 v[66:69], v169 offset:30592
	s_waitcnt lgkmcnt(0)
	v_mfma_f32_16x16x32_bf16 v[62:65], v[66:69], v[22:25], v[62:65]
	ds_read_b128 v[66:69], v169 offset:30656
	s_waitcnt lgkmcnt(0)
; #define LAS __attribute__((address_space(3)))
; #define MFMA16(a, b, c) __builtin_amdgcn_mfma_f32_16x16x32_bf16(a, b, c, 0, 0, 0)
; __device__ __forceinline__ void memattn_group(const Params& p, LAS unsigned char* lds, int grp, const int tid) {
;     ...
;         for (int ct = 0; ct < 16; ++ct) { st[ct] = (f32x4){0.f, 0.f, 0.f, 0.f};
; #pragma unroll
;             for (int ks = 0; ks < 4; ++ks) { const bf16x8 kb = *(const LAS bf16x8*)(lds + MA_KS + (16 * ct + fr) * 272 + (32 * ks + 8 * fq) * 2); st[ct] = MFMA16(kb, qa[ks], st[ct]); }
;             mx = fmaxf(fmaxf(mx, fmaxf(st[ct][0], st[ct][1])), fmaxf(st[ct][2], st[ct][3])); }
	v_mfma_f32_16x16x32_bf16 v[62:65], v[66:69], v[18:21], v[62:65]
	s_nop 7
	v_max_f32_e32 v66, v63, v63
	v_max_f32_e32 v67, v62, v62
	v_max_f32_e32 v66, v67, v66
	v_max_f32_e32 v67, v65, v65
	v_max_f32_e32 v68, v64, v64
	v_max_f32_e32 v67, v68, v67
	v_max3_f32 v74, v70, v66, v67
	ds_read_b128 v[66:69], v169 offset:34816
	ds_read_b128 v[70:73], v169 offset:34880
	s_waitcnt lgkmcnt(1)
	v_mfma_f32_16x16x32_bf16 v[66:69], v[66:69], v[30:33], 0
	s_waitcnt lgkmcnt(0)
	v_mfma_f32_16x16x32_bf16 v[66:69], v[70:73], v[26:29], v[66:69]
	ds_read_b128 v[70:73], v169 offset:34944
	s_waitcnt lgkmcnt(0)
	v_mfma_f32_16x16x32_bf16 v[66:69], v[70:73], v[22:25], v[66:69]
	ds_read_b128 v[70:73], v169 offset:35008
	s_waitcnt lgkmcnt(0)
	v_mfma_f32_16x16x32_bf16 v[66:69], v[70:73], v[18:21], v[66:69]
	s_nop 7
	v_max_f32_e32 v70, v67, v67
	v_max_f32_e32 v71, v66, v66
	v_max_f32_e32 v70, v71, v70
	v_max_f32_e32 v71, v69, v69
	v_max_f32_e32 v72, v68, v68
	v_max_f32_e32 v71, v72, v71
	v_max3_f32 v78, v74, v70, v71
	ds_read_b128 v[70:73], v169 offset:39168
	ds_read_b128 v[74:77], v169 offset:39232
	s_waitcnt lgkmcnt(1)
	v_mfma_f32_16x16x32_bf16 v[70:73], v[70:73], v[30:33], 0
	s_waitcnt lgkmcnt(0)
	v_mfma_f32_16x16x32_bf16 v[70:73], v[74:77], v[26:29], v[70:73]
	ds_read_b128 v[74:77], v169 offset:39296
	s_waitcnt lgkmcnt(0)
	v_mfma_f32_16x16x32_bf16 v[70:73], v[74:77], v[22:25], v[70:73]
	ds_read_b128 v[74:77], v169 offset:39360
	s_waitcnt lgkmcnt(0)
	v_mfma_f32_16x16x32_bf16 v[70:73], v[74:77], v[18:21], v[70:73]
	s_nop 7
	v_max_f32_e32 v74, v71, v71
	v_max_f32_e32 v75, v70, v70
	v_max_f32_e32 v74, v75, v74
	v_max_f32_e32 v75, v73, v73
	v_max_f32_e32 v76, v72, v72
	v_max_f32_e32 v75, v76, v75
	v_max3_f32 v82, v78, v74, v75
	ds_read_b128 v[74:77], v169 offset:43520
	ds_read_b128 v[78:81], v169 offset:43584
	s_waitcnt lgkmcnt(1)
	v_mfma_f32_16x16x32_bf16 v[74:77], v[74:77], v[30:33], 0
	s_waitcnt lgkmcnt(0)
	v_mfma_f32_16x16x32_bf16 v[74:77], v[78:81], v[26:29], v[74:77]
	ds_read_b128 v[78:81], v169 offset:43648
	s_waitcnt lgkmcnt(0)
	v_mfma_f32_16x16x32_bf16 v[74:77], v[78:81], v[22:25], v[74:77]
	ds_read_b128 v[78:81], v169 offset:43712
	s_waitcnt lgkmcnt(0)
	v_mfma_f32_16x16x32_bf16 v[74:77], v[78:81], v[18:21], v[74:77]
	s_nop 7
	v_max_f32_e32 v78, v75, v75
	v_max_f32_e32 v79, v74, v74
	v_max_f32_e32 v78, v79, v78
	v_max_f32_e32 v79, v77, v77
	v_max_f32_e32 v80, v76, v76
	v_max_f32_e32 v79, v80, v79
	v_max3_f32 v86, v82, v78, v79
	ds_read_b128 v[78:81], v169 offset:47872
	ds_read_b128 v[82:85], v169 offset:47936
	s_waitcnt lgkmcnt(1)
	v_mfma_f32_16x16x32_bf16 v[78:81], v[78:81], v[30:33], 0
	s_waitcnt lgkmcnt(0)
	v_mfma_f32_16x16x32_bf16 v[78:81], v[82:85], v[26:29], v[78:81]
	ds_read_b128 v[82:85], v169 offset:48000
	s_waitcnt lgkmcnt(0)
	v_mfma_f32_16x16x32_bf16 v[78:81], v[82:85], v[22:25], v[78:81]
	ds_read_b128 v[82:85], v169 offset:48064
	s_waitcnt lgkmcnt(0)
	v_mfma_f32_16x16x32_bf16 v[78:81], v[82:85], v[18:21], v[78:81]
	s_nop 7
	v_max_f32_e32 v82, v79, v79
	v_max_f32_e32 v83, v78, v78
	v_max_f32_e32 v82, v83, v82
	v_max_f32_e32 v83, v81, v81
	v_max_f32_e32 v84, v80, v80
	v_max_f32_e32 v83, v84, v83
	v_max3_f32 v90, v86, v82, v83
	ds_read_b128 v[82:85], v169 offset:52224
	ds_read_b128 v[86:89], v169 offset:52288
	s_waitcnt lgkmcnt(1)
	v_mfma_f32_16x16x32_bf16 v[82:85], v[82:85], v[30:33], 0
	s_waitcnt lgkmcnt(0)
	v_mfma_f32_16x16x32_bf16 v[82:85], v[86:89], v[26:29], v[82:85]
	ds_read_b128 v[86:89], v169 offset:52352
	s_waitcnt lgkmcnt(0)
	v_mfma_f32_16x16x32_bf16 v[82:85], v[86:89], v[22:25], v[82:85]
	ds_read_b128 v[86:89], v169 offset:52416
	s_waitcnt lgkmcnt(0)
	v_mfma_f32_16x16x32_bf16 v[82:85], v[86:89], v[18:21], v[82:85]
	s_nop 7
	v_max_f32_e32 v86, v83, v83
	v_max_f32_e32 v87, v82, v82
	v_max_f32_e32 v86, v87, v86
	v_max_f32_e32 v87, v85, v85
	v_max_f32_e32 v88, v84, v84
	v_max_f32_e32 v87, v88, v87
	v_max3_f32 v115, v90, v86, v87
	ds_read_b128 v[86:89], v169 offset:56576
	ds_read_b128 v[90:93], v169 offset:56640
	s_waitcnt lgkmcnt(1)
	v_mfma_f32_16x16x32_bf16 v[86:89], v[86:89], v[30:33], 0
	s_waitcnt lgkmcnt(0)
	v_mfma_f32_16x16x32_bf16 v[86:89], v[90:93], v[26:29], v[86:89]
	ds_read_b128 v[90:93], v169 offset:56704
	s_waitcnt lgkmcnt(0)
	v_mfma_f32_16x16x32_bf16 v[86:89], v[90:93], v[22:25], v[86:89]
	ds_read_b128 v[90:93], v169 offset:56768
	s_waitcnt lgkmcnt(0)
	v_mfma_f32_16x16x32_bf16 v[86:89], v[90:93], v[18:21], v[86:89]
	s_nop 7
	v_max_f32_e32 v90, v87, v87
	v_max_f32_e32 v91, v86, v86
	v_max_f32_e32 v90, v91, v90
	v_max_f32_e32 v91, v89, v89
	v_max_f32_e32 v92, v88, v88
	v_max_f32_e32 v91, v92, v91
	v_max3_f32 v115, v115, v90, v91
	ds_read_b128 v[90:93], v169 offset:60928
	s_waitcnt lgkmcnt(0)
	v_mfma_f32_16x16x32_bf16 v[90:93], v[90:93], v[30:33], 0
	v_mfma_f32_16x16x32_bf16 v[90:93], v[150:153], v[26:29], v[90:93]
	ds_read_b128 v[150:153], v169 offset:61056
	s_waitcnt lgkmcnt(0)
	v_mfma_f32_16x16x32_bf16 v[90:93], v[150:153], v[22:25], v[90:93]
	ds_read_b128 v[150:153], v169 offset:61120
	s_waitcnt lgkmcnt(0)
	v_mfma_f32_16x16x32_bf16 v[90:93], v[150:153], v[18:21], v[90:93]
	s_nop 7
	v_max_f32_e32 v117, v91, v91
	v_max_f32_e32 v123, v90, v90
	v_max_f32_e32 v117, v123, v117
	v_max_f32_e32 v123, v93, v93
	v_max_f32_e32 v150, v92, v92
	v_max_f32_e32 v123, v150, v123
	ds_read_b128 v[150:153], v169 offset:65280
	s_waitcnt lgkmcnt(0)
	v_mfma_f32_16x16x32_bf16 v[30:33], v[150:153], v[30:33], 0
	ds_read_b128 v[150:153], v169 offset:65344
	v_max3_f32 v115, v115, v117, v123
	s_waitcnt lgkmcnt(0)
	v_mfma_f32_16x16x32_bf16 v[26:29], v[150:153], v[26:29], v[30:33]
	s_nop 3
	ds_read_b128 v[30:33], v169 offset:65408
	s_waitcnt lgkmcnt(0)
; #define LAS __attribute__((address_space(3)))
; #define MFMA16(a, b, c) __builtin_amdgcn_mfma_f32_16x16x32_bf16(a, b, c, 0, 0, 0)
; __device__ __forceinline__ void memattn_group(const Params& p, LAS unsigned char* lds, int grp, const int tid) {
;     ...
;         for (int ct = 0; ct < 16; ++ct) { st[ct] = (f32x4){0.f, 0.f, 0.f, 0.f};
; #pragma unroll
;             for (int ks = 0; ks < 4; ++ks) { const bf16x8 kb = *(const LAS bf16x8*)(lds + MA_KS + (16 * ct + fr) * 272 + (32 * ks + 8 * fq) * 2); st[ct] = MFMA16(kb, qa[ks], st[ct]); }
;             mx = fmaxf(fmaxf(mx, fmaxf(st[ct][0], st[ct][1])), fmaxf(st[ct][2], st[ct][3])); }
;         mx = fmaxf(mx, __shfl_xor(mx, 16)); mx = fmaxf(mx, __shfl_xor(mx, 32));
;         float sm = 0.f;
; #pragma unroll
;         for (int ct = 0; ct < 16; ++ct)
; #pragma unroll
;             for (int e = 0; e < 4; ++e) { const float pv = __expf(st[ct][e] - mx); st[ct][e] = pv; sm += pv; }
;         sm += __shfl_xor(sm, 16); sm += __shfl_xor(sm, 32);
	v_mfma_f32_16x16x32_bf16 v[22:25], v[30:33], v[22:25], v[26:29]
	s_nop 2
	ds_read_b128 v[26:29], v169 offset:65472
	s_waitcnt lgkmcnt(0)
	v_mfma_f32_16x16x32_bf16 v[18:21], v[26:29], v[18:21], v[22:25]
	s_nop 7
	v_max_f32_e32 v22, v19, v19
	v_max_f32_e32 v23, v18, v18
	v_max_f32_e32 v22, v23, v22
	v_max_f32_e32 v23, v21, v21
	v_max_f32_e32 v24, v20, v20
	v_max_f32_e32 v23, v24, v23
	v_and_b32_e32 v24, 64, v231
	v_max3_f32 v22, v115, v22, v23
	v_xor_b32_e32 v23, 16, v231
	v_add_u32_e32 v24, 64, v24
	v_cmp_lt_i32_e32 vcc, v23, v24
	s_nop 1
	v_cndmask_b32_e32 v23, v231, v23, vcc
	v_lshlrev_b32_e32 v26, 2, v23
	ds_bpermute_b32 v23, v26, v22
	s_waitcnt lgkmcnt(0)
	v_max_f32_e32 v23, v23, v23
	v_max_f32_e32 v22, v22, v23
	v_xor_b32_e32 v23, 32, v231
	v_cmp_lt_i32_e32 vcc, v23, v24
	s_nop 1
	v_cndmask_b32_e32 v23, v231, v23, vcc
	v_lshlrev_b32_e32 v27, 2, v23
	ds_bpermute_b32 v23, v27, v22
	s_waitcnt lgkmcnt(0)
	v_max_f32_e32 v23, v23, v23
	v_max_f32_e32 v150, v22, v23
	v_sub_f32_e32 v23, v35, v150
	v_mul_f32_e32 v23, 0x3fb8aa3b, v23
	v_exp_f32_e32 v185, v23
	v_sub_f32_e32 v23, v36, v150
	v_mul_f32_e32 v23, 0x3fb8aa3b, v23
	v_exp_f32_e32 v184, v23
	v_sub_f32_e32 v23, v37, v150
	v_mul_f32_e32 v23, 0x3fb8aa3b, v23
	v_exp_f32_e32 v186, v23
	v_sub_f32_e32 v23, v38, v150
	v_mul_f32_e32 v23, 0x3fb8aa3b, v23
	v_exp_f32_e32 v187, v23
	v_sub_f32_e32 v23, v39, v150
	v_mul_f32_e32 v23, 0x3fb8aa3b, v23
	v_exp_f32_e32 v188, v23
	v_sub_f32_e32 v23, v40, v150
	v_mul_f32_e32 v23, 0x3fb8aa3b, v23
	v_exp_f32_e32 v190, v23
	v_sub_f32_e32 v23, v41, v150
	v_mul_f32_e32 v23, 0x3fb8aa3b, v23
	v_exp_f32_e32 v191, v23
	v_sub_f32_e32 v23, v42, v150
	v_mul_f32_e32 v23, 0x3fb8aa3b, v23
	v_exp_f32_e32 v175, v23
	v_sub_f32_e32 v23, v43, v150
	v_mul_f32_e32 v23, 0x3fb8aa3b, v23
	v_exp_f32_e32 v176, v23
	v_sub_f32_e32 v23, v44, v150
	v_mul_f32_e32 v23, 0x3fb8aa3b, v23
	v_exp_f32_e32 v177, v23
	v_sub_f32_e32 v23, v45, v150
	v_mul_f32_e32 v23, 0x3fb8aa3b, v23
	v_exp_f32_e32 v178, v23
	v_sub_f32_e32 v23, v46, v150
	v_mul_f32_e32 v23, 0x3fb8aa3b, v23
	v_exp_f32_e32 v179, v23
	v_sub_f32_e32 v23, v47, v150
	v_mul_f32_e32 v23, 0x3fb8aa3b, v23
	v_exp_f32_e32 v180, v23
	v_sub_f32_e32 v23, v48, v150
	v_mul_f32_e32 v23, 0x3fb8aa3b, v23
	v_exp_f32_e32 v181, v23
	v_sub_f32_e32 v23, v49, v150
	v_mul_f32_e32 v23, 0x3fb8aa3b, v23
	v_exp_f32_e32 v182, v23
	v_sub_f32_e32 v23, v50, v150
	v_mul_f32_e32 v23, 0x3fb8aa3b, v23
	v_exp_f32_e32 v115, v23
	v_sub_f32_e32 v23, v51, v150
	v_mul_f32_e32 v23, 0x3fb8aa3b, v23
	v_exp_f32_e32 v117, v23
	v_sub_f32_e32 v23, v52, v150
	v_mul_f32_e32 v23, 0x3fb8aa3b, v23
	v_exp_f32_e32 v123, v23
	v_sub_f32_e32 v23, v53, v150
	v_mul_f32_e32 v23, 0x3fb8aa3b, v23
	v_exp_f32_e32 v170, v23
	v_sub_f32_e32 v23, v54, v150
	v_mul_f32_e32 v23, 0x3fb8aa3b, v23
	v_exp_f32_e32 v171, v23
	v_sub_f32_e32 v23, v55, v150
	v_mul_f32_e32 v23, 0x3fb8aa3b, v23
	v_exp_f32_e32 v172, v23
	v_sub_f32_e32 v23, v56, v150
	v_mul_f32_e32 v23, 0x3fb8aa3b, v23
	v_exp_f32_e32 v173, v23
	v_sub_f32_e32 v23, v57, v150
	v_sub_f32_e32 v22, v34, v150
	v_mul_f32_e32 v23, 0x3fb8aa3b, v23
	v_mul_f32_e32 v22, 0x3fb8aa3b, v22
	v_exp_f32_e32 v174, v23
	v_sub_f32_e32 v23, v58, v150
	v_exp_f32_e32 v183, v22
	v_mul_f32_e32 v23, 0x3fb8aa3b, v23
	v_exp_f32_e32 v56, v23
	v_sub_f32_e32 v23, v59, v150
	v_mul_f32_e32 v23, 0x3fb8aa3b, v23
	v_exp_f32_e32 v57, v23
	v_sub_f32_e32 v23, v60, v150
	v_add_f32_e32 v22, 0, v183
	v_mul_f32_e32 v23, 0x3fb8aa3b, v23
	v_add_f32_e32 v22, v185, v22
	v_exp_f32_e32 v58, v23
	v_sub_f32_e32 v23, v61, v150
	v_add_f32_e32 v22, v184, v22
	v_mul_f32_e32 v23, 0x3fb8aa3b, v23
	v_add_f32_e32 v22, v186, v22
	v_exp_f32_e32 v59, v23
	v_sub_f32_e32 v23, v62, v150
	v_add_f32_e32 v22, v187, v22
	v_mul_f32_e32 v23, 0x3fb8aa3b, v23
	v_add_f32_e32 v22, v188, v22
	v_exp_f32_e32 v60, v23
	v_sub_f32_e32 v23, v63, v150
	v_add_f32_e32 v22, v190, v22
	v_mul_f32_e32 v23, 0x3fb8aa3b, v23
	v_add_f32_e32 v22, v191, v22
	v_exp_f32_e32 v61, v23
	v_sub_f32_e32 v23, v64, v150
	v_add_f32_e32 v22, v175, v22
	v_mul_f32_e32 v23, 0x3fb8aa3b, v23
	v_add_f32_e32 v22, v176, v22
	v_exp_f32_e32 v62, v23
	v_sub_f32_e32 v23, v65, v150
	v_add_f32_e32 v22, v177, v22
	v_mul_f32_e32 v23, 0x3fb8aa3b, v23
	v_add_f32_e32 v22, v178, v22
	v_exp_f32_e32 v63, v23
	v_sub_f32_e32 v23, v66, v150
	v_add_f32_e32 v22, v179, v22
	v_mul_f32_e32 v23, 0x3fb8aa3b, v23
	v_add_f32_e32 v22, v180, v22
	v_exp_f32_e32 v48, v23
	v_sub_f32_e32 v23, v67, v150
	v_add_f32_e32 v22, v181, v22
	v_mul_f32_e32 v23, 0x3fb8aa3b, v23
	v_add_f32_e32 v22, v182, v22
	v_exp_f32_e32 v49, v23
	v_sub_f32_e32 v23, v68, v150
	v_add_f32_e32 v22, v115, v22
	v_mul_f32_e32 v23, 0x3fb8aa3b, v23
	v_add_f32_e32 v22, v117, v22
	v_exp_f32_e32 v50, v23
	v_sub_f32_e32 v23, v69, v150
	v_add_f32_e32 v22, v123, v22
	v_mul_f32_e32 v23, 0x3fb8aa3b, v23
	v_add_f32_e32 v22, v170, v22
	v_exp_f32_e32 v52, v23
	v_sub_f32_e32 v23, v70, v150
	v_add_f32_e32 v22, v171, v22
	v_mul_f32_e32 v23, 0x3fb8aa3b, v23
	v_add_f32_e32 v22, v172, v22
	v_exp_f32_e32 v51, v23
	v_sub_f32_e32 v23, v71, v150
	v_add_f32_e32 v22, v173, v22
	v_mul_f32_e32 v23, 0x3fb8aa3b, v23
	v_add_f32_e32 v22, v174, v22
	v_exp_f32_e32 v54, v23
	v_sub_f32_e32 v23, v72, v150
	v_add_f32_e32 v22, v56, v22
	v_mul_f32_e32 v23, 0x3fb8aa3b, v23
	v_add_f32_e32 v22, v57, v22
	v_exp_f32_e32 v53, v23
	v_sub_f32_e32 v23, v73, v150
	v_add_f32_e32 v22, v58, v22
	v_mul_f32_e32 v23, 0x3fb8aa3b, v23
	v_add_f32_e32 v22, v59, v22
	v_exp_f32_e32 v55, v23
	v_sub_f32_e32 v23, v74, v150
	v_add_f32_e32 v22, v60, v22
	v_mul_f32_e32 v23, 0x3fb8aa3b, v23
	v_add_f32_e32 v22, v61, v22
	v_exp_f32_e32 v40, v23
	v_sub_f32_e32 v23, v75, v150
	v_add_f32_e32 v22, v62, v22
; #define LAS __attribute__((address_space(3)))
; __device__ __forceinline__ unsigned pk2(float lo, float hi) { return f2bf(lo) | (f2bf(hi) << 16); }
; #define MFMA16(a, b, c) __builtin_amdgcn_mfma_f32_16x16x32_bf16(a, b, c, 0, 0, 0)
; __device__ __forceinline__ v4i16_t vtr(const LAS unsigned char* p) { return __builtin_amdgcn_ds_read_tr16_b64_v4i16((LAS v4i16_t*)p); }
; __device__ __forceinline__ void memattn_group(const Params& p, LAS unsigned char* lds, int grp, const int tid) {
;     ...
;         for (int ct = 0; ct < 16; ++ct)
; #pragma unroll
;             for (int e = 0; e < 4; ++e) { const float pv = __expf(st[ct][e] - mx); st[ct][e] = pv; sm += pv; }
;         sm += __shfl_xor(sm, 16); sm += __shfl_xor(sm, 32);
;         f32x4 ot[8];
; #pragma unroll
;         for (int dt = 0; dt < 8; ++dt) ot[dt] = (f32x4){0.f, 0.f, 0.f, 0.f};
; #pragma unroll
;         for (int ks = 0; ks < 8; ++ks) { v4u pw; pw.x = pk2(st[2 * ks][0], st[2 * ks][1]); pw.y = pk2(st[2 * ks][2], st[2 * ks][3]); pw.z = pk2(st[2 * ks + 1][0], st[2 * ks + 1][1]); pw.w = pk2(st[2 * ks + 1][2], st[2 * ks + 1][3]);
;             const bf16x8 pb = __builtin_bit_cast(bf16x8, pw);
; #pragma unroll
;             for (int dt = 0; dt < 8; ++dt) { const LAS unsigned char* vr = lds + MA_VT + (32 * ks + 4 * fq + (fr >> 2)) * 288 + (16 * dt + 4 * (fr & 3)) * 2;
;                 const v4i16_t lo = vtr(vr), hi = vtr(vr + 16 * 288);
;                 ot[dt] = MFMA16(__builtin_shufflevector(lo, hi, 0, 1, 2, 3, 4, 5, 6, 7), pb, ot[dt]); } }
	v_mul_f32_e32 v23, 0x3fb8aa3b, v23
	v_add_f32_e32 v22, v63, v22
	v_exp_f32_e32 v42, v23
	v_sub_f32_e32 v23, v76, v150
	v_add_f32_e32 v22, v48, v22
	v_mul_f32_e32 v23, 0x3fb8aa3b, v23
	v_add_f32_e32 v22, v49, v22
	v_exp_f32_e32 v41, v23
	v_sub_f32_e32 v23, v77, v150
	v_add_f32_e32 v22, v50, v22
	v_mul_f32_e32 v23, 0x3fb8aa3b, v23
	v_add_f32_e32 v22, v52, v22
	v_exp_f32_e32 v44, v23
	v_sub_f32_e32 v23, v78, v150
	v_add_f32_e32 v22, v51, v22
	v_mul_f32_e32 v23, 0x3fb8aa3b, v23
	v_add_f32_e32 v22, v54, v22
	v_exp_f32_e32 v43, v23
	v_sub_f32_e32 v23, v79, v150
	v_add_f32_e32 v22, v53, v22
	v_mul_f32_e32 v23, 0x3fb8aa3b, v23
	v_add_f32_e32 v22, v55, v22
	v_exp_f32_e32 v46, v23
	v_sub_f32_e32 v23, v80, v150
	v_add_f32_e32 v22, v40, v22
	v_mul_f32_e32 v23, 0x3fb8aa3b, v23
	v_add_f32_e32 v22, v42, v22
	v_exp_f32_e32 v45, v23
	v_sub_f32_e32 v23, v81, v150
	v_add_f32_e32 v22, v41, v22
	v_mul_f32_e32 v23, 0x3fb8aa3b, v23
	v_add_f32_e32 v22, v44, v22
	v_exp_f32_e32 v47, v23
	v_add_f32_e32 v22, v43, v22
	v_add_f32_e32 v22, v46, v22
	v_add_f32_e32 v22, v45, v22
	v_add_f32_e32 v23, v47, v22
	v_sub_f32_e32 v22, v82, v150
	v_mul_f32_e32 v22, 0x3fb8aa3b, v22
	v_sub_f32_e32 v24, v83, v150
	v_exp_f32_e32 v22, v22
	v_mul_f32_e32 v24, 0x3fb8aa3b, v24
	v_exp_f32_e32 v24, v24
	v_sub_f32_e32 v28, v85, v150
	v_add_f32_e32 v23, v22, v23
	v_mul_f32_e32 v28, 0x3fb8aa3b, v28
	v_add_f32_e32 v25, v24, v23
	v_sub_f32_e32 v23, v84, v150
	v_mul_f32_e32 v23, 0x3fb8aa3b, v23
	v_exp_f32_e32 v23, v23
	v_exp_f32_e32 v36, v28
	v_sub_f32_e32 v29, v87, v150
	v_mul_f32_e32 v29, 0x3fb8aa3b, v29
	v_add_f32_e32 v25, v23, v25
	v_add_f32_e32 v28, v36, v25
	v_sub_f32_e32 v25, v86, v150
	v_mul_f32_e32 v25, 0x3fb8aa3b, v25
	v_exp_f32_e32 v38, v29
	v_sub_f32_e32 v29, v88, v150
	v_exp_f32_e32 v25, v25
	v_mul_f32_e32 v29, 0x3fb8aa3b, v29
	v_exp_f32_e32 v37, v29
	v_sub_f32_e32 v29, v89, v150
	v_mul_f32_e32 v29, 0x3fb8aa3b, v29
	v_exp_f32_e32 v39, v29
	v_add_f32_e32 v28, v25, v28
	v_add_f32_e32 v28, v38, v28
	v_add_f32_e32 v28, v37, v28
	v_add_f32_e32 v29, v39, v28
	v_sub_f32_e32 v28, v90, v150
	v_mul_f32_e32 v28, 0x3fb8aa3b, v28
	v_sub_f32_e32 v30, v91, v150
	v_exp_f32_e32 v28, v28
	v_mul_f32_e32 v30, 0x3fb8aa3b, v30
	v_exp_f32_e32 v30, v30
	v_sub_f32_e32 v32, v93, v150
	v_add_f32_e32 v29, v28, v29
	v_mul_f32_e32 v32, 0x3fb8aa3b, v32
	v_add_f32_e32 v31, v30, v29
	v_sub_f32_e32 v29, v92, v150
	v_mul_f32_e32 v29, 0x3fb8aa3b, v29
	v_exp_f32_e32 v29, v29
	v_exp_f32_e32 v32, v32
	v_sub_f32_e32 v18, v18, v150
	v_mul_f32_e32 v18, 0x3fb8aa3b, v18
	v_add_f32_e32 v31, v29, v31
	v_add_f32_e32 v33, v32, v31
	v_exp_f32_e32 v31, v18
	v_sub_f32_e32 v19, v19, v150
	v_mul_f32_e32 v19, 0x3fb8aa3b, v19
	v_exp_f32_e32 v34, v19
	v_sub_f32_e32 v19, v20, v150
	v_mul_f32_e32 v19, 0x3fb8aa3b, v19
	v_add_f32_e32 v18, v31, v33
	v_exp_f32_e32 v33, v19
	v_sub_f32_e32 v19, v21, v150
	v_mul_f32_e32 v19, 0x3fb8aa3b, v19
	v_exp_f32_e32 v35, v19
	v_add_f32_e32 v18, v34, v18
	v_add_f32_e32 v18, v33, v18
	v_bfe_u32 v20, v186, 16, 1
	v_add_f32_e32 v18, v35, v18
	ds_bpermute_b32 v19, v26, v18
	v_bfe_u32 v21, v185, 16, 1
	v_add3_u32 v64, v185, v21, s33
	v_add3_u32 v65, v186, v20, s33
	v_bfe_u32 v20, v183, 16, 1
	v_bfe_u32 v21, v184, 16, 1
	s_waitcnt lgkmcnt(0)
	v_add_f32_e32 v26, v18, v19
	v_cvt_pk_bf16_f32 v21, v190, v191
	v_cvt_pk_bf16_f32 v20, v187, v188
	v_cvt_pk_bf16_f32 v19, v184, v186
	v_cvt_pk_bf16_f32 v18, v183, v185
	ds_read_b64_tr_b16 v[66:67], v128 offset:4608
	ds_read_b64_tr_b16 v[64:65], v128
	ds_read_b64_tr_b16 v[68:69], v128 offset:32
	ds_read_b64_tr_b16 v[70:71], v128 offset:4640
	ds_read_b64_tr_b16 v[72:73], v128 offset:64
	ds_read_b64_tr_b16 v[74:75], v128 offset:4672
	ds_read_b64_tr_b16 v[76:77], v128 offset:96
	ds_read_b64_tr_b16 v[78:79], v128 offset:4704
	ds_read_b64_tr_b16 v[80:81], v128 offset:128
	ds_read_b64_tr_b16 v[82:83], v128 offset:4736
	ds_read_b64_tr_b16 v[84:85], v128 offset:160
	ds_read_b64_tr_b16 v[86:87], v128 offset:4768
	ds_read_b64_tr_b16 v[88:89], v128 offset:192
	ds_read_b64_tr_b16 v[90:91], v128 offset:4800
	ds_read_b64_tr_b16 v[150:151], v128 offset:224
	ds_read_b64_tr_b16 v[152:153], v128 offset:4832
	s_waitcnt lgkmcnt(14)
	v_mfma_f32_16x16x32_bf16 v[64:67], v[64:67], v[18:21], 0
	v_bfe_u32 v92, v182, 16, 1
	v_bfe_u32 v93, v180, 16, 1
	v_add3_u32 v93, v180, v93, s33
	s_waitcnt lgkmcnt(12)
	v_mfma_f32_16x16x32_bf16 v[68:71], v[68:71], v[18:21], 0
	v_add3_u32 v92, v182, v92, s33
	ds_bpermute_b32 v27, v27, v26
	s_waitcnt lgkmcnt(0)
	v_add_f32_e32 v26, v26, v27
	v_mfma_f32_16x16x32_bf16 v[72:75], v[72:75], v[18:21], 0
	v_div_scale_f32 v27, s[0:1], v26, v26, 1.0
	v_mfma_f32_16x16x32_bf16 v[76:79], v[76:79], v[18:21], 0
	v_mfma_f32_16x16x32_bf16 v[80:83], v[80:83], v[18:21], 0
	v_mfma_f32_16x16x32_bf16 v[84:87], v[84:87], v[18:21], 0
	v_mfma_f32_16x16x32_bf16 v[88:91], v[88:91], v[18:21], 0
	v_mfma_f32_16x16x32_bf16 v[18:21], v[150:153], v[18:21], 0
	v_bfe_u32 v151, v176, 16, 1
	v_bfe_u32 v150, v178, 16, 1
	v_add3_u32 v176, v176, v151, s33
	v_bfe_u32 v151, v175, 16, 1
	v_bfe_u32 v152, v177, 16, 1
	v_add3_u32 v150, v178, v150, s33
	v_bfe_u32 v153, v179, 16, 1
	v_add3_u32 v152, v177, v152, s33
	v_add3_u32 v151, v175, v151, s33
	v_add3_u32 v153, v179, v153, s33
	v_lshrrev_b32_e32 v175, 16, v151
	v_lshrrev_b32_e32 v151, 16, v152
	v_lshrrev_b32_e32 v152, 16, v153
	v_and_or_b32 v151, v150, s11, v151
	v_and_or_b32 v150, v176, s11, v175
	ds_read_b64_tr_b16 v[176:177], v128 offset:9216
	ds_read_b64_tr_b16 v[178:179], v128 offset:13824
	v_cvt_pk_bf16_f32 v153, v181, v182
	v_and_or_b32 v152, v93, s11, v152
	v_bfe_u32 v93, v172, 16, 1
	v_add3_u32 v93, v172, v93, s33
	s_waitcnt lgkmcnt(0)
; #define LAS __attribute__((address_space(3)))
; __device__ __forceinline__ unsigned pk2(float lo, float hi) { return f2bf(lo) | (f2bf(hi) << 16); }
; #define MFMA16(a, b, c) __builtin_amdgcn_mfma_f32_16x16x32_bf16(a, b, c, 0, 0, 0)
; __device__ __forceinline__ v4i16_t vtr(const LAS unsigned char* p) { return __builtin_amdgcn_ds_read_tr16_b64_v4i16((LAS v4i16_t*)p); }
; __device__ __forceinline__ void memattn_group(const Params& p, LAS unsigned char* lds, int grp, const int tid) {
;     ...
; #pragma unroll
;         for (int ks = 0; ks < 8; ++ks) { v4u pw; pw.x = pk2(st[2 * ks][0], st[2 * ks][1]); pw.y = pk2(st[2 * ks][2], st[2 * ks][3]); pw.z = pk2(st[2 * ks + 1][0], st[2 * ks + 1][1]); pw.w = pk2(st[2 * ks + 1][2], st[2 * ks + 1][3]);
;             const bf16x8 pb = __builtin_bit_cast(bf16x8, pw);
; #pragma unroll
;             for (int dt = 0; dt < 8; ++dt) { const LAS unsigned char* vr = lds + MA_VT + (32 * ks + 4 * fq + (fr >> 2)) * 288 + (16 * dt + 4 * (fr & 3)) * 2;
;                 const v4i16_t lo = vtr(vr), hi = vtr(vr + 16 * 288);
;                 ot[dt] = MFMA16(__builtin_shufflevector(lo, hi, 0, 1, 2, 3, 4, 5, 6, 7), pb, ot[dt]); } }
	v_mfma_f32_16x16x32_bf16 v[64:67], v[176:179], v[150:153], v[64:67]
	ds_read_b64_tr_b16 v[176:177], v128 offset:9248
	ds_read_b64_tr_b16 v[178:179], v128 offset:13856
	v_bfe_u32 v92, v174, 16, 1
	v_add3_u32 v92, v174, v92, s33
	s_waitcnt lgkmcnt(0)
	v_mfma_f32_16x16x32_bf16 v[68:71], v[176:179], v[150:153], v[68:71]
	ds_read_b64_tr_b16 v[176:177], v128 offset:9280
	ds_read_b64_tr_b16 v[178:179], v128 offset:13888
	s_waitcnt lgkmcnt(0)
	v_mfma_f32_16x16x32_bf16 v[72:75], v[176:179], v[150:153], v[72:75]
	ds_read_b64_tr_b16 v[176:177], v128 offset:9312
	ds_read_b64_tr_b16 v[178:179], v128 offset:13920
	s_waitcnt lgkmcnt(0)
	v_mfma_f32_16x16x32_bf16 v[76:79], v[176:179], v[150:153], v[76:79]
	ds_read_b64_tr_b16 v[176:177], v128 offset:9344
	ds_read_b64_tr_b16 v[178:179], v128 offset:13952
	s_waitcnt lgkmcnt(0)
	v_mfma_f32_16x16x32_bf16 v[80:83], v[176:179], v[150:153], v[80:83]
	ds_read_b64_tr_b16 v[176:177], v128 offset:9376
	ds_read_b64_tr_b16 v[178:179], v128 offset:13984
	s_waitcnt lgkmcnt(0)
	v_mfma_f32_16x16x32_bf16 v[84:87], v[176:179], v[150:153], v[84:87]
	ds_read_b64_tr_b16 v[176:177], v128 offset:9408
	ds_read_b64_tr_b16 v[178:179], v128 offset:14016
	s_waitcnt lgkmcnt(0)
	v_mfma_f32_16x16x32_bf16 v[88:91], v[176:179], v[150:153], v[88:91]
	ds_read_b64_tr_b16 v[176:177], v128 offset:9440
	ds_read_b64_tr_b16 v[178:179], v128 offset:14048
	s_waitcnt lgkmcnt(0)
	v_mfma_f32_16x16x32_bf16 v[18:21], v[176:179], v[150:153], v[18:21]
	v_bfe_u32 v150, v170, 16, 1
	v_add3_u32 v150, v170, v150, s33
	v_bfe_u32 v170, v173, 16, 1
	v_bfe_u32 v152, v123, 16, 1
	v_bfe_u32 v153, v171, 16, 1
	v_add3_u32 v170, v173, v170, s33
	v_add3_u32 v153, v171, v153, s33
	v_add3_u32 v123, v123, v152, s33
	v_lshrrev_b32_e32 v152, 16, v170
	ds_read_b64_tr_b16 v[170:171], v128 offset:18432
	ds_read_b64_tr_b16 v[172:173], v128 offset:23040
	v_lshrrev_b32_e32 v123, 16, v123
	v_lshrrev_b32_e32 v151, 16, v153
	v_and_or_b32 v153, v92, s11, v152
	v_and_or_b32 v152, v93, s11, v151
	v_and_or_b32 v151, v150, s11, v123
	v_cvt_pk_bf16_f32 v150, v115, v117
	v_bfe_u32 v92, v63, 16, 1
	v_bfe_u32 v93, v61, 16, 1
	s_waitcnt lgkmcnt(0)
	v_mfma_f32_16x16x32_bf16 v[64:67], v[170:173], v[150:153], v[64:67]
	ds_read_b64_tr_b16 v[170:171], v128 offset:18464
	ds_read_b64_tr_b16 v[172:173], v128 offset:23072
	v_bfe_u32 v115, v59, 16, 1
	v_bfe_u32 v117, v57, 16, 1
	s_waitcnt lgkmcnt(0)
	v_mfma_f32_16x16x32_bf16 v[68:71], v[170:173], v[150:153], v[68:71]
	ds_read_b64_tr_b16 v[170:171], v128 offset:18496
	ds_read_b64_tr_b16 v[172:173], v128 offset:23104
	v_add3_u32 v117, v57, v117, s33
	v_add3_u32 v57, v59, v115, s33
	s_waitcnt lgkmcnt(0)
	v_mfma_f32_16x16x32_bf16 v[72:75], v[170:173], v[150:153], v[72:75]
	ds_read_b64_tr_b16 v[170:171], v128 offset:18528
	ds_read_b64_tr_b16 v[172:173], v128 offset:23136
	v_add3_u32 v61, v61, v93, s33
	v_add3_u32 v59, v63, v92, s33
	s_waitcnt lgkmcnt(0)
	v_mfma_f32_16x16x32_bf16 v[76:79], v[170:173], v[150:153], v[76:79]
	ds_read_b64_tr_b16 v[170:171], v128 offset:18560
	ds_read_b64_tr_b16 v[172:173], v128 offset:23168
	v_bfe_u32 v92, v58, 16, 1
	v_bfe_u32 v93, v60, 16, 1
	s_waitcnt lgkmcnt(0)
	v_mfma_f32_16x16x32_bf16 v[80:83], v[170:173], v[150:153], v[80:83]
	ds_read_b64_tr_b16 v[170:171], v128 offset:18592
	ds_read_b64_tr_b16 v[172:173], v128 offset:23200
	v_bfe_u32 v115, v62, 16, 1
	v_bfe_u32 v63, v56, 16, 1
	s_waitcnt lgkmcnt(0)
	v_mfma_f32_16x16x32_bf16 v[84:87], v[170:173], v[150:153], v[84:87]
	ds_read_b64_tr_b16 v[170:171], v128 offset:18624
	ds_read_b64_tr_b16 v[172:173], v128 offset:23232
	v_add3_u32 v62, v62, v115, s33
	v_add3_u32 v60, v60, v93, s33
	v_add3_u32 v58, v58, v92, s33
	v_add3_u32 v56, v56, v63, s33
	v_lshrrev_b32_e32 v63, 16, v58
	v_lshrrev_b32_e32 v58, 16, v60
	v_lshrrev_b32_e32 v60, 16, v62
	s_waitcnt lgkmcnt(0)
	v_mfma_f32_16x16x32_bf16 v[88:91], v[170:173], v[150:153], v[88:91]
	ds_read_b64_tr_b16 v[170:171], v128 offset:18656
	ds_read_b64_tr_b16 v[172:173], v128 offset:23264
	v_and_or_b32 v59, v59, s11, v60
	v_and_or_b32 v58, v61, s11, v58
	v_and_or_b32 v57, v57, s11, v63
	ds_read_b64_tr_b16 v[60:61], v128 offset:27648
	ds_read_b64_tr_b16 v[62:63], v128 offset:32256
	v_lshrrev_b32_e32 v56, 16, v56
	v_and_or_b32 v56, v117, s11, v56
	s_waitcnt lgkmcnt(2)
	v_mfma_f32_16x16x32_bf16 v[18:21], v[170:173], v[150:153], v[18:21]
	v_ashrrev_i32_e32 v123, 31, v122
	s_waitcnt lgkmcnt(0)
	v_mfma_f32_16x16x32_bf16 v[60:63], v[60:63], v[56:59], v[64:67]
	s_nop 2
	ds_read_b64_tr_b16 v[64:65], v128 offset:27680
	ds_read_b64_tr_b16 v[66:67], v128 offset:32288
	s_waitcnt lgkmcnt(0)
	v_mfma_f32_16x16x32_bf16 v[64:67], v[64:67], v[56:59], v[68:71]
	s_nop 2
	ds_read_b64_tr_b16 v[68:69], v128 offset:27712
	ds_read_b64_tr_b16 v[70:71], v128 offset:32320
	s_waitcnt lgkmcnt(0)
	v_mfma_f32_16x16x32_bf16 v[68:71], v[68:71], v[56:59], v[72:75]
	s_nop 2
	ds_read_b64_tr_b16 v[72:73], v128 offset:27744
	ds_read_b64_tr_b16 v[74:75], v128 offset:32352
	s_waitcnt lgkmcnt(0)
	v_mfma_f32_16x16x32_bf16 v[72:75], v[72:75], v[56:59], v[76:79]
	s_nop 2
	ds_read_b64_tr_b16 v[76:77], v128 offset:27776
	ds_read_b64_tr_b16 v[78:79], v128 offset:32384
	s_waitcnt lgkmcnt(0)
	v_mfma_f32_16x16x32_bf16 v[76:79], v[76:79], v[56:59], v[80:83]
	s_nop 2
	ds_read_b64_tr_b16 v[80:81], v128 offset:27808
	ds_read_b64_tr_b16 v[82:83], v128 offset:32416
	s_waitcnt lgkmcnt(0)
	v_mfma_f32_16x16x32_bf16 v[80:83], v[80:83], v[56:59], v[84:87]
	s_nop 2
	ds_read_b64_tr_b16 v[84:85], v128 offset:27840
	ds_read_b64_tr_b16 v[86:87], v128 offset:32448
	s_waitcnt lgkmcnt(0)
	v_mfma_f32_16x16x32_bf16 v[84:87], v[84:87], v[56:59], v[88:91]
	s_nop 2
	ds_read_b64_tr_b16 v[88:89], v128 offset:27872
	ds_read_b64_tr_b16 v[90:91], v128 offset:32480
	s_waitcnt lgkmcnt(0)
; #define LAS __attribute__((address_space(3)))
; __device__ __forceinline__ unsigned pk2(float lo, float hi) { return f2bf(lo) | (f2bf(hi) << 16); }
; #define MFMA16(a, b, c) __builtin_amdgcn_mfma_f32_16x16x32_bf16(a, b, c, 0, 0, 0)
; __device__ __forceinline__ v4i16_t vtr(const LAS unsigned char* p) { return __builtin_amdgcn_ds_read_tr16_b64_v4i16((LAS v4i16_t*)p); }
; __device__ __forceinline__ void memattn_group(const Params& p, LAS unsigned char* lds, int grp, const int tid) {
;     ...
; #pragma unroll
;         for (int ks = 0; ks < 8; ++ks) { v4u pw; pw.x = pk2(st[2 * ks][0], st[2 * ks][1]); pw.y = pk2(st[2 * ks][2], st[2 * ks][3]); pw.z = pk2(st[2 * ks + 1][0], st[2 * ks + 1][1]); pw.w = pk2(st[2 * ks + 1][2], st[2 * ks + 1][3]);
;             const bf16x8 pb = __builtin_bit_cast(bf16x8, pw);
; #pragma unroll
;             for (int dt = 0; dt < 8; ++dt) { const LAS unsigned char* vr = lds + MA_VT + (32 * ks + 4 * fq + (fr >> 2)) * 288 + (16 * dt + 4 * (fr & 3)) * 2;
;                 const v4i16_t lo = vtr(vr), hi = vtr(vr + 16 * 288);
;                 ot[dt] = MFMA16(__builtin_shufflevector(lo, hi, 0, 1, 2, 3, 4, 5, 6, 7), pb, ot[dt]); } }
	v_mfma_f32_16x16x32_bf16 v[18:21], v[88:91], v[56:59], v[18:21]
	v_bfe_u32 v56, v55, 16, 1
	v_bfe_u32 v57, v54, 16, 1
	v_bfe_u32 v58, v52, 16, 1
	v_bfe_u32 v59, v49, 16, 1
	v_add3_u32 v59, v49, v59, s33
	v_add3_u32 v49, v52, v58, s33
	v_add3_u32 v52, v54, v57, s33
	v_add3_u32 v54, v55, v56, s33
	v_bfe_u32 v55, v48, 16, 1
	v_bfe_u32 v56, v50, 16, 1
	v_bfe_u32 v57, v51, 16, 1
	v_bfe_u32 v58, v53, 16, 1
	v_add3_u32 v53, v53, v58, s33
	v_add3_u32 v51, v51, v57, s33
	v_add3_u32 v50, v50, v56, s33
	v_add3_u32 v48, v48, v55, s33
	v_lshrrev_b32_e32 v48, 16, v48
	v_lshrrev_b32_e32 v55, 16, v50
	v_lshrrev_b32_e32 v50, 16, v51
	v_lshrrev_b32_e32 v51, 16, v53
	v_and_or_b32 v51, v54, s11, v51
	v_and_or_b32 v50, v52, s11, v50
	v_and_or_b32 v49, v49, s11, v55
	v_and_or_b32 v48, v59, s11, v48
	ds_read_b64_tr_b16 v[52:53], v128 offset:36864
	ds_read_b64_tr_b16 v[54:55], v128 offset:41472
	ds_read_b64_tr_b16 v[56:57], v128 offset:36896
	ds_read_b64_tr_b16 v[58:59], v128 offset:41504
	s_waitcnt lgkmcnt(2)
	v_mfma_f32_16x16x32_bf16 v[52:55], v[52:55], v[48:51], v[60:63]
	s_nop 2
	ds_read_b64_tr_b16 v[60:61], v128 offset:36928
	ds_read_b64_tr_b16 v[62:63], v128 offset:41536
	s_waitcnt lgkmcnt(2)
	v_mfma_f32_16x16x32_bf16 v[56:59], v[56:59], v[48:51], v[64:67]
	s_nop 2
	ds_read_b64_tr_b16 v[64:65], v128 offset:36960
	ds_read_b64_tr_b16 v[66:67], v128 offset:41568
	s_waitcnt lgkmcnt(2)
	v_mfma_f32_16x16x32_bf16 v[60:63], v[60:63], v[48:51], v[68:71]
	s_nop 2
	ds_read_b64_tr_b16 v[68:69], v128 offset:36992
	ds_read_b64_tr_b16 v[70:71], v128 offset:41600
	s_waitcnt lgkmcnt(2)
	v_mfma_f32_16x16x32_bf16 v[64:67], v[64:67], v[48:51], v[72:75]
	s_nop 2
	ds_read_b64_tr_b16 v[72:73], v128 offset:37024
	ds_read_b64_tr_b16 v[74:75], v128 offset:41632
	s_waitcnt lgkmcnt(2)
	v_mfma_f32_16x16x32_bf16 v[68:71], v[68:71], v[48:51], v[76:79]
	s_nop 2
	ds_read_b64_tr_b16 v[76:77], v128 offset:37056
	ds_read_b64_tr_b16 v[78:79], v128 offset:41664
	s_waitcnt lgkmcnt(2)
	v_mfma_f32_16x16x32_bf16 v[72:75], v[72:75], v[48:51], v[80:83]
	s_nop 2
	ds_read_b64_tr_b16 v[80:81], v128 offset:37088
	ds_read_b64_tr_b16 v[82:83], v128 offset:41696
	s_waitcnt lgkmcnt(2)
	v_mfma_f32_16x16x32_bf16 v[76:79], v[76:79], v[48:51], v[84:87]
	s_waitcnt lgkmcnt(0)
	v_mfma_f32_16x16x32_bf16 v[18:21], v[80:83], v[48:51], v[18:21]
	v_bfe_u32 v48, v47, 16, 1
	v_bfe_u32 v49, v46, 16, 1
	v_bfe_u32 v50, v44, 16, 1
	v_bfe_u32 v51, v42, 16, 1
	v_add3_u32 v51, v42, v51, s33
	v_add3_u32 v42, v46, v49, s33
	v_add3_u32 v46, v47, v48, s33
	v_bfe_u32 v47, v40, 16, 1
	v_bfe_u32 v49, v43, 16, 1
	v_bfe_u32 v50, v45, 16, 1
	v_add3_u32 v45, v45, v50, s33
	v_add3_u32 v43, v43, v49, s33
	v_add3_u32 v40, v40, v47, s33
	v_lshrrev_b32_e32 v40, 16, v40
	v_lshrrev_b32_e32 v47, 16, v43
	v_lshrrev_b32_e32 v43, 16, v45
	v_and_or_b32 v43, v46, s11, v43
	v_and_or_b32 v42, v42, s11, v47
	v_cvt_pk_bf16_f32 v41, v41, v44
	v_and_or_b32 v40, v51, s11, v40
	ds_read_b64_tr_b16 v[44:45], v128 offset:46080
	ds_read_b64_tr_b16 v[46:47], v128 offset:50688
	ds_read_b64_tr_b16 v[48:49], v128 offset:46112
	ds_read_b64_tr_b16 v[50:51], v128 offset:50720
	s_waitcnt lgkmcnt(2)
	v_mfma_f32_16x16x32_bf16 v[44:47], v[44:47], v[40:43], v[52:55]
	s_nop 2
	ds_read_b64_tr_b16 v[52:53], v128 offset:46144
	ds_read_b64_tr_b16 v[54:55], v128 offset:50752
	s_waitcnt lgkmcnt(2)
	v_mfma_f32_16x16x32_bf16 v[48:51], v[48:51], v[40:43], v[56:59]
	s_nop 2
	ds_read_b64_tr_b16 v[56:57], v128 offset:46176
	ds_read_b64_tr_b16 v[58:59], v128 offset:50784
	s_waitcnt lgkmcnt(2)
	v_mfma_f32_16x16x32_bf16 v[52:55], v[52:55], v[40:43], v[60:63]
	s_nop 2
	ds_read_b64_tr_b16 v[60:61], v128 offset:46208
	ds_read_b64_tr_b16 v[62:63], v128 offset:50816
	s_waitcnt lgkmcnt(2)
	v_mfma_f32_16x16x32_bf16 v[56:59], v[56:59], v[40:43], v[64:67]
	s_nop 2
	ds_read_b64_tr_b16 v[64:65], v128 offset:46240
	ds_read_b64_tr_b16 v[66:67], v128 offset:50848
	s_waitcnt lgkmcnt(2)
	v_mfma_f32_16x16x32_bf16 v[60:63], v[60:63], v[40:43], v[68:71]
	s_nop 2
	ds_read_b64_tr_b16 v[68:69], v128 offset:46272
	ds_read_b64_tr_b16 v[70:71], v128 offset:50880
	s_waitcnt lgkmcnt(2)
	v_mfma_f32_16x16x32_bf16 v[64:67], v[64:67], v[40:43], v[72:75]
	s_nop 2
	ds_read_b64_tr_b16 v[72:73], v128 offset:46304
	ds_read_b64_tr_b16 v[74:75], v128 offset:50912
	s_waitcnt lgkmcnt(2)
	v_mfma_f32_16x16x32_bf16 v[68:71], v[68:71], v[40:43], v[76:79]
	s_waitcnt lgkmcnt(0)
	v_mfma_f32_16x16x32_bf16 v[40:43], v[72:75], v[40:43], v[18:21]
	s_nop 2
	v_bfe_u32 v18, v39, 16, 1
	v_bfe_u32 v19, v38, 16, 1
	v_bfe_u32 v20, v36, 16, 1
	v_bfe_u32 v21, v24, 16, 1
	v_add3_u32 v21, v24, v21, s33
	v_add3_u32 v20, v36, v20, s33
	v_add3_u32 v19, v38, v19, s33
	v_add3_u32 v18, v39, v18, s33
	v_bfe_u32 v24, v22, 16, 1
	v_bfe_u32 v36, v23, 16, 1
	v_bfe_u32 v38, v25, 16, 1
	v_bfe_u32 v39, v37, 16, 1
	v_add3_u32 v37, v37, v39, s33
	v_add3_u32 v25, v25, v38, s33
	v_add3_u32 v23, v23, v36, s33
	v_add3_u32 v22, v22, v24, s33
	v_lshrrev_b32_e32 v22, 16, v22
	v_lshrrev_b32_e32 v23, 16, v23
	v_lshrrev_b32_e32 v24, 16, v25
	v_lshrrev_b32_e32 v25, 16, v37
	v_and_or_b32 v39, v18, s11, v25
	v_and_or_b32 v38, v19, s11, v24
	v_and_or_b32 v37, v20, s11, v23
	v_and_or_b32 v36, v21, s11, v22
	ds_read_b64_tr_b16 v[18:19], v128 offset:55296
	ds_read_b64_tr_b16 v[20:21], v128 offset:59904
	s_waitcnt lgkmcnt(0)
	v_mfma_f32_16x16x32_bf16 v[44:47], v[18:21], v[36:39], v[44:47]
	ds_read_b64_tr_b16 v[18:19], v128 offset:55328
	ds_read_b64_tr_b16 v[20:21], v128 offset:59936
	s_waitcnt lgkmcnt(0)
	v_mfma_f32_16x16x32_bf16 v[48:51], v[18:21], v[36:39], v[48:51]
	ds_read_b64_tr_b16 v[18:19], v128 offset:55360
	ds_read_b64_tr_b16 v[20:21], v128 offset:59968
	s_waitcnt lgkmcnt(0)
; #define LAS __attribute__((address_space(3)))
; __device__ __forceinline__ unsigned pk2(float lo, float hi) { return f2bf(lo) | (f2bf(hi) << 16); }
; #define MFMA16(a, b, c) __builtin_amdgcn_mfma_f32_16x16x32_bf16(a, b, c, 0, 0, 0)
; __device__ __forceinline__ v4i16_t vtr(const LAS unsigned char* p) { return __builtin_amdgcn_ds_read_tr16_b64_v4i16((LAS v4i16_t*)p); }
; __device__ __forceinline__ void memattn_group(const Params& p, LAS unsigned char* lds, int grp, const int tid) {
;     ...
; #pragma unroll
;         for (int ks = 0; ks < 8; ++ks) { v4u pw; pw.x = pk2(st[2 * ks][0], st[2 * ks][1]); pw.y = pk2(st[2 * ks][2], st[2 * ks][3]); pw.z = pk2(st[2 * ks + 1][0], st[2 * ks + 1][1]); pw.w = pk2(st[2 * ks + 1][2], st[2 * ks + 1][3]);
;             const bf16x8 pb = __builtin_bit_cast(bf16x8, pw);
; #pragma unroll
;             for (int dt = 0; dt < 8; ++dt) { const LAS unsigned char* vr = lds + MA_VT + (32 * ks + 4 * fq + (fr >> 2)) * 288 + (16 * dt + 4 * (fr & 3)) * 2;
;                 const v4i16_t lo = vtr(vr), hi = vtr(vr + 16 * 288);
;                 ot[dt] = MFMA16(__builtin_shufflevector(lo, hi, 0, 1, 2, 3, 4, 5, 6, 7), pb, ot[dt]); } }
;         { const size_t m = (size_t)(m0 + 16 * w + fr); const float inv = 1.f / sm;
; #pragma unroll
;           for (int dt = 0; dt < 8; ++dt) { unsigned long long wv = (unsigned long long)pk2(ot[dt][0] * inv, ot[dt][1] * inv) | ((unsigned long long)pk2(ot[dt][2] * inv, ot[dt][3] * inv) << 32);
;               *(unsigned long long*)(QM + m * 512 + h * 128 + 16 * dt + 4 * fq) = wv; } }
	v_mfma_f32_16x16x32_bf16 v[52:55], v[18:21], v[36:39], v[52:55]
	ds_read_b64_tr_b16 v[18:19], v128 offset:55392
	ds_read_b64_tr_b16 v[20:21], v128 offset:60000
	s_waitcnt lgkmcnt(0)
	v_mfma_f32_16x16x32_bf16 v[56:59], v[18:21], v[36:39], v[56:59]
	ds_read_b64_tr_b16 v[18:19], v128 offset:55424
	ds_read_b64_tr_b16 v[20:21], v128 offset:60032
	ds_read_b64_tr_b16 v[22:23], v128 offset:55456
	ds_read_b64_tr_b16 v[24:25], v128 offset:60064
	s_waitcnt lgkmcnt(2)
	v_mfma_f32_16x16x32_bf16 v[18:21], v[18:21], v[36:39], v[60:63]
	s_waitcnt lgkmcnt(0)
	v_mfma_f32_16x16x32_bf16 v[60:63], v[22:25], v[36:39], v[64:67]
	ds_read_b64_tr_b16 v[22:23], v128 offset:55488
	ds_read_b64_tr_b16 v[24:25], v128 offset:60096
	s_nop 0
	ds_read_b64_tr_b16 v[64:65], v128 offset:55520
	ds_read_b64_tr_b16 v[66:67], v128 offset:60128
	s_waitcnt lgkmcnt(2)
	v_mfma_f32_16x16x32_bf16 v[22:25], v[22:25], v[36:39], v[68:71]
	s_waitcnt lgkmcnt(0)
	v_mfma_f32_16x16x32_bf16 v[36:39], v[64:67], v[36:39], v[40:43]
	s_nop 2
	v_bfe_u32 v40, v35, 16, 1
	v_bfe_u32 v41, v34, 16, 1
	v_bfe_u32 v42, v32, 16, 1
	v_bfe_u32 v43, v30, 16, 1
	v_add3_u32 v43, v30, v43, s33
	v_add3_u32 v30, v34, v41, s33
	v_add3_u32 v34, v35, v40, s33
	v_bfe_u32 v41, v31, 16, 1
	v_bfe_u32 v42, v33, 16, 1
	v_bfe_u32 v35, v28, 16, 1
	v_add3_u32 v33, v33, v42, s33
	v_add3_u32 v31, v31, v41, s33
	v_add3_u32 v28, v28, v35, s33
	v_lshrrev_b32_e32 v35, 16, v31
	v_lshrrev_b32_e32 v31, 16, v33
	v_and_or_b32 v31, v34, s11, v31
	v_and_or_b32 v30, v30, s11, v35
	v_cvt_pk_bf16_f32 v29, v29, v32
	ds_read_b64_tr_b16 v[32:33], v128 offset:64512
	ds_read_b64_tr_b16 v[34:35], v129
	v_lshrrev_b32_e32 v28, 16, v28
	v_and_or_b32 v28, v43, s11, v28
	ds_read_b64_tr_b16 v[40:41], v128 offset:64544
	ds_read_b64_tr_b16 v[42:43], v130
	s_waitcnt lgkmcnt(2)
	v_mfma_f32_16x16x32_bf16 v[32:35], v[32:35], v[28:31], v[44:47]
	s_nop 2
	ds_read_b64_tr_b16 v[44:45], v128 offset:64576
	ds_read_b64_tr_b16 v[46:47], v131
	s_waitcnt lgkmcnt(2)
	v_mfma_f32_16x16x32_bf16 v[40:43], v[40:43], v[28:31], v[48:51]
	s_nop 2
	ds_read_b64_tr_b16 v[48:49], v128 offset:64608
	ds_read_b64_tr_b16 v[50:51], v132
	s_waitcnt lgkmcnt(2)
	v_mfma_f32_16x16x32_bf16 v[44:47], v[44:47], v[28:31], v[52:55]
	s_nop 2
	ds_read_b64_tr_b16 v[52:53], v128 offset:64640
	ds_read_b64_tr_b16 v[54:55], v133
	s_waitcnt lgkmcnt(2)
	v_mfma_f32_16x16x32_bf16 v[48:51], v[48:51], v[28:31], v[56:59]
	s_waitcnt lgkmcnt(0)
	v_mfma_f32_16x16x32_bf16 v[18:21], v[52:55], v[28:31], v[18:21]
	ds_read_b64_tr_b16 v[52:53], v128 offset:64672
	ds_read_b64_tr_b16 v[54:55], v134
	ds_read_b64_tr_b16 v[56:57], v128 offset:64704
	ds_read_b64_tr_b16 v[58:59], v135
	s_waitcnt lgkmcnt(0)
	v_mfma_f32_16x16x32_bf16 v[22:25], v[56:59], v[28:31], v[22:25]
	ds_read_b64_tr_b16 v[56:57], v128 offset:64736
	ds_read_b64_tr_b16 v[58:59], v136
	v_mfma_f32_16x16x32_bf16 v[52:55], v[52:55], v[28:31], v[60:63]
	s_waitcnt lgkmcnt(0)
	v_mfma_f32_16x16x32_bf16 v[28:31], v[56:59], v[28:31], v[36:39]
	s_nop 2
	v_rcp_f32_e32 v36, v27
	s_nop 0
	v_fma_f32 v37, -v27, v36, 1.0
	v_fmac_f32_e32 v36, v37, v36
	v_div_scale_f32 v37, vcc, 1.0, v26, 1.0
	v_mul_f32_e32 v38, v37, v36
	v_fma_f32 v39, -v27, v38, v37
	v_fmac_f32_e32 v38, v39, v36
	v_fma_f32 v27, -v27, v38, v37
	v_div_fmas_f32 v27, v27, v36, v38
	v_div_fixup_f32 v36, v27, v26, 1.0
	v_mul_f32_e32 v32, v36, v32
	v_mul_f32_e32 v33, v36, v33
	v_bfe_u32 v37, v32, 16, 1
	v_add3_u32 v32, v32, v37, s33
	v_bfe_u32 v37, v33, 16, 1
	v_lshrrev_b32_e32 v32, 16, v32
	v_add3_u32 v33, v33, v37, s33
	v_and_or_b32 v32, v33, s11, v32
	v_mul_f32_e32 v33, v36, v34
	v_mul_f32_e32 v34, v36, v35
	v_lshlrev_b64 v[26:27], 10, v[122:123]
	v_lshl_add_u64 v[26:27], v[120:121], 0, v[26:27]
	v_cvt_pk_bf16_f32 v33, v33, v34
	global_store_dwordx2 v[26:27], v[32:33], off
	v_mul_f32_e32 v32, v36, v40
	v_mul_f32_e32 v33, v36, v41
	v_cvt_pk_bf16_f32 v32, v32, v33
	v_mul_f32_e32 v33, v36, v42
	v_mul_f32_e32 v34, v36, v43
	v_cvt_pk_bf16_f32 v33, v33, v34
	global_store_dwordx2 v[26:27], v[32:33], off offset:32
	v_mul_f32_e32 v32, v36, v44
	v_mul_f32_e32 v33, v36, v45
	v_cvt_pk_bf16_f32 v32, v32, v33
	v_mul_f32_e32 v33, v36, v46
	v_mul_f32_e32 v34, v36, v47
	v_cvt_pk_bf16_f32 v33, v33, v34
	global_store_dwordx2 v[26:27], v[32:33], off offset:64
	v_mul_f32_e32 v32, v36, v48
	v_mul_f32_e32 v33, v36, v49
	v_cvt_pk_bf16_f32 v32, v32, v33
	v_mul_f32_e32 v33, v36, v50
	v_mul_f32_e32 v34, v36, v51
	v_bfe_u32 v35, v33, 16, 1
	v_add3_u32 v33, v33, v35, s33
	v_bfe_u32 v35, v34, 16, 1
	v_lshrrev_b32_e32 v33, 16, v33
	v_add3_u32 v34, v34, v35, s33
	v_and_or_b32 v33, v34, s11, v33
	v_mul_f32_e32 v18, v36, v18
	global_store_dwordx2 v[26:27], v[32:33], off offset:96
	v_mul_f32_e32 v19, v36, v19
	v_cvt_pk_bf16_f32 v18, v18, v19
	v_mul_f32_e32 v19, v36, v20
	v_mul_f32_e32 v20, v36, v21
	v_cvt_pk_bf16_f32 v19, v19, v20
	global_store_dwordx2 v[26:27], v[18:19], off offset:128
	v_mul_f32_e32 v18, v36, v52
	v_mul_f32_e32 v19, v36, v53
	v_cvt_pk_bf16_f32 v18, v18, v19
	v_mul_f32_e32 v19, v36, v54
	v_mul_f32_e32 v20, v36, v55
	v_cvt_pk_bf16_f32 v19, v19, v20
	global_store_dwordx2 v[26:27], v[18:19], off offset:160
	v_mul_f32_e32 v18, v36, v22
	v_mul_f32_e32 v19, v36, v23
	v_cvt_pk_bf16_f32 v18, v18, v19
	v_mul_f32_e32 v19, v36, v24
	v_mul_f32_e32 v20, v36, v25
	v_cvt_pk_bf16_f32 v19, v19, v20
	global_store_dwordx2 v[26:27], v[18:19], off offset:192
	v_mul_f32_e32 v18, v36, v28
	v_mul_f32_e32 v19, v36, v29
	v_cvt_pk_bf16_f32 v18, v18, v19
	v_mul_f32_e32 v19, v36, v30
	v_mul_f32_e32 v20, v36, v31
	v_cvt_pk_bf16_f32 v19, v19, v20
	global_store_dwordx2 v[26:27], v[18:19], off offset:224
	v_mov_b64_e32 v[32:33], v[8:9]
	v_mov_b64_e32 v[28:29], v[12:13]
	v_mov_b64_e32 v[24:25], v[16:17]
	v_mov_b64_e32 v[20:21], v[4:5]
	v_mov_b64_e32 v[30:31], v[6:7]
	v_mov_b64_e32 v[26:27], v[10:11]
	v_mov_b64_e32 v[22:23], v[14:15]
	v_mov_b64_e32 v[18:19], v[2:3]
	s_cbranch_scc0 .LBB0_494

; #define LAS __attribute__((address_space(3)))
; __device__ __forceinline__ unsigned pk2(float lo, float hi) { return f2bf(lo) | (f2bf(hi) << 16); }
; template <bool PHASE_B>
; __device__ __forceinline__ void lru_item(const Params& p, LAS unsigned char* lds, int ci, int ci_next, int jb, const int tid, v4u (&xvn)[3]) {
;     ...
;     for (int ks = 0; ks < 2; ++ks) { const int cb0 = 32 * ks + 8 * fq;
;         f32x4 s0 = *(const LAS f32x4*)(CB + cb0), s1 = *(const LAS f32x4*)(CB + cb0 + 4);
; #pragma unroll
;         for (int tap = 0; tap < 4; ++tap) { const v4u v = *(const LAS v4u*)(lds + LR_XR + (16 * rt + fr + tap) * 144 + cb0 * 2);
;             const f32x4 w0 = *(const LAS f32x4*)(CW + tap * 64 + cb0), w1 = *(const LAS f32x4*)(CW + tap * 64 + cb0 + 4);
;             s0 += (f32x4){bflo(v.x), bfhi(v.x), bflo(v.y), bfhi(v.y)} * w0; s1 += (f32x4){bflo(v.z), bfhi(v.z), bflo(v.w), bfhi(v.w)} * w1; }
;         v4u o; o.x = pk2(s0[0], s0[1]); o.y = pk2(s0[2], s0[3]); o.z = pk2(s1[0], s1[1]); o.w = pk2(s1[2], s1[3]);
;         af[ks] = __builtin_bit_cast(bf16x8, o); }
.LBB0_541:
	ds_read_b128 v[14:17], v88
	ds_read_b128 v[18:21], v78 offset:56832
	ds_read_b128 v[26:29], v78 offset:56848
	ds_read_b128 v[30:33], v78 offset:55808
	ds_read_b128 v[34:37], v78 offset:55824
	ds_read_b128 v[38:41], v88 offset:144
	s_waitcnt lgkmcnt(5)
	v_lshlrev_b32_e32 v42, 16, v14
	v_and_b32_e32 v43, 0xffff0000, v14
	v_lshlrev_b32_e32 v14, 16, v15
	v_and_b32_e32 v15, 0xffff0000, v15
	s_waitcnt lgkmcnt(2)
	v_pk_fma_f32 v[32:33], v[32:33], v[14:15], v[20:21]
	v_lshlrev_b32_e32 v14, 16, v16
	v_and_b32_e32 v15, 0xffff0000, v16
	v_lshlrev_b32_e32 v16, 16, v17
	v_and_b32_e32 v17, 0xffff0000, v17
	v_pk_fma_f32 v[30:31], v[30:31], v[42:43], v[18:19]
	s_waitcnt lgkmcnt(1)
	v_pk_fma_f32 v[26:27], v[34:35], v[14:15], v[26:27]
	v_pk_fma_f32 v[28:29], v[36:37], v[16:17], v[28:29]
	ds_read_b128 v[14:17], v78 offset:56064
	ds_read_b128 v[18:21], v78 offset:56080
	s_waitcnt lgkmcnt(2)
	v_lshlrev_b32_e32 v34, 16, v38
	v_and_b32_e32 v35, 0xffff0000, v38
	v_lshlrev_b32_e32 v36, 16, v39
	v_and_b32_e32 v37, 0xffff0000, v39
	s_waitcnt lgkmcnt(1)
	v_pk_fma_f32 v[34:35], v[14:15], v[34:35], v[30:31]
	v_lshlrev_b32_e32 v14, 16, v41
	v_and_b32_e32 v15, 0xffff0000, v41
	v_pk_fma_f32 v[36:37], v[16:17], v[36:37], v[32:33]
	s_waitcnt lgkmcnt(0)
	v_pk_fma_f32 v[38:39], v[20:21], v[14:15], v[28:29]
	ds_read_b128 v[14:17], v88 offset:288
	v_lshlrev_b32_e32 v30, 16, v40
	v_and_b32_e32 v31, 0xffff0000, v40
	v_pk_fma_f32 v[40:41], v[18:19], v[30:31], v[26:27]
	ds_read_b128 v[18:21], v78 offset:56320
	ds_read_b128 v[26:29], v78 offset:56336
	ds_read_b128 v[30:33], v88 offset:432
	s_waitcnt lgkmcnt(3)
	v_lshlrev_b32_e32 v42, 16, v14
	v_and_b32_e32 v43, 0xffff0000, v14
	v_lshlrev_b32_e32 v14, 16, v15
	v_and_b32_e32 v15, 0xffff0000, v15
	s_waitcnt lgkmcnt(2)
	v_pk_fma_f32 v[36:37], v[20:21], v[14:15], v[36:37]
	v_lshlrev_b32_e32 v14, 16, v16
	v_and_b32_e32 v15, 0xffff0000, v16
	v_lshlrev_b32_e32 v16, 16, v17
	v_and_b32_e32 v17, 0xffff0000, v17
	v_pk_fma_f32 v[34:35], v[18:19], v[42:43], v[34:35]
	s_waitcnt lgkmcnt(1)
	v_pk_fma_f32 v[26:27], v[26:27], v[14:15], v[40:41]
	v_pk_fma_f32 v[28:29], v[28:29], v[16:17], v[38:39]
	ds_read_b128 v[14:17], v78 offset:56576
	ds_read_b128 v[18:21], v78 offset:56592
	s_waitcnt lgkmcnt(2)
	v_lshlrev_b32_e32 v38, 16, v30
	v_and_b32_e32 v39, 0xffff0000, v30
	v_lshlrev_b32_e32 v30, 16, v31
	s_waitcnt lgkmcnt(1)
	v_pk_fma_f32 v[14:15], v[14:15], v[38:39], v[34:35]
	v_and_b32_e32 v31, 0xffff0000, v31
	v_bfe_u32 v1, v14, 16, 1
	v_add3_u32 v1, v14, v1, s33
	v_bfe_u32 v14, v15, 16, 1
	v_pk_fma_f32 v[16:17], v[16:17], v[30:31], v[36:37]
	v_lshrrev_b32_e32 v1, 16, v1
	v_add3_u32 v14, v15, v14, s33
	v_and_or_b32 v14, v14, s11, v1
	v_lshlrev_b32_e32 v30, 16, v32
	v_and_b32_e32 v31, 0xffff0000, v32
	s_waitcnt lgkmcnt(0)
	v_pk_fma_f32 v[18:19], v[18:19], v[30:31], v[26:27]
	v_cvt_pk_bf16_f32 v15, v16, v17
	v_lshlrev_b32_e32 v32, 16, v33
	v_and_b32_e32 v33, 0xffff0000, v33
	v_pk_fma_f32 v[20:21], v[20:21], v[32:33], v[28:29]
	v_cvt_pk_bf16_f32 v16, v18, v19
	v_bfe_u32 v1, v20, 16, 1
	v_bfe_u32 v17, v21, 16, 1
	v_add3_u32 v1, v20, v1, s33
	v_add3_u32 v17, v21, v17, s33
	ds_read_b128 v[18:21], v89
	ds_read_b128 v[26:29], v78 offset:56960
	ds_read_b128 v[30:33], v78 offset:56976
	ds_read_b128 v[34:37], v78 offset:55936
	ds_read_b128 v[38:41], v78 offset:55952
	ds_read_b128 v[42:45], v89 offset:144
	s_waitcnt lgkmcnt(5)
	v_lshlrev_b32_e32 v46, 16, v18
	v_and_b32_e32 v47, 0xffff0000, v18
	v_lshlrev_b32_e32 v18, 16, v19
	v_and_b32_e32 v19, 0xffff0000, v19
	s_waitcnt lgkmcnt(2)
	v_pk_fma_f32 v[36:37], v[36:37], v[18:19], v[28:29]
	v_lshlrev_b32_e32 v18, 16, v20
	v_and_b32_e32 v19, 0xffff0000, v20
	v_lshlrev_b32_e32 v20, 16, v21
	v_and_b32_e32 v21, 0xffff0000, v21
	v_pk_fma_f32 v[34:35], v[34:35], v[46:47], v[26:27]
	s_waitcnt lgkmcnt(1)
	v_pk_fma_f32 v[30:31], v[38:39], v[18:19], v[30:31]
	v_pk_fma_f32 v[32:33], v[40:41], v[20:21], v[32:33]
	ds_read_b128 v[18:21], v78 offset:56192
	ds_read_b128 v[26:29], v78 offset:56208
	s_waitcnt lgkmcnt(2)
	v_lshlrev_b32_e32 v38, 16, v42
	v_and_b32_e32 v39, 0xffff0000, v42
	v_lshlrev_b32_e32 v40, 16, v43
	v_and_b32_e32 v41, 0xffff0000, v43
	s_waitcnt lgkmcnt(1)
	v_pk_fma_f32 v[38:39], v[18:19], v[38:39], v[34:35]
	v_lshlrev_b32_e32 v18, 16, v45
	v_and_b32_e32 v19, 0xffff0000, v45
	v_pk_fma_f32 v[40:41], v[20:21], v[40:41], v[36:37]
	s_waitcnt lgkmcnt(0)
	v_pk_fma_f32 v[42:43], v[28:29], v[18:19], v[32:33]
	ds_read_b128 v[18:21], v89 offset:288
	v_lshlrev_b32_e32 v34, 16, v44
	v_and_b32_e32 v35, 0xffff0000, v44
	v_pk_fma_f32 v[44:45], v[26:27], v[34:35], v[30:31]
	ds_read_b128 v[26:29], v78 offset:56448
	ds_read_b128 v[30:33], v78 offset:56464
	ds_read_b128 v[34:37], v89 offset:432
	s_waitcnt lgkmcnt(3)
	v_lshlrev_b32_e32 v46, 16, v18
	v_and_b32_e32 v47, 0xffff0000, v18
	v_lshlrev_b32_e32 v18, 16, v19
	v_and_b32_e32 v19, 0xffff0000, v19
	s_waitcnt lgkmcnt(2)
	v_pk_fma_f32 v[40:41], v[28:29], v[18:19], v[40:41]
	v_lshlrev_b32_e32 v18, 16, v20
	v_and_b32_e32 v19, 0xffff0000, v20
	v_lshlrev_b32_e32 v20, 16, v21
	v_and_b32_e32 v21, 0xffff0000, v21
	v_pk_fma_f32 v[38:39], v[26:27], v[46:47], v[38:39]
	s_waitcnt lgkmcnt(1)
	v_pk_fma_f32 v[30:31], v[30:31], v[18:19], v[44:45]
	v_pk_fma_f32 v[32:33], v[32:33], v[20:21], v[42:43]
	ds_read_b128 v[18:21], v78 offset:56704
	ds_read_b128 v[26:29], v78 offset:56720
	s_waitcnt lgkmcnt(2)
	v_lshlrev_b32_e32 v42, 16, v34
	v_and_b32_e32 v43, 0xffff0000, v34
	v_lshlrev_b32_e32 v34, 16, v35
	s_waitcnt lgkmcnt(1)
; template <bool PHASE_B>
; __device__ __forceinline__ void lru_item(const Params& p, LAS unsigned char* lds, int ci, int ci_next, int jb, const int tid, v4u (&xvn)[3]) {
;     ...
;     for (int ks = 0; ks < 2; ++ks) { const int cb0 = 32 * ks + 8 * fq;
;         f32x4 s0 = *(const LAS f32x4*)(CB + cb0), s1 = *(const LAS f32x4*)(CB + cb0 + 4);
; #pragma unroll
;         for (int tap = 0; tap < 4; ++tap) { const v4u v = *(const LAS v4u*)(lds + LR_XR + (16 * rt + fr + tap) * 144 + cb0 * 2);
;             const f32x4 w0 = *(const LAS f32x4*)(CW + tap * 64 + cb0), w1 = *(const LAS f32x4*)(CW + tap * 64 + cb0 + 4);
;             s0 += (f32x4){bflo(v.x), bfhi(v.x), bflo(v.y), bfhi(v.y)} * w0; s1 += (f32x4){bflo(v.z), bfhi(v.z), bflo(v.w), bfhi(v.w)} * w1; }
;         v4u o; o.x = pk2(s0[0], s0[1]); o.y = pk2(s0[2], s0[3]); o.z = pk2(s1[0], s1[1]); o.w = pk2(s1[2], s1[3]);
;         af[ks] = __builtin_bit_cast(bf16x8, o); }
;     float xc[4][4];
; #pragma unroll
;     for (int ct = 0; ct < 4; ++ct) { const int ch = 16 * ct + fr; float xr7[7];
; #pragma unroll
;         for (int j = 0; j < 7; ++j) xr7[j] = __builtin_bit_cast(float, (unsigned)(*(const LAS bf16*)(lds + LR_XR + (16 * rt + 4 * fq + j) * 144 + ch * 2)) << 16);
;         const float w0 = CW[ch], w1 = CW[64 + ch], w2 = CW[128 + ch], w3 = CW[192 + ch], b = CB[ch];
; #pragma unroll
;         for (int e = 0; e < 4; ++e) xc[ct][e] = b + xr7[e] * w0 + xr7[e + 1] * w1 + xr7[e + 2] * w2 + xr7[e + 3] * w3; }
;     float av[2][4][4], uv[2][4][4], pA[2][4], pH[2][4];
; #pragma unroll
;     for (int dir = 0; dir < 2; ++dir) {
; #pragma unroll
;         for (int ct = 0; ct < 4; ++ct) {
;             f32x4 ga = (f32x4){0.f, 0.f, 0.f, 0.f}, gx = (f32x4){0.f, 0.f, 0.f, 0.f};
; #pragma unroll
;             for (int ks = 0; ks < 2; ++ks) {
;                 const bf16x8 wa = *(const LAS bf16x8*)(lds + LR_WG + ((dir * 2 + 0) * 64 + 16 * ct + fr) * 144 + (32 * ks + 8 * fq) * 2);
;                 const bf16x8 wx = *(const LAS bf16x8*)(lds + LR_WG + ((dir * 2 + 1) * 64 + 16 * ct + fr) * 144 + (32 * ks + 8 * fq) * 2);
;                 ga = MFMA16(af[ks], wa, ga); gx = MFMA16(af[ks], wx, gx); }
;             const int ch = 16 * ct + fr; const float bav = GC[(dir * 3 + 0) * 64 + ch], bxv = GC[(dir * 3 + 1) * 64 + ch], c8 = GC[(dir * 3 + 2) * 64 + ch];
;             float Al = 1.f, Hl = 0.f;
; #pragma unroll
	v_pk_fma_f32 v[18:19], v[18:19], v[42:43], v[38:39]
	v_and_b32_e32 v35, 0xffff0000, v35
	v_pk_fma_f32 v[20:21], v[20:21], v[34:35], v[40:41]
	v_cvt_pk_bf16_f32 v18, v18, v19
	v_bfe_u32 v19, v20, 16, 1
	v_lshlrev_b32_e32 v34, 16, v36
	v_and_b32_e32 v35, 0xffff0000, v36
	v_lshlrev_b32_e32 v36, 16, v37
	v_and_b32_e32 v37, 0xffff0000, v37
	v_add3_u32 v19, v20, v19, s33
	v_bfe_u32 v20, v21, 16, 1
	s_waitcnt lgkmcnt(0)
	v_pk_fma_f32 v[28:29], v[28:29], v[36:37], v[32:33]
	v_pk_fma_f32 v[26:27], v[26:27], v[34:35], v[30:31]
	v_lshrrev_b32_e32 v19, 16, v19
	v_add3_u32 v20, v21, v20, s33
	v_and_or_b32 v19, v20, s11, v19
	v_bfe_u32 v20, v26, 16, 1
	v_bfe_u32 v23, v29, 16, 1
	v_add3_u32 v20, v26, v20, s33
	v_bfe_u32 v21, v27, 16, 1
	v_add3_u32 v32, v29, v23, s33
	v_add_u32_e32 v23, v80, v81
	v_add_u32_e32 v30, 0xd800, v82
	v_add_u32_e32 v58, 0xdc00, v82
	v_lshrrev_b32_e32 v20, 16, v20
	v_add3_u32 v21, v27, v21, s33
	ds_read_u16 v49, v23
	ds_read_u16 v51, v23 offset:144
	ds_read_u16 v60, v23 offset:288
	ds_read_u16 v26, v23 offset:864
	ds_read_u16 v70, v23 offset:432
	ds_read_u16 v109, v23 offset:576
	ds_read_u16 v116, v90
	ds_read_u16 v110, v23 offset:720
	ds_read2_b32 v[46:47], v30 offset0:128 offset1:144
	ds_read2_b32 v[40:41], v30 offset0:192 offset1:208
	ds_read2_b32 v[52:53], v58 offset1:16
	ds_read2_b32 v[44:45], v58 offset0:64 offset1:80
	ds_read2_b32 v[34:35], v58 offset0:128 offset1:144
	ds_read_u16 v117, v90 offset:144
	ds_read_u16 v118, v90 offset:288
	ds_read_u16 v119, v90 offset:432
	ds_read_u16 v23, v90 offset:864
	ds_read_u16 v120, v90 offset:576
	ds_read_u16 v123, v91
	ds_read_u16 v122, v91 offset:144
	ds_read_u16 v121, v90 offset:720
	v_and_or_b32 v20, v21, s11, v20
	v_bfe_u32 v21, v28, 16, 1
	s_waitcnt lgkmcnt(4)
	v_lshlrev_b32_e32 v50, 16, v23
	v_add_u32_e32 v23, v85, v79
	v_add3_u32 v21, v28, v21, s33
	v_lshlrev_b32_e32 v48, 16, v26
	ds_read_u16 v124, v91 offset:288
	ds_read_u16 v125, v91 offset:432
	ds_read_u16 v126, v91 offset:576
	ds_read_u16 v127, v91 offset:720
	ds_read_u16 v31, v91 offset:864
	ds_read_u16 v43, v92
	ds_read_u16 v61, v92 offset:144
	ds_read_u16 v103, v92 offset:288
	ds_read_b128 v[26:29], v23 offset:18944
	v_perm_b32 v17, v17, v1, s65
	ds_read2_b32 v[38:39], v30 offset0:160 offset1:176
	ds_read_b128 v[54:57], v23 offset:28160
	ds_read_b128 v[62:65], v23 offset:19008
	v_perm_b32 v21, v32, v21, s65
	s_waitcnt lgkmcnt(3)
	v_mfma_f32_16x16x32_bf16 v[66:69], v[14:17], v[26:29], 0
	v_lshlrev_b32_e32 v42, 16, v31
	ds_read2_b32 v[30:31], v30 offset0:224 offset1:240
	ds_read_b128 v[104:107], v23 offset:28224
	ds_read2_b32 v[36:37], v58 offset0:32 offset1:48
	ds_read2_b32 v[32:33], v58 offset0:96 offset1:112
	ds_read2_b32 v[26:27], v58 offset0:160 offset1:176
	s_waitcnt lgkmcnt(6)
	v_mfma_f32_16x16x32_bf16 v[54:57], v[14:17], v[54:57], 0
	v_lshlrev_b32_e32 v71, 16, v49
	v_lshlrev_b32_e32 v122, 16, v122
	v_lshlrev_b32_e32 v123, 16, v123
	s_waitcnt lgkmcnt(5)
	v_mfma_f32_16x16x32_bf16 v[62:65], v[18:21], v[62:65], v[66:69]
	s_nop 2
	ds_read_b32 v66, v93 offset:57088
	ds_read_u16 v128, v92 offset:432
	ds_read_u16 v102, v92 offset:576
	ds_read_u16 v29, v92 offset:720
	ds_read_u16 v1, v92 offset:864
	v_mov_b32_e32 v67, v46
	s_waitcnt lgkmcnt(4)
	v_add_f32_e32 v28, v62, v66
	v_mfma_f32_16x16x32_bf16 v[56:59], v[18:21], v[104:107], v[54:57]
	s_nop 2
	ds_read_b32 v54, v93 offset:57344
	ds_read_b32 v55, v93 offset:57600
	v_mul_f32_e32 v28, 0xbfb8aa3b, v28
	v_exp_f32_e32 v28, v28
	s_waitcnt lgkmcnt(1)
	v_add_f32_e32 v56, v56, v54
	v_mul_f32_e32 v56, 0xbfb8aa3b, v56
	v_exp_f32_e32 v56, v56
	v_add_f32_e32 v28, 1.0, v28
	v_rcp_f32_e32 v62, v28
	v_lshlrev_b32_e32 v28, 16, v1
	v_add_f32_e32 v1, 1.0, v56
	v_rcp_f32_e32 v129, v1
	s_waitcnt lgkmcnt(0)
	v_mul_f32_e32 v1, v62, v55
	v_mul_f32_e32 v1, 0xbfb8aa3b, v1
	v_exp_f32_e32 v56, v1
	v_add_f32_e32 v1, v63, v66
	v_mul_f32_e32 v1, 0xbfb8aa3b, v1
	v_exp_f32_e32 v1, v1
	v_add_f32_e32 v57, v57, v54
	v_sub_f32_e32 v62, 1.0, v56
	v_add_f32_e32 v63, 1.0, v56
	v_add_f32_e32 v1, 1.0, v1
	v_rcp_f32_e32 v1, v1
	v_mul_f32_e32 v57, 0xbfb8aa3b, v57
	v_mul_f32_e32 v62, v62, v63
	v_exp_f32_e32 v57, v57
	v_mul_f32_e32 v1, v1, v55
	v_mul_f32_e32 v1, 0xbfb8aa3b, v1
	v_exp_f32_e32 v130, v1
	v_sqrt_f32_e32 v1, v62
	v_add_f32_e32 v62, v64, v66
	v_mul_f32_e32 v62, 0xbfb8aa3b, v62
	v_exp_f32_e32 v62, v62
	v_add_f32_e32 v57, 1.0, v57
	v_rcp_f32_e32 v131, v57
	v_sub_f32_e32 v57, 1.0, v130
	v_add_f32_e32 v63, 1.0, v130
	v_mul_f32_e32 v57, v57, v63
	v_sqrt_f32_e32 v63, v57
	v_add_f32_e32 v57, 1.0, v62
	v_rcp_f32_e32 v57, v57
	v_add_f32_e32 v58, v58, v54
	v_mul_f32_e32 v58, 0xbfb8aa3b, v58
	v_exp_f32_e32 v58, v58
	v_mul_f32_e32 v57, v57, v55
	v_mul_f32_e32 v57, 0xbfb8aa3b, v57
	v_exp_f32_e32 v105, v57
	v_add_f32_e32 v62, v65, v66
	v_mul_f32_e32 v62, 0xbfb8aa3b, v62
	v_exp_f32_e32 v62, v62
	v_add_f32_e32 v58, 1.0, v58
	v_rcp_f32_e32 v132, v58
	v_sub_f32_e32 v58, 1.0, v105
	v_add_f32_e32 v64, 1.0, v105
	v_mul_f32_e32 v58, v58, v64
	v_sqrt_f32_e32 v65, v58
	v_add_f32_e32 v58, 1.0, v62
	v_rcp_f32_e32 v58, v58
	v_add_f32_e32 v54, v59, v54
	v_mul_f32_e32 v54, 0xbfb8aa3b, v54
	v_exp_f32_e32 v54, v54
	v_mul_f32_e32 v55, v58, v55
	v_mul_f32_e32 v55, 0xbfb8aa3b, v55
	v_exp_f32_e32 v59, v55
	v_add_f32_e32 v54, 1.0, v54
	v_rcp_f32_e32 v58, v54
	v_mov_b32_e32 v66, v40
	v_sub_f32_e32 v54, 1.0, v59
	v_add_f32_e32 v55, 1.0, v59
	v_mul_f32_e32 v54, v54, v55
	v_sqrt_f32_e32 v133, v54
	v_lshlrev_b32_e32 v55, 16, v60
	v_lshlrev_b32_e32 v54, 16, v70
	v_lshlrev_b32_e32 v70, 16, v51
	v_pk_mul_f32 v[106:107], v[66:67], v[70:71]
	v_pk_mov_b32 v[70:71], v[54:55], v[70:71] op_sel:[1,0]
	v_pk_mul_f32 v[68:69], v[66:67], v[54:55]
; #define LAS __attribute__((address_space(3)))
; #define MFMA16(a, b, c) __builtin_amdgcn_mfma_f32_16x16x32_bf16(a, b, c, 0, 0, 0)
; template <bool PHASE_B>
; __device__ __forceinline__ void lru_item(const Params& p, LAS unsigned char* lds, int ci, int ci_next, int jb, const int tid, v4u (&xvn)[3]) {
;     ...
;             for (int ks = 0; ks < 2; ++ks) {
;                 const bf16x8 wa = *(const LAS bf16x8*)(lds + LR_WG + ((dir * 2 + 0) * 64 + 16 * ct + fr) * 144 + (32 * ks + 8 * fq) * 2);
;                 const bf16x8 wx = *(const LAS bf16x8*)(lds + LR_WG + ((dir * 2 + 1) * 64 + 16 * ct + fr) * 144 + (32 * ks + 8 * fq) * 2);
;                 ga = MFMA16(af[ks], wa, ga); gx = MFMA16(af[ks], wx, gx); }
;             const int ch = 16 * ct + fr; const float bav = GC[(dir * 3 + 0) * 64 + ch], bxv = GC[(dir * 3 + 1) * 64 + ch], c8 = GC[(dir * 3 + 2) * 64 + ch];
;             float Al = 1.f, Hl = 0.f;
; #pragma unroll
;             for (int ee = 0; ee < 4; ++ee) { const int e = dir ? 3 - ee : ee;
;                 const float r = __builtin_amdgcn_rcpf(1.f + __expf(-(ga[e] + bav))), ig = __builtin_amdgcn_rcpf(1.f + __expf(-(gx[e] + bxv)));
;                 const float la = -c8 * r; const float a = __expf(la); const float u = __builtin_amdgcn_sqrtf((1.f - a) * (1.f + a)) * (ig * xc[ct][e]);
;                 av[dir][ct][e] = a; uv[dir][ct][e] = u; Hl = a * Hl + u; Al *= a; }
;             const int o = dir ? 3 - fq : fq; const bool odd = (o & 1) != 0, hi2 = (o & 2) != 0;
;             const float A1 = __shfl_xor(Al, 16), H1 = __shfl_xor(Hl, 16);
;             const float pxA = odd ? A1 : 1.f, pxH = odd ? H1 : 0.f;
;             const float gA = Al * A1, gH = odd ? (Al * H1 + Hl) : (A1 * Hl + H1);
;             const float A2 = __shfl_xor(gA, 32), H2 = __shfl_xor(gH, 32);
;             const float PA = hi2 ? pxA * A2 : pxA, PH = hi2 ? (pxA * H2 + pxH) : pxH;
;             const float TA = gA * A2, TH = hi2 ? (gA * H2 + gH) : (A2 * gH + H2);
;             pA[dir][ct] = PA; pH[dir][ct] = PH;
;             ((LAS f32x2*)(lds + LR_SEG))[(dir * 8 + rt) * 64 + ch] = (f32x2){TA, TH};
	v_pk_mul_f32 v[66:67], v[66:67], v[70:71]
	v_add_f32_e32 v49, v107, v34
	v_add_f32_e32 v51, v67, v34
	v_mov_b32_e32 v62, v40
	v_add_f32_e32 v40, v69, v34
	v_fma_f32 v108, v46, v54, v34
	v_add_f32_e32 v34, v106, v49
	v_add_f32_e32 v46, v66, v51
	v_lshlrev_b32_e32 v107, 16, v109
	v_lshlrev_b32_e32 v106, 16, v110
	v_mov_b32_e32 v66, v44
	v_mov_b32_e32 v67, v52
	v_pk_mul_f32 v[110:111], v[66:67], v[54:55]
	v_pk_mov_b32 v[54:55], v[106:107], v[54:55] op_sel:[1,0]
	v_add_f32_e32 v40, v68, v40
	v_pk_mul_f32 v[112:113], v[66:67], v[54:55]
	v_pk_mul_f32 v[114:115], v[66:67], v[106:107]
	v_add_f32_e32 v49, v113, v46
	v_lshlrev_b32_e32 v67, 16, v118
	v_lshlrev_b32_e32 v66, 16, v119
	v_mov_b32_e32 v46, v41
	v_lshlrev_b32_e32 v68, 16, v117
	v_lshlrev_b32_e32 v69, 16, v116
	v_pk_mul_f32 v[70:71], v[46:47], v[68:69]
	v_pk_mov_b32 v[68:69], v[66:67], v[68:69] op_sel:[1,0]
	v_mul_f32_e32 v57, v56, v130
	v_pk_mul_f32 v[68:69], v[46:47], v[68:69]
	v_mul_f32_e32 v57, v105, v57
	v_mul_f32_e32 v104, v52, v106
	v_pk_mul_f32 v[54:55], v[46:47], v[66:67]
	v_add_f32_e32 v52, v71, v35
	v_add_f32_e32 v46, v69, v35
	v_mov_b32_e32 v64, v44
	v_mul_f32_e32 v44, v59, v57
	v_add_f32_e32 v113, v115, v40
	v_add_f32_e32 v40, v55, v35
	v_fmac_f32_e32 v35, v47, v66
	v_add_f32_e32 v55, v70, v52
	v_add_f32_e32 v57, v68, v46
	v_lshlrev_b32_e32 v47, 16, v120
	v_lshlrev_b32_e32 v46, 16, v121
	v_mov_b32_e32 v52, v45
	v_add_f32_e32 v34, v111, v34
	v_pk_mul_f32 v[70:71], v[52:53], v[66:67]
	v_pk_mov_b32 v[66:67], v[46:47], v[66:67] op_sel:[1,0]
	v_add_f32_e32 v34, v110, v34
	v_pk_mul_f32 v[68:69], v[52:53], v[66:67]
	v_add_f32_e32 v40, v54, v40
	v_add_f32_e32 v69, v69, v57
	v_mul_f32_e32 v57, v34, v129
	v_mul_f32_e32 v54, v53, v46
	v_pk_mul_f32 v[66:67], v[52:53], v[46:47]
	v_pk_mul_f32 v[52:53], v[56:57], v[0:1]
	v_add_f32_e32 v67, v67, v40
	v_add_f32_e32 v1, v52, v53
	v_add_f32_e32 v40, v112, v49
	v_mul_f32_e32 v109, v130, v1
	v_mul_f32_e32 v53, v40, v131
	v_mov_b32_e32 v52, v107
	v_pk_fma_f32 v[52:53], v[62:63], v[52:53], v[108:109]
	v_add_f32_e32 v46, v114, v113
	v_pk_add_f32 v[56:57], v[104:105], v[52:53]
	v_pk_mul_f32 v[52:53], v[104:105], v[52:53]
	v_mul_f32_e32 v49, v46, v132
	v_mov_b32_e32 v57, v53
	v_pk_fma_f32 v[52:53], v[64:65], v[48:49], v[56:57]
	ds_bpermute_b32 v51, v83, v44
	v_pk_mul_f32 v[48:49], v[52:53], v[58:59]
	v_lshlrev_b32_e32 v121, 16, v124
	v_fmac_f32_e32 v49, v48, v133
	ds_bpermute_b32 v1, v83, v49
	s_waitcnt lgkmcnt(1)
	v_mul_f32_e32 v60, v44, v51
	ds_bpermute_b32 v111, v84, v60
	v_lshlrev_b32_e32 v120, 16, v125
	v_mov_b32_e32 v116, v30
	s_waitcnt lgkmcnt(1)
	v_fma_f32 v44, v44, v1, v49
	v_fmac_f32_e32 v1, v49, v51
	v_cndmask_b32_e64 v1, v44, v1, s[42:43]
	ds_bpermute_b32 v44, v84, v1
	v_mov_b32_e32 v117, v38
	v_pk_mul_f32 v[58:59], v[116:117], v[122:123]
	v_pk_mov_b32 v[56:57], v[120:121], v[122:123] op_sel:[1,0]
	v_pk_mul_f32 v[118:119], v[116:117], v[120:121]
	v_add_f32_e32 v48, v59, v26
	v_pk_mul_f32 v[62:63], v[116:117], v[56:57]
	v_add_f32_e32 v71, v71, v55
	v_add_f32_e32 v55, v119, v26
	v_add_f32_e32 v49, v63, v26
	v_fma_f32 v56, v38, v120, v26
	v_add_f32_e32 v26, v58, v48
	s_waitcnt lgkmcnt(0)
	v_fma_f32 v48, v60, v44, v1
	v_fmac_f32_e32 v44, v1, v111
	v_mul_f32_e32 v106, v60, v111
	v_cndmask_b32_e64 v107, v48, v44, s[44:45]
	ds_write_b64 v86, v[106:107] offset:58624
	v_add_f32_e32 v38, v62, v49
	ds_read_b128 v[62:65], v23 offset:21248
	ds_read_b128 v[104:107], v23 offset:30464
	ds_read_b128 v[108:111], v23 offset:21312
	s_waitcnt lgkmcnt(2)
	v_mfma_f32_16x16x32_bf16 v[112:115], v[14:17], v[62:65], 0
	v_mov_b32_e32 v122, v32
	v_mov_b32_e32 v123, v36
	v_lshlrev_b32_e32 v58, 16, v127
	v_pk_mul_f32 v[62:63], v[122:123], v[120:121]
	v_add_f32_e32 v53, v118, v55
	ds_read_b128 v[116:119], v23 offset:30528
	v_mul_f32_e32 v60, v36, v58
	v_add_f32_e32 v36, v63, v26
	ds_read_b32 v26, v93 offset:57152
	s_waitcnt lgkmcnt(2)
	v_mfma_f32_16x16x32_bf16 v[108:111], v[18:21], v[108:111], v[112:115]
	ds_read_b32 v51, v93 offset:57408
	ds_read_b32 v57, v93 offset:57664
	v_lshlrev_b32_e32 v59, 16, v126
	v_pk_mov_b32 v[48:49], v[58:59], v[120:121] op_sel:[1,0]
	v_mfma_f32_16x16x32_bf16 v[104:107], v[14:17], v[104:107], 0
	s_waitcnt lgkmcnt(2)
	s_nop 1
	v_add_f32_e32 v1, v108, v26
	v_mul_f32_e32 v1, 0xbfb8aa3b, v1
	v_exp_f32_e32 v1, v1
	v_mfma_f32_16x16x32_bf16 v[104:107], v[18:21], v[116:119], v[104:107]
	v_mul_f32_e64 v64, v122, v48
	v_mul_f32_e64 v65, v123, v49
	v_lshlrev_b32_e32 v117, 16, v103
	v_add_f32_e32 v1, 1.0, v1
	v_rcp_f32_e32 v1, v1
	v_lshlrev_b32_e32 v116, 16, v128
	s_waitcnt lgkmcnt(1)
	s_nop 0
	v_add_f32_e32 v44, v104, v51
	v_mul_f32_e32 v44, 0xbfb8aa3b, v44
	v_exp_f32_e32 v44, v44
	s_waitcnt lgkmcnt(0)
; #define LAS __attribute__((address_space(3)))
; #define MFMA16(a, b, c) __builtin_amdgcn_mfma_f32_16x16x32_bf16(a, b, c, 0, 0, 0)
; template <bool PHASE_B>
; __device__ __forceinline__ void lru_item(const Params& p, LAS unsigned char* lds, int ci, int ci_next, int jb, const int tid, v4u (&xvn)[3]) {
;     ...
;             for (int ks = 0; ks < 2; ++ks) {
;                 const bf16x8 wa = *(const LAS bf16x8*)(lds + LR_WG + ((dir * 2 + 0) * 64 + 16 * ct + fr) * 144 + (32 * ks + 8 * fq) * 2);
;                 const bf16x8 wx = *(const LAS bf16x8*)(lds + LR_WG + ((dir * 2 + 1) * 64 + 16 * ct + fr) * 144 + (32 * ks + 8 * fq) * 2);
;                 ga = MFMA16(af[ks], wa, ga); gx = MFMA16(af[ks], wx, gx); }
;             const int ch = 16 * ct + fr; const float bav = GC[(dir * 3 + 0) * 64 + ch], bxv = GC[(dir * 3 + 1) * 64 + ch], c8 = GC[(dir * 3 + 2) * 64 + ch];
;             float Al = 1.f, Hl = 0.f;
; #pragma unroll
;             for (int ee = 0; ee < 4; ++ee) { const int e = dir ? 3 - ee : ee;
;                 const float r = __builtin_amdgcn_rcpf(1.f + __expf(-(ga[e] + bav))), ig = __builtin_amdgcn_rcpf(1.f + __expf(-(gx[e] + bxv)));
;                 const float la = -c8 * r; const float a = __expf(la); const float u = __builtin_amdgcn_sqrtf((1.f - a) * (1.f + a)) * (ig * xc[ct][e]);
;                 av[dir][ct][e] = a; uv[dir][ct][e] = u; Hl = a * Hl + u; Al *= a; }
;             const int o = dir ? 3 - fq : fq; const bool odd = (o & 1) != 0, hi2 = (o & 2) != 0;
;             const float A1 = __shfl_xor(Al, 16), H1 = __shfl_xor(Hl, 16);
;             const float pxA = odd ? A1 : 1.f, pxH = odd ? H1 : 0.f;
;             const float gA = Al * A1, gH = odd ? (Al * H1 + Hl) : (A1 * Hl + H1);
;             const float A2 = __shfl_xor(gA, 32), H2 = __shfl_xor(gH, 32);
;             const float PA = hi2 ? pxA * A2 : pxA, PH = hi2 ? (pxA * H2 + pxH) : pxH;
;             const float TA = gA * A2, TH = hi2 ? (gA * H2 + gH) : (A2 * gH + H2);
;             pA[dir][ct] = PA; pH[dir][ct] = PH;
;             ((LAS f32x2*)(lds + LR_SEG))[(dir * 8 + rt) * 64 + ch] = (f32x2){TA, TH};
	v_mul_f32_e32 v1, v1, v57
	v_mul_f32_e32 v1, 0xbfb8aa3b, v1
	v_add_f32_e32 v44, 1.0, v44
	v_rcp_f32_e32 v63, v44
	v_exp_f32_e32 v44, v1
	v_add_f32_e32 v1, v109, v26
	v_mul_f32_e32 v1, 0xbfb8aa3b, v1
	v_exp_f32_e32 v1, v1
	v_sub_f32_e32 v48, 1.0, v44
	v_add_f32_e32 v49, 1.0, v44
	v_mul_f32_e32 v48, v48, v49
	v_add_f32_e32 v1, 1.0, v1
	v_rcp_f32_e32 v1, v1
	v_add_f32_e32 v49, v105, v51
	v_mul_f32_e32 v49, 0xbfb8aa3b, v49
	v_exp_f32_e32 v49, v49
	v_mul_f32_e32 v1, v1, v57
	v_mul_f32_e32 v1, 0xbfb8aa3b, v1
	v_exp_f32_e32 v108, v1
	v_sqrt_f32_e32 v1, v48
	v_add_f32_e32 v48, 1.0, v49
	v_add_f32_e32 v49, v110, v26
	v_mul_f32_e32 v49, 0xbfb8aa3b, v49
	v_add_f32_e32 v26, v111, v26
	v_exp_f32_e32 v55, v49
	v_mul_f32_e32 v26, 0xbfb8aa3b, v26
	v_exp_f32_e32 v26, v26
	v_rcp_f32_e32 v109, v48
	v_sub_f32_e32 v48, 1.0, v108
	v_add_f32_e32 v49, 1.0, v108
	v_mul_f32_e32 v48, v48, v49
	v_sqrt_f32_e32 v49, v48
	v_add_f32_e32 v48, 1.0, v55
	v_rcp_f32_e32 v48, v48
	v_add_f32_e32 v26, 1.0, v26
	v_rcp_f32_e32 v26, v26
	v_add_f32_e32 v55, v106, v51
	v_mul_f32_e32 v48, v48, v57
	v_add_f32_e32 v51, v107, v51
	v_mul_f32_e32 v55, 0xbfb8aa3b, v55
	v_mul_f32_e32 v48, 0xbfb8aa3b, v48
	v_mul_f32_e32 v51, 0xbfb8aa3b, v51
	v_mul_f32_e32 v26, v26, v57
	v_exp_f32_e32 v104, v55
	v_exp_f32_e32 v55, v48
	v_exp_f32_e32 v51, v51
	v_mul_f32_e32 v26, 0xbfb8aa3b, v26
	v_exp_f32_e32 v107, v26
	v_mul_f32_e32 v48, v44, v108
	v_mul_f32_e32 v26, v55, v48
	v_add_f32_e32 v48, 1.0, v51
	v_add_f32_e32 v104, 1.0, v104
	v_rcp_f32_e32 v106, v48
	v_sub_f32_e32 v48, 1.0, v107
	v_add_f32_e32 v51, 1.0, v107
	v_rcp_f32_e32 v110, v104
	v_sub_f32_e32 v104, 1.0, v55
	v_add_f32_e32 v105, 1.0, v55
	v_mul_f32_e32 v48, v48, v51
	v_mul_f32_e32 v104, v104, v105
	v_sqrt_f32_e32 v57, v48
	v_mov_b32_e32 v48, v41
	v_mul_f32_e32 v41, v107, v26
	v_add_f32_e32 v26, v70, v71
	v_sqrt_f32_e32 v105, v104
	v_mov_b32_e32 v104, v45
	v_mul_f32_e32 v45, v26, v63
	v_pk_mul_f32 v[44:45], v[44:45], v[0:1]
	v_mov_b32_e32 v70, v35
	v_add_f32_e32 v1, v44, v45
	v_add_f32_e32 v44, v68, v69
	v_mul_f32_e32 v71, v108, v1
	v_mul_f32_e32 v69, v44, v109
	v_mov_b32_e32 v68, v47
	v_pk_fma_f32 v[48:49], v[48:49], v[68:69], v[70:71]
	ds_bpermute_b32 v111, v83, v41
	v_pk_add_f32 v[68:69], v[54:55], v[48:49]
	v_pk_mul_f32 v[48:49], v[54:55], v[48:49]
	v_add_f32_e32 v35, v65, v38
	v_add_f32_e32 v48, v66, v67
	v_mov_b32_e32 v69, v49
	v_mul_f32_e32 v51, v48, v110
	v_pk_fma_f32 v[54:55], v[104:105], v[50:51], v[68:69]
	s_waitcnt lgkmcnt(0)
	v_mul_f32_e32 v38, v41, v111
	v_pk_mul_f32 v[50:51], v[54:55], v[106:107]
	ds_bpermute_b32 v45, v84, v38
	v_fmac_f32_e32 v51, v50, v57
	ds_bpermute_b32 v1, v83, v51
	v_pk_mul_f32 v[70:71], v[122:123], v[58:59]
	s_waitcnt lgkmcnt(1)
	v_mul_f32_e32 v50, v38, v45
	v_add_f32_e32 v47, v71, v53
	s_waitcnt lgkmcnt(0)
	v_fma_f32 v41, v41, v1, v51
	v_fmac_f32_e32 v1, v51, v111
	v_cndmask_b32_e64 v1, v41, v1, s[42:43]
	ds_bpermute_b32 v41, v84, v1
	s_waitcnt lgkmcnt(0)
	v_fma_f32 v38, v38, v41, v1
	v_fmac_f32_e32 v41, v1, v45
	v_cndmask_b32_e64 v51, v38, v41, s[44:45]
	ds_write_b64 v86, v[50:51] offset:58752
	ds_read_b128 v[66:69], v23 offset:23552
	ds_read_b128 v[104:107], v23 offset:32768
	ds_read_b128 v[108:111], v23 offset:23616
	s_waitcnt lgkmcnt(2)
	v_mfma_f32_16x16x32_bf16 v[66:69], v[14:17], v[66:69], 0
	ds_read_b128 v[112:115], v23 offset:32832
	v_lshlrev_b32_e32 v51, 16, v43
	ds_read_b32 v43, v93 offset:57216
	s_waitcnt lgkmcnt(2)
	v_mfma_f32_16x16x32_bf16 v[66:69], v[18:21], v[108:111], v[66:69]
	v_mov_b32_e32 v38, v31
	v_lshlrev_b32_e32 v50, 16, v61
	v_pk_mul_f32 v[120:121], v[38:39], v[50:51]
	v_mfma_f32_16x16x32_bf16 v[104:107], v[14:17], v[104:107], 0
	v_pk_mov_b32 v[50:51], v[116:117], v[50:51] op_sel:[1,0]
	s_waitcnt lgkmcnt(0)
	s_nop 1
	v_add_f32_e32 v1, v66, v43
	v_mul_f32_e32 v1, 0xbfb8aa3b, v1
	v_pk_mul_f32 v[118:119], v[38:39], v[116:117]
	v_pk_mul_f32 v[108:109], v[38:39], v[50:51]
	v_mfma_f32_16x16x32_bf16 v[104:107], v[18:21], v[112:115], v[104:107]
	ds_read_b32 v38, v93 offset:57472
	ds_read_b32 v49, v93 offset:57728
	v_exp_f32_e32 v1, v1
	v_add_f32_e32 v61, v68, v43
	v_mul_f32_e32 v61, 0xbfb8aa3b, v61
	s_waitcnt lgkmcnt(1)
	s_nop 1
	v_add_f32_e32 v50, v104, v38
	v_add_f32_e32 v1, 1.0, v1
	v_mul_f32_e32 v50, 0xbfb8aa3b, v50
	v_rcp_f32_e32 v1, v1
	v_exp_f32_e32 v50, v50
	v_exp_f32_e32 v61, v61
	v_mov_b32_e32 v68, v32
	s_waitcnt lgkmcnt(0)
	v_mul_f32_e32 v1, v1, v49
	v_add_f32_e32 v50, 1.0, v50
	v_mul_f32_e32 v1, 0xbfb8aa3b, v1
	v_rcp_f32_e32 v51, v50
	v_exp_f32_e32 v50, v1
	v_add_f32_e32 v1, v67, v43
	v_mul_f32_e32 v1, 0xbfb8aa3b, v1
	v_exp_f32_e32 v1, v1
	v_sub_f32_e32 v55, 1.0, v50
	v_add_f32_e32 v57, 1.0, v50
	v_mul_f32_e32 v55, v55, v57
	v_add_f32_e32 v1, 1.0, v1
	v_rcp_f32_e32 v1, v1
	v_add_f32_e32 v57, v105, v38
	v_mul_f32_e32 v57, 0xbfb8aa3b, v57
	v_exp_f32_e32 v57, v57
	v_mul_f32_e32 v1, v1, v49
	v_mul_f32_e32 v1, 0xbfb8aa3b, v1
	v_exp_f32_e32 v58, v1
	v_add_f32_e32 v43, v69, v43
	v_mul_f32_e32 v43, 0xbfb8aa3b, v43
	v_sqrt_f32_e32 v1, v55
	v_add_f32_e32 v55, 1.0, v57
	v_sub_f32_e32 v57, 1.0, v58
	v_add_f32_e32 v63, 1.0, v58
	v_exp_f32_e32 v43, v43
	v_mul_f32_e32 v57, v57, v63
	v_sqrt_f32_e32 v67, v57
	v_add_f32_e32 v57, 1.0, v61
	v_rcp_f32_e32 v57, v57
	v_add_f32_e32 v43, 1.0, v43
	v_rcp_f32_e32 v43, v43
	v_add_f32_e32 v61, v106, v38
	v_mul_f32_e32 v57, v57, v49
	v_mul_f32_e32 v61, 0xbfb8aa3b, v61
	v_mul_f32_e32 v57, 0xbfb8aa3b, v57
	v_add_f32_e32 v38, v107, v38
	v_exp_f32_e32 v63, v61
	v_exp_f32_e32 v61, v57
	v_mul_f32_e32 v38, 0xbfb8aa3b, v38
	v_mul_f32_e32 v43, v43, v49
	v_exp_f32_e32 v38, v38
	v_mul_f32_e32 v43, 0xbfb8aa3b, v43
	v_exp_f32_e32 v105, v43
	v_sub_f32_e32 v65, 1.0, v61
	v_add_f32_e32 v66, 1.0, v61
	v_rcp_f32_e32 v55, v55
	v_mul_f32_e32 v65, v65, v66
	v_add_f32_e32 v38, 1.0, v38
	v_mov_b32_e32 v66, v30
	v_add_f32_e32 v30, v62, v36
	v_rcp_f32_e32 v104, v38
	v_sub_f32_e32 v38, 1.0, v105
	v_add_f32_e32 v49, 1.0, v105
	v_mul_f32_e32 v51, v30, v51
	v_mul_f32_e32 v57, v50, v58
	v_mul_f32_e32 v38, v38, v49
	v_pk_mul_f32 v[50:51], v[50:51], v[0:1]
	v_add_f32_e32 v63, 1.0, v63
	v_sqrt_f32_e32 v49, v38
	v_add_f32_e32 v1, v50, v51
	v_add_f32_e32 v38, v64, v35
	v_rcp_f32_e32 v63, v63
	v_mul_f32_e32 v43, v61, v57
	v_mul_f32_e32 v57, v58, v1
	v_mul_f32_e32 v51, v38, v55
	v_mov_b32_e32 v50, v59
	v_sqrt_f32_e32 v69, v65
	v_pk_fma_f32 v[50:51], v[66:67], v[50:51], v[56:57]
	v_mul_f32_e32 v32, v105, v43
	v_pk_add_f32 v[56:57], v[60:61], v[50:51]
	v_pk_mul_f32 v[50:51], v[60:61], v[50:51]
	ds_bpermute_b32 v65, v83, v32
	v_add_f32_e32 v50, v70, v47
	v_mov_b32_e32 v57, v51
	v_mul_f32_e32 v43, v50, v63
	v_pk_fma_f32 v[56:57], v[68:69], v[42:43], v[56:57]
	s_waitcnt lgkmcnt(0)
; #define LAS __attribute__((address_space(3)))
; #define MFMA16(a, b, c) __builtin_amdgcn_mfma_f32_16x16x32_bf16(a, b, c, 0, 0, 0)
; template <bool PHASE_B>
; __device__ __forceinline__ void lru_item(const Params& p, LAS unsigned char* lds, int ci, int ci_next, int jb, const int tid, v4u (&xvn)[3]) {
;     ...
;             for (int ks = 0; ks < 2; ++ks) {
;                 const bf16x8 wa = *(const LAS bf16x8*)(lds + LR_WG + ((dir * 2 + 0) * 64 + 16 * ct + fr) * 144 + (32 * ks + 8 * fq) * 2);
;                 const bf16x8 wx = *(const LAS bf16x8*)(lds + LR_WG + ((dir * 2 + 1) * 64 + 16 * ct + fr) * 144 + (32 * ks + 8 * fq) * 2);
;                 ga = MFMA16(af[ks], wa, ga); gx = MFMA16(af[ks], wx, gx); }
;             const int ch = 16 * ct + fr; const float bav = GC[(dir * 3 + 0) * 64 + ch], bxv = GC[(dir * 3 + 1) * 64 + ch], c8 = GC[(dir * 3 + 2) * 64 + ch];
;             float Al = 1.f, Hl = 0.f;
; #pragma unroll
;             for (int ee = 0; ee < 4; ++ee) { const int e = dir ? 3 - ee : ee;
;                 const float r = __builtin_amdgcn_rcpf(1.f + __expf(-(ga[e] + bav))), ig = __builtin_amdgcn_rcpf(1.f + __expf(-(gx[e] + bxv)));
;                 const float la = -c8 * r; const float a = __expf(la); const float u = __builtin_amdgcn_sqrtf((1.f - a) * (1.f + a)) * (ig * xc[ct][e]);
;                 av[dir][ct][e] = a; uv[dir][ct][e] = u; Hl = a * Hl + u; Al *= a; }
;             const int o = dir ? 3 - fq : fq; const bool odd = (o & 1) != 0, hi2 = (o & 2) != 0;
;             const float A1 = __shfl_xor(Al, 16), H1 = __shfl_xor(Hl, 16);
;             const float pxA = odd ? A1 : 1.f, pxH = odd ? H1 : 0.f;
;             const float gA = Al * A1, gH = odd ? (Al * H1 + Hl) : (A1 * Hl + H1);
;             const float A2 = __shfl_xor(gA, 32), H2 = __shfl_xor(gH, 32);
;             const float PA = hi2 ? pxA * A2 : pxA, PH = hi2 ? (pxA * H2 + pxH) : pxH;
;             const float TA = gA * A2, TH = hi2 ? (gA * H2 + gH) : (A2 * gH + H2);
;             pA[dir][ct] = PA; pH[dir][ct] = PH;
;             ((LAS f32x2*)(lds + LR_SEG))[(dir * 8 + rt) * 64 + ch] = (f32x2){TA, TH};
	v_mul_f32_e32 v36, v32, v65
	v_pk_mul_f32 v[42:43], v[56:57], v[104:105]
	v_add_f32_e32 v41, v119, v27
	v_fmac_f32_e32 v43, v42, v49
	ds_bpermute_b32 v1, v83, v43
	v_add_f32_e32 v45, v121, v27
	v_add_f32_e32 v53, v109, v27
	v_fmac_f32_e32 v27, v39, v116
	ds_bpermute_b32 v39, v84, v36
	s_waitcnt lgkmcnt(1)
	v_fma_f32 v32, v32, v1, v43
	v_fmac_f32_e32 v1, v43, v65
	v_cndmask_b32_e64 v1, v32, v1, s[42:43]
	ds_bpermute_b32 v32, v84, v1
	s_waitcnt lgkmcnt(1)
	v_mul_f32_e32 v58, v36, v39
	v_lshlrev_b32_e32 v43, 16, v102
	v_lshlrev_b32_e32 v42, 16, v29
	v_add_f32_e32 v35, v120, v45
	s_waitcnt lgkmcnt(0)
	v_fma_f32 v36, v36, v32, v1
	v_fmac_f32_e32 v32, v1, v39
	v_cndmask_b32_e64 v59, v36, v32, s[44:45]
	ds_write_b64 v86, v[58:59] offset:58880
	ds_read_b128 v[58:61], v23 offset:25856
	ds_read_b128 v[62:65], v23 offset:35072
	ds_read_b128 v[66:69], v23 offset:25920
	s_waitcnt lgkmcnt(2)
	v_mfma_f32_16x16x32_bf16 v[58:61], v[14:17], v[58:61], 0
	ds_read_b128 v[102:105], v23 offset:35136
	ds_read_b32 v32, v93 offset:57280
	v_add_f32_e32 v45, v108, v53
	s_waitcnt lgkmcnt(2)
	v_mfma_f32_16x16x32_bf16 v[58:61], v[18:21], v[66:69], v[58:61]
	v_mov_b32_e32 v36, v33
	v_pk_mov_b32 v[108:109], v[42:43], v[116:117] op_sel:[1,0]
	v_mul_f32_e32 v70, v37, v42
	v_mfma_f32_16x16x32_bf16 v[62:65], v[14:17], v[62:65], 0
	v_mul_f32_e64 v106, v36, v116
	v_mul_f32_e64 v107, v37, v117
	s_waitcnt lgkmcnt(0)
	s_nop 0
	v_add_f32_e32 v1, v58, v32
	v_mul_f32_e32 v1, 0xbfb8aa3b, v1
	v_pk_mul_f32 v[108:109], v[36:37], v[108:109]
	v_pk_mul_f32 v[66:67], v[36:37], v[42:43]
	v_mfma_f32_16x16x32_bf16 v[62:65], v[18:21], v[102:105], v[62:65]
	ds_read_b32 v37, v93 offset:57536
	ds_read_b32 v39, v93 offset:57792
	v_exp_f32_e32 v1, v1
	v_add_f32_e32 v29, v107, v35
	v_add_f32_e32 v35, v109, v45
	s_waitcnt lgkmcnt(1)
	s_nop 1
	v_add_f32_e32 v36, v62, v37
	v_add_f32_e32 v1, 1.0, v1
	v_mul_f32_e32 v36, 0xbfb8aa3b, v36
	v_rcp_f32_e32 v1, v1
	v_exp_f32_e32 v36, v36
	v_add_f32_e32 v51, v60, v32
	v_mul_f32_e32 v51, 0xbfb8aa3b, v51
	s_waitcnt lgkmcnt(0)
	v_mul_f32_e32 v1, v1, v39
	v_add_f32_e32 v36, 1.0, v36
	v_mul_f32_e32 v1, 0xbfb8aa3b, v1
	v_rcp_f32_e32 v42, v36
	v_exp_f32_e32 v36, v1
	v_add_f32_e32 v1, v59, v32
	v_mul_f32_e32 v1, 0xbfb8aa3b, v1
	v_exp_f32_e32 v1, v1
	v_sub_f32_e32 v45, 1.0, v36
	v_add_f32_e32 v47, 1.0, v36
	v_mul_f32_e32 v45, v45, v47
	v_add_f32_e32 v1, 1.0, v1
	v_rcp_f32_e32 v1, v1
	v_add_f32_e32 v47, v63, v37
	v_mul_f32_e32 v47, 0xbfb8aa3b, v47
	v_exp_f32_e32 v47, v47
	v_mul_f32_e32 v1, v1, v39
	v_mul_f32_e32 v1, 0xbfb8aa3b, v1
	v_exp_f32_e32 v49, v1
	v_add_f32_e32 v32, v61, v32
	v_mul_f32_e32 v32, 0xbfb8aa3b, v32
	v_exp_f32_e32 v51, v51
	v_exp_f32_e32 v32, v32
	v_sqrt_f32_e32 v1, v45
	v_add_f32_e32 v45, 1.0, v47
	v_sub_f32_e32 v47, 1.0, v49
	v_add_f32_e32 v53, 1.0, v49
	v_mul_f32_e32 v47, v47, v53
	v_sqrt_f32_e32 v59, v47
	v_add_f32_e32 v47, 1.0, v51
	v_add_f32_e32 v32, 1.0, v32
	v_rcp_f32_e32 v47, v47
	v_rcp_f32_e32 v32, v32
	v_add_f32_e32 v51, v64, v37
	v_add_f32_e32 v37, v65, v37
	v_mul_f32_e32 v47, v47, v39
	v_mul_f32_e32 v37, 0xbfb8aa3b, v37
	v_mul_f32_e32 v32, v32, v39
	v_mul_f32_e32 v47, 0xbfb8aa3b, v47
	v_exp_f32_e32 v37, v37
	v_mul_f32_e32 v32, 0xbfb8aa3b, v32
	v_exp_f32_e32 v71, v47
	v_exp_f32_e32 v63, v32
	v_mul_f32_e32 v51, 0xbfb8aa3b, v51
	v_mul_f32_e32 v47, v36, v49
	v_add_f32_e32 v37, 1.0, v37
	v_exp_f32_e32 v51, v51
	v_mul_f32_e32 v32, v71, v47
	v_rcp_f32_e32 v62, v37
	v_sub_f32_e32 v37, 1.0, v63
	v_add_f32_e32 v39, 1.0, v63
	v_rcp_f32_e32 v45, v45
	v_mul_f32_e32 v37, v37, v39
	v_mov_b32_e32 v58, v31
	v_mul_f32_e32 v31, v63, v32
	v_add_f32_e32 v32, v106, v29
	v_sqrt_f32_e32 v39, v37
	v_mul_f32_e32 v37, v32, v42
	v_pk_mul_f32 v[36:37], v[36:37], v[0:1]
	v_add_f32_e32 v51, 1.0, v51
	v_sub_f32_e32 v53, 1.0, v71
	v_add_f32_e32 v55, 1.0, v71
	v_add_f32_e32 v1, v36, v37
	v_add_f32_e32 v36, v108, v35
	v_rcp_f32_e32 v51, v51
	v_mul_f32_e32 v53, v53, v55
	v_mul_f32_e32 v65, v49, v1
	v_mov_b32_e32 v64, v27
	v_mul_f32_e32 v69, v36, v45
	v_mov_b32_e32 v68, v43
	v_add_f32_e32 v41, v118, v41
	v_sqrt_f32_e32 v61, v53
	v_pk_fma_f32 v[42:43], v[58:59], v[68:69], v[64:65]
	v_add_f32_e32 v41, v67, v41
	v_pk_add_f32 v[58:59], v[70:71], v[42:43]
	v_pk_mul_f32 v[42:43], v[70:71], v[42:43]
	v_mov_b32_e32 v60, v33
	v_add_f32_e32 v42, v66, v41
	v_mov_b32_e32 v59, v43
	v_mul_f32_e32 v29, v42, v51
	v_pk_fma_f32 v[28:29], v[60:61], v[28:29], v[58:59]
	ds_bpermute_b32 v33, v83, v31
	v_pk_mul_f32 v[58:59], v[28:29], v[62:63]
	s_waitcnt lgkmcnt(0)
	v_mul_f32_e32 v27, v31, v33
	v_fmac_f32_e32 v59, v58, v39
	ds_bpermute_b32 v1, v83, v59
	ds_bpermute_b32 v29, v84, v27
	s_waitcnt lgkmcnt(1)
	v_fma_f32 v31, v31, v1, v59
	v_fmac_f32_e32 v1, v59, v33
	v_cndmask_b32_e64 v1, v31, v1, s[42:43]
	ds_bpermute_b32 v31, v84, v1
	s_waitcnt lgkmcnt(1)
	v_mul_f32_e32 v58, v27, v29
	s_waitcnt lgkmcnt(0)
	v_fma_f32 v27, v27, v31, v1
	v_fmac_f32_e32 v31, v1, v29
	v_cndmask_b32_e64 v59, v27, v31, s[44:45]
	ds_write_b64 v86, v[58:59] offset:59008
	ds_read_b128 v[58:61], v23 offset:37376
	ds_read_b128 v[62:65], v23 offset:37440
	s_waitcnt lgkmcnt(1)
	v_mfma_f32_16x16x32_bf16 v[58:61], v[14:17], v[58:61], 0
	ds_read_b128 v[66:69], v23 offset:46592
	ds_read_b128 v[102:105], v23 offset:46656
	ds_read_b32 v27, v93 offset:57856
	ds_read_b32 v29, v93 offset:58112
	ds_read_b32 v31, v93 offset:58368
	s_waitcnt lgkmcnt(5)
	v_mfma_f32_16x16x32_bf16 v[58:61], v[18:21], v[62:65], v[58:61]
	s_waitcnt lgkmcnt(4)
	v_mfma_f32_16x16x32_bf16 v[66:69], v[14:17], v[66:69], 0
	s_waitcnt lgkmcnt(3)
	v_mfma_f32_16x16x32_bf16 v[62:65], v[18:21], v[102:105], v[66:69]
	s_waitcnt lgkmcnt(2)
; #define LAS __attribute__((address_space(3)))
; #define MFMA16(a, b, c) __builtin_amdgcn_mfma_f32_16x16x32_bf16(a, b, c, 0, 0, 0)
; template <bool PHASE_B>
; __device__ __forceinline__ void lru_item(const Params& p, LAS unsigned char* lds, int ci, int ci_next, int jb, const int tid, v4u (&xvn)[3]) {
;     ...
;             for (int ks = 0; ks < 2; ++ks) {
;                 const bf16x8 wa = *(const LAS bf16x8*)(lds + LR_WG + ((dir * 2 + 0) * 64 + 16 * ct + fr) * 144 + (32 * ks + 8 * fq) * 2);
;                 const bf16x8 wx = *(const LAS bf16x8*)(lds + LR_WG + ((dir * 2 + 1) * 64 + 16 * ct + fr) * 144 + (32 * ks + 8 * fq) * 2);
;                 ga = MFMA16(af[ks], wa, ga); gx = MFMA16(af[ks], wx, gx); }
;             const int ch = 16 * ct + fr; const float bav = GC[(dir * 3 + 0) * 64 + ch], bxv = GC[(dir * 3 + 1) * 64 + ch], c8 = GC[(dir * 3 + 2) * 64 + ch];
;             float Al = 1.f, Hl = 0.f;
; #pragma unroll
;             for (int ee = 0; ee < 4; ++ee) { const int e = dir ? 3 - ee : ee;
;                 const float r = __builtin_amdgcn_rcpf(1.f + __expf(-(ga[e] + bav))), ig = __builtin_amdgcn_rcpf(1.f + __expf(-(gx[e] + bxv)));
;                 const float la = -c8 * r; const float a = __expf(la); const float u = __builtin_amdgcn_sqrtf((1.f - a) * (1.f + a)) * (ig * xc[ct][e]);
;                 av[dir][ct][e] = a; uv[dir][ct][e] = u; Hl = a * Hl + u; Al *= a; }
;             const int o = dir ? 3 - fq : fq; const bool odd = (o & 1) != 0, hi2 = (o & 2) != 0;
;             const float A1 = __shfl_xor(Al, 16), H1 = __shfl_xor(Hl, 16);
;             const float pxA = odd ? A1 : 1.f, pxH = odd ? H1 : 0.f;
;             const float gA = Al * A1, gH = odd ? (Al * H1 + Hl) : (A1 * Hl + H1);
;             const float A2 = __shfl_xor(gA, 32), H2 = __shfl_xor(gH, 32);
;             const float PA = hi2 ? pxA * A2 : pxA, PH = hi2 ? (pxA * H2 + pxH) : pxH;
;             const float TA = gA * A2, TH = hi2 ? (gA * H2 + gH) : (A2 * gH + H2);
;             pA[dir][ct] = PA; pH[dir][ct] = PH;
;             ((LAS f32x2*)(lds + LR_SEG))[(dir * 8 + rt) * 64 + ch] = (f32x2){TA, TH};
	s_nop 2
	v_add_f32_e32 v1, v61, v27
	v_mul_f32_e32 v1, 0xbfb8aa3b, v1
	v_exp_f32_e32 v1, v1
	s_nop 0
	v_add_f32_e32 v1, 1.0, v1
	v_rcp_f32_e32 v1, v1
	s_waitcnt lgkmcnt(1)
	v_add_f32_e32 v33, v65, v29
	v_mul_f32_e32 v33, 0xbfb8aa3b, v33
	v_exp_f32_e32 v33, v33
	s_waitcnt lgkmcnt(0)
	v_mul_f32_e32 v1, v1, v31
	v_mul_f32_e32 v1, 0xbfb8aa3b, v1
	v_exp_f32_e32 v66, v1
	v_add_f32_e32 v1, 1.0, v33
	v_rcp_f32_e32 v33, v1
	v_sub_f32_e32 v1, 1.0, v66
	v_add_f32_e32 v35, 1.0, v66
	v_mul_f32_e32 v1, v1, v35
	v_add_f32_e32 v35, v60, v27
	v_mul_f32_e32 v35, 0xbfb8aa3b, v35
	v_exp_f32_e32 v35, v35
	v_mul_f32_e32 v67, v52, v33
	v_sqrt_f32_e32 v1, v1
	v_mul_f32_e32 v52, 0, v66
	v_add_f32_e32 v33, 1.0, v35
	v_rcp_f32_e32 v33, v33
	v_add_f32_e32 v35, v64, v29
	v_mul_f32_e32 v35, 0xbfb8aa3b, v35
	v_exp_f32_e32 v35, v35
	v_mul_f32_e32 v33, v33, v31
	v_mul_f32_e32 v33, 0xbfb8aa3b, v33
	v_exp_f32_e32 v53, v33
	s_nop 0
	v_pk_fma_f32 v[60:61], v[66:67], v[0:1], v[52:53] op_sel_hi:[1,1,0]
	v_add_f32_e32 v1, 1.0, v35
	v_rcp_f32_e32 v52, v1
	v_sub_f32_e32 v1, 1.0, v53
	v_add_f32_e32 v33, 1.0, v53
	v_mul_f32_e32 v1, v1, v33
	v_add_f32_e32 v33, v59, v27
	v_mul_f32_e32 v33, 0xbfb8aa3b, v33
	v_sqrt_f32_e32 v1, v1
	v_exp_f32_e32 v33, v33
	v_add_f32_e32 v27, v58, v27
	v_mov_b32_e32 v47, v61
	v_mul_f32_e32 v27, 0xbfb8aa3b, v27
	v_pk_mul_f32 v[46:47], v[46:47], v[52:53]
	v_exp_f32_e32 v27, v27
	v_fmac_f32_e32 v47, v46, v1
	v_add_f32_e32 v1, 1.0, v33
	v_rcp_f32_e32 v1, v1
	v_add_f32_e32 v27, 1.0, v27
	v_add_f32_e32 v33, v63, v29
	v_rcp_f32_e32 v27, v27
	v_mul_f32_e32 v33, 0xbfb8aa3b, v33
	v_mul_f32_e32 v1, v1, v31
	v_exp_f32_e32 v33, v33
	v_mul_f32_e32 v1, 0xbfb8aa3b, v1
	v_exp_f32_e32 v61, v1
	v_add_f32_e32 v29, v62, v29
	v_mul_f32_e32 v29, 0xbfb8aa3b, v29
	v_mul_f32_e32 v27, v27, v31
	v_exp_f32_e32 v29, v29
	v_mul_f32_e32 v27, 0xbfb8aa3b, v27
	v_add_f32_e32 v33, 1.0, v33
	v_mov_b32_e32 v41, v47
	v_exp_f32_e32 v47, v27
	v_rcp_f32_e32 v60, v33
	v_sub_f32_e32 v33, 1.0, v61
	v_add_f32_e32 v35, 1.0, v61
	v_mul_f32_e32 v33, v33, v35
	v_sqrt_f32_e32 v33, v33
	v_add_f32_e32 v27, 1.0, v29
	v_rcp_f32_e32 v46, v27
	v_sub_f32_e32 v27, 1.0, v47
	v_add_f32_e32 v29, 1.0, v47
	v_mul_f32_e32 v27, v27, v29
	v_pk_mul_f32 v[40:41], v[40:41], v[60:61]
	v_sqrt_f32_e32 v27, v27
	v_fmac_f32_e32 v41, v40, v33
	v_mul_f32_e32 v1, v66, v53
	v_mov_b32_e32 v35, v41
	v_mul_f32_e32 v1, v61, v1
	v_pk_mul_f32 v[34:35], v[34:35], v[46:47]
	v_mul_f32_e32 v1, v47, v1
	v_fmac_f32_e32 v35, v34, v27
	ds_bpermute_b32 v27, v83, v1
	ds_bpermute_b32 v29, v83, v35
	s_waitcnt lgkmcnt(1)
	v_mul_f32_e32 v31, v1, v27
	s_waitcnt lgkmcnt(0)
	v_fma_f32 v1, v1, v29, v35
	v_fmac_f32_e32 v29, v35, v27
	v_cndmask_b32_e64 v1, v1, v29, s[46:47]
	ds_bpermute_b32 v27, v84, v31
	ds_bpermute_b32 v29, v84, v1
	s_waitcnt lgkmcnt(1)
	v_mul_f32_e32 v34, v31, v27
	s_waitcnt lgkmcnt(0)
	v_fma_f32 v31, v31, v29, v1
	v_fmac_f32_e32 v29, v1, v27
	v_cndmask_b32_e64 v35, v31, v29, s[48:49]
	ds_write_b64 v86, v[34:35] offset:62720
	ds_read_b128 v[58:61], v23 offset:39680
	ds_read_b128 v[62:65], v23 offset:39744
	s_waitcnt lgkmcnt(1)
	v_mfma_f32_16x16x32_bf16 v[58:61], v[14:17], v[58:61], 0
	ds_read_b128 v[66:69], v23 offset:48896
	ds_read_b128 v[102:105], v23 offset:48960
	ds_read_b32 v27, v93 offset:57920
	ds_read_b32 v29, v93 offset:58176
	ds_read_b32 v31, v93 offset:58432
	s_waitcnt lgkmcnt(5)
	v_mfma_f32_16x16x32_bf16 v[58:61], v[18:21], v[62:65], v[58:61]
	s_waitcnt lgkmcnt(4)
	v_mfma_f32_16x16x32_bf16 v[66:69], v[14:17], v[66:69], 0
	s_waitcnt lgkmcnt(3)
	v_mfma_f32_16x16x32_bf16 v[62:65], v[18:21], v[102:105], v[66:69]
	s_waitcnt lgkmcnt(2)
	s_nop 2
	v_add_f32_e32 v1, v61, v27
	v_mul_f32_e32 v1, 0xbfb8aa3b, v1
	v_exp_f32_e32 v1, v1
	s_nop 0
	v_add_f32_e32 v1, 1.0, v1
	v_rcp_f32_e32 v1, v1
	s_waitcnt lgkmcnt(1)
	v_add_f32_e32 v33, v65, v29
	v_mul_f32_e32 v33, 0xbfb8aa3b, v33
	v_exp_f32_e32 v33, v33
	s_waitcnt lgkmcnt(0)
	v_mul_f32_e32 v1, v1, v31
	v_mul_f32_e32 v1, 0xbfb8aa3b, v1
	v_exp_f32_e32 v34, v1
	v_add_f32_e32 v1, 1.0, v33
	v_rcp_f32_e32 v33, v1
	v_sub_f32_e32 v1, 1.0, v34
	v_add_f32_e32 v35, 1.0, v34
	v_mul_f32_e32 v1, v1, v35
	v_add_f32_e32 v35, v60, v27
	v_mul_f32_e32 v35, 0xbfb8aa3b, v35
	v_exp_f32_e32 v37, v35
	v_mul_f32_e32 v35, v54, v33
	v_sqrt_f32_e32 v1, v1
	v_mul_f32_e32 v40, 0, v34
	v_add_f32_e32 v33, 1.0, v37
	v_rcp_f32_e32 v33, v33
	v_add_f32_e32 v37, v64, v29
	v_mul_f32_e32 v37, 0xbfb8aa3b, v37
	v_exp_f32_e32 v37, v37
	v_mul_f32_e32 v33, v33, v31
	v_mul_f32_e32 v33, 0xbfb8aa3b, v33
	v_exp_f32_e32 v41, v33
	s_nop 0
	v_pk_fma_f32 v[46:47], v[34:35], v[0:1], v[40:41] op_sel_hi:[1,1,0]
	v_add_f32_e32 v1, 1.0, v37
	v_rcp_f32_e32 v40, v1
	v_sub_f32_e32 v1, 1.0, v41
	v_add_f32_e32 v33, 1.0, v41
	v_mul_f32_e32 v1, v1, v33
	v_add_f32_e32 v33, v59, v27
	v_mul_f32_e32 v33, 0xbfb8aa3b, v33
	v_sqrt_f32_e32 v1, v1
	v_exp_f32_e32 v33, v33
	v_mov_b32_e32 v49, v47
	v_add_f32_e32 v27, v58, v27
	v_pk_mul_f32 v[46:47], v[48:49], v[40:41]
	v_mul_f32_e32 v27, 0xbfb8aa3b, v27
	v_fmac_f32_e32 v47, v46, v1
	v_add_f32_e32 v1, 1.0, v33
	v_add_f32_e32 v33, v63, v29
	v_exp_f32_e32 v27, v27
	v_rcp_f32_e32 v1, v1
	v_mul_f32_e32 v33, 0xbfb8aa3b, v33
	v_exp_f32_e32 v33, v33
	v_add_f32_e32 v27, 1.0, v27
	v_mul_f32_e32 v1, v1, v31
	v_rcp_f32_e32 v27, v27
	v_mul_f32_e32 v1, 0xbfb8aa3b, v1
	v_add_f32_e32 v33, 1.0, v33
	v_exp_f32_e32 v35, v1
	v_mul_f32_e32 v1, v34, v41
	v_rcp_f32_e32 v34, v33
	v_add_f32_e32 v29, v62, v29
	v_mul_f32_e32 v29, 0xbfb8aa3b, v29
	v_mul_f32_e32 v27, v27, v31
	v_mov_b32_e32 v45, v47
	v_exp_f32_e32 v29, v29
	v_mul_f32_e32 v27, 0xbfb8aa3b, v27
	v_pk_mul_f32 v[40:41], v[44:45], v[34:35]
	v_exp_f32_e32 v45, v27
	v_sub_f32_e32 v33, 1.0, v35
	v_add_f32_e32 v37, 1.0, v35
	v_mul_f32_e32 v33, v33, v37
	v_sqrt_f32_e32 v33, v33
	v_add_f32_e32 v27, 1.0, v29
	v_rcp_f32_e32 v44, v27
	v_sub_f32_e32 v27, 1.0, v45
	v_add_f32_e32 v29, 1.0, v45
	v_mul_f32_e32 v27, v27, v29
	v_sqrt_f32_e32 v29, v27
	v_fmac_f32_e32 v41, v40, v33
	v_mov_b32_e32 v27, v41
	v_mul_f32_e32 v1, v35, v1
	v_pk_mul_f32 v[26:27], v[26:27], v[44:45]
	v_mul_f32_e32 v1, v45, v1
	v_fmac_f32_e32 v27, v26, v29
	ds_bpermute_b32 v26, v83, v1
	ds_bpermute_b32 v29, v83, v27
	s_waitcnt lgkmcnt(1)
; #define LAS __attribute__((address_space(3)))
; #define MFMA16(a, b, c) __builtin_amdgcn_mfma_f32_16x16x32_bf16(a, b, c, 0, 0, 0)
; template <bool PHASE_B>
; __device__ __forceinline__ void lru_item(const Params& p, LAS unsigned char* lds, int ci, int ci_next, int jb, const int tid, v4u (&xvn)[3]) {
;     ...
;             for (int ks = 0; ks < 2; ++ks) {
;                 const bf16x8 wa = *(const LAS bf16x8*)(lds + LR_WG + ((dir * 2 + 0) * 64 + 16 * ct + fr) * 144 + (32 * ks + 8 * fq) * 2);
;                 const bf16x8 wx = *(const LAS bf16x8*)(lds + LR_WG + ((dir * 2 + 1) * 64 + 16 * ct + fr) * 144 + (32 * ks + 8 * fq) * 2);
;                 ga = MFMA16(af[ks], wa, ga); gx = MFMA16(af[ks], wx, gx); }
;             const int ch = 16 * ct + fr; const float bav = GC[(dir * 3 + 0) * 64 + ch], bxv = GC[(dir * 3 + 1) * 64 + ch], c8 = GC[(dir * 3 + 2) * 64 + ch];
;             float Al = 1.f, Hl = 0.f;
; #pragma unroll
;             for (int ee = 0; ee < 4; ++ee) { const int e = dir ? 3 - ee : ee;
;                 const float r = __builtin_amdgcn_rcpf(1.f + __expf(-(ga[e] + bav))), ig = __builtin_amdgcn_rcpf(1.f + __expf(-(gx[e] + bxv)));
;                 const float la = -c8 * r; const float a = __expf(la); const float u = __builtin_amdgcn_sqrtf((1.f - a) * (1.f + a)) * (ig * xc[ct][e]);
;                 av[dir][ct][e] = a; uv[dir][ct][e] = u; Hl = a * Hl + u; Al *= a; }
;             const int o = dir ? 3 - fq : fq; const bool odd = (o & 1) != 0, hi2 = (o & 2) != 0;
;             const float A1 = __shfl_xor(Al, 16), H1 = __shfl_xor(Hl, 16);
;             const float pxA = odd ? A1 : 1.f, pxH = odd ? H1 : 0.f;
;             const float gA = Al * A1, gH = odd ? (Al * H1 + Hl) : (A1 * Hl + H1);
;             const float A2 = __shfl_xor(gA, 32), H2 = __shfl_xor(gH, 32);
;             const float PA = hi2 ? pxA * A2 : pxA, PH = hi2 ? (pxA * H2 + pxH) : pxH;
;             const float TA = gA * A2, TH = hi2 ? (gA * H2 + gH) : (A2 * gH + H2);
;             pA[dir][ct] = PA; pH[dir][ct] = PH;
;             ((LAS f32x2*)(lds + LR_SEG))[(dir * 8 + rt) * 64 + ch] = (f32x2){TA, TH};
	v_mul_f32_e32 v31, v1, v26
	s_waitcnt lgkmcnt(0)
	v_fma_f32 v1, v1, v29, v27
	v_fmac_f32_e32 v29, v27, v26
	v_cndmask_b32_e64 v1, v1, v29, s[46:47]
	ds_bpermute_b32 v27, v84, v31
	ds_bpermute_b32 v29, v84, v1
	s_waitcnt lgkmcnt(1)
	v_mul_f32_e32 v26, v31, v27
	s_waitcnt lgkmcnt(0)
	v_fma_f32 v31, v31, v29, v1
	v_fmac_f32_e32 v29, v1, v27
	v_cndmask_b32_e64 v27, v31, v29, s[48:49]
	ds_write_b64 v86, v[26:27] offset:62848
	ds_read_b128 v[44:47], v23 offset:41984
	ds_read_b128 v[52:55], v23 offset:42048
	s_waitcnt lgkmcnt(1)
	v_mfma_f32_16x16x32_bf16 v[44:47], v[14:17], v[44:47], 0
	ds_read_b128 v[58:61], v23 offset:51200
	ds_read_b128 v[62:65], v23 offset:51264
	ds_read_b32 v29, v93 offset:57984
	ds_read_b32 v31, v93 offset:58240
	ds_read_b32 v33, v93 offset:58496
	s_waitcnt lgkmcnt(5)
	v_mfma_f32_16x16x32_bf16 v[44:47], v[18:21], v[52:55], v[44:47]
	s_waitcnt lgkmcnt(4)
	v_mfma_f32_16x16x32_bf16 v[58:61], v[14:17], v[58:61], 0
	s_waitcnt lgkmcnt(3)
	v_mfma_f32_16x16x32_bf16 v[52:55], v[18:21], v[62:65], v[58:61]
	s_waitcnt lgkmcnt(2)
	s_nop 2
	v_add_f32_e32 v1, v47, v29
	v_mul_f32_e32 v1, 0xbfb8aa3b, v1
	v_exp_f32_e32 v1, v1
	s_nop 0
	v_add_f32_e32 v1, 1.0, v1
	v_rcp_f32_e32 v1, v1
	s_waitcnt lgkmcnt(1)
	v_add_f32_e32 v26, v55, v31
	v_mul_f32_e32 v26, 0xbfb8aa3b, v26
	v_exp_f32_e32 v27, v26
	s_waitcnt lgkmcnt(0)
	v_mul_f32_e32 v1, v1, v33
	v_mul_f32_e32 v1, 0xbfb8aa3b, v1
	v_exp_f32_e32 v26, v1
	v_add_f32_e32 v1, 1.0, v27
	v_rcp_f32_e32 v27, v1
	v_add_f32_e32 v37, v54, v31
	v_sub_f32_e32 v1, 1.0, v26
	v_add_f32_e32 v34, 1.0, v26
	v_mul_f32_e32 v1, v1, v34
	v_add_f32_e32 v34, v46, v29
	v_mul_f32_e32 v34, 0xbfb8aa3b, v34
	v_exp_f32_e32 v35, v34
	v_mul_f32_e32 v37, 0xbfb8aa3b, v37
	v_sqrt_f32_e32 v1, v1
	v_exp_f32_e32 v37, v37
	v_add_f32_e32 v35, 1.0, v35
	v_rcp_f32_e32 v35, v35
	v_mul_f32_e32 v27, v56, v27
	v_mul_f32_e32 v34, 0, v26
	v_mul_f32_e32 v35, v35, v33
	v_mul_f32_e32 v35, 0xbfb8aa3b, v35
	v_exp_f32_e32 v35, v35
	s_nop 0
	v_pk_fma_f32 v[40:41], v[26:27], v[0:1], v[34:35] op_sel_hi:[1,1,0]
	v_add_f32_e32 v1, 1.0, v37
	v_rcp_f32_e32 v34, v1
	v_sub_f32_e32 v1, 1.0, v35
	v_add_f32_e32 v27, 1.0, v35
	v_mul_f32_e32 v1, v1, v27
	v_add_f32_e32 v27, v45, v29
	v_mul_f32_e32 v27, 0xbfb8aa3b, v27
	v_sqrt_f32_e32 v1, v1
	v_exp_f32_e32 v27, v27
	v_mov_b32_e32 v51, v41
	v_pk_mul_f32 v[40:41], v[50:51], v[34:35]
	v_add_f32_e32 v29, v44, v29
	v_fmac_f32_e32 v41, v40, v1
	v_add_f32_e32 v1, 1.0, v27
	v_rcp_f32_e32 v1, v1
	v_add_f32_e32 v27, v53, v31
	v_mul_f32_e32 v27, 0xbfb8aa3b, v27
	v_exp_f32_e32 v34, v27
	v_mul_f32_e32 v1, v1, v33
	v_mul_f32_e32 v1, 0xbfb8aa3b, v1
	v_exp_f32_e32 v27, v1
	v_mul_f32_e32 v1, v26, v35
	v_add_f32_e32 v26, 1.0, v34
	v_mul_f32_e32 v29, 0xbfb8aa3b, v29
	v_rcp_f32_e32 v26, v26
	v_exp_f32_e32 v29, v29
	v_sub_f32_e32 v34, 1.0, v27
	v_add_f32_e32 v35, 1.0, v27
	v_mul_f32_e32 v34, v34, v35
	v_mov_b32_e32 v39, v41
	v_sqrt_f32_e32 v37, v34
	v_pk_mul_f32 v[34:35], v[38:39], v[26:27]
	v_add_f32_e32 v26, 1.0, v29
	v_rcp_f32_e32 v26, v26
	v_add_f32_e32 v29, v52, v31
	v_mul_f32_e32 v29, 0xbfb8aa3b, v29
	v_exp_f32_e32 v29, v29
	v_mul_f32_e32 v26, v26, v33
	v_mul_f32_e32 v26, 0xbfb8aa3b, v26
	v_exp_f32_e32 v39, v26
	v_add_f32_e32 v26, 1.0, v29
	v_rcp_f32_e32 v38, v26
	v_fmac_f32_e32 v35, v34, v37
	v_sub_f32_e32 v26, 1.0, v39
	v_add_f32_e32 v29, 1.0, v39
	v_mul_f32_e32 v26, v26, v29
	v_sqrt_f32_e32 v29, v26
	v_mov_b32_e32 v31, v35
	v_mul_f32_e32 v1, v27, v1
	v_pk_mul_f32 v[26:27], v[30:31], v[38:39]
	v_mul_f32_e32 v1, v39, v1
	v_fmac_f32_e32 v27, v26, v29
	ds_bpermute_b32 v26, v83, v1
	ds_bpermute_b32 v29, v83, v27
	s_waitcnt lgkmcnt(1)
	v_mul_f32_e32 v30, v1, v26
	s_waitcnt lgkmcnt(0)
	v_fma_f32 v1, v1, v29, v27
	v_fmac_f32_e32 v29, v27, v26
	v_cndmask_b32_e64 v1, v1, v29, s[46:47]
	ds_bpermute_b32 v27, v84, v30
	ds_bpermute_b32 v29, v84, v1
	s_waitcnt lgkmcnt(1)
	v_mul_f32_e32 v26, v30, v27
	s_waitcnt lgkmcnt(0)
	v_fma_f32 v30, v30, v29, v1
	v_fmac_f32_e32 v29, v1, v27
	v_cndmask_b32_e64 v27, v30, v29, s[48:49]
	ds_write_b64 v86, v[26:27] offset:62976
	ds_read_b128 v[38:41], v23 offset:44288
	ds_read_b128 v[44:47], v23 offset:44352
	s_waitcnt lgkmcnt(1)
	v_mfma_f32_16x16x32_bf16 v[38:41], v[14:17], v[38:41], 0
	ds_read_b128 v[48:51], v23 offset:53504
	ds_read_b128 v[52:55], v23 offset:53568
	ds_read_b32 v23, v93 offset:58048
	ds_read_b32 v26, v93 offset:58304
	ds_read_b32 v27, v93 offset:58560
	s_waitcnt lgkmcnt(5)
	v_mfma_f32_16x16x32_bf16 v[38:41], v[18:21], v[44:47], v[38:41]
	s_waitcnt lgkmcnt(4)
	v_mfma_f32_16x16x32_bf16 v[14:17], v[14:17], v[48:51], 0
	s_waitcnt lgkmcnt(3)
; template <bool PHASE_B>
; __device__ __forceinline__ void lru_item(const Params& p, LAS unsigned char* lds, int ci, int ci_next, int jb, const int tid, v4u (&xvn)[3]) {
;     ...
;             const int ch = 16 * ct + fr; const float bav = GC[(dir * 3 + 0) * 64 + ch], bxv = GC[(dir * 3 + 1) * 64 + ch], c8 = GC[(dir * 3 + 2) * 64 + ch];
;             float Al = 1.f, Hl = 0.f;
; #pragma unroll
;             for (int ee = 0; ee < 4; ++ee) { const int e = dir ? 3 - ee : ee;
;                 const float r = __builtin_amdgcn_rcpf(1.f + __expf(-(ga[e] + bav))), ig = __builtin_amdgcn_rcpf(1.f + __expf(-(gx[e] + bxv)));
;                 const float la = -c8 * r; const float a = __expf(la); const float u = __builtin_amdgcn_sqrtf((1.f - a) * (1.f + a)) * (ig * xc[ct][e]);
;                 av[dir][ct][e] = a; uv[dir][ct][e] = u; Hl = a * Hl + u; Al *= a; }
;             const int o = dir ? 3 - fq : fq; const bool odd = (o & 1) != 0, hi2 = (o & 2) != 0;
;             const float A1 = __shfl_xor(Al, 16), H1 = __shfl_xor(Hl, 16);
;             const float pxA = odd ? A1 : 1.f, pxH = odd ? H1 : 0.f;
;             const float gA = Al * A1, gH = odd ? (Al * H1 + Hl) : (A1 * Hl + H1);
;             const float A2 = __shfl_xor(gA, 32), H2 = __shfl_xor(gH, 32);
;             const float PA = hi2 ? pxA * A2 : pxA, PH = hi2 ? (pxA * H2 + pxH) : pxH;
;             const float TA = gA * A2, TH = hi2 ? (gA * H2 + gH) : (A2 * gH + H2);
;             pA[dir][ct] = PA; pH[dir][ct] = PH;
;             ((LAS f32x2*)(lds + LR_SEG))[(dir * 8 + rt) * 64 + ch] = (f32x2){TA, TH};
;         }
;     }
;     if constexpr (PHASE_B) {
; #pragma unroll
;         for (int dir = 0; dir < 2; ++dir)
; #pragma unroll
;             for (int ct = 0; ct < 4; ++ct) cin[dir][ct] = ((const float*)(p.ws + WS_CIN))[(size_t)(ci * 2 + dir) * 768 + jb * 64 + 16 * ct + fr];
;         const bf16* gp = (const bf16*)(p.ws + WS_GR) + (size_t)(t0 + (tid >> 2)) * 768 + jb * 64 + (tid & 3) * 16;
;         gv[0] = *(const v4u*)gp; gv[1] = *(const v4u*)(gp + 8);
;     }
;     __syncthreads();
;     if constexpr (!PHASE_B) {
;         if (tid < 128) { const int dir = tid >> 6, ch = tid & 63; float A = 1.f, H = 0.f;
; #pragma unroll
;             for (int q = 0; q < 8; ++q) { const f32x2 sh = ((const LAS f32x2*)(lds + LR_SEG))[(dir * 8 + (dir ? 7 - q : q)) * 64 + ch]; H = sh.x * H + sh.y; A *= sh.x; }
	v_mfma_f32_16x16x32_bf16 v[14:17], v[18:21], v[52:55], v[14:17]
	s_waitcnt lgkmcnt(2)
	s_nop 2
	v_add_f32_e32 v1, v41, v23
	v_mul_f32_e32 v1, 0xbfb8aa3b, v1
	v_exp_f32_e32 v1, v1
	s_nop 0
	v_add_f32_e32 v1, 1.0, v1
	v_rcp_f32_e32 v1, v1
	s_waitcnt lgkmcnt(1)
	v_add_f32_e32 v17, v17, v26
	v_mul_f32_e32 v17, 0xbfb8aa3b, v17
	v_exp_f32_e32 v17, v17
	s_waitcnt lgkmcnt(0)
	v_mul_f32_e32 v1, v1, v27
	v_mul_f32_e32 v1, 0xbfb8aa3b, v1
	v_exp_f32_e32 v18, v1
	v_add_f32_e32 v1, 1.0, v17
	v_rcp_f32_e32 v17, v1
	v_add_f32_e32 v16, v16, v26
	v_sub_f32_e32 v1, 1.0, v18
	v_add_f32_e32 v19, 1.0, v18
	v_mul_f32_e32 v1, v1, v19
	v_add_f32_e32 v19, v40, v23
	v_mul_f32_e32 v19, 0xbfb8aa3b, v19
	v_exp_f32_e32 v21, v19
	v_mul_f32_e32 v19, v28, v17
	v_mul_f32_e32 v16, 0xbfb8aa3b, v16
	v_sqrt_f32_e32 v1, v1
	v_add_f32_e32 v17, 1.0, v21
	v_rcp_f32_e32 v17, v17
	v_exp_f32_e32 v16, v16
	v_mul_f32_e32 v20, 0, v18
	v_pk_fma_f32 v[20:21], v[18:19], v[0:1], v[20:21] op_sel_hi:[1,1,0]
	v_mul_f32_e32 v17, v17, v27
	v_mul_f32_e32 v17, 0xbfb8aa3b, v17
	v_exp_f32_e32 v17, v17
	v_add_f32_e32 v1, 1.0, v16
	v_rcp_f32_e32 v16, v1
	v_mov_b32_e32 v43, v21
	v_sub_f32_e32 v1, 1.0, v17
	v_add_f32_e32 v19, 1.0, v17
	v_mul_f32_e32 v1, v1, v19
	v_add_f32_e32 v19, v39, v23
	v_mul_f32_e32 v19, 0xbfb8aa3b, v19
	v_sqrt_f32_e32 v1, v1
	v_exp_f32_e32 v19, v19
	v_pk_mul_f32 v[20:21], v[42:43], v[16:17]
	v_add_f32_e32 v15, v15, v26
	v_fmac_f32_e32 v21, v20, v1
	v_add_f32_e32 v1, 1.0, v19
	v_rcp_f32_e32 v1, v1
	v_mul_f32_e32 v15, 0xbfb8aa3b, v15
	v_exp_f32_e32 v15, v15
	v_add_f32_e32 v14, v14, v26
	v_mul_f32_e32 v1, v1, v27
	v_mul_f32_e32 v1, 0xbfb8aa3b, v1
	v_exp_f32_e32 v19, v1
	v_add_f32_e32 v15, 1.0, v15
	v_mul_f32_e32 v1, v18, v17
	v_rcp_f32_e32 v18, v15
	v_sub_f32_e32 v15, 1.0, v19
	v_add_f32_e32 v16, 1.0, v19
	v_mul_f32_e32 v15, v15, v16
	v_add_f32_e32 v16, v38, v23
	v_mul_f32_e32 v16, 0xbfb8aa3b, v16
	v_exp_f32_e32 v20, v16
	v_sqrt_f32_e32 v23, v15
	v_mul_f32_e32 v14, 0xbfb8aa3b, v14
	v_exp_f32_e32 v14, v14
	v_add_f32_e32 v15, 1.0, v20
	v_rcp_f32_e32 v15, v15
	v_mov_b32_e32 v37, v21
	v_pk_mul_f32 v[16:17], v[36:37], v[18:19]
	v_add_f32_e32 v14, 1.0, v14
	v_mul_f32_e32 v15, v15, v27
	v_mul_f32_e32 v15, 0xbfb8aa3b, v15
	v_exp_f32_e32 v15, v15
	v_fmac_f32_e32 v17, v16, v23
	v_rcp_f32_e32 v14, v14
	v_mov_b32_e32 v33, v17
	v_sub_f32_e32 v16, 1.0, v15
	v_add_f32_e32 v18, 1.0, v15
	v_mul_f32_e32 v16, v16, v18
	v_sqrt_f32_e32 v18, v16
	v_mul_f32_e32 v1, v19, v1
	v_pk_mul_f32 v[16:17], v[32:33], v[14:15]
	v_mul_f32_e32 v1, v15, v1
	v_fmac_f32_e32 v17, v16, v18
	ds_bpermute_b32 v14, v83, v1
	ds_bpermute_b32 v15, v83, v17
	s_waitcnt lgkmcnt(1)
	v_mul_f32_e32 v16, v1, v14
	s_waitcnt lgkmcnt(0)
	v_fma_f32 v1, v1, v15, v17
	v_fmac_f32_e32 v15, v17, v14
	v_cndmask_b32_e64 v1, v1, v15, s[46:47]
	ds_bpermute_b32 v15, v84, v16
	ds_bpermute_b32 v17, v84, v1
	s_waitcnt lgkmcnt(1)
	v_mul_f32_e32 v14, v16, v15
	s_waitcnt lgkmcnt(0)
	v_fma_f32 v16, v16, v17, v1
	v_fmac_f32_e32 v17, v1, v15
	v_cndmask_b32_e64 v15, v16, v17, s[48:49]
	ds_write_b64 v86, v[14:15] offset:63104
	s_waitcnt vmcnt(0) lgkmcnt(0)
	s_barrier
	s_and_saveexec_b64 s[12:13], s[50:51]
	s_cbranch_execz .LBB0_528
	ds_read_b64 v[14:15], v94 offset:58624
	ds_read_b64 v[16:17], v95 offset:58624
	ds_read_b64 v[18:19], v96 offset:58624
	ds_read_b64 v[20:21], v97 offset:58624
	s_waitcnt lgkmcnt(3)
	v_fma_f32 v1, 0, v14, v15
	s_waitcnt lgkmcnt(2)
	v_pk_mul_f32 v[14:15], v[14:15], v[16:17]
	v_fmac_f32_e32 v17, v16, v1
	s_waitcnt lgkmcnt(1)
	v_fma_f32 v1, v18, v17, v19
	ds_read_b64 v[16:17], v98 offset:58624
	ds_read_b64 v[26:27], v99 offset:58624
	ds_read_b64 v[28:29], v100 offset:58624
	ds_read_b64 v[30:31], v101 offset:58624
	s_waitcnt lgkmcnt(4)
	v_fma_f32 v1, v20, v1, v21
	v_mov_b32_e32 v32, v14
	v_mov_b32_e32 v34, v18
	s_waitcnt lgkmcnt(3)
	v_fma_f32 v33, v16, v1, v17
	s_waitcnt lgkmcnt(2)
	v_mov_b32_e32 v35, v26
	v_pk_mul_f32 v[14:15], v[14:15], v[18:19]
	v_pk_fma_f32 v[18:19], v[32:33], v[34:35], v[26:27]
	v_pk_mul_f32 v[14:15], v[14:15], v[20:21]
	s_waitcnt lgkmcnt(1)
	v_mov_b32_e32 v17, v28
	v_mov_b32_e32 v15, v19
	v_pk_mul_f32 v[18:19], v[14:15], v[16:17]
	v_pk_fma_f32 v[14:15], v[14:15], v[16:17], v[28:29]
	v_pk_mul_f32 v[18:19], v[18:19], v[26:27]
	v_mov_b32_e32 v16, v28
	v_mov_b32_e32 v14, v18
	s_waitcnt lgkmcnt(0)
	v_mov_b32_e32 v17, v30
	v_pk_mul_f32 v[18:19], v[18:19], v[28:29]
	v_pk_fma_f32 v[14:15], v[14:15], v[16:17], v[30:31]
	v_pk_mul_f32 v[18:19], v[18:19], v[30:31]
	s_nop 0
	v_mov_b32_e32 v19, v15
	v_mad_i64_i32 v[14:15], s[60:61], v87, s64, v[24:25]
	global_store_dwordx2 v[14:15], v[18:19], off
	s_branch .LBB0_528

; __device__ __forceinline__ unsigned pk2(float lo, float hi) { return f2bf(lo) | (f2bf(hi) << 16); }
; template <int NR>
; __device__ __forceinline__ void ln_rows(const _Float16* z, bf16* xb, float* st, float* outf, int m0, int stride, const float* g, const float* b, int lane, bool final_out) {
;     ...
;     for (int r = 0; r < NR; ++r) { const int m = m0 + r * stride; const float rstd = 1.f / sqrtf(s2[r] * (1.f / D) + LN_EPS);
;         if (!final_out && lane == 0) *(f32x2*)(st + 2 * (size_t)m) = (f32x2){mean[r], rstd};
;         f32x4* xr = (f32x4*)(outf + (size_t)m * D) + lane; unsigned long long* o8 = (unsigned long long*)(xb + (size_t)m * D) + lane;
; #pragma unroll
;         for (int j = 0; j < 4; ++j) { const f32x4 gg = ((const f32x4*)g)[lane + 64 * j], bb = ((const f32x4*)b)[lane + 64 * j];
;             const f32x4 y = v[r][j] * rstd * gg + bb;
;             if (final_out) xr[64 * j] = y;
;             else o8[64 * j] = (unsigned long long)pk2(y.x, y.y) | ((unsigned long long)pk2(y.z, y.w) << 32); } }
.LBB0_633:
	s_or_b64 exec, exec, s[0:1]
	s_nop 1
	v_mov_b64_e32 v[2:3], v[116:117]
	v_mov_b64_e32 v[4:5], v[118:119]
	v_mov_b64_e32 v[100:101], v[132:133]
	v_mov_b64_e32 v[102:103], v[134:135]
	v_pk_mul_f32 v[78:79], v[78:79], v[84:85] op_sel_hi:[1,0]
	v_pk_mul_f32 v[80:81], v[80:81], v[84:85] op_sel_hi:[1,0]
	v_lshl_add_u64 v[82:83], v[10:11], 0, s[54:55]
	s_mov_b64 s[0:1], -1
	s_and_b64 vcc, exec, s[8:9]
	v_pk_fma_f32 v[4:5], v[78:79], v[4:5], v[102:103]
	v_pk_fma_f32 v[2:3], v[80:81], v[2:3], v[100:101]
	s_cbranch_vccz .LBB0_635
	v_cvt_pk_bf16_f32 v78, v2, v3
	v_add3_u32 v80, v5, v80, s33
	v_cvt_pk_bf16_f32 v79, v4, v5
	flat_store_dwordx2 v[82:83], v[78:79]
	s_mov_b64 s[0:1], 0

; __device__ __forceinline__ unsigned pk2(float lo, float hi) { return f2bf(lo) | (f2bf(hi) << 16); }
; template <int NR>
; __device__ __forceinline__ void ln_rows(const _Float16* z, bf16* xb, float* st, float* outf, int m0, int stride, const float* g, const float* b, int lane, bool final_out) {
;     ...
;     for (int r = 0; r < NR; ++r) { const int m = m0 + r * stride; const float rstd = 1.f / sqrtf(s2[r] * (1.f / D) + LN_EPS);
;         if (!final_out && lane == 0) *(f32x2*)(st + 2 * (size_t)m) = (f32x2){mean[r], rstd};
;         f32x4* xr = (f32x4*)(outf + (size_t)m * D) + lane; unsigned long long* o8 = (unsigned long long*)(xb + (size_t)m * D) + lane;
; #pragma unroll
;         for (int j = 0; j < 4; ++j) { const f32x4 gg = ((const f32x4*)g)[lane + 64 * j], bb = ((const f32x4*)b)[lane + 64 * j];
;             const f32x4 y = v[r][j] * rstd * gg + bb;
;             if (final_out) xr[64 * j] = y;
;             else o8[64 * j] = (unsigned long long)pk2(y.x, y.y) | ((unsigned long long)pk2(y.z, y.w) << 32); } }
.LBB0_637:
	s_nop 1
	v_mov_b64_e32 v[2:3], v[120:121]
	v_mov_b64_e32 v[4:5], v[122:123]
	s_nop 0
	v_mov_b64_e32 v[100:101], v[136:137]
	v_mov_b64_e32 v[102:103], v[138:139]
	v_mov_b32_e32 v80, v84
	v_mov_b32_e32 v81, v84
	v_mov_b32_e32 v85, v84
	v_pk_mul_f32 v[74:75], v[74:75], v[80:81]
	v_pk_mul_f32 v[76:77], v[76:77], v[84:85]
	s_mov_b64 s[4:5], -1
	s_andn2_b64 vcc, exec, s[8:9]
	v_pk_fma_f32 v[4:5], v[74:75], v[4:5], v[102:103]
	v_cndmask_b32_e64 v74, 0, 1, s[8:9]
	v_pk_fma_f32 v[2:3], v[76:77], v[2:3], v[100:101]
	v_cmp_ne_u32_e64 s[0:1], 1, v74
	s_cbranch_vccnz .LBB0_639
	v_bfe_u32 v74, v2, 16, 1
	v_add3_u32 v74, v2, v74, s33
	v_bfe_u32 v75, v3, 16, 1
	v_lshrrev_b32_e32 v74, 16, v74
	v_cvt_pk_bf16_f32 v74, v2, v3
	v_add3_u32 v76, v5, v76, s33
	v_cvt_pk_bf16_f32 v75, v4, v5
	s_mov_b64 s[4:5], 0
	flat_store_dwordx2 v[82:83], v[74:75] offset:512

; __device__ __forceinline__ unsigned pk2(float lo, float hi) { return f2bf(lo) | (f2bf(hi) << 16); }
; template <int NR>
; __device__ __forceinline__ void ln_rows(const _Float16* z, bf16* xb, float* st, float* outf, int m0, int stride, const float* g, const float* b, int lane, bool final_out) {
;     ...
;     for (int r = 0; r < NR; ++r) { const int m = m0 + r * stride; const float rstd = 1.f / sqrtf(s2[r] * (1.f / D) + LN_EPS);
;         if (!final_out && lane == 0) *(f32x2*)(st + 2 * (size_t)m) = (f32x2){mean[r], rstd};
;         f32x4* xr = (f32x4*)(outf + (size_t)m * D) + lane; unsigned long long* o8 = (unsigned long long*)(xb + (size_t)m * D) + lane;
; #pragma unroll
;         for (int j = 0; j < 4; ++j) { const f32x4 gg = ((const f32x4*)g)[lane + 64 * j], bb = ((const f32x4*)b)[lane + 64 * j];
;             const f32x4 y = v[r][j] * rstd * gg + bb;
;             if (final_out) xr[64 * j] = y;
;             else o8[64 * j] = (unsigned long long)pk2(y.x, y.y) | ((unsigned long long)pk2(y.z, y.w) << 32); } }
.LBB0_641:
	s_nop 1
	v_mov_b64_e32 v[2:3], v[124:125]
	v_mov_b64_e32 v[4:5], v[126:127]
	s_nop 0
	v_mov_b64_e32 v[74:75], v[140:141]
	v_mov_b64_e32 v[76:77], v[142:143]
	v_mov_b32_e32 v80, v84
	v_mov_b32_e32 v81, v84
	v_pk_mul_f32 v[72:73], v[72:73], v[84:85]
	v_pk_mul_f32 v[70:71], v[70:71], v[80:81]
	s_and_b64 vcc, exec, s[0:1]
	s_mov_b64 s[4:5], -1
	v_pk_fma_f32 v[4:5], v[70:71], v[4:5], v[76:77]
	v_pk_fma_f32 v[2:3], v[72:73], v[2:3], v[74:75]
	s_cbranch_vccnz .LBB0_643
	v_cvt_pk_bf16_f32 v70, v2, v3
	v_add3_u32 v72, v5, v72, s33
	v_cvt_pk_bf16_f32 v71, v4, v5
	s_mov_b64 s[4:5], 0
	flat_store_dwordx2 v[82:83], v[70:71] offset:1024

; __device__ __forceinline__ unsigned pk2(float lo, float hi) { return f2bf(lo) | (f2bf(hi) << 16); }
; template <int NR>
; __device__ __forceinline__ void ln_rows(const _Float16* z, bf16* xb, float* st, float* outf, int m0, int stride, const float* g, const float* b, int lane, bool final_out) {
;     ...
;     for (int r = 0; r < NR; ++r) { const int m = m0 + r * stride; const float rstd = 1.f / sqrtf(s2[r] * (1.f / D) + LN_EPS);
;         if (!final_out && lane == 0) *(f32x2*)(st + 2 * (size_t)m) = (f32x2){mean[r], rstd};
;         f32x4* xr = (f32x4*)(outf + (size_t)m * D) + lane; unsigned long long* o8 = (unsigned long long*)(xb + (size_t)m * D) + lane;
; #pragma unroll
;         for (int j = 0; j < 4; ++j) { const f32x4 gg = ((const f32x4*)g)[lane + 64 * j], bb = ((const f32x4*)b)[lane + 64 * j];
;             const f32x4 y = v[r][j] * rstd * gg + bb;
;             if (final_out) xr[64 * j] = y;
;             else o8[64 * j] = (unsigned long long)pk2(y.x, y.y) | ((unsigned long long)pk2(y.z, y.w) << 32); } }
.LBB0_645:
	s_nop 1
	v_mov_b64_e32 v[2:3], v[128:129]
	v_mov_b64_e32 v[4:5], v[130:131]
	s_nop 0
	v_mov_b64_e32 v[70:71], v[144:145]
	v_mov_b64_e32 v[72:73], v[146:147]
	v_mov_b32_e32 v74, v84
	v_mov_b32_e32 v75, v84
	v_pk_mul_f32 v[68:69], v[68:69], v[84:85]
	v_pk_mul_f32 v[66:67], v[66:67], v[74:75]
	s_and_b64 vcc, exec, s[0:1]
	s_mov_b64 s[4:5], -1
	v_pk_fma_f32 v[4:5], v[66:67], v[4:5], v[72:73]
	v_pk_fma_f32 v[2:3], v[68:69], v[2:3], v[70:71]
	s_cbranch_vccnz .LBB0_647
	v_cvt_pk_bf16_f32 v66, v2, v3
	v_add3_u32 v68, v5, v68, s33
	v_cvt_pk_bf16_f32 v67, v4, v5
	s_mov_b64 s[4:5], 0
	flat_store_dwordx2 v[82:83], v[66:67] offset:1536

; __device__ __forceinline__ unsigned pk2(float lo, float hi) { return f2bf(lo) | (f2bf(hi) << 16); }
; template <int NR>
; __device__ __forceinline__ void ln_rows(const _Float16* z, bf16* xb, float* st, float* outf, int m0, int stride, const float* g, const float* b, int lane, bool final_out) {
;     ...
;     for (int r = 0; r < NR; ++r) { const int m = m0 + r * stride; const float rstd = 1.f / sqrtf(s2[r] * (1.f / D) + LN_EPS);
;         if (!final_out && lane == 0) *(f32x2*)(st + 2 * (size_t)m) = (f32x2){mean[r], rstd};
;         f32x4* xr = (f32x4*)(outf + (size_t)m * D) + lane; unsigned long long* o8 = (unsigned long long*)(xb + (size_t)m * D) + lane;
; #pragma unroll
;         for (int j = 0; j < 4; ++j) { const f32x4 gg = ((const f32x4*)g)[lane + 64 * j], bb = ((const f32x4*)b)[lane + 64 * j];
;             const f32x4 y = v[r][j] * rstd * gg + bb;
;             if (final_out) xr[64 * j] = y;
;             else o8[64 * j] = (unsigned long long)pk2(y.x, y.y) | ((unsigned long long)pk2(y.z, y.w) << 32); } }
.LBB0_651:
	s_or_b64 exec, exec, s[4:5]
	s_nop 1
	v_mov_b64_e32 v[2:3], v[116:117]
	v_mov_b64_e32 v[4:5], v[118:119]
	v_mov_b64_e32 v[70:71], v[132:133]
	v_mov_b64_e32 v[72:73], v[134:135]
	v_pk_mul_f32 v[62:63], v[62:63], v[68:69] op_sel_hi:[1,0]
	v_pk_mul_f32 v[64:65], v[64:65], v[68:69] op_sel_hi:[1,0]
	v_lshl_add_u64 v[66:67], v[10:11], 0, s[52:53]
	s_and_b64 vcc, exec, s[0:1]
	s_mov_b64 s[4:5], -1
	v_pk_fma_f32 v[4:5], v[62:63], v[4:5], v[72:73]
	v_pk_fma_f32 v[2:3], v[64:65], v[2:3], v[70:71]
	s_cbranch_vccnz .LBB0_653
	v_cvt_pk_bf16_f32 v62, v2, v3
	v_add3_u32 v64, v5, v64, s33
	v_cvt_pk_bf16_f32 v63, v4, v5
	s_mov_b64 s[4:5], 0
	flat_store_dwordx2 v[66:67], v[62:63]

; __device__ __forceinline__ unsigned pk2(float lo, float hi) { return f2bf(lo) | (f2bf(hi) << 16); }
; template <int NR>
; __device__ __forceinline__ void ln_rows(const _Float16* z, bf16* xb, float* st, float* outf, int m0, int stride, const float* g, const float* b, int lane, bool final_out) {
;     ...
;     for (int r = 0; r < NR; ++r) { const int m = m0 + r * stride; const float rstd = 1.f / sqrtf(s2[r] * (1.f / D) + LN_EPS);
;         if (!final_out && lane == 0) *(f32x2*)(st + 2 * (size_t)m) = (f32x2){mean[r], rstd};
;         f32x4* xr = (f32x4*)(outf + (size_t)m * D) + lane; unsigned long long* o8 = (unsigned long long*)(xb + (size_t)m * D) + lane;
; #pragma unroll
;         for (int j = 0; j < 4; ++j) { const f32x4 gg = ((const f32x4*)g)[lane + 64 * j], bb = ((const f32x4*)b)[lane + 64 * j];
;             const f32x4 y = v[r][j] * rstd * gg + bb;
;             if (final_out) xr[64 * j] = y;
;             else o8[64 * j] = (unsigned long long)pk2(y.x, y.y) | ((unsigned long long)pk2(y.z, y.w) << 32); } }
.LBB0_655:
	s_nop 1
	v_mov_b64_e32 v[2:3], v[120:121]
	v_mov_b64_e32 v[4:5], v[122:123]
	s_nop 0
	v_mov_b64_e32 v[70:71], v[136:137]
	v_mov_b64_e32 v[72:73], v[138:139]
	v_mov_b32_e32 v69, v68
	v_mov_b32_e32 v64, v68
	v_mov_b32_e32 v65, v68
	v_pk_mul_f32 v[58:59], v[58:59], v[64:65]
	v_pk_mul_f32 v[60:61], v[60:61], v[68:69]
	s_and_b64 vcc, exec, s[0:1]
	s_mov_b64 s[4:5], -1
	v_pk_fma_f32 v[4:5], v[58:59], v[4:5], v[72:73]
	v_pk_fma_f32 v[2:3], v[60:61], v[2:3], v[70:71]
	s_cbranch_vccnz .LBB0_657
	v_cvt_pk_bf16_f32 v58, v2, v3
	v_add3_u32 v60, v5, v60, s33
	v_cvt_pk_bf16_f32 v59, v4, v5
	s_mov_b64 s[4:5], 0
	flat_store_dwordx2 v[66:67], v[58:59] offset:512

; __device__ __forceinline__ unsigned pk2(float lo, float hi) { return f2bf(lo) | (f2bf(hi) << 16); }
; template <int NR>
; __device__ __forceinline__ void ln_rows(const _Float16* z, bf16* xb, float* st, float* outf, int m0, int stride, const float* g, const float* b, int lane, bool final_out) {
;     ...
;     for (int r = 0; r < NR; ++r) { const int m = m0 + r * stride; const float rstd = 1.f / sqrtf(s2[r] * (1.f / D) + LN_EPS);
;         if (!final_out && lane == 0) *(f32x2*)(st + 2 * (size_t)m) = (f32x2){mean[r], rstd};
;         f32x4* xr = (f32x4*)(outf + (size_t)m * D) + lane; unsigned long long* o8 = (unsigned long long*)(xb + (size_t)m * D) + lane;
; #pragma unroll
;         for (int j = 0; j < 4; ++j) { const f32x4 gg = ((const f32x4*)g)[lane + 64 * j], bb = ((const f32x4*)b)[lane + 64 * j];
;             const f32x4 y = v[r][j] * rstd * gg + bb;
;             if (final_out) xr[64 * j] = y;
;             else o8[64 * j] = (unsigned long long)pk2(y.x, y.y) | ((unsigned long long)pk2(y.z, y.w) << 32); } }
.LBB0_659:
	s_nop 1
	v_mov_b64_e32 v[2:3], v[124:125]
	v_mov_b64_e32 v[4:5], v[126:127]
	s_nop 0
	v_mov_b64_e32 v[58:59], v[140:141]
	v_mov_b64_e32 v[60:61], v[142:143]
	v_mov_b32_e32 v64, v68
	v_mov_b32_e32 v65, v68
	v_pk_mul_f32 v[56:57], v[56:57], v[68:69]
	v_pk_mul_f32 v[54:55], v[54:55], v[64:65]
	s_and_b64 vcc, exec, s[0:1]
	s_mov_b64 s[4:5], -1
	v_pk_fma_f32 v[4:5], v[54:55], v[4:5], v[60:61]
	v_pk_fma_f32 v[2:3], v[56:57], v[2:3], v[58:59]
	s_cbranch_vccnz .LBB0_661
	v_cvt_pk_bf16_f32 v54, v2, v3
	v_add3_u32 v56, v5, v56, s33
	v_cvt_pk_bf16_f32 v55, v4, v5
	s_mov_b64 s[4:5], 0
	flat_store_dwordx2 v[66:67], v[54:55] offset:1024

; __device__ __forceinline__ unsigned pk2(float lo, float hi) { return f2bf(lo) | (f2bf(hi) << 16); }
; template <int NR>
; __device__ __forceinline__ void ln_rows(const _Float16* z, bf16* xb, float* st, float* outf, int m0, int stride, const float* g, const float* b, int lane, bool final_out) {
;     ...
;     for (int r = 0; r < NR; ++r) { const int m = m0 + r * stride; const float rstd = 1.f / sqrtf(s2[r] * (1.f / D) + LN_EPS);
;         if (!final_out && lane == 0) *(f32x2*)(st + 2 * (size_t)m) = (f32x2){mean[r], rstd};
;         f32x4* xr = (f32x4*)(outf + (size_t)m * D) + lane; unsigned long long* o8 = (unsigned long long*)(xb + (size_t)m * D) + lane;
; #pragma unroll
;         for (int j = 0; j < 4; ++j) { const f32x4 gg = ((const f32x4*)g)[lane + 64 * j], bb = ((const f32x4*)b)[lane + 64 * j];
;             const f32x4 y = v[r][j] * rstd * gg + bb;
;             if (final_out) xr[64 * j] = y;
;             else o8[64 * j] = (unsigned long long)pk2(y.x, y.y) | ((unsigned long long)pk2(y.z, y.w) << 32); } }
.LBB0_663:
	s_nop 1
	v_mov_b64_e32 v[2:3], v[128:129]
	v_mov_b64_e32 v[4:5], v[130:131]
	s_nop 0
	v_mov_b64_e32 v[54:55], v[144:145]
	v_mov_b64_e32 v[56:57], v[146:147]
	v_mov_b32_e32 v58, v68
	v_mov_b32_e32 v59, v68
	v_pk_mul_f32 v[52:53], v[52:53], v[68:69]
	v_pk_mul_f32 v[50:51], v[50:51], v[58:59]
	s_and_b64 vcc, exec, s[0:1]
	s_mov_b64 s[4:5], -1
	v_pk_fma_f32 v[4:5], v[50:51], v[4:5], v[56:57]
	v_pk_fma_f32 v[2:3], v[52:53], v[2:3], v[54:55]
	s_cbranch_vccnz .LBB0_665
	v_cvt_pk_bf16_f32 v50, v2, v3
	v_add3_u32 v52, v5, v52, s33
	v_cvt_pk_bf16_f32 v51, v4, v5
	s_mov_b64 s[4:5], 0
	flat_store_dwordx2 v[66:67], v[50:51] offset:1536

; __device__ __forceinline__ unsigned pk2(float lo, float hi) { return f2bf(lo) | (f2bf(hi) << 16); }
; template <int NR>
; __device__ __forceinline__ void ln_rows(const _Float16* z, bf16* xb, float* st, float* outf, int m0, int stride, const float* g, const float* b, int lane, bool final_out) {
;     ...
;     for (int r = 0; r < NR; ++r) { const int m = m0 + r * stride; const float rstd = 1.f / sqrtf(s2[r] * (1.f / D) + LN_EPS);
;         if (!final_out && lane == 0) *(f32x2*)(st + 2 * (size_t)m) = (f32x2){mean[r], rstd};
;         f32x4* xr = (f32x4*)(outf + (size_t)m * D) + lane; unsigned long long* o8 = (unsigned long long*)(xb + (size_t)m * D) + lane;
; #pragma unroll
;         for (int j = 0; j < 4; ++j) { const f32x4 gg = ((const f32x4*)g)[lane + 64 * j], bb = ((const f32x4*)b)[lane + 64 * j];
;             const f32x4 y = v[r][j] * rstd * gg + bb;
;             if (final_out) xr[64 * j] = y;
;             else o8[64 * j] = (unsigned long long)pk2(y.x, y.y) | ((unsigned long long)pk2(y.z, y.w) << 32); } }
.LBB0_669:
	s_or_b64 exec, exec, s[4:5]
	s_nop 1
	v_mov_b64_e32 v[2:3], v[116:117]
	v_mov_b64_e32 v[4:5], v[118:119]
	v_mov_b64_e32 v[54:55], v[132:133]
	v_mov_b64_e32 v[56:57], v[134:135]
	v_pk_mul_f32 v[46:47], v[46:47], v[52:53] op_sel_hi:[1,0]
	v_pk_mul_f32 v[48:49], v[48:49], v[52:53] op_sel_hi:[1,0]
	v_lshl_add_u64 v[50:51], v[10:11], 0, s[50:51]
	s_and_b64 vcc, exec, s[0:1]
	s_mov_b64 s[4:5], -1
	v_pk_fma_f32 v[4:5], v[46:47], v[4:5], v[56:57]
	v_pk_fma_f32 v[2:3], v[48:49], v[2:3], v[54:55]
	s_cbranch_vccnz .LBB0_671
	v_cvt_pk_bf16_f32 v46, v2, v3
	v_add3_u32 v48, v5, v48, s33
	v_cvt_pk_bf16_f32 v47, v4, v5
	s_mov_b64 s[4:5], 0
	flat_store_dwordx2 v[50:51], v[46:47]

; __device__ __forceinline__ unsigned pk2(float lo, float hi) { return f2bf(lo) | (f2bf(hi) << 16); }
; template <int NR>
; __device__ __forceinline__ void ln_rows(const _Float16* z, bf16* xb, float* st, float* outf, int m0, int stride, const float* g, const float* b, int lane, bool final_out) {
;     ...
;     for (int r = 0; r < NR; ++r) { const int m = m0 + r * stride; const float rstd = 1.f / sqrtf(s2[r] * (1.f / D) + LN_EPS);
;         if (!final_out && lane == 0) *(f32x2*)(st + 2 * (size_t)m) = (f32x2){mean[r], rstd};
;         f32x4* xr = (f32x4*)(outf + (size_t)m * D) + lane; unsigned long long* o8 = (unsigned long long*)(xb + (size_t)m * D) + lane;
; #pragma unroll
;         for (int j = 0; j < 4; ++j) { const f32x4 gg = ((const f32x4*)g)[lane + 64 * j], bb = ((const f32x4*)b)[lane + 64 * j];
;             const f32x4 y = v[r][j] * rstd * gg + bb;
;             if (final_out) xr[64 * j] = y;
;             else o8[64 * j] = (unsigned long long)pk2(y.x, y.y) | ((unsigned long long)pk2(y.z, y.w) << 32); } }
.LBB0_673:
	s_nop 1
	v_mov_b64_e32 v[2:3], v[120:121]
	v_mov_b64_e32 v[4:5], v[122:123]
	s_nop 0
	v_mov_b64_e32 v[54:55], v[136:137]
	v_mov_b64_e32 v[56:57], v[138:139]
	v_mov_b32_e32 v53, v52
	v_mov_b32_e32 v48, v52
	v_mov_b32_e32 v49, v52
	v_pk_mul_f32 v[42:43], v[42:43], v[48:49]
	v_pk_mul_f32 v[44:45], v[44:45], v[52:53]
	s_and_b64 vcc, exec, s[0:1]
	s_mov_b64 s[4:5], -1
	v_pk_fma_f32 v[4:5], v[42:43], v[4:5], v[56:57]
	v_pk_fma_f32 v[2:3], v[44:45], v[2:3], v[54:55]
	s_cbranch_vccnz .LBB0_675
	v_cvt_pk_bf16_f32 v42, v2, v3
	v_add3_u32 v44, v5, v44, s33
	v_cvt_pk_bf16_f32 v43, v4, v5
	s_mov_b64 s[4:5], 0
	flat_store_dwordx2 v[50:51], v[42:43] offset:512

; __device__ __forceinline__ unsigned pk2(float lo, float hi) { return f2bf(lo) | (f2bf(hi) << 16); }
; template <int NR>
; __device__ __forceinline__ void ln_rows(const _Float16* z, bf16* xb, float* st, float* outf, int m0, int stride, const float* g, const float* b, int lane, bool final_out) {
;     ...
;     for (int r = 0; r < NR; ++r) { const int m = m0 + r * stride; const float rstd = 1.f / sqrtf(s2[r] * (1.f / D) + LN_EPS);
;         if (!final_out && lane == 0) *(f32x2*)(st + 2 * (size_t)m) = (f32x2){mean[r], rstd};
;         f32x4* xr = (f32x4*)(outf + (size_t)m * D) + lane; unsigned long long* o8 = (unsigned long long*)(xb + (size_t)m * D) + lane;
; #pragma unroll
;         for (int j = 0; j < 4; ++j) { const f32x4 gg = ((const f32x4*)g)[lane + 64 * j], bb = ((const f32x4*)b)[lane + 64 * j];
;             const f32x4 y = v[r][j] * rstd * gg + bb;
;             if (final_out) xr[64 * j] = y;
;             else o8[64 * j] = (unsigned long long)pk2(y.x, y.y) | ((unsigned long long)pk2(y.z, y.w) << 32); } }
.LBB0_677:
	s_nop 1
	v_mov_b64_e32 v[2:3], v[124:125]
	v_mov_b64_e32 v[4:5], v[126:127]
	s_nop 0
	v_mov_b64_e32 v[42:43], v[140:141]
	v_mov_b64_e32 v[44:45], v[142:143]
	v_mov_b32_e32 v48, v52
	v_mov_b32_e32 v49, v52
	v_pk_mul_f32 v[40:41], v[40:41], v[52:53]
	v_pk_mul_f32 v[38:39], v[38:39], v[48:49]
	s_and_b64 vcc, exec, s[0:1]
	s_mov_b64 s[4:5], -1
	v_pk_fma_f32 v[4:5], v[38:39], v[4:5], v[44:45]
	v_pk_fma_f32 v[2:3], v[40:41], v[2:3], v[42:43]
	s_cbranch_vccnz .LBB0_679
	v_cvt_pk_bf16_f32 v38, v2, v3
	v_add3_u32 v40, v5, v40, s33
	v_cvt_pk_bf16_f32 v39, v4, v5
	s_mov_b64 s[4:5], 0
	flat_store_dwordx2 v[50:51], v[38:39] offset:1024

; __device__ __forceinline__ unsigned pk2(float lo, float hi) { return f2bf(lo) | (f2bf(hi) << 16); }
; template <int NR>
; __device__ __forceinline__ void ln_rows(const _Float16* z, bf16* xb, float* st, float* outf, int m0, int stride, const float* g, const float* b, int lane, bool final_out) {
;     ...
;     for (int r = 0; r < NR; ++r) { const int m = m0 + r * stride; const float rstd = 1.f / sqrtf(s2[r] * (1.f / D) + LN_EPS);
;         if (!final_out && lane == 0) *(f32x2*)(st + 2 * (size_t)m) = (f32x2){mean[r], rstd};
;         f32x4* xr = (f32x4*)(outf + (size_t)m * D) + lane; unsigned long long* o8 = (unsigned long long*)(xb + (size_t)m * D) + lane;
; #pragma unroll
;         for (int j = 0; j < 4; ++j) { const f32x4 gg = ((const f32x4*)g)[lane + 64 * j], bb = ((const f32x4*)b)[lane + 64 * j];
;             const f32x4 y = v[r][j] * rstd * gg + bb;
;             if (final_out) xr[64 * j] = y;
;             else o8[64 * j] = (unsigned long long)pk2(y.x, y.y) | ((unsigned long long)pk2(y.z, y.w) << 32); } }
.LBB0_681:
	s_nop 1
	v_mov_b64_e32 v[2:3], v[128:129]
	v_mov_b64_e32 v[4:5], v[130:131]
	s_nop 0
	v_mov_b64_e32 v[38:39], v[144:145]
	v_mov_b64_e32 v[40:41], v[146:147]
	v_mov_b32_e32 v42, v52
	v_mov_b32_e32 v43, v52
	v_pk_mul_f32 v[36:37], v[36:37], v[52:53]
	v_pk_mul_f32 v[34:35], v[34:35], v[42:43]
	s_and_b64 vcc, exec, s[0:1]
	s_mov_b64 s[4:5], -1
	v_pk_fma_f32 v[4:5], v[34:35], v[4:5], v[40:41]
	v_pk_fma_f32 v[2:3], v[36:37], v[2:3], v[38:39]
	s_cbranch_vccnz .LBB0_683
	v_cvt_pk_bf16_f32 v34, v2, v3
	v_add3_u32 v36, v5, v36, s33
	v_cvt_pk_bf16_f32 v35, v4, v5
	s_mov_b64 s[4:5], 0
	flat_store_dwordx2 v[50:51], v[34:35] offset:1536

; __device__ __forceinline__ unsigned pk2(float lo, float hi) { return f2bf(lo) | (f2bf(hi) << 16); }
; template <int NR>
; __device__ __forceinline__ void ln_rows(const _Float16* z, bf16* xb, float* st, float* outf, int m0, int stride, const float* g, const float* b, int lane, bool final_out) {
;     ...
;     for (int r = 0; r < NR; ++r) { const int m = m0 + r * stride; const float rstd = 1.f / sqrtf(s2[r] * (1.f / D) + LN_EPS);
;         if (!final_out && lane == 0) *(f32x2*)(st + 2 * (size_t)m) = (f32x2){mean[r], rstd};
;         f32x4* xr = (f32x4*)(outf + (size_t)m * D) + lane; unsigned long long* o8 = (unsigned long long*)(xb + (size_t)m * D) + lane;
; #pragma unroll
;         for (int j = 0; j < 4; ++j) { const f32x4 gg = ((const f32x4*)g)[lane + 64 * j], bb = ((const f32x4*)b)[lane + 64 * j];
;             const f32x4 y = v[r][j] * rstd * gg + bb;
;             if (final_out) xr[64 * j] = y;
;             else o8[64 * j] = (unsigned long long)pk2(y.x, y.y) | ((unsigned long long)pk2(y.z, y.w) << 32); } }
.LBB0_687:
	s_or_b64 exec, exec, s[4:5]
	s_nop 1
	v_mov_b64_e32 v[2:3], v[116:117]
	v_mov_b64_e32 v[4:5], v[118:119]
	v_mov_b64_e32 v[38:39], v[132:133]
	v_mov_b64_e32 v[40:41], v[134:135]
	v_pk_mul_f32 v[30:31], v[30:31], v[36:37] op_sel_hi:[1,0]
	v_pk_mul_f32 v[32:33], v[32:33], v[36:37] op_sel_hi:[1,0]
	v_lshl_add_u64 v[34:35], v[10:11], 0, s[46:47]
	s_and_b64 vcc, exec, s[0:1]
	s_mov_b64 s[4:5], -1
	v_pk_fma_f32 v[4:5], v[30:31], v[4:5], v[40:41]
	v_pk_fma_f32 v[2:3], v[32:33], v[2:3], v[38:39]
	s_cbranch_vccnz .LBB0_689
	v_cvt_pk_bf16_f32 v30, v2, v3
	v_lshrrev_b32_e32 v7, 16, v7
	v_cvt_pk_bf16_f32 v31, v4, v5
	s_mov_b64 s[4:5], 0
	flat_store_dwordx2 v[34:35], v[30:31]

; __device__ __forceinline__ unsigned pk2(float lo, float hi) { return f2bf(lo) | (f2bf(hi) << 16); }
; template <int NR>
; __device__ __forceinline__ void ln_rows(const _Float16* z, bf16* xb, float* st, float* outf, int m0, int stride, const float* g, const float* b, int lane, bool final_out) {
;     ...
;     for (int r = 0; r < NR; ++r) { const int m = m0 + r * stride; const float rstd = 1.f / sqrtf(s2[r] * (1.f / D) + LN_EPS);
;         if (!final_out && lane == 0) *(f32x2*)(st + 2 * (size_t)m) = (f32x2){mean[r], rstd};
;         f32x4* xr = (f32x4*)(outf + (size_t)m * D) + lane; unsigned long long* o8 = (unsigned long long*)(xb + (size_t)m * D) + lane;
; #pragma unroll
;         for (int j = 0; j < 4; ++j) { const f32x4 gg = ((const f32x4*)g)[lane + 64 * j], bb = ((const f32x4*)b)[lane + 64 * j];
;             const f32x4 y = v[r][j] * rstd * gg + bb;
;             if (final_out) xr[64 * j] = y;
;             else o8[64 * j] = (unsigned long long)pk2(y.x, y.y) | ((unsigned long long)pk2(y.z, y.w) << 32); } }
.LBB0_691:
	s_nop 1
	v_mov_b64_e32 v[2:3], v[120:121]
	v_mov_b64_e32 v[4:5], v[122:123]
	s_nop 0
	v_mov_b64_e32 v[38:39], v[136:137]
	v_mov_b64_e32 v[40:41], v[138:139]
	v_mov_b32_e32 v37, v36
	v_mov_b32_e32 v32, v36
	v_mov_b32_e32 v33, v36
	v_pk_mul_f32 v[26:27], v[26:27], v[32:33]
	v_pk_mul_f32 v[28:29], v[28:29], v[36:37]
	s_and_b64 vcc, exec, s[0:1]
	s_mov_b64 s[4:5], -1
	v_pk_fma_f32 v[4:5], v[26:27], v[4:5], v[40:41]
	v_pk_fma_f32 v[2:3], v[28:29], v[2:3], v[38:39]
	s_cbranch_vccnz .LBB0_693
	v_cvt_pk_bf16_f32 v26, v2, v3
	v_lshrrev_b32_e32 v7, 16, v7
	v_add3_u32 v27, v5, v27, s33
	v_cvt_pk_bf16_f32 v27, v4, v5
	s_mov_b64 s[4:5], 0
	flat_store_dwordx2 v[34:35], v[26:27] offset:512

; __device__ __forceinline__ unsigned pk2(float lo, float hi) { return f2bf(lo) | (f2bf(hi) << 16); }
; template <int NR>
; __device__ __forceinline__ void ln_rows(const _Float16* z, bf16* xb, float* st, float* outf, int m0, int stride, const float* g, const float* b, int lane, bool final_out) {
;     ...
;     for (int r = 0; r < NR; ++r) { const int m = m0 + r * stride; const float rstd = 1.f / sqrtf(s2[r] * (1.f / D) + LN_EPS);
;         if (!final_out && lane == 0) *(f32x2*)(st + 2 * (size_t)m) = (f32x2){mean[r], rstd};
;         f32x4* xr = (f32x4*)(outf + (size_t)m * D) + lane; unsigned long long* o8 = (unsigned long long*)(xb + (size_t)m * D) + lane;
; #pragma unroll
;         for (int j = 0; j < 4; ++j) { const f32x4 gg = ((const f32x4*)g)[lane + 64 * j], bb = ((const f32x4*)b)[lane + 64 * j];
;             const f32x4 y = v[r][j] * rstd * gg + bb;
;             if (final_out) xr[64 * j] = y;
;             else o8[64 * j] = (unsigned long long)pk2(y.x, y.y) | ((unsigned long long)pk2(y.z, y.w) << 32); } }
.LBB0_695:
	s_nop 1
	v_mov_b64_e32 v[2:3], v[124:125]
	v_mov_b64_e32 v[4:5], v[126:127]
	s_nop 0
	v_mov_b64_e32 v[26:27], v[140:141]
	v_mov_b64_e32 v[28:29], v[142:143]
	v_mov_b32_e32 v32, v36
	v_mov_b32_e32 v33, v36
	v_pk_mul_f32 v[24:25], v[24:25], v[36:37]
	v_pk_mul_f32 v[22:23], v[22:23], v[32:33]
	s_and_b64 vcc, exec, s[0:1]
	s_mov_b64 s[4:5], -1
	v_pk_fma_f32 v[4:5], v[22:23], v[4:5], v[28:29]
	v_pk_fma_f32 v[2:3], v[24:25], v[2:3], v[26:27]
	s_cbranch_vccnz .LBB0_697
	v_cvt_pk_bf16_f32 v22, v2, v3
	v_lshrrev_b32_e32 v7, 16, v7
	v_add3_u32 v23, v5, v23, s33
	v_cvt_pk_bf16_f32 v23, v4, v5
	s_mov_b64 s[4:5], 0
	flat_store_dwordx2 v[34:35], v[22:23] offset:1024

; __device__ __forceinline__ unsigned pk2(float lo, float hi) { return f2bf(lo) | (f2bf(hi) << 16); }
; template <int NR>
; __device__ __forceinline__ void ln_rows(const _Float16* z, bf16* xb, float* st, float* outf, int m0, int stride, const float* g, const float* b, int lane, bool final_out) {
;     ...
;     for (int r = 0; r < NR; ++r) { const int m = m0 + r * stride; const float rstd = 1.f / sqrtf(s2[r] * (1.f / D) + LN_EPS);
;         if (!final_out && lane == 0) *(f32x2*)(st + 2 * (size_t)m) = (f32x2){mean[r], rstd};
;         f32x4* xr = (f32x4*)(outf + (size_t)m * D) + lane; unsigned long long* o8 = (unsigned long long*)(xb + (size_t)m * D) + lane;
; #pragma unroll
;         for (int j = 0; j < 4; ++j) { const f32x4 gg = ((const f32x4*)g)[lane + 64 * j], bb = ((const f32x4*)b)[lane + 64 * j];
;             const f32x4 y = v[r][j] * rstd * gg + bb;
;             if (final_out) xr[64 * j] = y;
;             else o8[64 * j] = (unsigned long long)pk2(y.x, y.y) | ((unsigned long long)pk2(y.z, y.w) << 32); } }
.LBB0_699:
	s_nop 1
	v_mov_b64_e32 v[2:3], v[128:129]
	v_mov_b64_e32 v[4:5], v[130:131]
	s_nop 0
	v_mov_b64_e32 v[22:23], v[144:145]
	v_mov_b64_e32 v[24:25], v[146:147]
	v_mov_b32_e32 v26, v36
	v_mov_b32_e32 v27, v36
	v_pk_mul_f32 v[20:21], v[20:21], v[36:37]
	v_pk_mul_f32 v[18:19], v[18:19], v[26:27]
	s_and_b64 vcc, exec, s[0:1]
	s_mov_b64 s[0:1], -1
	v_pk_fma_f32 v[4:5], v[18:19], v[4:5], v[24:25]
	v_pk_fma_f32 v[2:3], v[20:21], v[2:3], v[22:23]
	s_cbranch_vccnz .LBB0_701
	v_cvt_pk_bf16_f32 v18, v2, v3
	v_lshrrev_b32_e32 v7, 16, v7
	v_add3_u32 v19, v5, v19, s33
	v_cvt_pk_bf16_f32 v19, v4, v5
	s_mov_b64 s[0:1], 0
	flat_store_dwordx2 v[34:35], v[18:19] offset:1536

; __device__ __forceinline__ unsigned pk2(float lo, float hi) { return f2bf(lo) | (f2bf(hi) << 16); }
; template <int NR>
; __device__ __forceinline__ void ln_rows(const _Float16* z, bf16* xb, float* st, float* outf, int m0, int stride, const float* g, const float* b, int lane, bool final_out) {
;     ...
;     for (int r = 0; r < NR; ++r) { const int m = m0 + r * stride; const float rstd = 1.f / sqrtf(s2[r] * (1.f / D) + LN_EPS);
;         if (!final_out && lane == 0) *(f32x2*)(st + 2 * (size_t)m) = (f32x2){mean[r], rstd};
;         f32x4* xr = (f32x4*)(outf + (size_t)m * D) + lane; unsigned long long* o8 = (unsigned long long*)(xb + (size_t)m * D) + lane;
; #pragma unroll
;         for (int j = 0; j < 4; ++j) { const f32x4 gg = ((const f32x4*)g)[lane + 64 * j], bb = ((const f32x4*)b)[lane + 64 * j];
;             const f32x4 y = v[r][j] * rstd * gg + bb;
;             if (final_out) xr[64 * j] = y;
;             else o8[64 * j] = (unsigned long long)pk2(y.x, y.y) | ((unsigned long long)pk2(y.z, y.w) << 32); } }
.LBB0_708:
	s_or_b64 exec, exec, s[0:1]
	global_load_dwordx4 v[36:39], v[8:9], off
	global_load_dwordx4 v[40:43], v[10:11], off
	v_pk_mul_f32 v[2:3], v[2:3], v[28:29] op_sel_hi:[1,0]
	v_pk_mul_f32 v[44:45], v[4:5], v[28:29] op_sel_hi:[1,0]
	s_mov_b64 s[0:1], -1
	s_and_b64 vcc, exec, s[8:9]
	s_waitcnt vmcnt(0)
	v_pk_fma_f32 v[4:5], v[2:3], v[38:39], v[42:43]
	v_pk_fma_f32 v[2:3], v[44:45], v[36:37], v[40:41]
	s_cbranch_vccz .LBB0_710
	v_cvt_pk_bf16_f32 v36, v2, v3
	v_bfe_u32 v29, v4, 16, 1
	v_add3_u32 v29, v4, v29, s33
	v_bfe_u32 v35, v5, 16, 1
	v_lshrrev_b32_e32 v29, 16, v29
	v_add3_u32 v35, v5, v35, s33
	v_add_co_u32_e32 v38, vcc, 0x3d00000, v14
	v_cvt_pk_bf16_f32 v37, v4, v5
	s_nop 0
	v_addc_co_u32_e32 v39, vcc, 0, v15, vcc
	flat_store_dwordx2 v[38:39], v[36:37]
	s_mov_b64 s[0:1], 0

; __device__ __forceinline__ unsigned pk2(float lo, float hi) { return f2bf(lo) | (f2bf(hi) << 16); }
; template <int NR>
; __device__ __forceinline__ void ln_rows(const _Float16* z, bf16* xb, float* st, float* outf, int m0, int stride, const float* g, const float* b, int lane, bool final_out) {
;     ...
;     for (int r = 0; r < NR; ++r) { const int m = m0 + r * stride; const float rstd = 1.f / sqrtf(s2[r] * (1.f / D) + LN_EPS);
;         if (!final_out && lane == 0) *(f32x2*)(st + 2 * (size_t)m) = (f32x2){mean[r], rstd};
;         f32x4* xr = (f32x4*)(outf + (size_t)m * D) + lane; unsigned long long* o8 = (unsigned long long*)(xb + (size_t)m * D) + lane;
; #pragma unroll
;         for (int j = 0; j < 4; ++j) { const f32x4 gg = ((const f32x4*)g)[lane + 64 * j], bb = ((const f32x4*)b)[lane + 64 * j];
;             const f32x4 y = v[r][j] * rstd * gg + bb;
;             if (final_out) xr[64 * j] = y;
;             else o8[64 * j] = (unsigned long long)pk2(y.x, y.y) | ((unsigned long long)pk2(y.z, y.w) << 32); } }
.LBB0_712:
	global_load_dwordx4 v[2:5], v[8:9], off offset:1024
	s_nop 0
	global_load_dwordx4 v[36:39], v[10:11], off offset:1024
	v_mov_b32_e32 v40, v28
	v_mov_b32_e32 v41, v28
	v_mov_b32_e32 v29, v28
	v_pk_mul_f32 v[24:25], v[24:25], v[40:41]
	v_pk_mul_f32 v[26:27], v[26:27], v[28:29]
	s_mov_b64 s[44:45], -1
	s_andn2_b64 vcc, exec, s[8:9]
	s_waitcnt vmcnt(0)
	v_pk_fma_f32 v[4:5], v[24:25], v[4:5], v[38:39]
	v_cndmask_b32_e64 v24, 0, 1, s[8:9]
	v_pk_fma_f32 v[2:3], v[26:27], v[2:3], v[36:37]
	v_cmp_ne_u32_e64 s[0:1], 1, v24
	s_cbranch_vccnz .LBB0_714
	v_bfe_u32 v24, v2, 16, 1
	v_add3_u32 v24, v2, v24, s33
	v_bfe_u32 v25, v3, 16, 1
	v_lshrrev_b32_e32 v24, 16, v24
	v_cvt_pk_bf16_f32 v24, v2, v3
	v_add3_u32 v25, v4, v25, s33
	v_bfe_u32 v26, v5, 16, 1
	v_lshrrev_b32_e32 v25, 16, v25
	v_add3_u32 v26, v5, v26, s33
	v_cvt_pk_bf16_f32 v25, v4, v5
	v_add_co_u32_e32 v26, vcc, 0x3d00000, v14
	s_mov_b64 s[44:45], 0
	s_nop 0
	v_addc_co_u32_e32 v27, vcc, 0, v15, vcc
	flat_store_dwordx2 v[26:27], v[24:25] offset:512

; __device__ __forceinline__ unsigned pk2(float lo, float hi) { return f2bf(lo) | (f2bf(hi) << 16); }
; template <int NR>
; __device__ __forceinline__ void ln_rows(const _Float16* z, bf16* xb, float* st, float* outf, int m0, int stride, const float* g, const float* b, int lane, bool final_out) {
;     ...
;     for (int r = 0; r < NR; ++r) { const int m = m0 + r * stride; const float rstd = 1.f / sqrtf(s2[r] * (1.f / D) + LN_EPS);
;         if (!final_out && lane == 0) *(f32x2*)(st + 2 * (size_t)m) = (f32x2){mean[r], rstd};
;         f32x4* xr = (f32x4*)(outf + (size_t)m * D) + lane; unsigned long long* o8 = (unsigned long long*)(xb + (size_t)m * D) + lane;
; #pragma unroll
;         for (int j = 0; j < 4; ++j) { const f32x4 gg = ((const f32x4*)g)[lane + 64 * j], bb = ((const f32x4*)b)[lane + 64 * j];
;             const f32x4 y = v[r][j] * rstd * gg + bb;
;             if (final_out) xr[64 * j] = y;
;             else o8[64 * j] = (unsigned long long)pk2(y.x, y.y) | ((unsigned long long)pk2(y.z, y.w) << 32); } }
.LBB0_716:
	global_load_dwordx4 v[2:5], v[8:9], off offset:2048
	s_nop 0
	global_load_dwordx4 v[24:27], v[10:11], off offset:2048
	v_mov_b32_e32 v36, v28
	v_mov_b32_e32 v37, v28
	v_pk_mul_f32 v[22:23], v[22:23], v[28:29]
	v_pk_mul_f32 v[20:21], v[20:21], v[36:37]
	s_and_b64 vcc, exec, s[0:1]
	s_mov_b64 s[44:45], -1
	s_waitcnt vmcnt(0)
	v_pk_fma_f32 v[4:5], v[20:21], v[4:5], v[26:27]
	v_pk_fma_f32 v[2:3], v[22:23], v[2:3], v[24:25]
	s_cbranch_vccnz .LBB0_718
	v_cvt_pk_bf16_f32 v20, v2, v3
	v_add3_u32 v21, v4, v21, s33
	v_bfe_u32 v22, v5, 16, 1
	v_lshrrev_b32_e32 v21, 16, v21
	v_add3_u32 v22, v5, v22, s33
	v_cvt_pk_bf16_f32 v21, v4, v5
	v_add_co_u32_e32 v22, vcc, 0x3d00000, v14
	s_mov_b64 s[44:45], 0
	s_nop 0
	v_addc_co_u32_e32 v23, vcc, 0, v15, vcc
	flat_store_dwordx2 v[22:23], v[20:21] offset:1024

; __device__ __forceinline__ unsigned pk2(float lo, float hi) { return f2bf(lo) | (f2bf(hi) << 16); }
; template <int NR>
; __device__ __forceinline__ void ln_rows(const _Float16* z, bf16* xb, float* st, float* outf, int m0, int stride, const float* g, const float* b, int lane, bool final_out) {
;     ...
;     for (int r = 0; r < NR; ++r) { const int m = m0 + r * stride; const float rstd = 1.f / sqrtf(s2[r] * (1.f / D) + LN_EPS);
;         if (!final_out && lane == 0) *(f32x2*)(st + 2 * (size_t)m) = (f32x2){mean[r], rstd};
;         f32x4* xr = (f32x4*)(outf + (size_t)m * D) + lane; unsigned long long* o8 = (unsigned long long*)(xb + (size_t)m * D) + lane;
; #pragma unroll
;         for (int j = 0; j < 4; ++j) { const f32x4 gg = ((const f32x4*)g)[lane + 64 * j], bb = ((const f32x4*)b)[lane + 64 * j];
;             const f32x4 y = v[r][j] * rstd * gg + bb;
;             if (final_out) xr[64 * j] = y;
;             else o8[64 * j] = (unsigned long long)pk2(y.x, y.y) | ((unsigned long long)pk2(y.z, y.w) << 32); } }
.LBB0_720:
	global_load_dwordx4 v[2:5], v[8:9], off offset:3072
	s_nop 0
	global_load_dwordx4 v[20:23], v[10:11], off offset:3072
	v_mov_b32_e32 v24, v28
	v_mov_b32_e32 v25, v28
	v_pk_mul_f32 v[18:19], v[18:19], v[28:29]
	v_pk_mul_f32 v[16:17], v[16:17], v[24:25]
	s_and_b64 vcc, exec, s[0:1]
	s_mov_b64 s[0:1], -1
	s_waitcnt vmcnt(0)
	v_pk_fma_f32 v[4:5], v[16:17], v[4:5], v[22:23]
	v_pk_fma_f32 v[2:3], v[18:19], v[2:3], v[20:21]
	s_cbranch_vccnz .LBB0_722
	v_cvt_pk_bf16_f32 v16, v2, v3
	v_bfe_u32 v17, v4, 16, 1
	v_add3_u32 v17, v4, v17, s33
	v_bfe_u32 v18, v5, 16, 1
	v_lshrrev_b32_e32 v17, 16, v17
	v_add3_u32 v18, v5, v18, s33
	v_add_co_u32_e32 v14, vcc, 0x3d00000, v14
	v_cvt_pk_bf16_f32 v17, v4, v5
	s_nop 0
	v_addc_co_u32_e32 v15, vcc, 0, v15, vcc
	s_mov_b64 s[0:1], 0
	flat_store_dwordx2 v[14:15], v[16:17] offset:1536

; #define LAS __attribute__((address_space(3)))
; __device__ __forceinline__ void cvt_item(const float* W, int ldw, bf16* WT, int pitch, int drow0, int k0, int n0, LAS float* scr, int lane) {
;     float wv[32];
; #pragma unroll
;     for (int i = 0; i < 32; ++i) wv[i] = W[(size_t)(k0 + 2 * i + (lane >> 5)) * ldw + n0 + (lane & 31)];
; #pragma unroll
;     for (int i = 0; i < 32; ++i) scr[(2 * i + (lane >> 5)) * 33 + (lane & 31)] = wv[i];
; __device__ __forceinline__ void cvt_weights(const Params& p, int L, LAS unsigned char* lds, int gw, int ngw, int wave, int lane) {
;     ...
;         else { r -= 512; const int mi = r >> 1; r &= 1; const int g = mi / 24, dir = (mi % 24) / 12, blk = mi % 12;
;             src = (g ? p.lru_wx : p.lru_wa) + (size_t)((L * 2 + dir) * 12 + blk) * 4096; ldw = 64; K = 64; Nc = 64; dst = WT + WT_LRU + (size_t)(((dir * 12 + blk) * 2 + g) * 64) * 64; pitch = 64; }
;         const int nblk = Nc / 32, kb = r / nblk, nb = r % nblk;
;         const int n0 = 32 * nb, drow0 = gu < 0 ? n0 : (n0 >> 7) * 256 + (n0 & 127) + gu * 128;
;         cvt_item(src, ldw, dst, pitch, drow0, 64 * kb, n0, scr, lane);
.LBB0_732:
	v_cvt_f32_u32_e32 v3, s39
	s_sub_i32 s41, 0, s39
	s_abs_i32 s40, s37
	s_ashr_i32 s13, s37, 31
	v_rcp_iflag_f32_e32 v3, v3
	s_nop 0
	v_mul_f32_e32 v3, 0x4f7ffffe, v3
	v_cvt_u32_f32_e32 v3, v3
	s_nop 0
	v_readfirstlane_b32 s42, v3
	s_mul_i32 s41, s41, s42
	s_mul_hi_u32 s41, s42, s41
	s_add_i32 s42, s42, s41
	s_mul_hi_u32 s41, s40, s42
	s_mul_i32 s42, s41, s39
	s_sub_i32 s40, s40, s42
	s_add_i32 s42, s41, 1
	s_sub_i32 s43, s40, s39
	s_cmp_ge_u32 s40, s39
	s_cselect_b32 s41, s42, s41
	s_cselect_b32 s40, s43, s40
	s_add_i32 s42, s41, 1
	s_cmp_ge_u32 s40, s39
	s_cselect_b32 s40, s42, s41
	s_xor_b32 s40, s40, s13
	s_sub_i32 s13, s40, s13
	s_mul_i32 s39, s13, s39
	s_sub_i32 s37, s37, s39
	s_lshl_b32 s40, s37, 5
	s_lshl_b32 s37, s37, 6
	s_and_b32 s39, s40, 0x60
	s_lshl_b32 s41, s12, 7
	s_and_b32 s37, s37, 0xffffff00
	s_or_b32 s39, s39, s41
	s_add_i32 s39, s39, s37
	s_cmp_lt_i32 s12, 0
	s_cselect_b32 s37, s40, s39
	s_ashr_i32 s41, s40, 31
	s_lshl_b32 s12, s13, 6
	s_lshl_b64 s[40:41], s[40:41], 2
	s_add_u32 s8, s8, s40
	v_or_b32_e32 v5, s12, v1
	s_addc_u32 s9, s9, s41
	v_mov_b32_e32 v3, v0
	s_ashr_i32 s13, s12, 31
	v_lshl_add_u64 v[6:7], s[8:9], 0, v[2:3]
	s_mul_i32 s8, s6, s13
	v_mul_lo_u32 v3, s7, v5
	v_mad_u64_u32 v[14:15], s[40:41], s6, v5, 0
	v_add3_u32 v15, v15, s8, v3
	v_lshl_add_u64 v[14:15], v[14:15], 2, v[6:7]
	global_load_dword v3, v[14:15], off
	v_or_b32_e32 v14, 2, v5
	v_mul_lo_u32 v16, s7, v14
	v_mad_u64_u32 v[14:15], s[40:41], s6, v14, 0
	v_add3_u32 v15, v15, s8, v16
	v_lshl_add_u64 v[14:15], v[14:15], 2, v[6:7]
	global_load_dword v16, v[14:15], off
	v_or_b32_e32 v14, 4, v5
	v_mul_lo_u32 v17, s7, v14
	v_mad_u64_u32 v[14:15], s[40:41], s6, v14, 0
	v_add3_u32 v15, v15, s8, v17
	v_lshl_add_u64 v[14:15], v[14:15], 2, v[6:7]
	global_load_dword v17, v[14:15], off
	v_or_b32_e32 v14, 6, v5
	v_mul_lo_u32 v18, s7, v14
	v_mad_u64_u32 v[14:15], s[40:41], s6, v14, 0
	v_add3_u32 v15, v15, s8, v18
	v_lshl_add_u64 v[14:15], v[14:15], 2, v[6:7]
	global_load_dword v18, v[14:15], off
	v_or_b32_e32 v14, 8, v5
	v_mul_lo_u32 v19, s7, v14
	v_mad_u64_u32 v[14:15], s[40:41], s6, v14, 0
	v_add3_u32 v15, v15, s8, v19
	v_lshl_add_u64 v[14:15], v[14:15], 2, v[6:7]
	global_load_dword v19, v[14:15], off
	v_or_b32_e32 v14, 10, v5
	v_mul_lo_u32 v20, s7, v14
	v_mad_u64_u32 v[14:15], s[40:41], s6, v14, 0
	v_add3_u32 v15, v15, s8, v20
	v_lshl_add_u64 v[14:15], v[14:15], 2, v[6:7]
	global_load_dword v20, v[14:15], off
	v_or_b32_e32 v14, 12, v5
	v_mul_lo_u32 v21, s7, v14
	v_mad_u64_u32 v[14:15], s[40:41], s6, v14, 0
	v_add3_u32 v15, v15, s8, v21
	v_lshl_add_u64 v[14:15], v[14:15], 2, v[6:7]
	global_load_dword v21, v[14:15], off
	v_or_b32_e32 v14, 14, v5
	v_mul_lo_u32 v22, s7, v14
	v_mad_u64_u32 v[14:15], s[40:41], s6, v14, 0
	v_add3_u32 v15, v15, s8, v22
	v_lshl_add_u64 v[14:15], v[14:15], 2, v[6:7]
	global_load_dword v22, v[14:15], off
	v_or_b32_e32 v14, 16, v5
	v_mul_lo_u32 v23, s7, v14
	v_mad_u64_u32 v[14:15], s[40:41], s6, v14, 0
	v_add3_u32 v15, v15, s8, v23
	v_lshl_add_u64 v[14:15], v[14:15], 2, v[6:7]
	global_load_dword v23, v[14:15], off
	v_or_b32_e32 v14, 18, v5
	v_mul_lo_u32 v24, s7, v14
	v_mad_u64_u32 v[14:15], s[40:41], s6, v14, 0
	v_add3_u32 v15, v15, s8, v24
	v_lshl_add_u64 v[14:15], v[14:15], 2, v[6:7]
	global_load_dword v24, v[14:15], off
	v_or_b32_e32 v14, 20, v5
	v_mul_lo_u32 v25, s7, v14
	v_mad_u64_u32 v[14:15], s[40:41], s6, v14, 0
	v_add3_u32 v15, v15, s8, v25
	v_lshl_add_u64 v[14:15], v[14:15], 2, v[6:7]
	global_load_dword v25, v[14:15], off
	v_or_b32_e32 v14, 22, v5
	v_mul_lo_u32 v26, s7, v14
	v_mad_u64_u32 v[14:15], s[40:41], s6, v14, 0
	v_add3_u32 v15, v15, s8, v26
	v_lshl_add_u64 v[14:15], v[14:15], 2, v[6:7]
	global_load_dword v26, v[14:15], off
	v_or_b32_e32 v14, 24, v5
	v_mul_lo_u32 v27, s7, v14
	v_mad_u64_u32 v[14:15], s[40:41], s6, v14, 0
	v_add3_u32 v15, v15, s8, v27
	v_lshl_add_u64 v[14:15], v[14:15], 2, v[6:7]
	global_load_dword v27, v[14:15], off
	v_or_b32_e32 v14, 26, v5
	v_mul_lo_u32 v28, s7, v14
	v_mad_u64_u32 v[14:15], s[40:41], s6, v14, 0
	v_add3_u32 v15, v15, s8, v28
	v_lshl_add_u64 v[14:15], v[14:15], 2, v[6:7]
	global_load_dword v28, v[14:15], off
	v_or_b32_e32 v14, 28, v5
	v_mul_lo_u32 v29, s7, v14
	v_mad_u64_u32 v[14:15], s[40:41], s6, v14, 0
	v_add3_u32 v15, v15, s8, v29
	v_lshl_add_u64 v[14:15], v[14:15], 2, v[6:7]
	global_load_dword v29, v[14:15], off
	v_or_b32_e32 v14, 30, v5
	v_mul_lo_u32 v30, s7, v14
	v_mad_u64_u32 v[14:15], s[40:41], s6, v14, 0
	v_add3_u32 v15, v15, s8, v30
	v_lshl_add_u64 v[14:15], v[14:15], 2, v[6:7]
	global_load_dword v30, v[14:15], off
	v_or_b32_e32 v14, 32, v5
	v_mul_lo_u32 v31, s7, v14
	v_mad_u64_u32 v[14:15], s[40:41], s6, v14, 0
	v_add3_u32 v15, v15, s8, v31
	v_lshl_add_u64 v[14:15], v[14:15], 2, v[6:7]
	global_load_dword v31, v[14:15], off
	v_or_b32_e32 v14, 34, v5
	v_mul_lo_u32 v32, s7, v14
	v_mad_u64_u32 v[14:15], s[40:41], s6, v14, 0
	v_add3_u32 v15, v15, s8, v32
	v_lshl_add_u64 v[14:15], v[14:15], 2, v[6:7]
	global_load_dword v32, v[14:15], off
	v_or_b32_e32 v14, 36, v5
	v_mul_lo_u32 v33, s7, v14
	v_mad_u64_u32 v[14:15], s[40:41], s6, v14, 0
	v_add3_u32 v15, v15, s8, v33
	v_lshl_add_u64 v[14:15], v[14:15], 2, v[6:7]
	global_load_dword v33, v[14:15], off
	v_or_b32_e32 v14, 38, v5
	v_mul_lo_u32 v34, s7, v14
	v_mad_u64_u32 v[14:15], s[40:41], s6, v14, 0
	v_add3_u32 v15, v15, s8, v34
	v_lshl_add_u64 v[14:15], v[14:15], 2, v[6:7]
	global_load_dword v34, v[14:15], off
	v_or_b32_e32 v14, 40, v5
	v_mul_lo_u32 v35, s7, v14
	v_mad_u64_u32 v[14:15], s[40:41], s6, v14, 0
	v_add3_u32 v15, v15, s8, v35
	v_lshl_add_u64 v[14:15], v[14:15], 2, v[6:7]
	global_load_dword v35, v[14:15], off
; #define LAS __attribute__((address_space(3)))
; __device__ __forceinline__ unsigned pk2(float lo, float hi) { return f2bf(lo) | (f2bf(hi) << 16); }
; #define LDS_WAIT() asm volatile("s_waitcnt lgkmcnt(0)" ::: "memory")
; __device__ __forceinline__ void cvt_item(const float* W, int ldw, bf16* WT, int pitch, int drow0, int k0, int n0, LAS float* scr, int lane) {
;     float wv[32];
; #pragma unroll
;     for (int i = 0; i < 32; ++i) wv[i] = W[(size_t)(k0 + 2 * i + (lane >> 5)) * ldw + n0 + (lane & 31)];
; #pragma unroll
;     for (int i = 0; i < 32; ++i) scr[(2 * i + (lane >> 5)) * 33 + (lane & 31)] = wv[i];
;     LDS_WAIT(); asm volatile("" ::: "memory");
;     const int c = lane & 7;
; #pragma unroll
;     for (int j = 0; j < 4; ++j) { const int n = (lane >> 3) + 8 * j; const LAS float* s = scr + (8 * c) * 33 + n;
;         v4u o; o.x = pk2(s[0 * 33], s[1 * 33]); o.y = pk2(s[2 * 33], s[3 * 33]); o.z = pk2(s[4 * 33], s[5 * 33]); o.w = pk2(s[6 * 33], s[7 * 33]);
;         *(v4u*)(WT + (size_t)(drow0 + n) * pitch + k0 + 8 * c) = o; }
;     LDS_WAIT(); asm volatile("" ::: "memory");
; }
	v_or_b32_e32 v14, 42, v5
	v_mul_lo_u32 v36, s7, v14
	v_mad_u64_u32 v[14:15], s[40:41], s6, v14, 0
	v_add3_u32 v15, v15, s8, v36
	v_lshl_add_u64 v[14:15], v[14:15], 2, v[6:7]
	global_load_dword v36, v[14:15], off
	v_or_b32_e32 v14, 44, v5
	v_mul_lo_u32 v37, s7, v14
	v_mad_u64_u32 v[14:15], s[40:41], s6, v14, 0
	v_add3_u32 v15, v15, s8, v37
	v_lshl_add_u64 v[14:15], v[14:15], 2, v[6:7]
	global_load_dword v37, v[14:15], off
	v_or_b32_e32 v14, 46, v5
	v_mul_lo_u32 v38, s7, v14
	v_mad_u64_u32 v[14:15], s[40:41], s6, v14, 0
	v_add3_u32 v15, v15, s8, v38
	v_lshl_add_u64 v[14:15], v[14:15], 2, v[6:7]
	global_load_dword v38, v[14:15], off
	v_or_b32_e32 v14, 48, v5
	v_mul_lo_u32 v39, s7, v14
	v_mad_u64_u32 v[14:15], s[40:41], s6, v14, 0
	v_add3_u32 v15, v15, s8, v39
	v_lshl_add_u64 v[14:15], v[14:15], 2, v[6:7]
	global_load_dword v39, v[14:15], off
	v_or_b32_e32 v14, 50, v5
	v_mul_lo_u32 v40, s7, v14
	v_mad_u64_u32 v[14:15], s[40:41], s6, v14, 0
	v_add3_u32 v15, v15, s8, v40
	v_lshl_add_u64 v[14:15], v[14:15], 2, v[6:7]
	global_load_dword v40, v[14:15], off
	v_or_b32_e32 v14, 52, v5
	v_mul_lo_u32 v41, s7, v14
	v_mad_u64_u32 v[14:15], s[40:41], s6, v14, 0
	v_add3_u32 v15, v15, s8, v41
	v_lshl_add_u64 v[14:15], v[14:15], 2, v[6:7]
	global_load_dword v41, v[14:15], off
	v_or_b32_e32 v14, 54, v5
	v_mul_lo_u32 v42, s7, v14
	v_mad_u64_u32 v[14:15], s[40:41], s6, v14, 0
	v_add3_u32 v15, v15, s8, v42
	v_lshl_add_u64 v[14:15], v[14:15], 2, v[6:7]
	global_load_dword v42, v[14:15], off
	v_or_b32_e32 v14, 56, v5
	v_mul_lo_u32 v43, s7, v14
	v_mad_u64_u32 v[14:15], s[40:41], s6, v14, 0
	v_add3_u32 v15, v15, s8, v43
	v_lshl_add_u64 v[14:15], v[14:15], 2, v[6:7]
	global_load_dword v43, v[14:15], off
	v_or_b32_e32 v14, 58, v5
	v_mul_lo_u32 v44, s7, v14
	v_mad_u64_u32 v[14:15], s[40:41], s6, v14, 0
	v_add3_u32 v15, v15, s8, v44
	v_lshl_add_u64 v[14:15], v[14:15], 2, v[6:7]
	global_load_dword v44, v[14:15], off
	v_or_b32_e32 v14, 60, v5
	v_mul_lo_u32 v45, s7, v14
	v_mad_u64_u32 v[14:15], s[40:41], s6, v14, 0
	v_add3_u32 v15, v15, s8, v45
	v_lshl_add_u64 v[14:15], v[14:15], 2, v[6:7]
	v_or_b32_e32 v5, 62, v5
	global_load_dword v45, v[14:15], off
	v_mul_lo_u32 v46, s7, v5
	v_mad_u64_u32 v[14:15], s[6:7], s6, v5, 0
	v_add3_u32 v15, v15, s8, v46
	v_lshl_add_u64 v[6:7], v[14:15], 2, v[6:7]
	global_load_dword v5, v[6:7], off
	s_waitcnt vmcnt(0)
	ds_write2_b32 v13, v3, v16 offset1:66
	ds_write2_b32 v13, v17, v18 offset0:132 offset1:198
	v_add_u32_e32 v3, 0x400, v13
	ds_write2_b32 v3, v19, v20 offset0:8 offset1:74
	ds_write2_b32 v3, v21, v22 offset0:140 offset1:206
	v_add_u32_e32 v3, 0x800, v13
	ds_write2_b32 v3, v23, v24 offset0:16 offset1:82
	ds_write2_b32 v3, v25, v26 offset0:148 offset1:214
	v_add_u32_e32 v3, 0xc00, v13
	ds_write2_b32 v3, v27, v28 offset0:24 offset1:90
	ds_write2_b32 v3, v29, v30 offset0:156 offset1:222
	v_add_u32_e32 v3, 0x1000, v13
	ds_write2_b32 v3, v31, v32 offset0:32 offset1:98
	ds_write2_b32 v3, v33, v34 offset0:164 offset1:230
	v_add_u32_e32 v3, 0x1400, v13
	ds_write2_b32 v3, v35, v36 offset0:40 offset1:106
	ds_write2_b32 v3, v37, v38 offset0:172 offset1:238
	v_add_u32_e32 v3, 0x1800, v13
	ds_write2_b32 v3, v39, v40 offset0:48 offset1:114
	ds_write2_b32 v3, v41, v42 offset0:180 offset1:246
	v_add_u32_e32 v3, 0x1c00, v13
	ds_write2_b32 v3, v43, v44 offset0:56 offset1:122
	ds_write2_b32 v3, v45, v5 offset0:188 offset1:254
	s_waitcnt lgkmcnt(0)
	ds_read2_b32 v[18:19], v9 offset0:33 offset1:41
	ds_read2_b32 v[20:21], v9 offset1:8
	s_lshl_b64 s[6:7], s[12:13], 1
	s_add_u32 s4, s4, s6
	ds_read2_b32 v[22:23], v9 offset0:66 offset1:74
	ds_read2_b32 v[24:25], v9 offset0:99 offset1:107
	s_addc_u32 s5, s5, s7
	v_mov_b32_e32 v5, v0
	s_waitcnt lgkmcnt(2)
	v_lshl_add_u64 v[6:7], s[4:5], 0, v[4:5]
	ds_read2_b32 v[26:27], v9 offset0:132 offset1:140
	ds_read2_b32 v[28:29], v9 offset0:165 offset1:173
	v_cvt_pk_bf16_f32 v14, v20, v18
	s_waitcnt lgkmcnt(3)
	s_waitcnt lgkmcnt(2)
	ds_read2_b32 v[30:31], v9 offset0:198 offset1:206
	ds_read2_b32 v[32:33], v9 offset0:231 offset1:239
	v_cvt_pk_bf16_f32 v15, v22, v24
	s_waitcnt lgkmcnt(3)
	s_waitcnt lgkmcnt(2)
	v_cvt_pk_bf16_f32 v16, v26, v28
	s_waitcnt lgkmcnt(1)
	s_waitcnt lgkmcnt(0)
	v_bfe_u32 v5, v32, 16, 1
	v_lshrrev_b32_e32 v3, 16, v3
	v_add3_u32 v5, v32, v5, s33
	v_cvt_pk_bf16_f32 v17, v30, v32
	v_or_b32_e32 v3, s37, v8
	v_mad_u64_u32 v[34:35], s[4:5], s0, v3, 0
	s_ashr_i32 s4, s37, 31
	v_mul_lo_u32 v5, s1, v3
	s_mul_i32 s4, s0, s4
	v_bfe_u32 v3, v21, 16, 1
	v_add3_u32 v35, v35, s4, v5
	v_add3_u32 v3, v21, v3, s33
	v_bfe_u32 v5, v19, 16, 1
	v_lshl_add_u64 v[34:35], v[34:35], 1, v[6:7]
	v_lshrrev_b32_e32 v3, 16, v3
	v_add3_u32 v5, v19, v5, s33
	global_store_dwordx4 v[34:35], v[14:17], off
	s_add_i32 s38, s38, s14
	s_cmpk_gt_i32 s38, 0x36df
	v_cvt_pk_bf16_f32 v14, v21, v19
	v_bfe_u32 v3, v23, 16, 1
	v_add3_u32 v3, v23, v3, s33
	v_cvt_pk_bf16_f32 v15, v23, v25
	v_cvt_pk_bf16_f32 v16, v27, v29
	v_lshrrev_b32_e32 v3, 16, v3
	v_add3_u32 v5, v33, v5, s33
	v_cvt_pk_bf16_f32 v17, v31, v33
	v_or_b32_e32 v3, s37, v10
	v_mul_lo_u32 v5, s1, v3
	v_mad_u64_u32 v[18:19], s[6:7], s0, v3, 0
	v_add3_u32 v19, v19, s4, v5
	v_lshl_add_u64 v[18:19], v[18:19], 1, v[6:7]
	global_store_dwordx4 v[18:19], v[14:17], off
	ds_read2_b32 v[18:19], v9 offset0:16 offset1:24
	ds_read2_b32 v[20:21], v9 offset0:49 offset1:57
	ds_read2_b32 v[22:23], v9 offset0:82 offset1:90
	ds_read2_b32 v[24:25], v9 offset0:115 offset1:123
	ds_read2_b32 v[26:27], v9 offset0:148 offset1:156
	ds_read2_b32 v[28:29], v9 offset0:181 offset1:189
	ds_read2_b32 v[30:31], v9 offset0:214 offset1:222
	ds_read2_b32 v[32:33], v9 offset0:247 offset1:255
	s_waitcnt lgkmcnt(7)
	s_waitcnt lgkmcnt(6)
	v_cvt_pk_bf16_f32 v14, v18, v20
	s_waitcnt lgkmcnt(5)
	s_waitcnt lgkmcnt(4)
	v_cvt_pk_bf16_f32 v15, v22, v24
	s_waitcnt lgkmcnt(3)
	s_waitcnt lgkmcnt(2)
	v_cvt_pk_bf16_f32 v16, v26, v28
	s_waitcnt lgkmcnt(1)
	s_waitcnt lgkmcnt(0)
	v_lshrrev_b32_e32 v3, 16, v3
	v_add3_u32 v5, v32, v5, s33
	v_cvt_pk_bf16_f32 v17, v30, v32
	v_or_b32_e32 v3, s37, v11
	v_mul_lo_u32 v5, s1, v3
	v_mad_u64_u32 v[34:35], s[6:7], s0, v3, 0
	v_bfe_u32 v3, v19, 16, 1
	v_add3_u32 v35, v35, s4, v5
	v_add3_u32 v3, v19, v3, s33
	v_bfe_u32 v5, v21, 16, 1
	v_lshl_add_u64 v[34:35], v[34:35], 1, v[6:7]
	v_lshrrev_b32_e32 v3, 16, v3
	v_add3_u32 v5, v21, v5, s33
	global_store_dwordx4 v[34:35], v[14:17], off
	s_nop 1
	v_cvt_pk_bf16_f32 v14, v19, v21
	v_bfe_u32 v3, v23, 16, 1
	v_add3_u32 v3, v23, v3, s33
	v_bfe_u32 v5, v25, 16, 1
	v_lshrrev_b32_e32 v3, 16, v3
	v_cvt_pk_bf16_f32 v15, v23, v25
	v_cvt_pk_bf16_f32 v16, v27, v29
	v_lshrrev_b32_e32 v3, 16, v3
	v_add3_u32 v5, v33, v5, s33
	v_cvt_pk_bf16_f32 v17, v31, v33
	v_or_b32_e32 v3, s37, v12
	v_mul_lo_u32 v5, s1, v3
	v_mad_u64_u32 v[18:19], s[0:1], s0, v3, 0
	v_add3_u32 v19, v19, s4, v5
	v_lshl_add_u64 v[6:7], v[18:19], 1, v[6:7]
	global_store_dwordx4 v[6:7], v[14:17], off
	s_waitcnt lgkmcnt(0)
	s_cbranch_scc1 .LBB0_765

; #define LAS __attribute__((address_space(3)))
; __device__ __forceinline__ void cvt_item(const float* W, int ldw, bf16* WT, int pitch, int drow0, int k0, int n0, LAS float* scr, int lane) {
;     float wv[32];
; #pragma unroll
;     for (int i = 0; i < 32; ++i) wv[i] = W[(size_t)(k0 + 2 * i + (lane >> 5)) * ldw + n0 + (lane & 31)];
; #pragma unroll
;     for (int i = 0; i < 32; ++i) scr[(2 * i + (lane >> 5)) * 33 + (lane & 31)] = wv[i];
; __device__ __forceinline__ void cvt_weights(const Params& p, int L, LAS unsigned char* lds, int gw, int ngw, int wave, int lane) {
;     ...
;         else { r -= 512; const int mi = r >> 1; r &= 1; const int g = mi / 24, dir = (mi % 24) / 12, blk = mi % 12;
;             src = (g ? p.lru_wx : p.lru_wa) + (size_t)((L * 2 + dir) * 12 + blk) * 4096; ldw = 64; K = 64; Nc = 64; dst = WT + WT_LRU + (size_t)(((dir * 12 + blk) * 2 + g) * 64) * 64; pitch = 64; }
;         const int nblk = Nc / 32, kb = r / nblk, nb = r % nblk;
;         const int n0 = 32 * nb, drow0 = gu < 0 ? n0 : (n0 >> 7) * 256 + (n0 & 127) + gu * 128;
;         cvt_item(src, ldw, dst, pitch, drow0, 64 * kb, n0, scr, lane);
.LBB0_791:
	v_cvt_f32_u32_e32 v3, s38
	s_sub_i32 s40, 0, s38
	s_abs_i32 s39, s37
	s_ashr_i32 s13, s37, 31
	v_rcp_iflag_f32_e32 v3, v3
	s_nop 0
	v_mul_f32_e32 v3, 0x4f7ffffe, v3
	v_cvt_u32_f32_e32 v3, v3
	s_nop 0
	v_readfirstlane_b32 s41, v3
	s_mul_i32 s40, s40, s41
	s_mul_hi_u32 s40, s41, s40
	s_add_i32 s41, s41, s40
	s_mul_hi_u32 s40, s39, s41
	s_mul_i32 s41, s40, s38
	s_sub_i32 s39, s39, s41
	s_add_i32 s42, s40, 1
	s_sub_i32 s41, s39, s38
	s_cmp_ge_u32 s39, s38
	s_cselect_b32 s40, s42, s40
	s_cselect_b32 s39, s41, s39
	s_add_i32 s41, s40, 1
	s_cmp_ge_u32 s39, s38
	s_cselect_b32 s39, s41, s40
	s_xor_b32 s39, s39, s13
	s_sub_i32 s13, s39, s13
	s_mul_i32 s38, s13, s38
	s_sub_i32 s37, s37, s38
	s_lshl_b32 s38, s37, 5
	s_lshl_b32 s40, s12, 7
	s_lshl_b32 s37, s37, 6
	s_and_b32 s39, s38, 0x60
	s_and_b32 s37, s37, 0xffffff00
	s_or_b32 s39, s39, s40
	s_add_i32 s39, s39, s37
	s_cmp_lt_i32 s12, 0
	s_cselect_b32 s37, s38, s39
	s_ashr_i32 s39, s38, 31
	s_lshl_b32 s12, s13, 6
	s_lshl_b64 s[38:39], s[38:39], 2
	s_add_u32 s8, s8, s38
	v_or_b32_e32 v5, s12, v1
	s_addc_u32 s9, s9, s39
	v_mov_b32_e32 v3, v0
	s_ashr_i32 s13, s12, 31
	v_lshl_add_u64 v[6:7], s[8:9], 0, v[2:3]
	s_mul_i32 s8, s6, s13
	v_mul_lo_u32 v3, s7, v5
	v_mad_u64_u32 v[14:15], s[38:39], s6, v5, 0
	v_add3_u32 v15, v15, s8, v3
	v_or_b32_e32 v3, 2, v5
	v_mul_lo_u32 v18, s7, v3
	v_mad_u64_u32 v[16:17], s[38:39], s6, v3, 0
	v_or_b32_e32 v3, 4, v5
	v_add3_u32 v17, v17, s8, v18
	v_mul_lo_u32 v20, s7, v3
	v_mad_u64_u32 v[18:19], s[38:39], s6, v3, 0
	v_or_b32_e32 v3, 6, v5
	v_add3_u32 v19, v19, s8, v20
	v_mul_lo_u32 v22, s7, v3
	v_mad_u64_u32 v[20:21], s[38:39], s6, v3, 0
	v_or_b32_e32 v3, 8, v5
	v_add3_u32 v21, v21, s8, v22
	v_mul_lo_u32 v24, s7, v3
	v_mad_u64_u32 v[22:23], s[38:39], s6, v3, 0
	v_or_b32_e32 v3, 10, v5
	v_add3_u32 v23, v23, s8, v24
	v_mul_lo_u32 v26, s7, v3
	v_mad_u64_u32 v[24:25], s[38:39], s6, v3, 0
	v_or_b32_e32 v3, 12, v5
	v_add3_u32 v25, v25, s8, v26
	v_mul_lo_u32 v28, s7, v3
	v_mad_u64_u32 v[26:27], s[38:39], s6, v3, 0
	v_or_b32_e32 v3, 14, v5
	v_add3_u32 v27, v27, s8, v28
	v_mul_lo_u32 v30, s7, v3
	v_mad_u64_u32 v[28:29], s[38:39], s6, v3, 0
	v_lshl_add_u64 v[14:15], v[14:15], 2, v[6:7]
	v_add3_u32 v29, v29, s8, v30
	v_lshl_add_u64 v[16:17], v[16:17], 2, v[6:7]
	v_lshl_add_u64 v[18:19], v[18:19], 2, v[6:7]
	v_lshl_add_u64 v[20:21], v[20:21], 2, v[6:7]
	v_lshl_add_u64 v[22:23], v[22:23], 2, v[6:7]
	v_lshl_add_u64 v[24:25], v[24:25], 2, v[6:7]
	v_lshl_add_u64 v[26:27], v[26:27], 2, v[6:7]
	v_lshl_add_u64 v[28:29], v[28:29], 2, v[6:7]
	global_load_dword v3, v[14:15], off
	global_load_dword v30, v[16:17], off
	global_load_dword v31, v[18:19], off
	global_load_dword v32, v[20:21], off
	global_load_dword v33, v[22:23], off
	global_load_dword v34, v[24:25], off
	global_load_dword v35, v[26:27], off
	global_load_dword v36, v[28:29], off
	v_or_b32_e32 v14, 16, v5
	v_mul_lo_u32 v16, s7, v14
	v_mad_u64_u32 v[14:15], s[38:39], s6, v14, 0
	v_add3_u32 v15, v15, s8, v16
	v_or_b32_e32 v16, 18, v5
	v_mul_lo_u32 v18, s7, v16
	v_mad_u64_u32 v[16:17], s[38:39], s6, v16, 0
	v_add3_u32 v17, v17, s8, v18
	v_or_b32_e32 v18, 20, v5
	v_mul_lo_u32 v20, s7, v18
	v_mad_u64_u32 v[18:19], s[38:39], s6, v18, 0
	v_add3_u32 v19, v19, s8, v20
	v_or_b32_e32 v20, 22, v5
	v_mul_lo_u32 v22, s7, v20
	v_mad_u64_u32 v[20:21], s[38:39], s6, v20, 0
	v_add3_u32 v21, v21, s8, v22
	v_or_b32_e32 v22, 24, v5
	v_mul_lo_u32 v24, s7, v22
	v_mad_u64_u32 v[22:23], s[38:39], s6, v22, 0
	v_add3_u32 v23, v23, s8, v24
	v_or_b32_e32 v24, 26, v5
	v_mul_lo_u32 v26, s7, v24
	v_mad_u64_u32 v[24:25], s[38:39], s6, v24, 0
	v_add3_u32 v25, v25, s8, v26
	v_or_b32_e32 v26, 28, v5
	v_mul_lo_u32 v28, s7, v26
	v_mad_u64_u32 v[26:27], s[38:39], s6, v26, 0
	v_add3_u32 v27, v27, s8, v28
	v_or_b32_e32 v28, 30, v5
	v_mul_lo_u32 v37, s7, v28
	v_mad_u64_u32 v[28:29], s[38:39], s6, v28, 0
	v_lshl_add_u64 v[14:15], v[14:15], 2, v[6:7]
	v_add3_u32 v29, v29, s8, v37
	v_lshl_add_u64 v[16:17], v[16:17], 2, v[6:7]
	v_lshl_add_u64 v[18:19], v[18:19], 2, v[6:7]
	v_lshl_add_u64 v[20:21], v[20:21], 2, v[6:7]
	v_lshl_add_u64 v[22:23], v[22:23], 2, v[6:7]
	v_lshl_add_u64 v[24:25], v[24:25], 2, v[6:7]
	v_lshl_add_u64 v[26:27], v[26:27], 2, v[6:7]
	v_lshl_add_u64 v[28:29], v[28:29], 2, v[6:7]
	global_load_dword v37, v[14:15], off
	global_load_dword v38, v[16:17], off
	global_load_dword v39, v[18:19], off
	global_load_dword v40, v[20:21], off
	global_load_dword v41, v[22:23], off
	global_load_dword v42, v[24:25], off
	global_load_dword v43, v[26:27], off
	global_load_dword v44, v[28:29], off
	v_or_b32_e32 v14, 32, v5
	v_mul_lo_u32 v16, s7, v14
	v_mad_u64_u32 v[14:15], s[38:39], s6, v14, 0
	v_add3_u32 v15, v15, s8, v16
	v_or_b32_e32 v16, 34, v5
	v_mul_lo_u32 v18, s7, v16
	v_mad_u64_u32 v[16:17], s[38:39], s6, v16, 0
	v_add3_u32 v17, v17, s8, v18
	v_or_b32_e32 v18, 36, v5
	v_mul_lo_u32 v20, s7, v18
	v_mad_u64_u32 v[18:19], s[38:39], s6, v18, 0
	v_add3_u32 v19, v19, s8, v20
	v_or_b32_e32 v20, 38, v5
	v_mul_lo_u32 v22, s7, v20
	v_mad_u64_u32 v[20:21], s[38:39], s6, v20, 0
	v_add3_u32 v21, v21, s8, v22
	v_or_b32_e32 v22, 40, v5
	v_mul_lo_u32 v24, s7, v22
	v_mad_u64_u32 v[22:23], s[38:39], s6, v22, 0
	v_add3_u32 v23, v23, s8, v24
	v_or_b32_e32 v24, 42, v5
	v_mul_lo_u32 v26, s7, v24
	v_mad_u64_u32 v[24:25], s[38:39], s6, v24, 0
	v_add3_u32 v25, v25, s8, v26
	v_or_b32_e32 v26, 44, v5
	v_mul_lo_u32 v28, s7, v26
	v_mad_u64_u32 v[26:27], s[38:39], s6, v26, 0
	v_add3_u32 v27, v27, s8, v28
	v_or_b32_e32 v28, 46, v5
	v_mul_lo_u32 v45, s7, v28
	v_mad_u64_u32 v[28:29], s[38:39], s6, v28, 0
	v_lshl_add_u64 v[14:15], v[14:15], 2, v[6:7]
	v_add3_u32 v29, v29, s8, v45
; #define LAS __attribute__((address_space(3)))
; __device__ __forceinline__ unsigned pk2(float lo, float hi) { return f2bf(lo) | (f2bf(hi) << 16); }
; #define LDS_WAIT() asm volatile("s_waitcnt lgkmcnt(0)" ::: "memory")
; __device__ __forceinline__ void cvt_item(const float* W, int ldw, bf16* WT, int pitch, int drow0, int k0, int n0, LAS float* scr, int lane) {
;     float wv[32];
; #pragma unroll
;     for (int i = 0; i < 32; ++i) wv[i] = W[(size_t)(k0 + 2 * i + (lane >> 5)) * ldw + n0 + (lane & 31)];
; #pragma unroll
;     for (int i = 0; i < 32; ++i) scr[(2 * i + (lane >> 5)) * 33 + (lane & 31)] = wv[i];
;     LDS_WAIT(); asm volatile("" ::: "memory");
;     const int c = lane & 7;
; #pragma unroll
;     for (int j = 0; j < 4; ++j) { const int n = (lane >> 3) + 8 * j; const LAS float* s = scr + (8 * c) * 33 + n;
;         v4u o; o.x = pk2(s[0 * 33], s[1 * 33]); o.y = pk2(s[2 * 33], s[3 * 33]); o.z = pk2(s[4 * 33], s[5 * 33]); o.w = pk2(s[6 * 33], s[7 * 33]);
;         *(v4u*)(WT + (size_t)(drow0 + n) * pitch + k0 + 8 * c) = o; }
;     LDS_WAIT(); asm volatile("" ::: "memory");
; }
	v_lshl_add_u64 v[16:17], v[16:17], 2, v[6:7]
	v_lshl_add_u64 v[18:19], v[18:19], 2, v[6:7]
	v_lshl_add_u64 v[20:21], v[20:21], 2, v[6:7]
	v_lshl_add_u64 v[22:23], v[22:23], 2, v[6:7]
	v_lshl_add_u64 v[24:25], v[24:25], 2, v[6:7]
	v_lshl_add_u64 v[26:27], v[26:27], 2, v[6:7]
	v_lshl_add_u64 v[28:29], v[28:29], 2, v[6:7]
	global_load_dword v45, v[14:15], off
	global_load_dword v46, v[16:17], off
	global_load_dword v47, v[18:19], off
	global_load_dword v48, v[20:21], off
	global_load_dword v49, v[22:23], off
	global_load_dword v50, v[24:25], off
	global_load_dword v51, v[26:27], off
	global_load_dword v52, v[28:29], off
	v_or_b32_e32 v14, 48, v5
	v_mul_lo_u32 v16, s7, v14
	v_mad_u64_u32 v[14:15], s[38:39], s6, v14, 0
	v_add3_u32 v15, v15, s8, v16
	v_or_b32_e32 v16, 50, v5
	v_mul_lo_u32 v18, s7, v16
	v_mad_u64_u32 v[16:17], s[38:39], s6, v16, 0
	v_add3_u32 v17, v17, s8, v18
	v_or_b32_e32 v18, 52, v5
	v_mul_lo_u32 v20, s7, v18
	v_mad_u64_u32 v[18:19], s[38:39], s6, v18, 0
	v_add3_u32 v19, v19, s8, v20
	v_or_b32_e32 v20, 54, v5
	v_mul_lo_u32 v22, s7, v20
	v_mad_u64_u32 v[20:21], s[38:39], s6, v20, 0
	v_add3_u32 v21, v21, s8, v22
	v_or_b32_e32 v22, 56, v5
	v_mul_lo_u32 v24, s7, v22
	v_mad_u64_u32 v[22:23], s[38:39], s6, v22, 0
	v_add3_u32 v23, v23, s8, v24
	v_or_b32_e32 v24, 58, v5
	v_mul_lo_u32 v26, s7, v24
	v_mad_u64_u32 v[24:25], s[38:39], s6, v24, 0
	v_add3_u32 v25, v25, s8, v26
	v_or_b32_e32 v26, 60, v5
	v_mul_lo_u32 v28, s7, v26
	v_mad_u64_u32 v[26:27], s[38:39], s6, v26, 0
	v_or_b32_e32 v5, 62, v5
	v_add3_u32 v27, v27, s8, v28
	v_mul_lo_u32 v53, s7, v5
	v_mad_u64_u32 v[28:29], s[6:7], s6, v5, 0
	v_add3_u32 v29, v29, s8, v53
	v_lshl_add_u64 v[14:15], v[14:15], 2, v[6:7]
	v_lshl_add_u64 v[16:17], v[16:17], 2, v[6:7]
	v_lshl_add_u64 v[18:19], v[18:19], 2, v[6:7]
	v_lshl_add_u64 v[20:21], v[20:21], 2, v[6:7]
	v_lshl_add_u64 v[22:23], v[22:23], 2, v[6:7]
	v_lshl_add_u64 v[24:25], v[24:25], 2, v[6:7]
	v_lshl_add_u64 v[26:27], v[26:27], 2, v[6:7]
	v_lshl_add_u64 v[6:7], v[28:29], 2, v[6:7]
	global_load_dword v5, v[14:15], off
	s_nop 0
	global_load_dword v14, v[16:17], off
	global_load_dword v15, v[18:19], off
	s_nop 0
	global_load_dword v16, v[20:21], off
	global_load_dword v17, v[22:23], off
	global_load_dword v18, v[24:25], off
	global_load_dword v19, v[26:27], off
	s_nop 0
	global_load_dword v6, v[6:7], off
	s_waitcnt vmcnt(0)
	ds_write2_b32 v13, v3, v30 offset1:66
	ds_write2_b32 v13, v31, v32 offset0:132 offset1:198
	v_add_u32_e32 v3, 0x400, v13
	ds_write2_b32 v3, v33, v34 offset0:8 offset1:74
	ds_write2_b32 v3, v35, v36 offset0:140 offset1:206
	v_add_u32_e32 v3, 0x800, v13
	ds_write2_b32 v3, v37, v38 offset0:16 offset1:82
	ds_write2_b32 v3, v39, v40 offset0:148 offset1:214
	v_add_u32_e32 v3, 0xc00, v13
	ds_write2_b32 v3, v41, v42 offset0:24 offset1:90
	ds_write2_b32 v3, v43, v44 offset0:156 offset1:222
	v_add_u32_e32 v3, 0x1000, v13
	ds_write2_b32 v3, v45, v46 offset0:32 offset1:98
	ds_write2_b32 v3, v47, v48 offset0:164 offset1:230
	v_add_u32_e32 v3, 0x1400, v13
	ds_write2_b32 v3, v49, v50 offset0:40 offset1:106
	ds_write2_b32 v3, v51, v52 offset0:172 offset1:238
	v_add_u32_e32 v3, 0x1800, v13
	ds_write2_b32 v3, v5, v14 offset0:48 offset1:114
	ds_write2_b32 v3, v15, v16 offset0:180 offset1:246
	v_add_u32_e32 v3, 0x1c00, v13
	ds_write2_b32 v3, v17, v18 offset0:56 offset1:122
	ds_write2_b32 v3, v19, v6 offset0:188 offset1:254
	s_waitcnt lgkmcnt(0)
	ds_read2_b32 v[6:7], v9 offset1:8
	ds_read2_b32 v[20:21], v9 offset0:33 offset1:41
	s_lshl_b64 s[6:7], s[12:13], 1
	ds_read2_b32 v[22:23], v9 offset0:66 offset1:74
	s_add_u32 s4, s4, s6
	ds_read2_b32 v[24:25], v9 offset0:99 offset1:107
	s_addc_u32 s5, s5, s7
	v_mov_b32_e32 v5, v0
	s_waitcnt lgkmcnt(0)
	v_lshl_add_u64 v[18:19], s[4:5], 0, v[4:5]
	ds_read2_b32 v[26:27], v9 offset0:132 offset1:140
	ds_read2_b32 v[28:29], v9 offset0:165 offset1:173
	v_cvt_pk_bf16_f32 v14, v6, v20
	ds_read2_b32 v[30:31], v9 offset0:198 offset1:206
	ds_read2_b32 v[32:33], v9 offset0:231 offset1:239
	v_cvt_pk_bf16_f32 v15, v22, v24
	s_waitcnt lgkmcnt(3)
	s_waitcnt lgkmcnt(2)
	v_cvt_pk_bf16_f32 v16, v26, v28
	s_waitcnt lgkmcnt(1)
	s_waitcnt lgkmcnt(0)
	v_bfe_u32 v5, v32, 16, 1
	v_lshrrev_b32_e32 v3, 16, v3
	v_add3_u32 v5, v32, v5, s33
	v_cvt_pk_bf16_f32 v17, v30, v32
	v_or_b32_e32 v3, s37, v8
	v_mad_u64_u32 v[34:35], s[4:5], s0, v3, 0
	s_ashr_i32 s4, s37, 31
	v_mul_lo_u32 v5, s1, v3
	s_mul_i32 s6, s0, s4
	v_bfe_u32 v3, v7, 16, 1
	v_add3_u32 v35, v35, s6, v5
	v_add3_u32 v3, v7, v3, s33
	v_bfe_u32 v5, v21, 16, 1
	v_lshl_add_u64 v[34:35], v[34:35], 1, v[18:19]
	v_lshrrev_b32_e32 v3, 16, v3
	v_add3_u32 v5, v21, v5, s33
	global_store_dwordx4 v[34:35], v[14:17], off
	ds_read2_b32 v[20:21], v9 offset0:16 offset1:24
	s_add_i32 s15, s15, s14
	v_and_or_b32 v14, v5, s11, v3
	v_bfe_u32 v3, v23, 16, 1
	v_add3_u32 v3, v23, v3, s33
	v_cvt_pk_bf16_f32 v15, v23, v25
	v_cvt_pk_bf16_f32 v16, v27, v29
	v_lshrrev_b32_e32 v3, 16, v3
	v_add3_u32 v5, v33, v5, s33
	v_cvt_pk_bf16_f32 v17, v31, v33
	v_or_b32_e32 v3, s37, v10
	v_mul_lo_u32 v5, s1, v3
	v_mad_u64_u32 v[6:7], s[4:5], s0, v3, 0
	v_add3_u32 v7, v7, s6, v5
	v_lshl_add_u64 v[6:7], v[6:7], 1, v[18:19]
	global_store_dwordx4 v[6:7], v[14:17], off
	ds_read2_b32 v[6:7], v9 offset0:49 offset1:57
	ds_read2_b32 v[22:23], v9 offset0:82 offset1:90
	ds_read2_b32 v[24:25], v9 offset0:115 offset1:123
	s_waitcnt lgkmcnt(3)
	v_bfe_u32 v3, v20, 16, 1
	s_waitcnt lgkmcnt(2)
	ds_read2_b32 v[26:27], v9 offset0:148 offset1:156
	ds_read2_b32 v[28:29], v9 offset0:181 offset1:189
	v_cvt_pk_bf16_f32 v14, v20, v6
	s_waitcnt lgkmcnt(3)
	s_waitcnt lgkmcnt(2)
	ds_read2_b32 v[30:31], v9 offset0:214 offset1:222
	ds_read2_b32 v[32:33], v9 offset0:247 offset1:255
	v_cvt_pk_bf16_f32 v15, v22, v24
	s_waitcnt lgkmcnt(3)
	s_waitcnt lgkmcnt(2)
	v_cvt_pk_bf16_f32 v16, v26, v28
	s_waitcnt lgkmcnt(1)
	s_waitcnt lgkmcnt(0)
	v_lshrrev_b32_e32 v3, 16, v3
	v_add3_u32 v5, v32, v5, s33
	v_cvt_pk_bf16_f32 v17, v30, v32
	v_or_b32_e32 v3, s37, v11
	v_mul_lo_u32 v5, s1, v3
	v_mad_u64_u32 v[34:35], s[4:5], s0, v3, 0
	v_bfe_u32 v3, v21, 16, 1
	v_add3_u32 v35, v35, s6, v5
	v_add3_u32 v3, v21, v3, s33
	v_bfe_u32 v5, v7, 16, 1
	v_lshl_add_u64 v[34:35], v[34:35], 1, v[18:19]
	v_lshrrev_b32_e32 v3, 16, v3
	v_add3_u32 v5, v7, v5, s33
	global_store_dwordx4 v[34:35], v[14:17], off
	s_cmpk_lt_i32 s15, 0x36e0
	s_nop 0
	v_cvt_pk_bf16_f32 v14, v21, v7
	v_bfe_u32 v3, v23, 16, 1
	v_add3_u32 v3, v23, v3, s33
	v_bfe_u32 v5, v25, 16, 1
	v_lshrrev_b32_e32 v3, 16, v3
	v_cvt_pk_bf16_f32 v15, v23, v25
	v_cvt_pk_bf16_f32 v16, v27, v29
	v_lshrrev_b32_e32 v3, 16, v3
	v_add3_u32 v5, v33, v5, s33
	v_cvt_pk_bf16_f32 v17, v31, v33
	v_or_b32_e32 v3, s37, v12
	v_mul_lo_u32 v5, s1, v3
	v_mad_u64_u32 v[6:7], s[0:1], s0, v3, 0
	v_add3_u32 v7, v7, s6, v5
	v_lshl_add_u64 v[6:7], v[6:7], 1, v[18:19]
	global_store_dwordx4 v[6:7], v[14:17], off
	s_waitcnt lgkmcnt(0)
	s_cbranch_scc0 .LBB0_824

; __device__ __forceinline__ unsigned pk2(float lo, float hi) { return f2bf(lo) | (f2bf(hi) << 16); }
; __global__ void __launch_bounds__(NTHR, 2) fwd_kernel(Params p) {
;     ...
;               for (; m + 3 * ngw < T; m += 4 * ngw) { f32x4 v[4][4];
; #pragma unroll
;                   for (int r = 0; r < 4; ++r) { const int mm = m + r * ngw; const f32x4* xr = (const f32x4*)(mm < 16384 ? p.x_prompt + (size_t)mm * D : p.x_sample + (size_t)(mm - 16384) * D) + lane;
; #pragma unroll
;                       for (int j = 0; j < 4; ++j) v[r][j] = xr[64 * j]; }
; #pragma unroll
;                   for (int r = 0; r < 4; ++r) { unsigned long long* o8 = (unsigned long long*)(XB + (size_t)(m + r * ngw) * D) + lane;
; #pragma unroll
;                       for (int j = 0; j < 4; ++j) o8[64 * j] = (unsigned long long)pk2(v[r][j].x, v[r][j].y) | ((unsigned long long)pk2(v[r][j].z, v[r][j].w) << 32); } }
.LBB0_826:
	global_load_dwordx4 v[54:57], v1, s[44:45]
	global_load_dwordx4 v[58:61], v1, s[44:45] offset:1024
	global_load_dwordx4 v[62:65], v1, s[44:45] offset:2048
	global_load_dwordx4 v[66:69], v1, s[44:45] offset:3072
	s_waitcnt vmcnt(0)
	v_bfe_u32 v1, v46, 16, 1
	v_add3_u32 v1, v46, v1, s33
	v_bfe_u32 v46, v47, 16, 1
	v_lshrrev_b32_e32 v1, 16, v1
	v_add3_u32 v46, v47, v46, s33
	v_and_or_b32 v46, v46, s11, v1
	v_cvt_pk_bf16_f32 v47, v48, v49
	v_bfe_u32 v1, v42, 16, 1
	v_add3_u32 v1, v42, v1, s33
	v_bfe_u32 v42, v43, 16, 1
	v_lshrrev_b32_e32 v1, 16, v1
	v_add3_u32 v42, v43, v42, s33
	v_and_or_b32 v42, v42, s11, v1
	v_cvt_pk_bf16_f32 v43, v44, v45
	v_bfe_u32 v1, v38, 16, 1
	v_add3_u32 v1, v38, v1, s33
	v_bfe_u32 v38, v39, 16, 1
	v_lshrrev_b32_e32 v1, 16, v1
	v_add3_u32 v38, v39, v38, s33
	v_and_or_b32 v38, v38, s11, v1
	v_cvt_pk_bf16_f32 v39, v40, v41
	v_bfe_u32 v1, v30, 16, 1
	v_add3_u32 v1, v30, v1, s33
	v_bfe_u32 v30, v31, 16, 1
	v_lshrrev_b32_e32 v1, 16, v1
	v_add3_u32 v30, v31, v30, s33
	v_and_or_b32 v30, v30, s11, v1
	v_cvt_pk_bf16_f32 v31, v32, v33
	v_cvt_pk_bf16_f32 v32, v34, v35
	v_cvt_pk_bf16_f32 v33, v36, v37
	v_bfe_u32 v1, v26, 16, 1
	v_add3_u32 v1, v26, v1, s33
	v_bfe_u32 v26, v27, 16, 1
	v_lshrrev_b32_e32 v1, 16, v1
	v_add3_u32 v26, v27, v26, s33
	v_and_or_b32 v26, v26, s11, v1
	v_cvt_pk_bf16_f32 v27, v28, v29
	v_bfe_u32 v1, v22, 16, 1
	v_add3_u32 v1, v22, v1, s33
	v_bfe_u32 v22, v23, 16, 1
	v_lshrrev_b32_e32 v1, 16, v1
	v_add3_u32 v22, v23, v22, s33
	v_and_or_b32 v22, v22, s11, v1
	v_cvt_pk_bf16_f32 v23, v24, v25
	v_bfe_u32 v1, v14, 16, 1
	v_add3_u32 v1, v14, v1, s33
	v_bfe_u32 v14, v15, 16, 1
	v_lshrrev_b32_e32 v1, 16, v1
	v_add3_u32 v14, v15, v14, s33
	v_and_or_b32 v14, v14, s11, v1
	v_cvt_pk_bf16_f32 v15, v16, v17
	v_cvt_pk_bf16_f32 v16, v18, v19
	v_cvt_pk_bf16_f32 v17, v20, v21
	v_bfe_u32 v1, v10, 16, 1
	v_add3_u32 v1, v10, v1, s33
	v_bfe_u32 v10, v11, 16, 1
	v_lshrrev_b32_e32 v1, 16, v1
	v_add3_u32 v10, v11, v10, s33
	v_and_or_b32 v10, v10, s11, v1
	v_cvt_pk_bf16_f32 v11, v12, v13
	v_bfe_u32 v1, v6, 16, 1
	v_add3_u32 v1, v6, v1, s33
	v_bfe_u32 v6, v7, 16, 1
	v_lshrrev_b32_e32 v1, 16, v1
	v_add3_u32 v6, v7, v6, s33
	v_and_or_b32 v6, v6, s11, v1
	v_cvt_pk_bf16_f32 v7, v8, v9
	v_bfe_u32 v1, v2, 16, 1
	v_add3_u32 v1, v2, v1, s33
	v_bfe_u32 v2, v3, 16, 1
	v_lshrrev_b32_e32 v1, 16, v1
	v_add3_u32 v2, v3, v2, s33
	v_and_or_b32 v2, v2, s11, v1
	v_add3_u32 v1, v4, v1, s33
	v_bfe_u32 v3, v5, 16, 1
	v_lshl_add_u64 v[70:71], s[4:5], 0, v[50:51]
	v_lshrrev_b32_e32 v1, 16, v1
	v_add3_u32 v3, v5, v3, s33
	v_add_co_u32_e32 v48, vcc, s51, v70
	v_cvt_pk_bf16_f32 v3, v4, v5
	v_bfe_u32 v1, v54, 16, 1
	v_addc_co_u32_e32 v49, vcc, 0, v71, vcc
	v_add3_u32 v1, v54, v1, s33
	v_bfe_u32 v4, v55, 16, 1
	flat_store_dwordx2 v[48:49], v[30:31] offset:1536
	v_lshl_add_u64 v[30:31], s[12:13], 0, v[50:51]
	v_lshrrev_b32_e32 v1, 16, v1
	v_add3_u32 v4, v55, v4, s33
	v_add_co_u32_e32 v30, vcc, s51, v30
	v_cvt_pk_bf16_f32 v4, v54, v55
	v_bfe_u32 v1, v56, 16, 1
	v_addc_co_u32_e32 v31, vcc, 0, v31, vcc
	s_lshl_b64 s[42:43], s[42:43], 11
	v_add3_u32 v1, v56, v1, s33
	v_bfe_u32 v5, v57, 16, 1
	flat_store_dwordx2 v[48:49], v[46:47]
	flat_store_dwordx2 v[48:49], v[42:43] offset:512
	flat_store_dwordx2 v[48:49], v[38:39] offset:1024
	flat_store_dwordx2 v[30:31], v[14:15] offset:1536
	v_lshl_add_u64 v[14:15], v[52:53], 0, s[42:43]
	s_lshl_b64 s[40:41], s[40:41], 11
	flat_store_dwordx2 v[30:31], v[32:33]
	flat_store_dwordx2 v[30:31], v[26:27] offset:512
	flat_store_dwordx2 v[30:31], v[22:23] offset:1024
	flat_store_dwordx2 v[14:15], v[2:3] offset:1536
	v_lshl_add_u64 v[2:3], v[52:53], 0, s[40:41]
	v_cvt_pk_bf16_f32 v5, v56, v57
	flat_store_dwordx2 v[14:15], v[16:17]
	flat_store_dwordx2 v[2:3], v[4:5]
	v_cvt_pk_bf16_f32 v4, v58, v59
	v_cvt_pk_bf16_f32 v5, v60, v61
	flat_store_dwordx2 v[14:15], v[10:11] offset:512
	flat_store_dwordx2 v[2:3], v[4:5] offset:512
	v_cvt_pk_bf16_f32 v4, v62, v63
	s_add_i32 s48, s48, s0
	s_add_u32 s4, s4, s6
	v_cvt_pk_bf16_f32 v5, v64, v65
	s_addc_u32 s5, s5, s7
	flat_store_dwordx2 v[14:15], v[6:7] offset:1024
	flat_store_dwordx2 v[2:3], v[4:5] offset:1024
	s_add_u32 s38, s38, s0
	s_addc_u32 s39, s39, s1
	s_add_i32 s40, s48, 0x4000
	v_cvt_pk_bf16_f32 v4, v66, v67
	s_add_i32 s41, s40, s15
	s_add_u32 s12, s12, s6
	v_lshrrev_b32_e32 v1, 16, v1
	v_add3_u32 v5, v69, v5, s33
	s_addc_u32 s13, s13, s7
	v_cvt_pk_bf16_f32 v5, v68, v69
	s_cmpk_gt_i32 s41, 0x7fff
	flat_store_dwordx2 v[2:3], v[4:5] offset:1536
	s_cbranch_scc1 .LBB0_831

; __device__ __forceinline__ unsigned pk2(float lo, float hi) { return f2bf(lo) | (f2bf(hi) << 16); }
; __device__ __forceinline__ void cvt_row(const float* xrow, bf16* orow, int lane) {
;     const f32x4* xr = (const f32x4*)xrow + lane; unsigned long long* o8 = (unsigned long long*)orow + lane;
; #pragma unroll
;     for (int j = 0; j < 4; ++j) { const f32x4 v = xr[64 * j]; o8[64 * j] = (unsigned long long)pk2(v.x, v.y) | ((unsigned long long)pk2(v.z, v.w) << 32); }
; }
; __global__ void __launch_bounds__(NTHR, 2) fwd_kernel(Params p) {
;     ...
;               for (; m < T; m += ngw) cvt_row((m < 16384 ? p.x_prompt + (size_t)m * D : p.x_sample + (size_t)(m - 16384) * D), XB + (size_t)m * D, lane); }
.LBB0_833:
	global_load_dwordx4 v[4:7], v1, s[6:7]
	s_lshl_b64 s[8:9], s[8:9], 11
	v_lshl_add_u64 v[8:9], v[2:3], 0, s[8:9]
	s_add_u32 s40, s40, s14
	s_addc_u32 s41, s41, s15
	s_add_u32 s0, s0, s4
	s_addc_u32 s1, s1, s5
	s_cmp_lt_i32 s40, 0x8000
	s_waitcnt vmcnt(0)
	v_cvt_pk_bf16_f32 v4, v4, v5
	v_cvt_pk_bf16_f32 v5, v6, v7
	flat_store_dwordx2 v[8:9], v[4:5]
	global_load_dwordx4 v[4:7], v1, s[6:7] offset:1024
	s_waitcnt vmcnt(0)
	v_cvt_pk_bf16_f32 v4, v4, v5
	v_cvt_pk_bf16_f32 v5, v6, v7
	flat_store_dwordx2 v[8:9], v[4:5] offset:512
	global_load_dwordx4 v[4:7], v1, s[6:7] offset:2048
	s_waitcnt vmcnt(0)
	v_cvt_pk_bf16_f32 v4, v4, v5
	v_cvt_pk_bf16_f32 v5, v6, v7
	flat_store_dwordx2 v[8:9], v[4:5] offset:1024
	global_load_dwordx4 v[4:7], v1, s[6:7] offset:3072
	s_waitcnt vmcnt(0)
	v_bfe_u32 v10, v4, 16, 1
	v_bfe_u32 v12, v6, 16, 1
	v_bfe_u32 v11, v5, 16, 1
	v_bfe_u32 v13, v7, 16, 1
	v_add3_u32 v4, v4, v10, s33
	v_add3_u32 v6, v6, v12, s33
	v_add3_u32 v5, v5, v11, s33
	v_add3_u32 v7, v7, v13, s33
	v_lshrrev_b32_e32 v4, 16, v4
	v_lshrrev_b32_e32 v6, 16, v6
	v_and_or_b32 v4, v5, s11, v4
	v_and_or_b32 v5, v7, s11, v6
	flat_store_dwordx2 v[8:9], v[4:5] offset:1536
	s_cbranch_scc0 .LBB0_836

; __device__ __forceinline__ unsigned pk2(float lo, float hi) { return f2bf(lo) | (f2bf(hi) << 16); }
; __device__ __forceinline__ void cvt_row(const float* xrow, bf16* orow, int lane) {
;     const f32x4* xr = (const f32x4*)xrow + lane; unsigned long long* o8 = (unsigned long long*)orow + lane;
; #pragma unroll
;     for (int j = 0; j < 4; ++j) { const f32x4 v = xr[64 * j]; o8[64 * j] = (unsigned long long)pk2(v.x, v.y) | ((unsigned long long)pk2(v.z, v.w) << 32); }
; }
; __global__ void __launch_bounds__(NTHR, 2) fwd_kernel(Params p) {
;     ...
;             for (int m = gw; m < 2560; m += ngw) cvt_row((m < 512 ? p.mem_prompt + (size_t)m * D : p.mem_sample + (size_t)(m - 512) * D), MB + (size_t)m * D, lane);
.LBB0_838:
	global_load_dwordx4 v[4:7], v1, s[6:7]
	s_lshl_b64 s[8:9], s[8:9], 11
	v_lshl_add_u64 v[8:9], v[2:3], 0, s[8:9]
	s_add_u32 s36, s36, s14
	s_addc_u32 s37, s37, s15
	s_add_u32 s0, s0, s4
	s_addc_u32 s1, s1, s5
	s_cmpk_gt_i32 s36, 0x9ff
	s_waitcnt vmcnt(0)
	v_cvt_pk_bf16_f32 v4, v4, v5
	v_cvt_pk_bf16_f32 v5, v6, v7
	global_store_dwordx2 v[8:9], v[4:5], off
	global_load_dwordx4 v[4:7], v1, s[6:7] offset:1024
	s_waitcnt vmcnt(0)
	v_cvt_pk_bf16_f32 v4, v4, v5
	v_cvt_pk_bf16_f32 v5, v6, v7
	global_store_dwordx2 v[8:9], v[4:5], off offset:512
	global_load_dwordx4 v[4:7], v1, s[6:7] offset:2048
	s_waitcnt vmcnt(0)
	v_cvt_pk_bf16_f32 v4, v4, v5
	v_cvt_pk_bf16_f32 v5, v6, v7
	global_store_dwordx2 v[8:9], v[4:5], off offset:1024
	global_load_dwordx4 v[4:7], v1, s[6:7] offset:3072
	s_waitcnt vmcnt(0)
	v_bfe_u32 v10, v4, 16, 1
	v_bfe_u32 v12, v6, 16, 1
	v_bfe_u32 v11, v5, 16, 1
	v_bfe_u32 v13, v7, 16, 1
	v_add3_u32 v4, v4, v10, s33
	v_add3_u32 v6, v6, v12, s33
	v_add3_u32 v5, v5, v11, s33
	v_add3_u32 v7, v7, v13, s33
	v_lshrrev_b32_e32 v4, 16, v4
	v_lshrrev_b32_e32 v6, 16, v6
	v_and_or_b32 v4, v5, s11, v4
	v_and_or_b32 v5, v7, s11, v6
	global_store_dwordx2 v[8:9], v[4:5], off offset:1536
	s_cbranch_scc0 .LBB0_839
	s_getpc_b64 s[98:99]
